# GEMM mainloops: LDS-DMA loads with (SGPR base + VGPR offset) addresses use the saddr form, 64-bit VALU address adds removed (104 sites)
# baseline (speedup 1.0000x reference)
; #define PG8_STAGE(bufoff, gbase, voff) do { _Pragma("unroll") for (int _i = 0; _i < 2; ++_i) \
;         __builtin_amdgcn_global_load_lds((const unsigned*)((const char*)(gbase) + (voff)[_i]), (LAS unsigned*)(lds + (bufoff) + ldsw + _i * 8192), 16, 0, 0); } while (0)
; #define PG8_LDA(dst, b, h) do { _Pragma("unroll") for (int m = 0; m < 4; ++m) _Pragma("unroll") for (int k = 0; k < 2; ++k) dst[m][k] = *(const LAS bf16x8*)(lds + PG8_SA(b, h) + aoff + m * 2048 + k * 1024); } while (0)
; #define PG8_LDB(dst, b, h) do { _Pragma("unroll") for (int n = 0; n < 2; ++n) _Pragma("unroll") for (int k = 0; k < 2; ++k) dst[n][k] = *(const LAS bf16x8*)(lds + PG8_SB(b, h) + boff + n * 2048 + k * 1024); } while (0)
; #define PG8_MMA(ai, bj, At, Bt) do { __builtin_amdgcn_s_setprio(1); _Pragma("unroll") for (int m = 0; m < 4; ++m) _Pragma("unroll") for (int n = 0; n < 2; ++n) _Pragma("unroll") for (int k = 0; k < 2; ++k) \
;         acc[ai][bj][m][n] = __builtin_amdgcn_mfma_f32_16x16x32_bf16(Bt[n][k], At[m][k], acc[ai][bj][m][n], 0, 0, 0); __builtin_amdgcn_s_setprio(0); } while (0)
; #define PG8_WAIT_V(n) asm volatile("s_waitcnt vmcnt(" #n ")" ::: "memory")
; #define PG8_WAIT_L(n) asm volatile("s_waitcnt lgkmcnt(" #n ")" ::: "memory")
; #define PG8_BAR __builtin_amdgcn_s_barrier()
; #define PG8_SCHED __builtin_amdgcn_sched_barrier(0)
; template <class Epi>
; DEVI void gemm_phase(LAS unsigned char* lds, const Gemm g, const Epi& E) {
;     ...
;             const char* a1 = cA + (size_t)(t + 1) * kstep;
;             const char* a2 = last ? nA : cA + (size_t)(t + 2) * kstep; const char* b2 = last ? nB : cB + (size_t)(t + 2) * kstep;
;             const char* a3 = a2 + kstep; const char* b3 = b2 + kstep;
;             PG8_LDB(B0, 0, 0); PG8_SCHED; PG8_LDA(At, 0, 0); PG8_STAGE(PG8_SA(1, 1), a1 + hstepA, voffA);
;             PG8_WAIT_L(8); PG8_BAR; PG8_WAIT_L(0); PG8_MMA(0, 0, At, B0); PG8_BAR; PG8_SCHED;
;             PG8_LDB(B1, 0, 1); PG8_STAGE(PG8_SB(0, 0), b2, voffB);
;             PG8_BAR; PG8_WAIT_L(0); PG8_MMA(0, 1, At, B1); PG8_BAR;
;             PG8_LDA(At, 0, 1); PG8_STAGE(PG8_SA(0, 0), a2, voffA);
;             PG8_BAR; PG8_WAIT_L(0); PG8_MMA(1, 0, At, B0); PG8_BAR; PG8_SCHED;
;             PG8_STAGE(PG8_SB(0, 1), b2 + hstepB, voffB);
;             PG8_WAIT_V(6); PG8_BAR; PG8_MMA(1, 1, At, B1); PG8_BAR;
.LBB0_187:
	ds_read_b128 v[156:159], v150
	ds_read_b128 v[160:163], v150 offset:1024
	ds_read_b128 v[164:167], v150 offset:2048
	ds_read_b128 v[168:171], v150 offset:3072
	s_add_u32 s26, s0, 0xfffc0080
	s_addc_u32 s27, s1, -1
	s_cmp_eq_u32 s50, 12
	s_cselect_b32 s29, s13, s27
	s_cselect_b32 s28, s15, s26
	s_cselect_b32 s27, s19, s49
	s_cselect_b32 s26, s18, s17
	s_add_i32 m0, s38, 0xc000
	ds_read_b128 v[172:175], v151
	ds_read_b128 v[176:179], v151 offset:1024
	ds_read_b128 v[180:183], v151 offset:2048
	ds_read_b128 v[184:187], v151 offset:3072
	ds_read_b128 v[188:191], v151 offset:4096
	ds_read_b128 v[192:195], v151 offset:5120
	ds_read_b128 v[196:199], v151 offset:6144
	ds_read_b128 v[200:203], v151 offset:7168
	global_load_lds_dwordx4 v138, s[0:1]
	s_add_i32 m0, s38, 0xe000
	s_nop 0
	global_load_lds_dwordx4 v140, s[0:1]
	s_waitcnt lgkmcnt(8)
	s_barrier
	s_waitcnt lgkmcnt(0)
	v_mfma_f32_16x16x32_bf16 v[124:127], v[156:159], v[172:175], v[124:127]
	v_mfma_f32_16x16x32_bf16 v[120:123], v[164:167], v[172:175], v[120:123]
	v_mfma_f32_16x16x32_bf16 v[116:119], v[156:159], v[180:183], v[116:119]
	v_mfma_f32_16x16x32_bf16 v[108:111], v[164:167], v[180:183], v[108:111]
	v_mfma_f32_16x16x32_bf16 v[100:103], v[156:159], v[188:191], v[100:103]
	v_mfma_f32_16x16x32_bf16 v[96:99], v[164:167], v[188:191], v[96:99]
	v_mfma_f32_16x16x32_bf16 v[84:87], v[156:159], v[196:199], v[84:87]
	v_mfma_f32_16x16x32_bf16 v[80:83], v[164:167], v[196:199], v[80:83]
	v_mfma_f32_16x16x32_bf16 v[124:127], v[160:163], v[176:179], v[124:127]
	v_mfma_f32_16x16x32_bf16 v[120:123], v[168:171], v[176:179], v[120:123]
	v_mfma_f32_16x16x32_bf16 v[116:119], v[160:163], v[184:187], v[116:119]
	v_mfma_f32_16x16x32_bf16 v[108:111], v[168:171], v[184:187], v[108:111]
	v_mfma_f32_16x16x32_bf16 v[100:103], v[160:163], v[192:195], v[100:103]
	v_mfma_f32_16x16x32_bf16 v[96:99], v[168:171], v[192:195], v[96:99]
	v_mfma_f32_16x16x32_bf16 v[84:87], v[160:163], v[200:203], v[84:87]
	v_mfma_f32_16x16x32_bf16 v[80:83], v[168:171], v[200:203], v[80:83]
	s_barrier
	s_add_i32 s51, s46, s35
	v_lshl_add_u64 v[220:221], s[26:27], 0, v[130:131]
	s_mov_b32 m0, s51
	ds_read_b128 v[204:207], v152
	ds_read_b128 v[208:211], v152 offset:1024
	ds_read_b128 v[212:215], v152 offset:2048
	ds_read_b128 v[216:219], v152 offset:3072
	global_load_lds_dwordx4 v[220:221], off
	s_add_i32 m0, s51, 0x2000
	v_lshl_add_u64 v[222:223], s[26:27], 0, v[134:135]
	global_load_lds_dwordx4 v[222:223], off
	s_barrier
	s_waitcnt lgkmcnt(0)
	v_mfma_f32_16x16x32_bf16 v[112:115], v[204:207], v[172:175], v[112:115]
	v_mfma_f32_16x16x32_bf16 v[104:107], v[212:215], v[172:175], v[104:107]
	v_mfma_f32_16x16x32_bf16 v[92:95], v[204:207], v[180:183], v[92:95]
	v_mfma_f32_16x16x32_bf16 v[88:91], v[212:215], v[180:183], v[88:91]
	v_mfma_f32_16x16x32_bf16 v[76:79], v[204:207], v[188:191], v[76:79]
	v_mfma_f32_16x16x32_bf16 v[72:75], v[212:215], v[188:191], v[72:75]
	v_mfma_f32_16x16x32_bf16 v[68:71], v[204:207], v[196:199], v[68:71]
	v_mfma_f32_16x16x32_bf16 v[64:67], v[212:215], v[196:199], v[64:67]
	v_mfma_f32_16x16x32_bf16 v[112:115], v[208:211], v[176:179], v[112:115]
	v_mfma_f32_16x16x32_bf16 v[104:107], v[216:219], v[176:179], v[104:107]
	v_mfma_f32_16x16x32_bf16 v[92:95], v[208:211], v[184:187], v[92:95]
	v_mfma_f32_16x16x32_bf16 v[88:91], v[216:219], v[184:187], v[88:91]
	v_mfma_f32_16x16x32_bf16 v[76:79], v[208:211], v[192:195], v[76:79]
	v_mfma_f32_16x16x32_bf16 v[72:75], v[216:219], v[192:195], v[72:75]
	v_mfma_f32_16x16x32_bf16 v[68:71], v[208:211], v[200:203], v[68:71]
	v_mfma_f32_16x16x32_bf16 v[64:67], v[216:219], v[200:203], v[64:67]
	s_mov_b32 m0, s38
	v_lshl_add_u64 v[224:225], s[28:29], 0, v[128:129]
	s_barrier
	ds_read_b128 v[172:175], v151 offset:16384
	ds_read_b128 v[176:179], v151 offset:17408
	ds_read_b128 v[180:183], v151 offset:18432
	ds_read_b128 v[184:187], v151 offset:19456
	ds_read_b128 v[188:191], v151 offset:20480
	ds_read_b128 v[192:195], v151 offset:21504
	ds_read_b128 v[196:199], v151 offset:22528
	ds_read_b128 v[200:203], v151 offset:23552
	global_load_lds_dwordx4 v[224:225], off
	s_mov_b32 m0, s39
	v_lshl_add_u64 v[226:227], s[28:29], 0, v[132:133]
	global_load_lds_dwordx4 v[226:227], off
	s_barrier
	s_waitcnt lgkmcnt(0)
	v_mfma_f32_16x16x32_bf16 v[60:63], v[156:159], v[172:175], v[60:63]
	v_mfma_f32_16x16x32_bf16 v[56:59], v[164:167], v[172:175], v[56:59]
	v_mfma_f32_16x16x32_bf16 v[52:55], v[156:159], v[180:183], v[52:55]
	v_mfma_f32_16x16x32_bf16 v[48:51], v[164:167], v[180:183], v[48:51]
	v_mfma_f32_16x16x32_bf16 v[36:39], v[156:159], v[188:191], v[36:39]
	v_mfma_f32_16x16x32_bf16 v[32:35], v[164:167], v[188:191], v[32:35]
	v_mfma_f32_16x16x32_bf16 v[20:23], v[156:159], v[196:199], v[20:23]
	v_mfma_f32_16x16x32_bf16 v[16:19], v[164:167], v[196:199], v[16:19]
	v_mfma_f32_16x16x32_bf16 v[60:63], v[160:163], v[176:179], v[60:63]
	v_mfma_f32_16x16x32_bf16 v[56:59], v[168:171], v[176:179], v[56:59]
	v_mfma_f32_16x16x32_bf16 v[52:55], v[160:163], v[184:187], v[52:55]
	v_mfma_f32_16x16x32_bf16 v[48:51], v[168:171], v[184:187], v[48:51]
	v_mfma_f32_16x16x32_bf16 v[36:39], v[160:163], v[192:195], v[36:39]
	v_mfma_f32_16x16x32_bf16 v[32:35], v[168:171], v[192:195], v[32:35]
	v_mfma_f32_16x16x32_bf16 v[20:23], v[160:163], v[200:203], v[20:23]
	v_mfma_f32_16x16x32_bf16 v[16:19], v[168:171], v[200:203], v[16:19]
	s_barrier
	s_add_u32 s52, s26, 0x40000
	s_addc_u32 s53, s27, 0
	s_add_i32 s51, s47, s35
	s_mov_b32 m0, s51
	s_nop 0
	global_load_lds_dwordx4 v130, s[52:53]
	s_add_i32 m0, s51, 0x2000
	s_nop 0
	global_load_lds_dwordx4 v134, s[52:53]
	s_waitcnt vmcnt(6)
	s_barrier
; #define PG8_STAGE(bufoff, gbase, voff) do { _Pragma("unroll") for (int _i = 0; _i < 2; ++_i) \
;         __builtin_amdgcn_global_load_lds((const unsigned*)((const char*)(gbase) + (voff)[_i]), (LAS unsigned*)(lds + (bufoff) + ldsw + _i * 8192), 16, 0, 0); } while (0)
; #define PG8_LDA(dst, b, h) do { _Pragma("unroll") for (int m = 0; m < 4; ++m) _Pragma("unroll") for (int k = 0; k < 2; ++k) dst[m][k] = *(const LAS bf16x8*)(lds + PG8_SA(b, h) + aoff + m * 2048 + k * 1024); } while (0)
; #define PG8_LDB(dst, b, h) do { _Pragma("unroll") for (int n = 0; n < 2; ++n) _Pragma("unroll") for (int k = 0; k < 2; ++k) dst[n][k] = *(const LAS bf16x8*)(lds + PG8_SB(b, h) + boff + n * 2048 + k * 1024); } while (0)
; #define PG8_MMA(ai, bj, At, Bt) do { __builtin_amdgcn_s_setprio(1); _Pragma("unroll") for (int m = 0; m < 4; ++m) _Pragma("unroll") for (int n = 0; n < 2; ++n) _Pragma("unroll") for (int k = 0; k < 2; ++k) \
;         acc[ai][bj][m][n] = __builtin_amdgcn_mfma_f32_16x16x32_bf16(Bt[n][k], At[m][k], acc[ai][bj][m][n], 0, 0, 0); __builtin_amdgcn_s_setprio(0); } while (0)
; #define PG8_WAIT_V(n) asm volatile("s_waitcnt vmcnt(" #n ")" ::: "memory")
; #define PG8_WAIT_L(n) asm volatile("s_waitcnt lgkmcnt(" #n ")" ::: "memory")
; #define PG8_BAR __builtin_amdgcn_s_barrier()
; #define PG8_SCHED __builtin_amdgcn_sched_barrier(0)
; template <class Epi>
; DEVI void gemm_phase(LAS unsigned char* lds, const Gemm g, const Epi& E) {
;     ...
;             PG8_WAIT_V(6); PG8_BAR; PG8_MMA(1, 1, At, B1); PG8_BAR;
;             PG8_LDB(B0, 1, 0); PG8_SCHED; PG8_LDA(At, 1, 0); PG8_STAGE(PG8_SA(0, 1), a2 + hstepA, voffA);
;             PG8_WAIT_L(8); PG8_BAR; PG8_WAIT_L(0); PG8_MMA(0, 0, At, B0); PG8_BAR; PG8_SCHED;
;             PG8_LDB(B1, 1, 1); PG8_STAGE(PG8_SB(1, 0), b3, voffB);
;             PG8_BAR; PG8_WAIT_L(0); PG8_MMA(0, 1, At, B1); PG8_BAR;
;             PG8_LDA(At, 1, 1); PG8_STAGE(PG8_SA(1, 0), a3, voffA);
	v_mfma_f32_16x16x32_bf16 v[44:47], v[204:207], v[172:175], v[44:47]
	v_mfma_f32_16x16x32_bf16 v[40:43], v[212:215], v[172:175], v[40:43]
	v_mfma_f32_16x16x32_bf16 v[28:31], v[204:207], v[180:183], v[28:31]
	v_mfma_f32_16x16x32_bf16 v[24:27], v[212:215], v[180:183], v[24:27]
	v_mfma_f32_16x16x32_bf16 v[12:15], v[204:207], v[188:191], v[12:15]
	v_mfma_f32_16x16x32_bf16 v[8:11], v[212:215], v[188:191], v[8:11]
	v_mfma_f32_16x16x32_bf16 v[4:7], v[204:207], v[196:199], v[4:7]
	v_mfma_f32_16x16x32_bf16 v[0:3], v[212:215], v[196:199], v[0:3]
	v_mfma_f32_16x16x32_bf16 v[44:47], v[208:211], v[176:179], v[44:47]
	v_mfma_f32_16x16x32_bf16 v[40:43], v[216:219], v[176:179], v[40:43]
	v_mfma_f32_16x16x32_bf16 v[28:31], v[208:211], v[184:187], v[28:31]
	v_mfma_f32_16x16x32_bf16 v[24:27], v[216:219], v[184:187], v[24:27]
	v_mfma_f32_16x16x32_bf16 v[12:15], v[208:211], v[192:195], v[12:15]
	v_mfma_f32_16x16x32_bf16 v[8:11], v[216:219], v[192:195], v[8:11]
	v_mfma_f32_16x16x32_bf16 v[4:7], v[208:211], v[200:203], v[4:7]
	v_mfma_f32_16x16x32_bf16 v[0:3], v[216:219], v[200:203], v[0:3]
	s_add_i32 s51, 0, 0x18000
	v_add_u32_e32 v136, s51, v148
	s_barrier
	ds_read_b128 v[156:159], v136
	ds_read_b128 v[160:163], v136 offset:1024
	ds_read_b128 v[164:167], v136 offset:2048
	ds_read_b128 v[168:171], v136 offset:3072
	s_add_u32 s28, s28, 0x40000
	s_addc_u32 s29, s29, 0
	s_mov_b32 m0, s40
	ds_read_b128 v[172:175], v151 offset:32768
	ds_read_b128 v[176:179], v151 offset:33792
	ds_read_b128 v[180:183], v151 offset:34816
	ds_read_b128 v[184:187], v151 offset:35840
	ds_read_b128 v[188:191], v151 offset:36864
	ds_read_b128 v[192:195], v151 offset:37888
	ds_read_b128 v[196:199], v151 offset:38912
	ds_read_b128 v[200:203], v151 offset:39936
	global_load_lds_dwordx4 v128, s[28:29]
	s_mov_b32 m0, s41
	s_nop 0
	global_load_lds_dwordx4 v132, s[28:29]
	s_waitcnt lgkmcnt(8)
	s_barrier
	s_waitcnt lgkmcnt(0)
	v_mfma_f32_16x16x32_bf16 v[124:127], v[156:159], v[172:175], v[124:127]
	v_mfma_f32_16x16x32_bf16 v[120:123], v[164:167], v[172:175], v[120:123]
	v_mfma_f32_16x16x32_bf16 v[116:119], v[156:159], v[180:183], v[116:119]
	v_mfma_f32_16x16x32_bf16 v[108:111], v[164:167], v[180:183], v[108:111]
	v_mfma_f32_16x16x32_bf16 v[100:103], v[156:159], v[188:191], v[100:103]
	v_mfma_f32_16x16x32_bf16 v[96:99], v[164:167], v[188:191], v[96:99]
	v_mfma_f32_16x16x32_bf16 v[84:87], v[156:159], v[196:199], v[84:87]
	v_mfma_f32_16x16x32_bf16 v[80:83], v[164:167], v[196:199], v[80:83]
	v_mfma_f32_16x16x32_bf16 v[124:127], v[160:163], v[176:179], v[124:127]
	v_mfma_f32_16x16x32_bf16 v[120:123], v[168:171], v[176:179], v[120:123]
	v_mfma_f32_16x16x32_bf16 v[116:119], v[160:163], v[184:187], v[116:119]
	v_mfma_f32_16x16x32_bf16 v[108:111], v[168:171], v[184:187], v[108:111]
	v_mfma_f32_16x16x32_bf16 v[100:103], v[160:163], v[192:195], v[100:103]
	v_mfma_f32_16x16x32_bf16 v[96:99], v[168:171], v[192:195], v[96:99]
	v_mfma_f32_16x16x32_bf16 v[84:87], v[160:163], v[200:203], v[84:87]
	v_mfma_f32_16x16x32_bf16 v[80:83], v[168:171], v[200:203], v[80:83]
	s_barrier
	s_add_i32 s28, 0, 0x1c000
	s_add_i32 s29, s51, s35
	v_add_u32_e32 v136, s28, v148
	v_lshl_add_u64 v[220:221], v[220:221], 0, s[8:9]
	s_mov_b32 m0, s29
	ds_read_b128 v[204:207], v136
	ds_read_b128 v[208:211], v136 offset:1024
	ds_read_b128 v[212:215], v136 offset:2048
	ds_read_b128 v[216:219], v136 offset:3072
	global_load_lds_dwordx4 v[220:221], off
	s_add_i32 m0, s29, 0x2000
	v_lshl_add_u64 v[220:221], v[222:223], 0, s[8:9]
	global_load_lds_dwordx4 v[220:221], off
	s_barrier
	s_waitcnt lgkmcnt(0)
	v_mfma_f32_16x16x32_bf16 v[112:115], v[204:207], v[172:175], v[112:115]
	v_mfma_f32_16x16x32_bf16 v[104:107], v[212:215], v[172:175], v[104:107]
	v_mfma_f32_16x16x32_bf16 v[92:95], v[204:207], v[180:183], v[92:95]
	v_mfma_f32_16x16x32_bf16 v[88:91], v[212:215], v[180:183], v[88:91]
	v_mfma_f32_16x16x32_bf16 v[76:79], v[204:207], v[188:191], v[76:79]
	v_mfma_f32_16x16x32_bf16 v[72:75], v[212:215], v[188:191], v[72:75]
	v_mfma_f32_16x16x32_bf16 v[68:71], v[204:207], v[196:199], v[68:71]
	v_mfma_f32_16x16x32_bf16 v[64:67], v[212:215], v[196:199], v[64:67]
	v_mfma_f32_16x16x32_bf16 v[112:115], v[208:211], v[176:179], v[112:115]
	v_mfma_f32_16x16x32_bf16 v[104:107], v[216:219], v[176:179], v[104:107]
	v_mfma_f32_16x16x32_bf16 v[92:95], v[208:211], v[184:187], v[92:95]
	v_mfma_f32_16x16x32_bf16 v[88:91], v[216:219], v[184:187], v[88:91]
	v_mfma_f32_16x16x32_bf16 v[76:79], v[208:211], v[192:195], v[76:79]
	v_mfma_f32_16x16x32_bf16 v[72:75], v[216:219], v[192:195], v[72:75]
	v_mfma_f32_16x16x32_bf16 v[68:71], v[208:211], v[200:203], v[68:71]
	v_mfma_f32_16x16x32_bf16 v[64:67], v[216:219], v[200:203], v[64:67]
	s_mov_b32 m0, s44
	v_lshl_add_u64 v[220:221], v[224:225], 0, s[8:9]
	s_barrier
	ds_read_b128 v[172:175], v151 offset:49152
	ds_read_b128 v[176:179], v151 offset:50176
	ds_read_b128 v[180:183], v151 offset:51200
	ds_read_b128 v[184:187], v151 offset:52224
	ds_read_b128 v[188:191], v151 offset:53248
	ds_read_b128 v[192:195], v151 offset:54272
	ds_read_b128 v[196:199], v151 offset:55296
	ds_read_b128 v[200:203], v151 offset:56320
	global_load_lds_dwordx4 v[220:221], off
	s_mov_b32 m0, s45
	v_lshl_add_u64 v[220:221], v[226:227], 0, s[8:9]
	global_load_lds_dwordx4 v[220:221], off
	s_barrier
; #define PG8_STAGE(bufoff, gbase, voff) do { _Pragma("unroll") for (int _i = 0; _i < 2; ++_i) \
;         __builtin_amdgcn_global_load_lds((const unsigned*)((const char*)(gbase) + (voff)[_i]), (LAS unsigned*)(lds + (bufoff) + ldsw + _i * 8192), 16, 0, 0); } while (0)
; #define PG8_MMA(ai, bj, At, Bt) do { __builtin_amdgcn_s_setprio(1); _Pragma("unroll") for (int m = 0; m < 4; ++m) _Pragma("unroll") for (int n = 0; n < 2; ++n) _Pragma("unroll") for (int k = 0; k < 2; ++k) \
;         acc[ai][bj][m][n] = __builtin_amdgcn_mfma_f32_16x16x32_bf16(Bt[n][k], At[m][k], acc[ai][bj][m][n], 0, 0, 0); __builtin_amdgcn_s_setprio(0); } while (0)
; #define PG8_WAIT_V(n) asm volatile("s_waitcnt vmcnt(" #n ")" ::: "memory")
; #define PG8_WAIT_L(n) asm volatile("s_waitcnt lgkmcnt(" #n ")" ::: "memory")
; #define PG8_BAR __builtin_amdgcn_s_barrier()
; #define PG8_SCHED __builtin_amdgcn_sched_barrier(0)
; template <class Epi>
; DEVI void gemm_phase(LAS unsigned char* lds, const Gemm g, const Epi& E) {
;     ...
;             PG8_BAR; PG8_WAIT_L(0); PG8_MMA(1, 0, At, B0); PG8_BAR; PG8_SCHED;
;             PG8_STAGE(PG8_SB(1, 1), b3 + hstepB, voffB);
;             PG8_WAIT_V(6); PG8_BAR; PG8_MMA(1, 1, At, B1); PG8_BAR;
;         }
	s_waitcnt lgkmcnt(0)
	v_mfma_f32_16x16x32_bf16 v[60:63], v[156:159], v[172:175], v[60:63]
	v_mfma_f32_16x16x32_bf16 v[56:59], v[164:167], v[172:175], v[56:59]
	v_mfma_f32_16x16x32_bf16 v[52:55], v[156:159], v[180:183], v[52:55]
	v_mfma_f32_16x16x32_bf16 v[48:51], v[164:167], v[180:183], v[48:51]
	v_mfma_f32_16x16x32_bf16 v[36:39], v[156:159], v[188:191], v[36:39]
	v_mfma_f32_16x16x32_bf16 v[32:35], v[164:167], v[188:191], v[32:35]
	v_mfma_f32_16x16x32_bf16 v[20:23], v[156:159], v[196:199], v[20:23]
	v_mfma_f32_16x16x32_bf16 v[16:19], v[164:167], v[196:199], v[16:19]
	v_mfma_f32_16x16x32_bf16 v[60:63], v[160:163], v[176:179], v[60:63]
	v_mfma_f32_16x16x32_bf16 v[56:59], v[168:171], v[176:179], v[56:59]
	v_mfma_f32_16x16x32_bf16 v[52:55], v[160:163], v[184:187], v[52:55]
	v_mfma_f32_16x16x32_bf16 v[48:51], v[168:171], v[184:187], v[48:51]
	v_mfma_f32_16x16x32_bf16 v[36:39], v[160:163], v[192:195], v[36:39]
	v_mfma_f32_16x16x32_bf16 v[32:35], v[168:171], v[192:195], v[32:35]
	v_mfma_f32_16x16x32_bf16 v[20:23], v[160:163], v[200:203], v[20:23]
	v_mfma_f32_16x16x32_bf16 v[16:19], v[168:171], v[200:203], v[16:19]
	s_barrier
	s_add_u32 s26, s26, 0x40080
	s_addc_u32 s27, s27, 0
	s_add_i32 s28, s28, s35
	s_mov_b32 m0, s28
	s_nop 0
	global_load_lds_dwordx4 v130, s[26:27]
	s_add_i32 m0, s28, 0x2000
	s_nop 0
	global_load_lds_dwordx4 v134, s[26:27]
	s_waitcnt vmcnt(6)
	s_barrier
	v_mfma_f32_16x16x32_bf16 v[44:47], v[204:207], v[172:175], v[44:47]
	v_mfma_f32_16x16x32_bf16 v[40:43], v[212:215], v[172:175], v[40:43]
	v_mfma_f32_16x16x32_bf16 v[28:31], v[204:207], v[180:183], v[28:31]
	v_mfma_f32_16x16x32_bf16 v[24:27], v[212:215], v[180:183], v[24:27]
	v_mfma_f32_16x16x32_bf16 v[12:15], v[204:207], v[188:191], v[12:15]
	v_mfma_f32_16x16x32_bf16 v[8:11], v[212:215], v[188:191], v[8:11]
	v_mfma_f32_16x16x32_bf16 v[4:7], v[204:207], v[196:199], v[4:7]
	v_mfma_f32_16x16x32_bf16 v[0:3], v[212:215], v[196:199], v[0:3]
	v_mfma_f32_16x16x32_bf16 v[44:47], v[208:211], v[176:179], v[44:47]
	v_mfma_f32_16x16x32_bf16 v[40:43], v[216:219], v[176:179], v[40:43]
	v_mfma_f32_16x16x32_bf16 v[28:31], v[208:211], v[184:187], v[28:31]
	v_mfma_f32_16x16x32_bf16 v[24:27], v[216:219], v[184:187], v[24:27]
	v_mfma_f32_16x16x32_bf16 v[12:15], v[208:211], v[192:195], v[12:15]
	v_mfma_f32_16x16x32_bf16 v[8:11], v[216:219], v[192:195], v[8:11]
	v_mfma_f32_16x16x32_bf16 v[4:7], v[208:211], v[200:203], v[4:7]
	v_mfma_f32_16x16x32_bf16 v[0:3], v[216:219], v[200:203], v[0:3]
	s_add_i32 s50, s50, 2
	s_add_u32 s0, s0, 0x100
	s_addc_u32 s1, s1, 0
	s_add_u32 s17, s17, 0x100
	s_addc_u32 s49, s49, 0
	s_cmp_gt_u32 s50, 13
	s_barrier
	s_cbranch_scc0 .LBB0_187
; template <class Epi>
; DEVI void gemm_phase(LAS unsigned char* lds, const Gemm g, const Epi& E) {
;     ...
;                     const int m = m0 + mm;
;                     const int r = row0 + ai * HALF + m * 16; float rs = 1.f, part = 0.f;
;                     if constexpr (Epi::RS) rs = rsv[ai * 4 + m];
;                     if constexpr (Epi::PAIR) E.pair8(cur.b, r, cur.pn * HALF + wc * 32 + 8 * fq, acc[ai][0][m][0] * rs, acc[ai][0][m][1] * rs, acc[ai][1][m][0] * rs, acc[ai][1][m][1] * rs);
;                     else
; #pragma unroll
;                     for (int bj = 0; bj < 2; ++bj) {
;                         const int c = col0 + bj * HALF; f32x4 v0 = acc[ai][bj][m][0], v1 = acc[ai][bj][m][1];
;                         if constexpr (Epi::RS) { v0 = v0 * rs; v1 = v1 * rs; }
;                         if constexpr (Epi::PRE) part += E.frag_pre8(cur.b, r, c, v0, v1, pre[mm][bj][0], pre[mm][bj][1]);
;                         else if constexpr (Epi::PERM) E.frag8(cur.b, r, c, v0, v1);
;                         else { E.frag(cur.b, r, c, v0); E.frag(cur.b, r, c + 16, v1); }
	s_setprio 0
	v_lshl_add_u32 v156, s48, 8, v147
	v_ashrrev_i32_e32 v157, 31, v156
	v_readlane_b32 s2, v252, 39
	v_lshlrev_b64 v[158:159], 11, v[156:157]
	v_lshl_or_b32 v155, s11, 8, v149
	v_mov_b32_e32 v157, s2
	v_readlane_b32 s2, v252, 37
	s_ashr_i32 s11, s10, 31
	v_cmp_gt_i32_e32 vcc, s42, v155
	v_mov_b32_e32 v162, s2
	v_readlane_b32 s2, v252, 38
	s_lshl_b64 s[0:1], s[10:11], 21
	v_cndmask_b32_e32 v161, v157, v162, vcc
	v_mov_b32_e32 v163, s2
	v_readlane_b32 s2, v252, 36
	v_cvt_pk_bf16_f32 v124, v124, v125
	v_cvt_pk_bf16_f32 v125, v126, v127
	v_mov_b32_e32 v164, s2
	v_cndmask_b32_e32 v160, v163, v164, vcc
	v_cvt_pk_bf16_f32 v126, v120, v121
	v_lshl_add_u64 v[120:121], v[160:161], 0, s[0:1]
	v_and_b32_e32 v136, 0x378, v155
	v_cvt_pk_bf16_f32 v127, v122, v123
	v_lshl_add_u64 v[122:123], v[120:121], 0, v[158:159]
	v_lshlrev_b32_e32 v136, 1, v136
	v_lshl_add_u64 v[122:123], v[122:123], 0, v[136:137]
	global_store_dwordx4 v[122:123], v[124:127], off
	v_or_b32_e32 v122, 0x80, v155
	v_cmp_gt_i32_e32 vcc, s42, v122
	v_cvt_pk_bf16_f32 v112, v112, v113
	v_cvt_pk_bf16_f32 v113, v114, v115
	v_cndmask_b32_e32 v123, v157, v162, vcc
	v_cndmask_b32_e32 v122, v163, v164, vcc
	v_lshl_add_u64 v[122:123], v[122:123], 0, s[0:1]
	s_movk_i32 s0, 0x3f8
	v_cvt_pk_bf16_f32 v115, v106, v107
	v_bitop3_b32 v106, v155, s0, v153 bitop3:0xc8
	v_cvt_pk_bf16_f32 v114, v104, v105
	v_lshl_add_u64 v[104:105], v[122:123], 0, v[158:159]
	v_lshlrev_b32_e32 v124, 1, v106
	v_mov_b32_e32 v125, v137
	v_lshl_add_u64 v[104:105], v[104:105], 0, v[124:125]
	global_store_dwordx4 v[104:105], v[112:115], off
	v_or_b32_e32 v104, 16, v156
	v_ashrrev_i32_e32 v105, 31, v104
	v_lshlrev_b64 v[112:113], 11, v[104:105]
	v_cvt_pk_bf16_f32 v106, v108, v109
	v_lshl_add_u64 v[108:109], v[120:121], 0, v[112:113]
	v_cvt_pk_bf16_f32 v92, v92, v93
	v_cvt_pk_bf16_f32 v93, v94, v95
	v_cvt_pk_bf16_f32 v94, v88, v89
	v_lshl_add_u64 v[88:89], v[122:123], 0, v[112:113]
	v_cvt_pk_bf16_f32 v104, v116, v117
	v_cvt_pk_bf16_f32 v105, v118, v119
	v_cvt_pk_bf16_f32 v107, v110, v111
	v_lshl_add_u64 v[108:109], v[108:109], 0, v[136:137]
	v_cvt_pk_bf16_f32 v95, v90, v91
	v_lshl_add_u64 v[88:89], v[88:89], 0, v[124:125]
	global_store_dwordx4 v[108:109], v[104:107], off
	global_store_dwordx4 v[88:89], v[92:95], off
	v_or_b32_e32 v88, 32, v156
	v_ashrrev_i32_e32 v89, 31, v88
	v_lshlrev_b64 v[92:93], 11, v[88:89]
	v_lshl_add_u64 v[94:95], v[120:121], 0, v[92:93]
	v_cvt_pk_bf16_f32 v76, v76, v77
	v_cvt_pk_bf16_f32 v77, v78, v79
	v_cvt_pk_bf16_f32 v78, v72, v73
	v_lshl_add_u64 v[72:73], v[122:123], 0, v[92:93]
	v_cvt_pk_bf16_f32 v88, v100, v101
	v_cvt_pk_bf16_f32 v89, v102, v103
	v_cvt_pk_bf16_f32 v90, v96, v97
	v_cvt_pk_bf16_f32 v91, v98, v99
	v_lshl_add_u64 v[94:95], v[94:95], 0, v[136:137]
	v_cvt_pk_bf16_f32 v79, v74, v75
	v_lshl_add_u64 v[72:73], v[72:73], 0, v[124:125]
	global_store_dwordx4 v[94:95], v[88:91], off
	global_store_dwordx4 v[72:73], v[76:79], off
	v_or_b32_e32 v72, 48, v156
	v_ashrrev_i32_e32 v73, 31, v72
	v_lshlrev_b64 v[76:77], 11, v[72:73]
	v_lshl_add_u64 v[78:79], v[120:121], 0, v[76:77]
	v_cvt_pk_bf16_f32 v68, v68, v69
	v_cvt_pk_bf16_f32 v69, v70, v71
	v_cvt_pk_bf16_f32 v70, v64, v65
	v_lshl_add_u64 v[64:65], v[122:123], 0, v[76:77]
	v_cvt_pk_bf16_f32 v72, v84, v85
	v_cvt_pk_bf16_f32 v73, v86, v87
	v_cvt_pk_bf16_f32 v74, v80, v81
	v_cvt_pk_bf16_f32 v75, v82, v83
	v_lshl_add_u64 v[78:79], v[78:79], 0, v[136:137]
	v_cvt_pk_bf16_f32 v71, v66, v67
	v_lshl_add_u64 v[64:65], v[64:65], 0, v[124:125]
	s_mov_b64 s[0:1], 0x40000
	global_store_dwordx4 v[78:79], v[72:75], off
	global_store_dwordx4 v[64:65], v[68:71], off
	v_lshl_add_u64 v[64:65], v[158:159], 0, s[0:1]
	v_cvt_pk_bf16_f32 v60, v60, v61
	v_cvt_pk_bf16_f32 v61, v62, v63
	v_cvt_pk_bf16_f32 v62, v56, v57
	v_lshl_add_u64 v[56:57], v[120:121], 0, v[64:65]
	v_cvt_pk_bf16_f32 v44, v44, v45
	v_cvt_pk_bf16_f32 v45, v46, v47
	v_cvt_pk_bf16_f32 v46, v40, v41
	v_lshl_add_u64 v[40:41], v[122:123], 0, v[64:65]
	v_cvt_pk_bf16_f32 v63, v58, v59
	v_lshl_add_u64 v[56:57], v[56:57], 0, v[136:137]
	v_cvt_pk_bf16_f32 v47, v42, v43
	v_lshl_add_u64 v[40:41], v[40:41], 0, v[124:125]
	s_mov_b64 s[0:1], 0x48000
	global_store_dwordx4 v[56:57], v[60:63], off
	global_store_dwordx4 v[40:41], v[44:47], off
	v_cvt_pk_bf16_f32 v28, v28, v29
	v_cvt_pk_bf16_f32 v29, v30, v31
	v_lshl_add_u64 v[44:45], v[158:159], 0, s[0:1]
	v_lshl_add_u64 v[46:47], v[120:121], 0, v[44:45]
	v_cvt_pk_bf16_f32 v30, v24, v25
	v_lshl_add_u64 v[24:25], v[122:123], 0, v[44:45]
	v_cvt_pk_bf16_f32 v40, v52, v53
	v_cvt_pk_bf16_f32 v41, v54, v55
	v_cvt_pk_bf16_f32 v42, v48, v49
	v_cvt_pk_bf16_f32 v43, v50, v51
	v_lshl_add_u64 v[46:47], v[46:47], 0, v[136:137]
	v_cvt_pk_bf16_f32 v31, v26, v27
	v_lshl_add_u64 v[24:25], v[24:25], 0, v[124:125]
	s_mov_b64 s[0:1], 0x50000
	global_store_dwordx4 v[46:47], v[40:43], off
	global_store_dwordx4 v[24:25], v[28:31], off
	v_cvt_pk_bf16_f32 v12, v12, v13
	v_cvt_pk_bf16_f32 v13, v14, v15
	v_lshl_add_u64 v[28:29], v[158:159], 0, s[0:1]
	v_lshl_add_u64 v[30:31], v[120:121], 0, v[28:29]
	v_cvt_pk_bf16_f32 v14, v8, v9
	v_lshl_add_u64 v[8:9], v[122:123], 0, v[28:29]
	v_cvt_pk_bf16_f32 v24, v36, v37
	v_cvt_pk_bf16_f32 v25, v38, v39
	v_cvt_pk_bf16_f32 v26, v32, v33
	v_cvt_pk_bf16_f32 v27, v34, v35
	v_lshl_add_u64 v[30:31], v[30:31], 0, v[136:137]
	v_cvt_pk_bf16_f32 v15, v10, v11
	v_lshl_add_u64 v[8:9], v[8:9], 0, v[124:125]
	s_mov_b64 s[0:1], 0x58000
	global_store_dwordx4 v[30:31], v[24:27], off
	global_store_dwordx4 v[8:9], v[12:15], off
	v_cvt_pk_bf16_f32 v4, v4, v5
	v_cvt_pk_bf16_f32 v5, v6, v7
	v_lshl_add_u64 v[12:13], v[158:159], 0, s[0:1]
	v_lshl_add_u64 v[14:15], v[120:121], 0, v[12:13]
	v_cvt_pk_bf16_f32 v6, v0, v1
	v_lshl_add_u64 v[0:1], v[122:123], 0, v[12:13]
	v_cvt_pk_bf16_f32 v8, v20, v21
	v_cvt_pk_bf16_f32 v9, v22, v23
	v_cvt_pk_bf16_f32 v10, v16, v17
	v_cvt_pk_bf16_f32 v11, v18, v19
	v_lshl_add_u64 v[14:15], v[14:15], 0, v[136:137]
	v_cvt_pk_bf16_f32 v7, v2, v3
	v_lshl_add_u64 v[0:1], v[0:1], 0, v[124:125]
	s_and_b64 vcc, exec, s[4:5]
	s_mov_b32 s10, s12
	s_mov_b32 s11, s14
	s_mov_b32 s48, s16
	s_mov_b64 s[28:29], s[18:19]
	s_mov_b64 s[26:27], s[24:25]
	global_store_dwordx4 v[14:15], v[8:11], off
	global_store_dwordx4 v[0:1], v[4:7], off
	s_cbranch_vccz .LBB0_178
	s_waitcnt vmcnt(0)
	s_cmpk_gt_u32 s34, 0xff
	s_cbranch_scc1 .LBB0_191
	s_barrier

; #define PG8_STAGE(bufoff, gbase, voff) do { _Pragma("unroll") for (int _i = 0; _i < 2; ++_i) \
;         __builtin_amdgcn_global_load_lds((const unsigned*)((const char*)(gbase) + (voff)[_i]), (LAS unsigned*)(lds + (bufoff) + ldsw + _i * 8192), 16, 0, 0); } while (0)
; #define PG8_LDA(dst, b, h) do { _Pragma("unroll") for (int m = 0; m < 4; ++m) _Pragma("unroll") for (int k = 0; k < 2; ++k) dst[m][k] = *(const LAS bf16x8*)(lds + PG8_SA(b, h) + aoff + m * 2048 + k * 1024); } while (0)
; #define PG8_LDB(dst, b, h) do { _Pragma("unroll") for (int n = 0; n < 2; ++n) _Pragma("unroll") for (int k = 0; k < 2; ++k) dst[n][k] = *(const LAS bf16x8*)(lds + PG8_SB(b, h) + boff + n * 2048 + k * 1024); } while (0)
; #define PG8_MMA(ai, bj, At, Bt) do { __builtin_amdgcn_s_setprio(1); _Pragma("unroll") for (int m = 0; m < 4; ++m) _Pragma("unroll") for (int n = 0; n < 2; ++n) _Pragma("unroll") for (int k = 0; k < 2; ++k) \
;         acc[ai][bj][m][n] = __builtin_amdgcn_mfma_f32_16x16x32_bf16(Bt[n][k], At[m][k], acc[ai][bj][m][n], 0, 0, 0); __builtin_amdgcn_s_setprio(0); } while (0)
; #define PG8_WAIT_L(n) asm volatile("s_waitcnt lgkmcnt(" #n ")" ::: "memory")
; #define PG8_BAR __builtin_amdgcn_s_barrier()
; #define PG8_SCHED __builtin_amdgcn_sched_barrier(0)
; template <class Epi>
; DEVI void gemm_phase(LAS unsigned char* lds, const Gemm g, const Epi& E) {
;     ...
;             const char* a1 = cA + (size_t)(t + 1) * kstep;
;             const char* a2 = last ? nA : cA + (size_t)(t + 2) * kstep; const char* b2 = last ? nB : cB + (size_t)(t + 2) * kstep;
;             const char* a3 = a2 + kstep; const char* b3 = b2 + kstep;
;             PG8_LDB(B0, 0, 0); PG8_SCHED; PG8_LDA(At, 0, 0); PG8_STAGE(PG8_SA(1, 1), a1 + hstepA, voffA);
;             PG8_WAIT_L(8); PG8_BAR; PG8_WAIT_L(0); PG8_MMA(0, 0, At, B0); PG8_BAR; PG8_SCHED;
.LBB0_276:
	s_add_u32 s19, s8, 0xfffc0080
	s_addc_u32 s26, s9, -1
	s_add_i32 s27, 0, 0x10000
	v_add_u32_e32 v8, s27, v214
	ds_read_b128 v[130:133], v8
	ds_read_b128 v[134:137], v8 offset:1024
	ds_read_b128 v[138:141], v8 offset:2048
	ds_read_b128 v[142:145], v8 offset:3072
	s_cmp_eq_u32 s18, 12
	s_cselect_b32 s69, s0, s26
	s_cselect_b32 s68, s1, s19
	s_cselect_b32 s47, s5, s15
	s_cselect_b32 s46, s7, s13
	s_add_i32 m0, s81, 0xc000
	ds_read_b128 v[146:149], v216
	ds_read_b128 v[150:153], v216 offset:1024
	ds_read_b128 v[188:191], v216 offset:2048
	ds_read_b128 v[192:195], v216 offset:3072
	ds_read_b128 v[196:199], v216 offset:4096
	ds_read_b128 v[200:203], v216 offset:5120
	ds_read_b128 v[204:207], v216 offset:6144
	ds_read_b128 v[218:221], v216 offset:7168
	global_load_lds_dwordx4 v184, s[8:9]
	s_add_i32 m0, s81, 0xe000
	s_nop 0
	global_load_lds_dwordx4 v186, s[8:9]
	s_waitcnt lgkmcnt(8)
	s_barrier
	s_waitcnt lgkmcnt(0)
	s_waitcnt lgkmcnt(0)
	s_cmp_lg_u32 s101, 0
	s_cbranch_scc1 .Lip13_a_0
	v_mfma_f32_16x16x32_bf16 v[126:129], v[130:133], v[146:149], v[126:129]
	v_mfma_f32_16x16x32_bf16 v[122:125], v[138:141], v[146:149], v[122:125]
	v_mfma_f32_16x16x32_bf16 v[114:117], v[130:133], v[188:191], v[114:117]
	v_mfma_f32_16x16x32_bf16 v[106:109], v[138:141], v[188:191], v[106:109]
	v_mfma_f32_16x16x32_bf16 v[94:97], v[130:133], v[196:199], v[94:97]
	v_mfma_f32_16x16x32_bf16 v[90:93], v[138:141], v[196:199], v[90:93]
	v_mfma_f32_16x16x32_bf16 v[82:85], v[130:133], v[204:207], v[82:85]
	v_mfma_f32_16x16x32_bf16 v[74:77], v[138:141], v[204:207], v[74:77]
	v_mfma_f32_16x16x32_bf16 v[126:129], v[134:137], v[150:153], v[126:129]
	v_mfma_f32_16x16x32_bf16 v[122:125], v[142:145], v[150:153], v[122:125]
	v_mfma_f32_16x16x32_bf16 v[114:117], v[134:137], v[192:195], v[114:117]
	v_mfma_f32_16x16x32_bf16 v[106:109], v[142:145], v[192:195], v[106:109]
	v_mfma_f32_16x16x32_bf16 v[94:97], v[134:137], v[200:203], v[94:97]
	v_mfma_f32_16x16x32_bf16 v[90:93], v[142:145], v[200:203], v[90:93]
	v_mfma_f32_16x16x32_bf16 v[82:85], v[134:137], v[218:221], v[82:85]
	v_mfma_f32_16x16x32_bf16 v[74:77], v[142:145], v[218:221], v[74:77]

; #define PG8_STAGE(bufoff, gbase, voff) do { _Pragma("unroll") for (int _i = 0; _i < 2; ++_i) \
;         __builtin_amdgcn_global_load_lds((const unsigned*)((const char*)(gbase) + (voff)[_i]), (LAS unsigned*)(lds + (bufoff) + ldsw + _i * 8192), 16, 0, 0); } while (0)
; #define PG8_LDA(dst, b, h) do { _Pragma("unroll") for (int m = 0; m < 4; ++m) _Pragma("unroll") for (int k = 0; k < 2; ++k) dst[m][k] = *(const LAS bf16x8*)(lds + PG8_SA(b, h) + aoff + m * 2048 + k * 1024); } while (0)
; #define PG8_LDB(dst, b, h) do { _Pragma("unroll") for (int n = 0; n < 2; ++n) _Pragma("unroll") for (int k = 0; k < 2; ++k) dst[n][k] = *(const LAS bf16x8*)(lds + PG8_SB(b, h) + boff + n * 2048 + k * 1024); } while (0)
; #define PG8_MMA(ai, bj, At, Bt) do { __builtin_amdgcn_s_setprio(1); _Pragma("unroll") for (int m = 0; m < 4; ++m) _Pragma("unroll") for (int n = 0; n < 2; ++n) _Pragma("unroll") for (int k = 0; k < 2; ++k) \
;         acc[ai][bj][m][n] = __builtin_amdgcn_mfma_f32_16x16x32_bf16(Bt[n][k], At[m][k], acc[ai][bj][m][n], 0, 0, 0); __builtin_amdgcn_s_setprio(0); } while (0)
; #define PG8_WAIT_V(n) asm volatile("s_waitcnt vmcnt(" #n ")" ::: "memory")
; #define PG8_WAIT_L(n) asm volatile("s_waitcnt lgkmcnt(" #n ")" ::: "memory")
; #define PG8_BAR __builtin_amdgcn_s_barrier()
; #define PG8_SCHED __builtin_amdgcn_sched_barrier(0)
; template <class Epi>
; DEVI void gemm_phase(LAS unsigned char* lds, const Gemm g, const Epi& E) {
;     ...
;             PG8_STAGE(PG8_SB(0, 1), b2 + hstepB, voffB);
;             PG8_WAIT_V(6); PG8_BAR; PG8_MMA(1, 1, At, B1); PG8_BAR;
;             PG8_LDB(B0, 1, 0); PG8_SCHED; PG8_LDA(At, 1, 0); PG8_STAGE(PG8_SA(0, 1), a2 + hstepA, voffA);
;             PG8_WAIT_L(8); PG8_BAR; PG8_WAIT_L(0); PG8_MMA(0, 0, At, B0); PG8_BAR; PG8_SCHED;
.Lip13_a_2:
	s_barrier
	s_add_u32 s26, s46, 0x40000
	s_addc_u32 s27, s47, 0
	s_add_i32 s19, s19, s80
	s_mov_b32 m0, s19
	s_nop 0
	global_load_lds_dwordx4 v178, s[26:27]
	s_add_i32 m0, s19, 0x2000
	s_nop 0
	global_load_lds_dwordx4 v182, s[26:27]
	s_waitcnt vmcnt(6)
	s_barrier
	s_cmp_lg_u32 s100, 0
	s_cbranch_scc1 .Lip13_a_3
	v_mfma_f32_16x16x32_bf16 v[50:53], v[222:225], v[146:149], v[50:53]
	v_mfma_f32_16x16x32_bf16 v[54:57], v[230:233], v[146:149], v[54:57]
	v_mfma_f32_16x16x32_bf16 v[34:37], v[222:225], v[188:191], v[34:37]
	v_mfma_f32_16x16x32_bf16 v[38:41], v[230:233], v[188:191], v[38:41]
	v_mfma_f32_16x16x32_bf16 v[18:21], v[222:225], v[196:199], v[18:21]
	v_mfma_f32_16x16x32_bf16 v[22:25], v[230:233], v[196:199], v[22:25]
	v_mfma_f32_16x16x32_bf16 v[0:3], v[222:225], v[204:207], v[0:3]
	v_mfma_f32_16x16x32_bf16 v[4:7], v[230:233], v[204:207], v[4:7]
	v_mfma_f32_16x16x32_bf16 v[50:53], v[226:229], v[150:153], v[50:53]
	v_mfma_f32_16x16x32_bf16 v[54:57], v[234:237], v[150:153], v[54:57]
	v_mfma_f32_16x16x32_bf16 v[34:37], v[226:229], v[192:195], v[34:37]
	v_mfma_f32_16x16x32_bf16 v[38:41], v[234:237], v[192:195], v[38:41]
	v_mfma_f32_16x16x32_bf16 v[18:21], v[226:229], v[200:203], v[18:21]
	v_mfma_f32_16x16x32_bf16 v[22:25], v[234:237], v[200:203], v[22:25]
	v_mfma_f32_16x16x32_bf16 v[0:3], v[226:229], v[218:221], v[0:3]
	v_mfma_f32_16x16x32_bf16 v[4:7], v[234:237], v[218:221], v[4:7]
.Lip13_a_3:
	s_add_i32 s19, 0, 0x18000
	v_add_u32_e32 v8, s19, v214
	s_barrier
	ds_read_b128 v[130:133], v8
	ds_read_b128 v[134:137], v8 offset:1024
	ds_read_b128 v[138:141], v8 offset:2048
	ds_read_b128 v[142:145], v8 offset:3072
	s_add_u32 s26, s68, 0x40000
	s_addc_u32 s27, s69, 0
	s_mov_b32 m0, s83
	ds_read_b128 v[146:149], v216 offset:32768
	ds_read_b128 v[150:153], v216 offset:33792
	ds_read_b128 v[188:191], v216 offset:34816
	ds_read_b128 v[192:195], v216 offset:35840
	ds_read_b128 v[196:199], v216 offset:36864
	ds_read_b128 v[200:203], v216 offset:37888
	ds_read_b128 v[204:207], v216 offset:38912
	ds_read_b128 v[218:221], v216 offset:39936
	global_load_lds_dwordx4 v176, s[26:27]
	s_mov_b32 m0, s84
	s_nop 0
	global_load_lds_dwordx4 v180, s[26:27]
	s_waitcnt lgkmcnt(8)
	s_barrier
	s_waitcnt lgkmcnt(0)
	s_waitcnt lgkmcnt(0)
	s_cmp_lg_u32 s101, 0
	s_cbranch_scc1 .Lip13_a_4
	v_mfma_f32_16x16x32_bf16 v[126:129], v[130:133], v[146:149], v[126:129]
	v_mfma_f32_16x16x32_bf16 v[122:125], v[138:141], v[146:149], v[122:125]
	v_mfma_f32_16x16x32_bf16 v[114:117], v[130:133], v[188:191], v[114:117]
	v_mfma_f32_16x16x32_bf16 v[106:109], v[138:141], v[188:191], v[106:109]
	v_mfma_f32_16x16x32_bf16 v[94:97], v[130:133], v[196:199], v[94:97]
	v_mfma_f32_16x16x32_bf16 v[90:93], v[138:141], v[196:199], v[90:93]
	v_mfma_f32_16x16x32_bf16 v[82:85], v[130:133], v[204:207], v[82:85]
	v_mfma_f32_16x16x32_bf16 v[74:77], v[138:141], v[204:207], v[74:77]
	v_mfma_f32_16x16x32_bf16 v[126:129], v[134:137], v[150:153], v[126:129]
	v_mfma_f32_16x16x32_bf16 v[122:125], v[142:145], v[150:153], v[122:125]
	v_mfma_f32_16x16x32_bf16 v[114:117], v[134:137], v[192:195], v[114:117]
	v_mfma_f32_16x16x32_bf16 v[106:109], v[142:145], v[192:195], v[106:109]
	v_mfma_f32_16x16x32_bf16 v[94:97], v[134:137], v[200:203], v[94:97]
	v_mfma_f32_16x16x32_bf16 v[90:93], v[142:145], v[200:203], v[90:93]
	v_mfma_f32_16x16x32_bf16 v[82:85], v[134:137], v[218:221], v[82:85]
	v_mfma_f32_16x16x32_bf16 v[74:77], v[142:145], v[218:221], v[74:77]

; #define PG8_STAGE(bufoff, gbase, voff) do { _Pragma("unroll") for (int _i = 0; _i < 2; ++_i) \
;         __builtin_amdgcn_global_load_lds((const unsigned*)((const char*)(gbase) + (voff)[_i]), (LAS unsigned*)(lds + (bufoff) + ldsw + _i * 8192), 16, 0, 0); } while (0)
; #define PG8_MMA(ai, bj, At, Bt) do { __builtin_amdgcn_s_setprio(1); _Pragma("unroll") for (int m = 0; m < 4; ++m) _Pragma("unroll") for (int n = 0; n < 2; ++n) _Pragma("unroll") for (int k = 0; k < 2; ++k) \
;         acc[ai][bj][m][n] = __builtin_amdgcn_mfma_f32_16x16x32_bf16(Bt[n][k], At[m][k], acc[ai][bj][m][n], 0, 0, 0); __builtin_amdgcn_s_setprio(0); } while (0)
; #define PG8_WAIT_V(n) asm volatile("s_waitcnt vmcnt(" #n ")" ::: "memory")
; #define PG8_BAR __builtin_amdgcn_s_barrier()
; template <class Epi>
; DEVI void gemm_phase(LAS unsigned char* lds, const Gemm g, const Epi& E) {
;     ...
;             PG8_STAGE(PG8_SB(1, 1), b3 + hstepB, voffB);
;             PG8_WAIT_V(6); PG8_BAR; PG8_MMA(1, 1, At, B1); PG8_BAR;
.Lip13_a_6:
	s_barrier
	s_add_u32 s26, s46, 0x40080
	s_addc_u32 s27, s47, 0
	s_add_i32 s19, s38, s80
	s_mov_b32 m0, s19
	s_nop 0
	global_load_lds_dwordx4 v178, s[26:27]
	s_add_i32 m0, s19, 0x2000
	s_nop 0
	global_load_lds_dwordx4 v182, s[26:27]
	s_waitcnt vmcnt(6)
	s_barrier
	s_cmp_lg_u32 s100, 0
	s_cbranch_scc1 .Lip13_a_7
	v_mfma_f32_16x16x32_bf16 v[50:53], v[222:225], v[146:149], v[50:53]
	v_mfma_f32_16x16x32_bf16 v[54:57], v[230:233], v[146:149], v[54:57]
	v_mfma_f32_16x16x32_bf16 v[34:37], v[222:225], v[188:191], v[34:37]
	v_mfma_f32_16x16x32_bf16 v[38:41], v[230:233], v[188:191], v[38:41]
	v_mfma_f32_16x16x32_bf16 v[18:21], v[222:225], v[196:199], v[18:21]
	v_mfma_f32_16x16x32_bf16 v[22:25], v[230:233], v[196:199], v[22:25]
	v_mfma_f32_16x16x32_bf16 v[0:3], v[222:225], v[204:207], v[0:3]
	v_mfma_f32_16x16x32_bf16 v[4:7], v[230:233], v[204:207], v[4:7]
	v_mfma_f32_16x16x32_bf16 v[50:53], v[226:229], v[150:153], v[50:53]
	v_mfma_f32_16x16x32_bf16 v[54:57], v[234:237], v[150:153], v[54:57]
	v_mfma_f32_16x16x32_bf16 v[34:37], v[226:229], v[192:195], v[34:37]
	v_mfma_f32_16x16x32_bf16 v[38:41], v[234:237], v[192:195], v[38:41]
	v_mfma_f32_16x16x32_bf16 v[18:21], v[226:229], v[200:203], v[18:21]
	v_mfma_f32_16x16x32_bf16 v[22:25], v[234:237], v[200:203], v[22:25]
	v_mfma_f32_16x16x32_bf16 v[0:3], v[226:229], v[218:221], v[0:3]
	v_mfma_f32_16x16x32_bf16 v[4:7], v[234:237], v[218:221], v[4:7]

; #define PG8_STAGE(bufoff, gbase, voff) do { _Pragma("unroll") for (int _i = 0; _i < 2; ++_i) \
;         __builtin_amdgcn_global_load_lds((const unsigned*)((const char*)(gbase) + (voff)[_i]), (LAS unsigned*)(lds + (bufoff) + ldsw + _i * 8192), 16, 0, 0); } while (0)
; #define PG8_LDA(dst, b, h) do { _Pragma("unroll") for (int m = 0; m < 4; ++m) _Pragma("unroll") for (int k = 0; k < 2; ++k) dst[m][k] = *(const LAS bf16x8*)(lds + PG8_SA(b, h) + aoff + m * 2048 + k * 1024); } while (0)
; #define PG8_LDB(dst, b, h) do { _Pragma("unroll") for (int n = 0; n < 2; ++n) _Pragma("unroll") for (int k = 0; k < 2; ++k) dst[n][k] = *(const LAS bf16x8*)(lds + PG8_SB(b, h) + boff + n * 2048 + k * 1024); } while (0)
; #define PG8_MMA(ai, bj, At, Bt) do { __builtin_amdgcn_s_setprio(1); _Pragma("unroll") for (int m = 0; m < 4; ++m) _Pragma("unroll") for (int n = 0; n < 2; ++n) _Pragma("unroll") for (int k = 0; k < 2; ++k) \
;         acc[ai][bj][m][n] = __builtin_amdgcn_mfma_f32_16x16x32_bf16(Bt[n][k], At[m][k], acc[ai][bj][m][n], 0, 0, 0); __builtin_amdgcn_s_setprio(0); } while (0)
; #define PG8_WAIT_L(n) asm volatile("s_waitcnt lgkmcnt(" #n ")" ::: "memory")
; #define PG8_BAR __builtin_amdgcn_s_barrier()
; #define PG8_SCHED __builtin_amdgcn_sched_barrier(0)
; template <class Epi>
; DEVI void gemm_phase(LAS unsigned char* lds, const Gemm g, const Epi& E) {
;     ...
;             const char* a1 = cA + (size_t)(t + 1) * kstep;
;             const char* a2 = last ? nA : cA + (size_t)(t + 2) * kstep; const char* b2 = last ? nB : cB + (size_t)(t + 2) * kstep;
;             const char* a3 = a2 + kstep; const char* b3 = b2 + kstep;
;             PG8_LDB(B0, 0, 0); PG8_SCHED; PG8_LDA(At, 0, 0); PG8_STAGE(PG8_SA(1, 1), a1 + hstepA, voffA);
;             PG8_WAIT_L(8); PG8_BAR; PG8_WAIT_L(0); PG8_MMA(0, 0, At, B0); PG8_BAR; PG8_SCHED;
.LBB0_356:
	s_add_u32 s19, s8, 0xfffc0080
	s_addc_u32 s26, s9, -1
	s_add_i32 s27, 0, 0x10000
	v_add_u32_e32 v142, s27, v209
	ds_read_b128 v[130:133], v142
	ds_read_b128 v[134:137], v142 offset:1024
	ds_read_b128 v[138:141], v142 offset:2048
	ds_read_b128 v[142:145], v142 offset:3072
	s_cmp_eq_u32 s18, 12
	s_cselect_b32 s69, s0, s26
	s_cselect_b32 s68, s1, s19
	s_cselect_b32 s47, s5, s13
	s_cselect_b32 s46, s7, s11
	s_add_i32 m0, s85, 0xc000
	ds_read_b128 v[146:149], v214
	ds_read_b128 v[150:153], v214 offset:1024
	ds_read_b128 v[186:189], v214 offset:2048
	ds_read_b128 v[190:193], v214 offset:3072
	ds_read_b128 v[194:197], v214 offset:4096
	ds_read_b128 v[198:201], v214 offset:5120
	ds_read_b128 v[202:205], v214 offset:6144
	ds_read_b128 v[216:219], v214 offset:7168
	global_load_lds_dwordx4 v182, s[8:9]
	s_add_i32 m0, s85, 0xe000
	s_nop 0
	global_load_lds_dwordx4 v184, s[8:9]
	s_waitcnt lgkmcnt(8)
	s_barrier
	s_waitcnt lgkmcnt(0)
	s_waitcnt lgkmcnt(0)
	s_cmp_lg_u32 s101, 0
	s_cbranch_scc1 .Lip13_b_0
	v_mfma_f32_16x16x32_bf16 v[126:129], v[130:133], v[146:149], v[126:129]
	v_mfma_f32_16x16x32_bf16 v[122:125], v[138:141], v[146:149], v[122:125]
	v_mfma_f32_16x16x32_bf16 v[114:117], v[130:133], v[186:189], v[114:117]
	v_mfma_f32_16x16x32_bf16 v[106:109], v[138:141], v[186:189], v[106:109]
	v_mfma_f32_16x16x32_bf16 v[94:97], v[130:133], v[194:197], v[94:97]
	v_mfma_f32_16x16x32_bf16 v[90:93], v[138:141], v[194:197], v[90:93]
	v_mfma_f32_16x16x32_bf16 v[82:85], v[130:133], v[202:205], v[82:85]
	v_mfma_f32_16x16x32_bf16 v[74:77], v[138:141], v[202:205], v[74:77]
	v_mfma_f32_16x16x32_bf16 v[126:129], v[134:137], v[150:153], v[126:129]
	v_mfma_f32_16x16x32_bf16 v[122:125], v[142:145], v[150:153], v[122:125]
	v_mfma_f32_16x16x32_bf16 v[114:117], v[134:137], v[190:193], v[114:117]
	v_mfma_f32_16x16x32_bf16 v[106:109], v[142:145], v[190:193], v[106:109]
	v_mfma_f32_16x16x32_bf16 v[94:97], v[134:137], v[198:201], v[94:97]
	v_mfma_f32_16x16x32_bf16 v[90:93], v[142:145], v[198:201], v[90:93]
	v_mfma_f32_16x16x32_bf16 v[82:85], v[134:137], v[216:219], v[82:85]
	v_mfma_f32_16x16x32_bf16 v[74:77], v[142:145], v[216:219], v[74:77]

; #define PG8_STAGE(bufoff, gbase, voff) do { _Pragma("unroll") for (int _i = 0; _i < 2; ++_i) \
;         __builtin_amdgcn_global_load_lds((const unsigned*)((const char*)(gbase) + (voff)[_i]), (LAS unsigned*)(lds + (bufoff) + ldsw + _i * 8192), 16, 0, 0); } while (0)
; #define PG8_LDA(dst, b, h) do { _Pragma("unroll") for (int m = 0; m < 4; ++m) _Pragma("unroll") for (int k = 0; k < 2; ++k) dst[m][k] = *(const LAS bf16x8*)(lds + PG8_SA(b, h) + aoff + m * 2048 + k * 1024); } while (0)
; #define PG8_LDB(dst, b, h) do { _Pragma("unroll") for (int n = 0; n < 2; ++n) _Pragma("unroll") for (int k = 0; k < 2; ++k) dst[n][k] = *(const LAS bf16x8*)(lds + PG8_SB(b, h) + boff + n * 2048 + k * 1024); } while (0)
; #define PG8_MMA(ai, bj, At, Bt) do { __builtin_amdgcn_s_setprio(1); _Pragma("unroll") for (int m = 0; m < 4; ++m) _Pragma("unroll") for (int n = 0; n < 2; ++n) _Pragma("unroll") for (int k = 0; k < 2; ++k) \
;         acc[ai][bj][m][n] = __builtin_amdgcn_mfma_f32_16x16x32_bf16(Bt[n][k], At[m][k], acc[ai][bj][m][n], 0, 0, 0); __builtin_amdgcn_s_setprio(0); } while (0)
; #define PG8_WAIT_V(n) asm volatile("s_waitcnt vmcnt(" #n ")" ::: "memory")
; #define PG8_WAIT_L(n) asm volatile("s_waitcnt lgkmcnt(" #n ")" ::: "memory")
; #define PG8_BAR __builtin_amdgcn_s_barrier()
; #define PG8_SCHED __builtin_amdgcn_sched_barrier(0)
; template <class Epi>
; DEVI void gemm_phase(LAS unsigned char* lds, const Gemm g, const Epi& E) {
;     ...
;             PG8_STAGE(PG8_SB(0, 1), b2 + hstepB, voffB);
;             PG8_WAIT_V(6); PG8_BAR; PG8_MMA(1, 1, At, B1); PG8_BAR;
;             PG8_LDB(B0, 1, 0); PG8_SCHED; PG8_LDA(At, 1, 0); PG8_STAGE(PG8_SA(0, 1), a2 + hstepA, voffA);
;             PG8_WAIT_L(8); PG8_BAR; PG8_WAIT_L(0); PG8_MMA(0, 0, At, B0); PG8_BAR; PG8_SCHED;
.Lip13_b_2:
	s_barrier
	s_add_u32 s26, s46, 0x40000
	s_addc_u32 s27, s47, 0
	s_add_i32 s19, s19, s84
	s_mov_b32 m0, s19
	s_nop 0
	global_load_lds_dwordx4 v8, s[26:27]
	s_add_i32 m0, s19, 0x2000
	s_nop 0
	global_load_lds_dwordx4 v180, s[26:27]
	s_waitcnt vmcnt(6)
	s_barrier
	s_cmp_lg_u32 s100, 0
	s_cbranch_scc1 .Lip13_b_3
	v_mfma_f32_16x16x32_bf16 v[50:53], v[220:223], v[146:149], v[50:53]
	v_mfma_f32_16x16x32_bf16 v[54:57], v[228:231], v[146:149], v[54:57]
	v_mfma_f32_16x16x32_bf16 v[34:37], v[220:223], v[186:189], v[34:37]
	v_mfma_f32_16x16x32_bf16 v[38:41], v[228:231], v[186:189], v[38:41]
	v_mfma_f32_16x16x32_bf16 v[18:21], v[220:223], v[194:197], v[18:21]
	v_mfma_f32_16x16x32_bf16 v[22:25], v[228:231], v[194:197], v[22:25]
	v_mfma_f32_16x16x32_bf16 v[0:3], v[220:223], v[202:205], v[0:3]
	v_mfma_f32_16x16x32_bf16 v[4:7], v[228:231], v[202:205], v[4:7]
	v_mfma_f32_16x16x32_bf16 v[50:53], v[224:227], v[150:153], v[50:53]
	v_mfma_f32_16x16x32_bf16 v[54:57], v[232:235], v[150:153], v[54:57]
	v_mfma_f32_16x16x32_bf16 v[34:37], v[224:227], v[190:193], v[34:37]
	v_mfma_f32_16x16x32_bf16 v[38:41], v[232:235], v[190:193], v[38:41]
	v_mfma_f32_16x16x32_bf16 v[18:21], v[224:227], v[198:201], v[18:21]
	v_mfma_f32_16x16x32_bf16 v[22:25], v[232:235], v[198:201], v[22:25]
	v_mfma_f32_16x16x32_bf16 v[0:3], v[224:227], v[216:219], v[0:3]
	v_mfma_f32_16x16x32_bf16 v[4:7], v[232:235], v[216:219], v[4:7]
.Lip13_b_3:
	s_add_i32 s19, 0, 0x18000
	v_add_u32_e32 v142, s19, v209
	s_barrier
	ds_read_b128 v[130:133], v142
	ds_read_b128 v[134:137], v142 offset:1024
	ds_read_b128 v[138:141], v142 offset:2048
	ds_read_b128 v[142:145], v142 offset:3072
	s_add_u32 s26, s68, 0x40000
	s_addc_u32 s27, s69, 0
	s_mov_b32 m0, s87
	ds_read_b128 v[146:149], v214 offset:32768
	ds_read_b128 v[150:153], v214 offset:33792
	ds_read_b128 v[186:189], v214 offset:34816
	ds_read_b128 v[190:193], v214 offset:35840
	ds_read_b128 v[194:197], v214 offset:36864
	ds_read_b128 v[198:201], v214 offset:37888
	ds_read_b128 v[202:205], v214 offset:38912
	ds_read_b128 v[216:219], v214 offset:39936
	global_load_lds_dwordx4 v176, s[26:27]
	s_mov_b32 m0, s88
	s_nop 0
	global_load_lds_dwordx4 v178, s[26:27]
	s_waitcnt lgkmcnt(8)
	s_barrier
	s_waitcnt lgkmcnt(0)
	s_waitcnt lgkmcnt(0)
	s_cmp_lg_u32 s101, 0
	s_cbranch_scc1 .Lip13_b_4
	v_mfma_f32_16x16x32_bf16 v[126:129], v[130:133], v[146:149], v[126:129]
	v_mfma_f32_16x16x32_bf16 v[122:125], v[138:141], v[146:149], v[122:125]
	v_mfma_f32_16x16x32_bf16 v[114:117], v[130:133], v[186:189], v[114:117]
	v_mfma_f32_16x16x32_bf16 v[106:109], v[138:141], v[186:189], v[106:109]
	v_mfma_f32_16x16x32_bf16 v[94:97], v[130:133], v[194:197], v[94:97]
	v_mfma_f32_16x16x32_bf16 v[90:93], v[138:141], v[194:197], v[90:93]
	v_mfma_f32_16x16x32_bf16 v[82:85], v[130:133], v[202:205], v[82:85]
	v_mfma_f32_16x16x32_bf16 v[74:77], v[138:141], v[202:205], v[74:77]
	v_mfma_f32_16x16x32_bf16 v[126:129], v[134:137], v[150:153], v[126:129]
	v_mfma_f32_16x16x32_bf16 v[122:125], v[142:145], v[150:153], v[122:125]
	v_mfma_f32_16x16x32_bf16 v[114:117], v[134:137], v[190:193], v[114:117]
	v_mfma_f32_16x16x32_bf16 v[106:109], v[142:145], v[190:193], v[106:109]
	v_mfma_f32_16x16x32_bf16 v[94:97], v[134:137], v[198:201], v[94:97]
	v_mfma_f32_16x16x32_bf16 v[90:93], v[142:145], v[198:201], v[90:93]
	v_mfma_f32_16x16x32_bf16 v[82:85], v[134:137], v[216:219], v[82:85]
	v_mfma_f32_16x16x32_bf16 v[74:77], v[142:145], v[216:219], v[74:77]

; #define PG8_STAGE(bufoff, gbase, voff) do { _Pragma("unroll") for (int _i = 0; _i < 2; ++_i) \
;         __builtin_amdgcn_global_load_lds((const unsigned*)((const char*)(gbase) + (voff)[_i]), (LAS unsigned*)(lds + (bufoff) + ldsw + _i * 8192), 16, 0, 0); } while (0)
; #define PG8_MMA(ai, bj, At, Bt) do { __builtin_amdgcn_s_setprio(1); _Pragma("unroll") for (int m = 0; m < 4; ++m) _Pragma("unroll") for (int n = 0; n < 2; ++n) _Pragma("unroll") for (int k = 0; k < 2; ++k) \
;         acc[ai][bj][m][n] = __builtin_amdgcn_mfma_f32_16x16x32_bf16(Bt[n][k], At[m][k], acc[ai][bj][m][n], 0, 0, 0); __builtin_amdgcn_s_setprio(0); } while (0)
; #define PG8_WAIT_V(n) asm volatile("s_waitcnt vmcnt(" #n ")" ::: "memory")
; #define PG8_BAR __builtin_amdgcn_s_barrier()
; template <class Epi>
; DEVI void gemm_phase(LAS unsigned char* lds, const Gemm g, const Epi& E) {
;     ...
;             PG8_STAGE(PG8_SB(1, 1), b3 + hstepB, voffB);
;             PG8_WAIT_V(6); PG8_BAR; PG8_MMA(1, 1, At, B1); PG8_BAR;
.Lip13_b_6:
	s_barrier
	s_add_u32 s26, s46, 0x40080
	s_addc_u32 s27, s47, 0
	s_add_i32 s19, s38, s84
	s_mov_b32 m0, s19
	s_nop 0
	global_load_lds_dwordx4 v8, s[26:27]
	s_add_i32 m0, s19, 0x2000
	s_nop 0
	global_load_lds_dwordx4 v180, s[26:27]
	s_waitcnt vmcnt(6)
	s_barrier
	s_cmp_lg_u32 s100, 0
	s_cbranch_scc1 .Lip13_b_7
	v_mfma_f32_16x16x32_bf16 v[50:53], v[220:223], v[146:149], v[50:53]
	v_mfma_f32_16x16x32_bf16 v[54:57], v[228:231], v[146:149], v[54:57]
	v_mfma_f32_16x16x32_bf16 v[34:37], v[220:223], v[186:189], v[34:37]
	v_mfma_f32_16x16x32_bf16 v[38:41], v[228:231], v[186:189], v[38:41]
	v_mfma_f32_16x16x32_bf16 v[18:21], v[220:223], v[194:197], v[18:21]
	v_mfma_f32_16x16x32_bf16 v[22:25], v[228:231], v[194:197], v[22:25]
	v_mfma_f32_16x16x32_bf16 v[0:3], v[220:223], v[202:205], v[0:3]
	v_mfma_f32_16x16x32_bf16 v[4:7], v[228:231], v[202:205], v[4:7]
	v_mfma_f32_16x16x32_bf16 v[50:53], v[224:227], v[150:153], v[50:53]
	v_mfma_f32_16x16x32_bf16 v[54:57], v[232:235], v[150:153], v[54:57]
	v_mfma_f32_16x16x32_bf16 v[34:37], v[224:227], v[190:193], v[34:37]
	v_mfma_f32_16x16x32_bf16 v[38:41], v[232:235], v[190:193], v[38:41]
	v_mfma_f32_16x16x32_bf16 v[18:21], v[224:227], v[198:201], v[18:21]
	v_mfma_f32_16x16x32_bf16 v[22:25], v[232:235], v[198:201], v[22:25]
	v_mfma_f32_16x16x32_bf16 v[0:3], v[224:227], v[216:219], v[0:3]
	v_mfma_f32_16x16x32_bf16 v[4:7], v[232:235], v[216:219], v[4:7]

; #define PG8_STAGE(bufoff, gbase, voff) do { _Pragma("unroll") for (int _i = 0; _i < 2; ++_i) \
;         __builtin_amdgcn_global_load_lds((const unsigned*)((const char*)(gbase) + (voff)[_i]), (LAS unsigned*)(lds + (bufoff) + ldsw + _i * 8192), 16, 0, 0); } while (0)
; #define PG8_LDA(dst, b, h) do { _Pragma("unroll") for (int m = 0; m < 4; ++m) _Pragma("unroll") for (int k = 0; k < 2; ++k) dst[m][k] = *(const LAS bf16x8*)(lds + PG8_SA(b, h) + aoff + m * 2048 + k * 1024); } while (0)
; #define PG8_LDB(dst, b, h) do { _Pragma("unroll") for (int n = 0; n < 2; ++n) _Pragma("unroll") for (int k = 0; k < 2; ++k) dst[n][k] = *(const LAS bf16x8*)(lds + PG8_SB(b, h) + boff + n * 2048 + k * 1024); } while (0)
; #define PG8_MMA(ai, bj, At, Bt) do { __builtin_amdgcn_s_setprio(1); _Pragma("unroll") for (int m = 0; m < 4; ++m) _Pragma("unroll") for (int n = 0; n < 2; ++n) _Pragma("unroll") for (int k = 0; k < 2; ++k) \
;         acc[ai][bj][m][n] = __builtin_amdgcn_mfma_f32_16x16x32_bf16(Bt[n][k], At[m][k], acc[ai][bj][m][n], 0, 0, 0); __builtin_amdgcn_s_setprio(0); } while (0)
; #define PG8_WAIT_V(n) asm volatile("s_waitcnt vmcnt(" #n ")" ::: "memory")
; #define PG8_WAIT_L(n) asm volatile("s_waitcnt lgkmcnt(" #n ")" ::: "memory")
; #define PG8_BAR __builtin_amdgcn_s_barrier()
; #define PG8_SCHED __builtin_amdgcn_sched_barrier(0)
; template <class Epi>
; DEVI void gemm_phase(LAS unsigned char* lds, const Gemm g, const Epi& E) {
;     ...
;             const bool last = (t == nt - 2);
;             const char* a1 = cA + (size_t)(t + 1) * kstep;
;             const char* a2 = last ? nA : cA + (size_t)(t + 2) * kstep; const char* b2 = last ? nB : cB + (size_t)(t + 2) * kstep;
;             const char* a3 = a2 + kstep; const char* b3 = b2 + kstep;
;             PG8_LDB(B0, 0, 0); PG8_SCHED; PG8_LDA(At, 0, 0); PG8_STAGE(PG8_SA(1, 1), a1 + hstepA, voffA);
;             PG8_WAIT_L(8); PG8_BAR; PG8_WAIT_L(0); PG8_MMA(0, 0, At, B0); PG8_BAR; PG8_SCHED;
;             PG8_LDB(B1, 0, 1); PG8_STAGE(PG8_SB(0, 0), b2, voffB);
;             PG8_BAR; PG8_WAIT_L(0); PG8_MMA(0, 1, At, B1); PG8_BAR;
;             PG8_LDA(At, 0, 1); PG8_STAGE(PG8_SA(0, 0), a2, voffA);
;             PG8_BAR; PG8_WAIT_L(0); PG8_MMA(1, 0, At, B0); PG8_BAR; PG8_SCHED;
;             PG8_STAGE(PG8_SB(0, 1), b2 + hstepB, voffB);
;             PG8_WAIT_V(6); PG8_BAR; PG8_MMA(1, 1, At, B1); PG8_BAR;
.LBB0_968:
	s_add_u32 s26, s68, 0xfffc0080
	s_addc_u32 s27, s69, -1
	s_add_i32 s38, 0, 0x10000
	v_add_u32_e32 v142, s38, v193
	ds_read_b128 v[130:133], v142
	ds_read_b128 v[134:137], v142 offset:1024
	ds_read_b128 v[138:141], v142 offset:2048
	ds_read_b128 v[142:145], v142 offset:3072
	s_cmp_eq_u32 s19, 12
	s_cselect_b32 s83, s0, s27
	s_cselect_b32 s82, s1, s26
	s_cselect_b32 s81, s9, s18
	s_cselect_b32 s80, s13, s15
	s_add_i32 m0, s85, 0xc000
	ds_read_b128 v[146:149], v198
	ds_read_b128 v[182:185], v198 offset:1024
	ds_read_b128 v[186:189], v198 offset:2048
	ds_read_b128 v[200:203], v198 offset:3072
	ds_read_b128 v[204:207], v198 offset:4096
	ds_read_b128 v[214:217], v198 offset:5120
	ds_read_b128 v[218:221], v198 offset:6144
	ds_read_b128 v[222:225], v198 offset:7168
	global_load_lds_dwordx4 v178, s[68:69]
	s_add_i32 m0, s85, 0xe000
	s_nop 0
	global_load_lds_dwordx4 v180, s[68:69]
	s_waitcnt lgkmcnt(8)
	s_barrier
	s_waitcnt lgkmcnt(0)
	v_mfma_f32_16x16x32_bf16 v[126:129], v[130:133], v[146:149], v[126:129]
	v_mfma_f32_16x16x32_bf16 v[122:125], v[138:141], v[146:149], v[122:125]
	v_mfma_f32_16x16x32_bf16 v[110:113], v[130:133], v[186:189], v[110:113]
	v_mfma_f32_16x16x32_bf16 v[106:109], v[138:141], v[186:189], v[106:109]
	v_mfma_f32_16x16x32_bf16 v[94:97], v[130:133], v[204:207], v[94:97]
	v_mfma_f32_16x16x32_bf16 v[90:93], v[138:141], v[204:207], v[90:93]
	v_mfma_f32_16x16x32_bf16 v[78:81], v[130:133], v[218:221], v[78:81]
	v_mfma_f32_16x16x32_bf16 v[74:77], v[138:141], v[218:221], v[74:77]
	v_mfma_f32_16x16x32_bf16 v[126:129], v[134:137], v[182:185], v[126:129]
	v_mfma_f32_16x16x32_bf16 v[122:125], v[142:145], v[182:185], v[122:125]
	v_mfma_f32_16x16x32_bf16 v[110:113], v[134:137], v[200:203], v[110:113]
	v_mfma_f32_16x16x32_bf16 v[106:109], v[142:145], v[200:203], v[106:109]
	v_mfma_f32_16x16x32_bf16 v[94:97], v[134:137], v[214:217], v[94:97]
	v_mfma_f32_16x16x32_bf16 v[90:93], v[142:145], v[214:217], v[90:93]
	v_mfma_f32_16x16x32_bf16 v[78:81], v[134:137], v[222:225], v[78:81]
	v_mfma_f32_16x16x32_bf16 v[74:77], v[142:145], v[222:225], v[74:77]
	s_barrier
	s_add_i32 s39, 0, 0x14000
	v_add_u32_e32 v162, s39, v193
	s_add_i32 s26, s38, s84
	ds_read_b128 v[226:229], v162
	ds_read_b128 v[230:233], v162 offset:1024
	ds_read_b128 v[234:237], v162 offset:2048
	ds_read_b128 v[238:241], v162 offset:3072
	v_lshl_add_u64 v[162:163], s[80:81], 0, v[8:9]
	s_mov_b32 m0, s26
	v_lshl_add_u64 v[164:165], s[80:81], 0, v[176:177]
	global_load_lds_dwordx4 v[162:163], off
	s_add_i32 m0, s26, 0x2000
	s_nop 0
	global_load_lds_dwordx4 v[164:165], off
	s_barrier
	s_waitcnt lgkmcnt(0)
	v_mfma_f32_16x16x32_bf16 v[118:121], v[226:229], v[146:149], v[118:121]
	v_mfma_f32_16x16x32_bf16 v[114:117], v[234:237], v[146:149], v[114:117]
	v_mfma_f32_16x16x32_bf16 v[102:105], v[226:229], v[186:189], v[102:105]
	v_mfma_f32_16x16x32_bf16 v[98:101], v[234:237], v[186:189], v[98:101]
	v_mfma_f32_16x16x32_bf16 v[86:89], v[226:229], v[204:207], v[86:89]
	v_mfma_f32_16x16x32_bf16 v[82:85], v[234:237], v[204:207], v[82:85]
	v_mfma_f32_16x16x32_bf16 v[70:73], v[226:229], v[218:221], v[70:73]
	v_mfma_f32_16x16x32_bf16 v[66:69], v[234:237], v[218:221], v[66:69]
	v_mfma_f32_16x16x32_bf16 v[118:121], v[230:233], v[182:185], v[118:121]
	v_mfma_f32_16x16x32_bf16 v[114:117], v[238:241], v[182:185], v[114:117]
	v_mfma_f32_16x16x32_bf16 v[102:105], v[230:233], v[200:203], v[102:105]
	v_mfma_f32_16x16x32_bf16 v[98:101], v[238:241], v[200:203], v[98:101]
	v_mfma_f32_16x16x32_bf16 v[86:89], v[230:233], v[214:217], v[86:89]
	v_mfma_f32_16x16x32_bf16 v[82:85], v[238:241], v[214:217], v[82:85]
	v_mfma_f32_16x16x32_bf16 v[70:73], v[230:233], v[222:225], v[70:73]
	v_mfma_f32_16x16x32_bf16 v[66:69], v[238:241], v[222:225], v[66:69]
	s_mov_b32 m0, s85
	v_lshl_add_u64 v[190:191], s[82:83], 0, v[150:151]
	s_barrier
	ds_read_b128 v[146:149], v198 offset:16384
	ds_read_b128 v[182:185], v198 offset:17408
	ds_read_b128 v[186:189], v198 offset:18432
	ds_read_b128 v[200:203], v198 offset:19456
	ds_read_b128 v[204:207], v198 offset:20480
	ds_read_b128 v[214:217], v198 offset:21504
	ds_read_b128 v[218:221], v198 offset:22528
	ds_read_b128 v[222:225], v198 offset:23552
	global_load_lds_dwordx4 v[190:191], off
	s_mov_b32 m0, s86
	v_lshl_add_u64 v[208:209], s[82:83], 0, v[152:153]
	global_load_lds_dwordx4 v[208:209], off
	s_barrier
	s_waitcnt lgkmcnt(0)
	v_mfma_f32_16x16x32_bf16 v[62:65], v[130:133], v[146:149], v[62:65]
	v_mfma_f32_16x16x32_bf16 v[58:61], v[138:141], v[146:149], v[58:61]
	v_mfma_f32_16x16x32_bf16 v[46:49], v[130:133], v[186:189], v[46:49]
	v_mfma_f32_16x16x32_bf16 v[42:45], v[138:141], v[186:189], v[42:45]
	v_mfma_f32_16x16x32_bf16 v[30:33], v[130:133], v[204:207], v[30:33]
	v_mfma_f32_16x16x32_bf16 v[26:29], v[138:141], v[204:207], v[26:29]
	v_mfma_f32_16x16x32_bf16 v[14:17], v[130:133], v[218:221], v[14:17]
	v_mfma_f32_16x16x32_bf16 v[10:13], v[138:141], v[218:221], v[10:13]
	v_mfma_f32_16x16x32_bf16 v[62:65], v[134:137], v[182:185], v[62:65]
	v_mfma_f32_16x16x32_bf16 v[58:61], v[142:145], v[182:185], v[58:61]
	v_mfma_f32_16x16x32_bf16 v[46:49], v[134:137], v[200:203], v[46:49]
	v_mfma_f32_16x16x32_bf16 v[42:45], v[142:145], v[200:203], v[42:45]
	v_mfma_f32_16x16x32_bf16 v[30:33], v[134:137], v[214:217], v[30:33]
	v_mfma_f32_16x16x32_bf16 v[26:29], v[142:145], v[214:217], v[26:29]
	v_mfma_f32_16x16x32_bf16 v[14:17], v[134:137], v[222:225], v[14:17]
	v_mfma_f32_16x16x32_bf16 v[10:13], v[142:145], v[222:225], v[10:13]
	s_barrier
	s_add_u32 s26, s80, 0x40000
	s_addc_u32 s27, s81, 0
	s_add_i32 s38, s39, s84
	s_mov_b32 m0, s38
	s_nop 0
	global_load_lds_dwordx4 v8, s[26:27]
	s_add_i32 m0, s38, 0x2000
	s_nop 0
	global_load_lds_dwordx4 v176, s[26:27]
	s_waitcnt vmcnt(6)
	s_barrier
; #define PG8_STAGE(bufoff, gbase, voff) do { _Pragma("unroll") for (int _i = 0; _i < 2; ++_i) \
;         __builtin_amdgcn_global_load_lds((const unsigned*)((const char*)(gbase) + (voff)[_i]), (LAS unsigned*)(lds + (bufoff) + ldsw + _i * 8192), 16, 0, 0); } while (0)
; #define PG8_LDA(dst, b, h) do { _Pragma("unroll") for (int m = 0; m < 4; ++m) _Pragma("unroll") for (int k = 0; k < 2; ++k) dst[m][k] = *(const LAS bf16x8*)(lds + PG8_SA(b, h) + aoff + m * 2048 + k * 1024); } while (0)
; #define PG8_LDB(dst, b, h) do { _Pragma("unroll") for (int n = 0; n < 2; ++n) _Pragma("unroll") for (int k = 0; k < 2; ++k) dst[n][k] = *(const LAS bf16x8*)(lds + PG8_SB(b, h) + boff + n * 2048 + k * 1024); } while (0)
; #define PG8_MMA(ai, bj, At, Bt) do { __builtin_amdgcn_s_setprio(1); _Pragma("unroll") for (int m = 0; m < 4; ++m) _Pragma("unroll") for (int n = 0; n < 2; ++n) _Pragma("unroll") for (int k = 0; k < 2; ++k) \
;         acc[ai][bj][m][n] = __builtin_amdgcn_mfma_f32_16x16x32_bf16(Bt[n][k], At[m][k], acc[ai][bj][m][n], 0, 0, 0); __builtin_amdgcn_s_setprio(0); } while (0)
; #define PG8_WAIT_V(n) asm volatile("s_waitcnt vmcnt(" #n ")" ::: "memory")
; #define PG8_WAIT_L(n) asm volatile("s_waitcnt lgkmcnt(" #n ")" ::: "memory")
; #define PG8_BAR __builtin_amdgcn_s_barrier()
; #define PG8_SCHED __builtin_amdgcn_sched_barrier(0)
; template <class Epi>
; DEVI void gemm_phase(LAS unsigned char* lds, const Gemm g, const Epi& E) {
;     ...
;             PG8_WAIT_V(6); PG8_BAR; PG8_MMA(1, 1, At, B1); PG8_BAR;
;             PG8_LDB(B0, 1, 0); PG8_SCHED; PG8_LDA(At, 1, 0); PG8_STAGE(PG8_SA(0, 1), a2 + hstepA, voffA);
;             PG8_WAIT_L(8); PG8_BAR; PG8_WAIT_L(0); PG8_MMA(0, 0, At, B0); PG8_BAR; PG8_SCHED;
;             PG8_LDB(B1, 1, 1); PG8_STAGE(PG8_SB(1, 0), b3, voffB);
;             PG8_BAR; PG8_WAIT_L(0); PG8_MMA(0, 1, At, B1); PG8_BAR;
;             PG8_LDA(At, 1, 1); PG8_STAGE(PG8_SA(1, 0), a3, voffA);
	v_mfma_f32_16x16x32_bf16 v[54:57], v[226:229], v[146:149], v[54:57]
	v_mfma_f32_16x16x32_bf16 v[50:53], v[234:237], v[146:149], v[50:53]
	v_mfma_f32_16x16x32_bf16 v[38:41], v[226:229], v[186:189], v[38:41]
	v_mfma_f32_16x16x32_bf16 v[34:37], v[234:237], v[186:189], v[34:37]
	v_mfma_f32_16x16x32_bf16 v[22:25], v[226:229], v[204:207], v[22:25]
	v_mfma_f32_16x16x32_bf16 v[18:21], v[234:237], v[204:207], v[18:21]
	v_mfma_f32_16x16x32_bf16 v[4:7], v[226:229], v[218:221], v[4:7]
	v_mfma_f32_16x16x32_bf16 v[0:3], v[234:237], v[218:221], v[0:3]
	v_mfma_f32_16x16x32_bf16 v[54:57], v[230:233], v[182:185], v[54:57]
	v_mfma_f32_16x16x32_bf16 v[50:53], v[238:241], v[182:185], v[50:53]
	v_mfma_f32_16x16x32_bf16 v[38:41], v[230:233], v[200:203], v[38:41]
	v_mfma_f32_16x16x32_bf16 v[34:37], v[238:241], v[200:203], v[34:37]
	v_mfma_f32_16x16x32_bf16 v[22:25], v[230:233], v[214:217], v[22:25]
	v_mfma_f32_16x16x32_bf16 v[18:21], v[238:241], v[214:217], v[18:21]
	v_mfma_f32_16x16x32_bf16 v[4:7], v[230:233], v[222:225], v[4:7]
	v_mfma_f32_16x16x32_bf16 v[0:3], v[238:241], v[222:225], v[0:3]
	s_add_i32 s38, 0, 0x18000
	v_add_u32_e32 v142, s38, v193
	s_barrier
	ds_read_b128 v[130:133], v142
	ds_read_b128 v[134:137], v142 offset:1024
	ds_read_b128 v[138:141], v142 offset:2048
	ds_read_b128 v[142:145], v142 offset:3072
	s_add_u32 s26, s82, 0x40000
	s_addc_u32 s27, s83, 0
	s_mov_b32 m0, s87
	ds_read_b128 v[146:149], v198 offset:32768
	ds_read_b128 v[182:185], v198 offset:33792
	ds_read_b128 v[186:189], v198 offset:34816
	ds_read_b128 v[200:203], v198 offset:35840
	ds_read_b128 v[204:207], v198 offset:36864
	ds_read_b128 v[214:217], v198 offset:37888
	ds_read_b128 v[218:221], v198 offset:38912
	ds_read_b128 v[222:225], v198 offset:39936
	global_load_lds_dwordx4 v150, s[26:27]
	s_mov_b32 m0, s88
	s_nop 0
	global_load_lds_dwordx4 v152, s[26:27]
	s_waitcnt lgkmcnt(8)
	s_barrier
	s_waitcnt lgkmcnt(0)
	v_mfma_f32_16x16x32_bf16 v[126:129], v[130:133], v[146:149], v[126:129]
	v_mfma_f32_16x16x32_bf16 v[122:125], v[138:141], v[146:149], v[122:125]
	v_mfma_f32_16x16x32_bf16 v[110:113], v[130:133], v[186:189], v[110:113]
	v_mfma_f32_16x16x32_bf16 v[106:109], v[138:141], v[186:189], v[106:109]
	v_mfma_f32_16x16x32_bf16 v[94:97], v[130:133], v[204:207], v[94:97]
	v_mfma_f32_16x16x32_bf16 v[90:93], v[138:141], v[204:207], v[90:93]
	v_mfma_f32_16x16x32_bf16 v[78:81], v[130:133], v[218:221], v[78:81]
	v_mfma_f32_16x16x32_bf16 v[74:77], v[138:141], v[218:221], v[74:77]
	v_mfma_f32_16x16x32_bf16 v[126:129], v[134:137], v[182:185], v[126:129]
	v_mfma_f32_16x16x32_bf16 v[122:125], v[142:145], v[182:185], v[122:125]
	v_mfma_f32_16x16x32_bf16 v[110:113], v[134:137], v[200:203], v[110:113]
	v_mfma_f32_16x16x32_bf16 v[106:109], v[142:145], v[200:203], v[106:109]
	v_mfma_f32_16x16x32_bf16 v[94:97], v[134:137], v[214:217], v[94:97]
	v_mfma_f32_16x16x32_bf16 v[90:93], v[142:145], v[214:217], v[90:93]
	v_mfma_f32_16x16x32_bf16 v[78:81], v[134:137], v[222:225], v[78:81]
	v_mfma_f32_16x16x32_bf16 v[74:77], v[142:145], v[222:225], v[74:77]
	s_barrier
	s_add_i32 s39, 0, 0x1c000
	s_add_i32 s26, s38, s84
	v_add_u32_e32 v199, s39, v193
	v_lshl_add_u64 v[162:163], v[162:163], 0, s[70:71]
	s_mov_b32 m0, s26
	ds_read_b128 v[226:229], v199
	ds_read_b128 v[230:233], v199 offset:1024
	ds_read_b128 v[234:237], v199 offset:2048
	ds_read_b128 v[238:241], v199 offset:3072
	global_load_lds_dwordx4 v[162:163], off
	s_add_i32 m0, s26, 0x2000
	v_lshl_add_u64 v[162:163], v[164:165], 0, s[70:71]
	global_load_lds_dwordx4 v[162:163], off
	s_barrier
	s_waitcnt lgkmcnt(0)
	v_mfma_f32_16x16x32_bf16 v[118:121], v[226:229], v[146:149], v[118:121]
	v_mfma_f32_16x16x32_bf16 v[114:117], v[234:237], v[146:149], v[114:117]
	v_mfma_f32_16x16x32_bf16 v[102:105], v[226:229], v[186:189], v[102:105]
	v_mfma_f32_16x16x32_bf16 v[98:101], v[234:237], v[186:189], v[98:101]
	v_mfma_f32_16x16x32_bf16 v[86:89], v[226:229], v[204:207], v[86:89]
	v_mfma_f32_16x16x32_bf16 v[82:85], v[234:237], v[204:207], v[82:85]
	v_mfma_f32_16x16x32_bf16 v[70:73], v[226:229], v[218:221], v[70:73]
	v_mfma_f32_16x16x32_bf16 v[66:69], v[234:237], v[218:221], v[66:69]
	v_mfma_f32_16x16x32_bf16 v[118:121], v[230:233], v[182:185], v[118:121]
	v_mfma_f32_16x16x32_bf16 v[114:117], v[238:241], v[182:185], v[114:117]
	v_mfma_f32_16x16x32_bf16 v[102:105], v[230:233], v[200:203], v[102:105]
	v_mfma_f32_16x16x32_bf16 v[98:101], v[238:241], v[200:203], v[98:101]
	v_mfma_f32_16x16x32_bf16 v[86:89], v[230:233], v[214:217], v[86:89]
	v_mfma_f32_16x16x32_bf16 v[82:85], v[238:241], v[214:217], v[82:85]
	v_mfma_f32_16x16x32_bf16 v[70:73], v[230:233], v[222:225], v[70:73]
	v_mfma_f32_16x16x32_bf16 v[66:69], v[238:241], v[222:225], v[66:69]
	s_mov_b32 m0, s89
	v_lshl_add_u64 v[162:163], v[190:191], 0, s[70:71]
	s_barrier
	ds_read_b128 v[146:149], v198 offset:49152
	ds_read_b128 v[182:185], v198 offset:50176
	ds_read_b128 v[186:189], v198 offset:51200
	ds_read_b128 v[200:203], v198 offset:52224
	ds_read_b128 v[204:207], v198 offset:53248
	ds_read_b128 v[214:217], v198 offset:54272
	ds_read_b128 v[218:221], v198 offset:55296
	ds_read_b128 v[222:225], v198 offset:56320
	global_load_lds_dwordx4 v[162:163], off
	s_mov_b32 m0, s90
	v_lshl_add_u64 v[162:163], v[208:209], 0, s[70:71]
	global_load_lds_dwordx4 v[162:163], off
	s_barrier
; #define LAS __attribute__((address_space(3)))
; #define PG8_STAGE(bufoff, gbase, voff) do { _Pragma("unroll") for (int _i = 0; _i < 2; ++_i) \
;         __builtin_amdgcn_global_load_lds((const unsigned*)((const char*)(gbase) + (voff)[_i]), (LAS unsigned*)(lds + (bufoff) + ldsw + _i * 8192), 16, 0, 0); } while (0)
; #define PG8_WAIT_V(n) asm volatile("s_waitcnt vmcnt(" #n ")" ::: "memory")
; template <class Epi>
; DEVI void gemm_phase(LAS unsigned char* lds, const Gemm g, const Epi& E) {
;     ...
;             PG8_BAR; PG8_WAIT_L(0); PG8_MMA(1, 0, At, B0); PG8_BAR; PG8_SCHED;
;             PG8_STAGE(PG8_SB(1, 1), b3 + hstepB, voffB);
;             PG8_WAIT_V(6); PG8_BAR; PG8_MMA(1, 1, At, B1); PG8_BAR;
;     ...
;                 if constexpr (Epi::PRE) {
; #pragma unroll
;                     for (int m = 0; m < 2; ++m)
; #pragma unroll
;                         for (int bj = 0; bj < 2; ++bj)
; #pragma unroll
;                             for (int n = 0; n < 2; ++n) pre[m][bj][n] = E.load(row0 + ai * HALF + (m0 + m) * 16, col0 + bj * HALF + n * NST);
;                 }
; #pragma unroll
;                 for (int mm = 0; mm < 2; ++mm) {
;                     const int m = m0 + mm;
;                     const int r = row0 + ai * HALF + m * 16; float rs = 1.f, part = 0.f;
;                     if constexpr (Epi::RS) rs = rsv[ai * 4 + m];
;                     if constexpr (Epi::PAIR) E.pair8(cur.b, r, cur.pn * HALF + wc * 32 + 8 * fq, acc[ai][0][m][0] * rs, acc[ai][0][m][1] * rs, acc[ai][1][m][0] * rs, acc[ai][1][m][1] * rs);
;                     else
; #pragma unroll
;                     for (int bj = 0; bj < 2; ++bj) {
;                         const int c = col0 + bj * HALF; f32x4 v0 = acc[ai][bj][m][0], v1 = acc[ai][bj][m][1];
;                         if constexpr (Epi::RS) { v0 = v0 * rs; v1 = v1 * rs; }
;                         if constexpr (Epi::PRE) part += E.frag_pre8(cur.b, r, c, v0, v1, pre[mm][bj][0], pre[mm][bj][1]);
;                         else if constexpr (Epi::PERM) E.frag8(cur.b, r, c, v0, v1);
;                         else { E.frag(cur.b, r, c, v0); E.frag(cur.b, r, c + 16, v1); }
;                     }
;                     if constexpr (Epi::SSQ) { part += __shfl_xor(part, 16); part += __shfl_xor(part, 32); if (fq == 0) ((LAS float*)(lds + 131072))[(wr * 4 + wc) * 128 + ai * 64 + m * 16 + fr] = part; }
	s_waitcnt lgkmcnt(0)
	v_mfma_f32_16x16x32_bf16 v[62:65], v[130:133], v[146:149], v[62:65]
	v_mfma_f32_16x16x32_bf16 v[58:61], v[138:141], v[146:149], v[58:61]
	v_mfma_f32_16x16x32_bf16 v[46:49], v[130:133], v[186:189], v[46:49]
	v_mfma_f32_16x16x32_bf16 v[42:45], v[138:141], v[186:189], v[42:45]
	v_mfma_f32_16x16x32_bf16 v[30:33], v[130:133], v[204:207], v[30:33]
	v_mfma_f32_16x16x32_bf16 v[26:29], v[138:141], v[204:207], v[26:29]
	v_mfma_f32_16x16x32_bf16 v[14:17], v[130:133], v[218:221], v[14:17]
	v_mfma_f32_16x16x32_bf16 v[10:13], v[138:141], v[218:221], v[10:13]
	v_mfma_f32_16x16x32_bf16 v[62:65], v[134:137], v[182:185], v[62:65]
	v_mfma_f32_16x16x32_bf16 v[58:61], v[142:145], v[182:185], v[58:61]
	v_mfma_f32_16x16x32_bf16 v[46:49], v[134:137], v[200:203], v[46:49]
	v_mfma_f32_16x16x32_bf16 v[42:45], v[142:145], v[200:203], v[42:45]
	v_mfma_f32_16x16x32_bf16 v[30:33], v[134:137], v[214:217], v[30:33]
	v_mfma_f32_16x16x32_bf16 v[26:29], v[142:145], v[214:217], v[26:29]
	v_mfma_f32_16x16x32_bf16 v[14:17], v[134:137], v[222:225], v[14:17]
	v_mfma_f32_16x16x32_bf16 v[10:13], v[142:145], v[222:225], v[10:13]
	s_barrier
	s_add_u32 s26, s80, 0x40080
	s_addc_u32 s27, s81, 0
	s_add_i32 s38, s39, s84
	s_mov_b32 m0, s38
	s_nop 0
	global_load_lds_dwordx4 v8, s[26:27]
	s_add_i32 m0, s38, 0x2000
	s_nop 0
	global_load_lds_dwordx4 v176, s[26:27]
	s_waitcnt vmcnt(6)
	s_barrier
	v_mfma_f32_16x16x32_bf16 v[54:57], v[226:229], v[146:149], v[54:57]
	v_mfma_f32_16x16x32_bf16 v[50:53], v[234:237], v[146:149], v[50:53]
	v_mfma_f32_16x16x32_bf16 v[38:41], v[226:229], v[186:189], v[38:41]
	v_mfma_f32_16x16x32_bf16 v[34:37], v[234:237], v[186:189], v[34:37]
	v_mfma_f32_16x16x32_bf16 v[22:25], v[226:229], v[204:207], v[22:25]
	v_mfma_f32_16x16x32_bf16 v[18:21], v[234:237], v[204:207], v[18:21]
	v_mfma_f32_16x16x32_bf16 v[4:7], v[226:229], v[218:221], v[4:7]
	v_mfma_f32_16x16x32_bf16 v[0:3], v[234:237], v[218:221], v[0:3]
	v_mfma_f32_16x16x32_bf16 v[54:57], v[230:233], v[182:185], v[54:57]
	v_mfma_f32_16x16x32_bf16 v[50:53], v[238:241], v[182:185], v[50:53]
	v_mfma_f32_16x16x32_bf16 v[38:41], v[230:233], v[200:203], v[38:41]
	v_mfma_f32_16x16x32_bf16 v[34:37], v[238:241], v[200:203], v[34:37]
	v_mfma_f32_16x16x32_bf16 v[22:25], v[230:233], v[214:217], v[22:25]
	v_mfma_f32_16x16x32_bf16 v[18:21], v[238:241], v[214:217], v[18:21]
	v_mfma_f32_16x16x32_bf16 v[4:7], v[230:233], v[222:225], v[4:7]
	v_mfma_f32_16x16x32_bf16 v[0:3], v[238:241], v[222:225], v[0:3]
	s_add_i32 s19, s19, 2
	s_add_u32 s68, s68, 0x100
	s_addc_u32 s69, s69, 0
	s_add_u32 s15, s15, 0x100
	s_addc_u32 s18, s18, 0
	s_cmp_gt_u32 s19, 13
	s_barrier
	s_cbranch_scc0 .LBB0_968
	s_setprio 0
	v_and_b32_e32 v131, 64, v155
	v_xor_b32_e32 v130, 16, v155
	v_add_u32_e32 v131, 64, v131
	v_cmp_lt_i32_e32 vcc, v130, v131
	s_lshl_b32 s9, s46, 8
	v_add_u32_e32 v186, s9, v192
	v_cndmask_b32_e32 v130, v155, v130, vcc
	v_lshlrev_b32_e32 v200, 2, v130
	v_xor_b32_e32 v130, 32, v155
	v_cmp_lt_i32_e32 vcc, v130, v131
	v_lshl_or_b32 v184, s8, 8, v197
	v_ashrrev_i32_e32 v187, 31, v186
	v_cndmask_b32_e32 v130, v155, v130, vcc
	v_lshlrev_b32_e32 v199, 2, v130
	v_lshlrev_b64 v[130:131], 12, v[186:187]
	v_ashrrev_i32_e32 v185, 31, v184
	v_lshl_add_u64 v[130:131], s[78:79], 0, v[130:131]
	v_lshlrev_b64 v[188:189], 2, v[184:185]
	v_lshl_add_u64 v[130:131], v[130:131], 0, v[188:189]
	global_load_dwordx4 v[202:205], v[130:131], off offset:16
	global_load_dwordx4 v[206:209], v[130:131], off
	global_load_dwordx4 v[146:149], v[130:131], off offset:528
	global_load_dwordx4 v[214:217], v[130:131], off offset:512
	v_or_b32_e32 v190, 16, v186
	v_ashrrev_i32_e32 v191, 31, v190
	v_lshlrev_b64 v[130:131], 12, v[190:191]
	v_lshl_add_u64 v[130:131], s[78:79], 0, v[130:131]
	v_lshl_add_u64 v[134:135], v[130:131], 0, v[188:189]
	global_load_dwordx4 v[138:141], v[134:135], off offset:16
	global_load_dwordx4 v[142:145], v[134:135], off
	global_load_dwordx4 v[130:133], v[134:135], off offset:528
	s_nop 0
	global_load_dwordx4 v[134:137], v[134:135], off offset:512
	v_lshlrev_b64 v[162:163], 10, v[186:187]
	v_lshl_add_u64 v[164:165], v[162:163], 0, v[184:185]
	v_or_b32_e32 v182, 0x80, v184
	v_ashrrev_i32_e32 v183, 31, v182
	s_waitcnt vmcnt(0)
	v_pk_add_f32 v[122:123], v[122:123], v[202:203]
	v_pk_add_f32 v[128:129], v[128:129], v[208:209]
	v_pk_add_f32 v[126:127], v[126:127], v[206:207]
	v_lshl_add_u64 v[206:207], v[164:165], 2, s[30:31]
	v_pk_add_f32 v[124:125], v[124:125], v[204:205]
	global_store_dwordx4 v[206:207], v[126:129], off
	global_store_dwordx4 v[206:207], v[122:125], off offset:16
	v_cvt_pk_bf16_f32 v202, v126, v127
	v_cvt_pk_bf16_f32 v204, v122, v123
	v_mul_f32_e32 v127, v127, v127
	v_mul_f32_e32 v123, v123, v123
	v_fmac_f32_e32 v127, v126, v126
	v_mul_f32_e32 v126, v129, v129
	v_fmac_f32_e32 v123, v122, v122
	v_mul_f32_e32 v122, v125, v125
	v_fmac_f32_e32 v126, v128, v128
	v_fmac_f32_e32 v122, v124, v124
	v_cvt_pk_bf16_f32 v203, v128, v129
	v_cvt_pk_bf16_f32 v205, v124, v125
	v_lshl_add_u64 v[164:165], v[164:165], 1, s[28:29]
	v_add_f32_e32 v126, v127, v126
	v_add_f32_e32 v122, v123, v122
	v_pk_add_f32 v[120:121], v[120:121], v[216:217]
	v_pk_add_f32 v[118:119], v[118:119], v[214:215]
	v_pk_add_f32 v[114:115], v[114:115], v[146:147]
	global_store_dwordx4 v[164:165], v[202:205], off
	v_add_f32_e32 v128, v126, v122
	v_pk_add_f32 v[116:117], v[116:117], v[148:149]
	global_store_dwordx4 v[206:207], v[118:121], off offset:512
	global_store_dwordx4 v[206:207], v[114:117], off offset:528
	v_cvt_pk_bf16_f32 v122, v118, v119
	v_cvt_pk_bf16_f32 v124, v114, v115
	v_mul_f32_e32 v119, v119, v119
	v_mul_f32_e32 v115, v115, v115
	v_fmac_f32_e32 v119, v118, v118
	v_mul_f32_e32 v118, v121, v121
	v_fmac_f32_e32 v115, v114, v114
	v_mul_f32_e32 v114, v117, v117
	v_fmac_f32_e32 v118, v120, v120
	v_fmac_f32_e32 v114, v116, v116
	v_add_f32_e32 v118, v119, v118
	v_add_f32_e32 v114, v115, v114
	v_add_f32_e32 v114, v118, v114
	v_add_f32_e32 v114, v128, v114
	ds_bpermute_b32 v115, v200, v114
	v_lshl_add_u64 v[126:127], v[162:163], 0, v[182:183]
	v_cvt_pk_bf16_f32 v123, v120, v121
	v_cvt_pk_bf16_f32 v125, v116, v117
	v_lshl_add_u64 v[126:127], v[126:127], 1, s[28:29]
	s_waitcnt lgkmcnt(0)
	v_add_f32_e32 v114, v114, v115
	ds_bpermute_b32 v115, v199, v114
	global_store_dwordx4 v[126:127], v[122:125], off
	s_and_saveexec_b64 s[46:47], s[2:3]
	s_cbranch_execz .LBB0_971
	s_waitcnt lgkmcnt(0)
	v_add_f32_e32 v114, v114, v115
	ds_write_b32 v194, v114

; #define PG8_STAGE(bufoff, gbase, voff) do { _Pragma("unroll") for (int _i = 0; _i < 2; ++_i) \
;         __builtin_amdgcn_global_load_lds((const unsigned*)((const char*)(gbase) + (voff)[_i]), (LAS unsigned*)(lds + (bufoff) + ldsw + _i * 8192), 16, 0, 0); } while (0)
; #define PG8_LDA(dst, b, h) do { _Pragma("unroll") for (int m = 0; m < 4; ++m) _Pragma("unroll") for (int k = 0; k < 2; ++k) dst[m][k] = *(const LAS bf16x8*)(lds + PG8_SA(b, h) + aoff + m * 2048 + k * 1024); } while (0)
; #define PG8_LDB(dst, b, h) do { _Pragma("unroll") for (int n = 0; n < 2; ++n) _Pragma("unroll") for (int k = 0; k < 2; ++k) dst[n][k] = *(const LAS bf16x8*)(lds + PG8_SB(b, h) + boff + n * 2048 + k * 1024); } while (0)
; #define PG8_MMA(ai, bj, At, Bt) do { __builtin_amdgcn_s_setprio(1); _Pragma("unroll") for (int m = 0; m < 4; ++m) _Pragma("unroll") for (int n = 0; n < 2; ++n) _Pragma("unroll") for (int k = 0; k < 2; ++k) \
;         acc[ai][bj][m][n] = __builtin_amdgcn_mfma_f32_16x16x32_bf16(Bt[n][k], At[m][k], acc[ai][bj][m][n], 0, 0, 0); __builtin_amdgcn_s_setprio(0); } while (0)
; #define PG8_WAIT_V(n) asm volatile("s_waitcnt vmcnt(" #n ")" ::: "memory")
; #define PG8_WAIT_L(n) asm volatile("s_waitcnt lgkmcnt(" #n ")" ::: "memory")
; #define PG8_BAR __builtin_amdgcn_s_barrier()
; #define PG8_SCHED __builtin_amdgcn_sched_barrier(0)
; template <class Epi>
; DEVI void gemm_phase(LAS unsigned char* lds, const Gemm g, const Epi& E) {
;     ...
;             const bool last = (t == nt - 2);
;             const char* a1 = cA + (size_t)(t + 1) * kstep;
;             const char* a2 = last ? nA : cA + (size_t)(t + 2) * kstep; const char* b2 = last ? nB : cB + (size_t)(t + 2) * kstep;
;             const char* a3 = a2 + kstep; const char* b3 = b2 + kstep;
;             PG8_LDB(B0, 0, 0); PG8_SCHED; PG8_LDA(At, 0, 0); PG8_STAGE(PG8_SA(1, 1), a1 + hstepA, voffA);
;             PG8_WAIT_L(8); PG8_BAR; PG8_WAIT_L(0); PG8_MMA(0, 0, At, B0); PG8_BAR; PG8_SCHED;
;             PG8_LDB(B1, 0, 1); PG8_STAGE(PG8_SB(0, 0), b2, voffB);
;             PG8_BAR; PG8_WAIT_L(0); PG8_MMA(0, 1, At, B1); PG8_BAR;
;             PG8_LDA(At, 0, 1); PG8_STAGE(PG8_SA(0, 0), a2, voffA);
;             PG8_BAR; PG8_WAIT_L(0); PG8_MMA(1, 0, At, B0); PG8_BAR; PG8_SCHED;
;             PG8_STAGE(PG8_SB(0, 1), b2 + hstepB, voffB);
;             PG8_WAIT_V(6); PG8_BAR; PG8_MMA(1, 1, At, B1); PG8_BAR;
.LBB0_1007:
	s_add_u32 s16, s14, 0xfffc0080
	s_addc_u32 s17, s15, -1
	s_add_i32 s26, 0, 0x10000
	v_add_u32_e32 v8, s26, v199
	ds_read_b128 v[130:133], v8
	ds_read_b128 v[134:137], v8 offset:1024
	ds_read_b128 v[138:141], v8 offset:2048
	ds_read_b128 v[142:145], v8 offset:3072
	s_cmp_eq_u32 s19, 12
	s_cselect_b32 s37, s0, s17
	s_cselect_b32 s36, s1, s16
	s_cselect_b32 s17, s5, s18
	s_cselect_b32 s16, s7, s9
	s_add_i32 m0, s66, 0xc000
	ds_read_b128 v[184:187], v204
	ds_read_b128 v[188:191], v204 offset:1024
	ds_read_b128 v[192:195], v204 offset:2048
	ds_read_b128 v[206:209], v204 offset:3072
	ds_read_b128 v[214:217], v204 offset:4096
	ds_read_b128 v[218:221], v204 offset:5120
	ds_read_b128 v[222:225], v204 offset:6144
	ds_read_b128 v[226:229], v204 offset:7168
	global_load_lds_dwordx4 v180, s[14:15]
	s_add_i32 m0, s66, 0xe000
	s_nop 0
	global_load_lds_dwordx4 v182, s[14:15]
	s_waitcnt lgkmcnt(8)
	s_barrier
	s_waitcnt lgkmcnt(0)
	v_mfma_f32_16x16x32_bf16 v[126:129], v[130:133], v[184:187], v[126:129]
	v_mfma_f32_16x16x32_bf16 v[122:125], v[138:141], v[184:187], v[122:125]
	v_mfma_f32_16x16x32_bf16 v[114:117], v[130:133], v[192:195], v[114:117]
	v_mfma_f32_16x16x32_bf16 v[106:109], v[138:141], v[192:195], v[106:109]
	v_mfma_f32_16x16x32_bf16 v[102:105], v[130:133], v[214:217], v[102:105]
	v_mfma_f32_16x16x32_bf16 v[94:97], v[138:141], v[214:217], v[94:97]
	v_mfma_f32_16x16x32_bf16 v[82:85], v[130:133], v[222:225], v[82:85]
	v_mfma_f32_16x16x32_bf16 v[74:77], v[138:141], v[222:225], v[74:77]
	v_mfma_f32_16x16x32_bf16 v[126:129], v[134:137], v[188:191], v[126:129]
	v_mfma_f32_16x16x32_bf16 v[122:125], v[142:145], v[188:191], v[122:125]
	v_mfma_f32_16x16x32_bf16 v[114:117], v[134:137], v[206:209], v[114:117]
	v_mfma_f32_16x16x32_bf16 v[106:109], v[142:145], v[206:209], v[106:109]
	v_mfma_f32_16x16x32_bf16 v[102:105], v[134:137], v[218:221], v[102:105]
	v_mfma_f32_16x16x32_bf16 v[94:97], v[142:145], v[218:221], v[94:97]
	v_mfma_f32_16x16x32_bf16 v[82:85], v[134:137], v[226:229], v[82:85]
	v_mfma_f32_16x16x32_bf16 v[74:77], v[142:145], v[226:229], v[74:77]
	s_barrier
	s_add_i32 s38, 0, 0x14000
	s_add_i32 s26, s26, s47
	v_add_u32_e32 v8, s38, v199
	v_lshl_add_u64 v[162:163], s[16:17], 0, v[148:149]
	s_mov_b32 m0, s26
	ds_read_b128 v[230:233], v8
	ds_read_b128 v[234:237], v8 offset:1024
	ds_read_b128 v[238:241], v8 offset:2048
	ds_read_b128 v[242:245], v8 offset:3072
	global_load_lds_dwordx4 v[162:163], off
	s_add_i32 m0, s26, 0x2000
	v_lshl_add_u64 v[164:165], s[16:17], 0, v[152:153]
	global_load_lds_dwordx4 v[164:165], off
	s_barrier
	s_waitcnt lgkmcnt(0)
	v_mfma_f32_16x16x32_bf16 v[118:121], v[230:233], v[184:187], v[118:121]
	v_mfma_f32_16x16x32_bf16 v[110:113], v[238:241], v[184:187], v[110:113]
	v_mfma_f32_16x16x32_bf16 v[98:101], v[230:233], v[192:195], v[98:101]
	v_mfma_f32_16x16x32_bf16 v[90:93], v[238:241], v[192:195], v[90:93]
	v_mfma_f32_16x16x32_bf16 v[86:89], v[230:233], v[214:217], v[86:89]
	v_mfma_f32_16x16x32_bf16 v[78:81], v[238:241], v[214:217], v[78:81]
	v_mfma_f32_16x16x32_bf16 v[54:57], v[230:233], v[222:225], v[54:57]
	v_mfma_f32_16x16x32_bf16 v[34:37], v[238:241], v[222:225], v[34:37]
	v_mfma_f32_16x16x32_bf16 v[118:121], v[234:237], v[188:191], v[118:121]
	v_mfma_f32_16x16x32_bf16 v[110:113], v[242:245], v[188:191], v[110:113]
	v_mfma_f32_16x16x32_bf16 v[98:101], v[234:237], v[206:209], v[98:101]
	v_mfma_f32_16x16x32_bf16 v[90:93], v[242:245], v[206:209], v[90:93]
	v_mfma_f32_16x16x32_bf16 v[86:89], v[234:237], v[218:221], v[86:89]
	v_mfma_f32_16x16x32_bf16 v[78:81], v[242:245], v[218:221], v[78:81]
	v_mfma_f32_16x16x32_bf16 v[54:57], v[234:237], v[226:229], v[54:57]
	v_mfma_f32_16x16x32_bf16 v[34:37], v[242:245], v[226:229], v[34:37]
	s_mov_b32 m0, s66
	v_lshl_add_u64 v[202:203], s[36:37], 0, v[146:147]
	s_barrier
	ds_read_b128 v[184:187], v204 offset:16384
	ds_read_b128 v[188:191], v204 offset:17408
	ds_read_b128 v[192:195], v204 offset:18432
	ds_read_b128 v[206:209], v204 offset:19456
	ds_read_b128 v[214:217], v204 offset:20480
	ds_read_b128 v[218:221], v204 offset:21504
	ds_read_b128 v[222:225], v204 offset:22528
	ds_read_b128 v[226:229], v204 offset:23552
	global_load_lds_dwordx4 v[202:203], off
	s_mov_b32 m0, s68
	v_lshl_add_u64 v[246:247], s[36:37], 0, v[150:151]
	global_load_lds_dwordx4 v[246:247], off
	s_barrier
	s_waitcnt lgkmcnt(0)
	v_mfma_f32_16x16x32_bf16 v[58:61], v[130:133], v[184:187], v[58:61]
	v_mfma_f32_16x16x32_bf16 v[62:65], v[138:141], v[184:187], v[62:65]
	v_mfma_f32_16x16x32_bf16 v[38:41], v[130:133], v[192:195], v[38:41]
	v_mfma_f32_16x16x32_bf16 v[42:45], v[138:141], v[192:195], v[42:45]
	v_mfma_f32_16x16x32_bf16 v[18:21], v[130:133], v[214:217], v[18:21]
	v_mfma_f32_16x16x32_bf16 v[22:25], v[138:141], v[214:217], v[22:25]
	v_mfma_f32_16x16x32_bf16 v[0:3], v[130:133], v[222:225], v[0:3]
	v_mfma_f32_16x16x32_bf16 v[4:7], v[138:141], v[222:225], v[4:7]
	v_mfma_f32_16x16x32_bf16 v[58:61], v[134:137], v[188:191], v[58:61]
	v_mfma_f32_16x16x32_bf16 v[62:65], v[142:145], v[188:191], v[62:65]
	v_mfma_f32_16x16x32_bf16 v[38:41], v[134:137], v[206:209], v[38:41]
	v_mfma_f32_16x16x32_bf16 v[42:45], v[142:145], v[206:209], v[42:45]
	v_mfma_f32_16x16x32_bf16 v[18:21], v[134:137], v[218:221], v[18:21]
	v_mfma_f32_16x16x32_bf16 v[22:25], v[142:145], v[218:221], v[22:25]
	v_mfma_f32_16x16x32_bf16 v[0:3], v[134:137], v[226:229], v[0:3]
	v_mfma_f32_16x16x32_bf16 v[4:7], v[142:145], v[226:229], v[4:7]
	s_barrier
	s_add_u32 s26, s16, 0x40000
	s_addc_u32 s27, s17, 0
	s_add_i32 s38, s38, s47
	s_mov_b32 m0, s38
	s_nop 0
	global_load_lds_dwordx4 v148, s[26:27]
	s_add_i32 m0, s38, 0x2000
	s_nop 0
	global_load_lds_dwordx4 v152, s[26:27]
	s_waitcnt vmcnt(6)
	s_barrier
; #define PG8_STAGE(bufoff, gbase, voff) do { _Pragma("unroll") for (int _i = 0; _i < 2; ++_i) \
;         __builtin_amdgcn_global_load_lds((const unsigned*)((const char*)(gbase) + (voff)[_i]), (LAS unsigned*)(lds + (bufoff) + ldsw + _i * 8192), 16, 0, 0); } while (0)
; #define PG8_LDA(dst, b, h) do { _Pragma("unroll") for (int m = 0; m < 4; ++m) _Pragma("unroll") for (int k = 0; k < 2; ++k) dst[m][k] = *(const LAS bf16x8*)(lds + PG8_SA(b, h) + aoff + m * 2048 + k * 1024); } while (0)
; #define PG8_LDB(dst, b, h) do { _Pragma("unroll") for (int n = 0; n < 2; ++n) _Pragma("unroll") for (int k = 0; k < 2; ++k) dst[n][k] = *(const LAS bf16x8*)(lds + PG8_SB(b, h) + boff + n * 2048 + k * 1024); } while (0)
; #define PG8_MMA(ai, bj, At, Bt) do { __builtin_amdgcn_s_setprio(1); _Pragma("unroll") for (int m = 0; m < 4; ++m) _Pragma("unroll") for (int n = 0; n < 2; ++n) _Pragma("unroll") for (int k = 0; k < 2; ++k) \
;         acc[ai][bj][m][n] = __builtin_amdgcn_mfma_f32_16x16x32_bf16(Bt[n][k], At[m][k], acc[ai][bj][m][n], 0, 0, 0); __builtin_amdgcn_s_setprio(0); } while (0)
; #define PG8_WAIT_V(n) asm volatile("s_waitcnt vmcnt(" #n ")" ::: "memory")
; #define PG8_WAIT_L(n) asm volatile("s_waitcnt lgkmcnt(" #n ")" ::: "memory")
; #define PG8_BAR __builtin_amdgcn_s_barrier()
; #define PG8_SCHED __builtin_amdgcn_sched_barrier(0)
; template <class Epi>
; DEVI void gemm_phase(LAS unsigned char* lds, const Gemm g, const Epi& E) {
;     ...
;             PG8_WAIT_V(6); PG8_BAR; PG8_MMA(1, 1, At, B1); PG8_BAR;
;             PG8_LDB(B0, 1, 0); PG8_SCHED; PG8_LDA(At, 1, 0); PG8_STAGE(PG8_SA(0, 1), a2 + hstepA, voffA);
;             PG8_WAIT_L(8); PG8_BAR; PG8_WAIT_L(0); PG8_MMA(0, 0, At, B0); PG8_BAR; PG8_SCHED;
;             PG8_LDB(B1, 1, 1); PG8_STAGE(PG8_SB(1, 0), b3, voffB);
;             PG8_BAR; PG8_WAIT_L(0); PG8_MMA(0, 1, At, B1); PG8_BAR;
;             PG8_LDA(At, 1, 1); PG8_STAGE(PG8_SA(1, 0), a3, voffA);
	v_mfma_f32_16x16x32_bf16 v[66:69], v[230:233], v[184:187], v[66:69]
	v_mfma_f32_16x16x32_bf16 v[70:73], v[238:241], v[184:187], v[70:73]
	v_mfma_f32_16x16x32_bf16 v[46:49], v[230:233], v[192:195], v[46:49]
	v_mfma_f32_16x16x32_bf16 v[50:53], v[238:241], v[192:195], v[50:53]
	v_mfma_f32_16x16x32_bf16 v[26:29], v[230:233], v[214:217], v[26:29]
	v_mfma_f32_16x16x32_bf16 v[30:33], v[238:241], v[214:217], v[30:33]
	v_mfma_f32_16x16x32_bf16 v[10:13], v[230:233], v[222:225], v[10:13]
	v_mfma_f32_16x16x32_bf16 v[14:17], v[238:241], v[222:225], v[14:17]
	v_mfma_f32_16x16x32_bf16 v[66:69], v[234:237], v[188:191], v[66:69]
	v_mfma_f32_16x16x32_bf16 v[70:73], v[242:245], v[188:191], v[70:73]
	v_mfma_f32_16x16x32_bf16 v[46:49], v[234:237], v[206:209], v[46:49]
	v_mfma_f32_16x16x32_bf16 v[50:53], v[242:245], v[206:209], v[50:53]
	v_mfma_f32_16x16x32_bf16 v[26:29], v[234:237], v[218:221], v[26:29]
	v_mfma_f32_16x16x32_bf16 v[30:33], v[242:245], v[218:221], v[30:33]
	v_mfma_f32_16x16x32_bf16 v[10:13], v[234:237], v[226:229], v[10:13]
	v_mfma_f32_16x16x32_bf16 v[14:17], v[242:245], v[226:229], v[14:17]
	s_add_i32 s38, 0, 0x18000
	v_add_u32_e32 v8, s38, v199
	s_barrier
	ds_read_b128 v[130:133], v8
	ds_read_b128 v[134:137], v8 offset:1024
	ds_read_b128 v[138:141], v8 offset:2048
	ds_read_b128 v[142:145], v8 offset:3072
	s_add_u32 s26, s36, 0x40000
	s_addc_u32 s27, s37, 0
	s_mov_b32 m0, s69
	ds_read_b128 v[184:187], v204 offset:32768
	ds_read_b128 v[188:191], v204 offset:33792
	ds_read_b128 v[192:195], v204 offset:34816
	ds_read_b128 v[206:209], v204 offset:35840
	ds_read_b128 v[214:217], v204 offset:36864
	ds_read_b128 v[218:221], v204 offset:37888
	ds_read_b128 v[222:225], v204 offset:38912
	ds_read_b128 v[226:229], v204 offset:39936
	global_load_lds_dwordx4 v146, s[26:27]
	s_mov_b32 m0, s80
	s_nop 0
	global_load_lds_dwordx4 v150, s[26:27]
	s_waitcnt lgkmcnt(8)
	s_barrier
	s_waitcnt lgkmcnt(0)
	v_mfma_f32_16x16x32_bf16 v[126:129], v[130:133], v[184:187], v[126:129]
	v_mfma_f32_16x16x32_bf16 v[122:125], v[138:141], v[184:187], v[122:125]
	v_mfma_f32_16x16x32_bf16 v[114:117], v[130:133], v[192:195], v[114:117]
	v_mfma_f32_16x16x32_bf16 v[106:109], v[138:141], v[192:195], v[106:109]
	v_mfma_f32_16x16x32_bf16 v[102:105], v[130:133], v[214:217], v[102:105]
	v_mfma_f32_16x16x32_bf16 v[94:97], v[138:141], v[214:217], v[94:97]
	v_mfma_f32_16x16x32_bf16 v[82:85], v[130:133], v[222:225], v[82:85]
	v_mfma_f32_16x16x32_bf16 v[74:77], v[138:141], v[222:225], v[74:77]
	v_mfma_f32_16x16x32_bf16 v[126:129], v[134:137], v[188:191], v[126:129]
	v_mfma_f32_16x16x32_bf16 v[122:125], v[142:145], v[188:191], v[122:125]
	v_mfma_f32_16x16x32_bf16 v[114:117], v[134:137], v[206:209], v[114:117]
	v_mfma_f32_16x16x32_bf16 v[106:109], v[142:145], v[206:209], v[106:109]
	v_mfma_f32_16x16x32_bf16 v[102:105], v[134:137], v[218:221], v[102:105]
	v_mfma_f32_16x16x32_bf16 v[94:97], v[142:145], v[218:221], v[94:97]
	v_mfma_f32_16x16x32_bf16 v[82:85], v[134:137], v[226:229], v[82:85]
	v_mfma_f32_16x16x32_bf16 v[74:77], v[142:145], v[226:229], v[74:77]
	s_barrier
	s_add_i32 s26, 0, 0x1c000
	s_add_i32 s27, s38, s47
	v_add_u32_e32 v8, s26, v199
	v_lshl_add_u64 v[162:163], v[162:163], 0, s[70:71]
	s_mov_b32 m0, s27
	ds_read_b128 v[230:233], v8
	ds_read_b128 v[234:237], v8 offset:1024
	ds_read_b128 v[238:241], v8 offset:2048
	ds_read_b128 v[242:245], v8 offset:3072
	global_load_lds_dwordx4 v[162:163], off
	s_add_i32 m0, s27, 0x2000
	v_lshl_add_u64 v[162:163], v[164:165], 0, s[70:71]
	global_load_lds_dwordx4 v[162:163], off
	s_barrier
	s_waitcnt lgkmcnt(0)
	v_mfma_f32_16x16x32_bf16 v[118:121], v[230:233], v[184:187], v[118:121]
	v_mfma_f32_16x16x32_bf16 v[110:113], v[238:241], v[184:187], v[110:113]
	v_mfma_f32_16x16x32_bf16 v[98:101], v[230:233], v[192:195], v[98:101]
	v_mfma_f32_16x16x32_bf16 v[90:93], v[238:241], v[192:195], v[90:93]
	v_mfma_f32_16x16x32_bf16 v[86:89], v[230:233], v[214:217], v[86:89]
	v_mfma_f32_16x16x32_bf16 v[78:81], v[238:241], v[214:217], v[78:81]
	v_mfma_f32_16x16x32_bf16 v[54:57], v[230:233], v[222:225], v[54:57]
	v_mfma_f32_16x16x32_bf16 v[34:37], v[238:241], v[222:225], v[34:37]
	v_mfma_f32_16x16x32_bf16 v[118:121], v[234:237], v[188:191], v[118:121]
	v_mfma_f32_16x16x32_bf16 v[110:113], v[242:245], v[188:191], v[110:113]
	v_mfma_f32_16x16x32_bf16 v[98:101], v[234:237], v[206:209], v[98:101]
	v_mfma_f32_16x16x32_bf16 v[90:93], v[242:245], v[206:209], v[90:93]
	v_mfma_f32_16x16x32_bf16 v[86:89], v[234:237], v[218:221], v[86:89]
	v_mfma_f32_16x16x32_bf16 v[78:81], v[242:245], v[218:221], v[78:81]
	v_mfma_f32_16x16x32_bf16 v[54:57], v[234:237], v[226:229], v[54:57]
	v_mfma_f32_16x16x32_bf16 v[34:37], v[242:245], v[226:229], v[34:37]
	s_mov_b32 m0, s81
	v_lshl_add_u64 v[162:163], v[202:203], 0, s[70:71]
	s_barrier
	ds_read_b128 v[184:187], v204 offset:49152
	ds_read_b128 v[188:191], v204 offset:50176
	ds_read_b128 v[192:195], v204 offset:51200
	ds_read_b128 v[206:209], v204 offset:52224
	ds_read_b128 v[214:217], v204 offset:53248
	ds_read_b128 v[218:221], v204 offset:54272
	ds_read_b128 v[222:225], v204 offset:55296
	ds_read_b128 v[226:229], v204 offset:56320
	global_load_lds_dwordx4 v[162:163], off
	s_mov_b32 m0, s82
	v_lshl_add_u64 v[162:163], v[246:247], 0, s[70:71]
	global_load_lds_dwordx4 v[162:163], off
	s_barrier
; #define PG8_STAGE(bufoff, gbase, voff) do { _Pragma("unroll") for (int _i = 0; _i < 2; ++_i) \
;         __builtin_amdgcn_global_load_lds((const unsigned*)((const char*)(gbase) + (voff)[_i]), (LAS unsigned*)(lds + (bufoff) + ldsw + _i * 8192), 16, 0, 0); } while (0)
; #define PG8_MMA(ai, bj, At, Bt) do { __builtin_amdgcn_s_setprio(1); _Pragma("unroll") for (int m = 0; m < 4; ++m) _Pragma("unroll") for (int n = 0; n < 2; ++n) _Pragma("unroll") for (int k = 0; k < 2; ++k) \
;         acc[ai][bj][m][n] = __builtin_amdgcn_mfma_f32_16x16x32_bf16(Bt[n][k], At[m][k], acc[ai][bj][m][n], 0, 0, 0); __builtin_amdgcn_s_setprio(0); } while (0)
; #define PG8_WAIT_V(n) asm volatile("s_waitcnt vmcnt(" #n ")" ::: "memory")
; #define PG8_WAIT_L(n) asm volatile("s_waitcnt lgkmcnt(" #n ")" ::: "memory")
; #define PG8_BAR __builtin_amdgcn_s_barrier()
; #define PG8_SCHED __builtin_amdgcn_sched_barrier(0)
; template <class Epi>
; DEVI void gemm_phase(LAS unsigned char* lds, const Gemm g, const Epi& E) {
;     ...
;             PG8_BAR; PG8_WAIT_L(0); PG8_MMA(1, 0, At, B0); PG8_BAR; PG8_SCHED;
;             PG8_STAGE(PG8_SB(1, 1), b3 + hstepB, voffB);
;             PG8_WAIT_V(6); PG8_BAR; PG8_MMA(1, 1, At, B1); PG8_BAR;
;         }
;         {
;             const int row0 = cur.pm * BM + wr * 64 + fr, col0 = cur.pn * BM + wc * 32 + (Epi::PERM ? 8 : 4) * fq; constexpr int NST = Epi::PERM ? 4 : 16;
;             float rsv[8];
;             if constexpr (Epi::RS) { f32x4 q4[8];
; #pragma unroll
;                 for (int i = 0; i < 8; ++i) q4[i] = *(const f32x4*)(E.ssq_in + (size_t)(row0 + (i >> 2) * HALF + (i & 3) * 16) * 4);
; #pragma unroll
;                 for (int i = 0; i < 8; ++i) rsv[i] = rsqrtf((((q4[i][0] + q4[i][1]) + q4[i][2]) + q4[i][3]) * (1.f / DM) + 1e-6f); }
	s_waitcnt lgkmcnt(0)
	v_mfma_f32_16x16x32_bf16 v[58:61], v[130:133], v[184:187], v[58:61]
	v_mfma_f32_16x16x32_bf16 v[62:65], v[138:141], v[184:187], v[62:65]
	v_mfma_f32_16x16x32_bf16 v[38:41], v[130:133], v[192:195], v[38:41]
	v_mfma_f32_16x16x32_bf16 v[42:45], v[138:141], v[192:195], v[42:45]
	v_mfma_f32_16x16x32_bf16 v[18:21], v[130:133], v[214:217], v[18:21]
	v_mfma_f32_16x16x32_bf16 v[22:25], v[138:141], v[214:217], v[22:25]
	v_mfma_f32_16x16x32_bf16 v[0:3], v[130:133], v[222:225], v[0:3]
	v_mfma_f32_16x16x32_bf16 v[4:7], v[138:141], v[222:225], v[4:7]
	v_mfma_f32_16x16x32_bf16 v[58:61], v[134:137], v[188:191], v[58:61]
	v_mfma_f32_16x16x32_bf16 v[62:65], v[142:145], v[188:191], v[62:65]
	v_mfma_f32_16x16x32_bf16 v[38:41], v[134:137], v[206:209], v[38:41]
	v_mfma_f32_16x16x32_bf16 v[42:45], v[142:145], v[206:209], v[42:45]
	v_mfma_f32_16x16x32_bf16 v[18:21], v[134:137], v[218:221], v[18:21]
	v_mfma_f32_16x16x32_bf16 v[22:25], v[142:145], v[218:221], v[22:25]
	v_mfma_f32_16x16x32_bf16 v[0:3], v[134:137], v[226:229], v[0:3]
	v_mfma_f32_16x16x32_bf16 v[4:7], v[142:145], v[226:229], v[4:7]
	s_barrier
	s_add_u32 s16, s16, 0x40080
	s_addc_u32 s17, s17, 0
	s_add_i32 s26, s26, s47
	s_mov_b32 m0, s26
	s_nop 0
	global_load_lds_dwordx4 v148, s[16:17]
	s_add_i32 m0, s26, 0x2000
	s_nop 0
	global_load_lds_dwordx4 v152, s[16:17]
	s_waitcnt vmcnt(6)
	s_barrier
	v_mfma_f32_16x16x32_bf16 v[66:69], v[230:233], v[184:187], v[66:69]
	v_mfma_f32_16x16x32_bf16 v[70:73], v[238:241], v[184:187], v[70:73]
	v_mfma_f32_16x16x32_bf16 v[46:49], v[230:233], v[192:195], v[46:49]
	v_mfma_f32_16x16x32_bf16 v[50:53], v[238:241], v[192:195], v[50:53]
	v_mfma_f32_16x16x32_bf16 v[26:29], v[230:233], v[214:217], v[26:29]
	v_mfma_f32_16x16x32_bf16 v[30:33], v[238:241], v[214:217], v[30:33]
	v_mfma_f32_16x16x32_bf16 v[10:13], v[230:233], v[222:225], v[10:13]
	v_mfma_f32_16x16x32_bf16 v[14:17], v[238:241], v[222:225], v[14:17]
	v_mfma_f32_16x16x32_bf16 v[66:69], v[234:237], v[188:191], v[66:69]
	v_mfma_f32_16x16x32_bf16 v[70:73], v[242:245], v[188:191], v[70:73]
	v_mfma_f32_16x16x32_bf16 v[46:49], v[234:237], v[206:209], v[46:49]
	v_mfma_f32_16x16x32_bf16 v[50:53], v[242:245], v[206:209], v[50:53]
	v_mfma_f32_16x16x32_bf16 v[26:29], v[234:237], v[218:221], v[26:29]
	v_mfma_f32_16x16x32_bf16 v[30:33], v[242:245], v[218:221], v[30:33]
	v_mfma_f32_16x16x32_bf16 v[10:13], v[234:237], v[226:229], v[10:13]
	v_mfma_f32_16x16x32_bf16 v[14:17], v[242:245], v[226:229], v[14:17]
	s_add_i32 s19, s19, 2
	s_add_u32 s14, s14, 0x100
	s_addc_u32 s15, s15, 0
	s_add_u32 s9, s9, 0x100
	s_addc_u32 s18, s18, 0
	s_cmp_gt_u32 s19, 13
	s_barrier
	s_cbranch_scc0 .LBB0_1007
	s_setprio 0
	v_lshl_add_u32 v194, s4, 8, v197
	v_add_u32_e32 v184, 0xb0, v194
	v_ashrrev_i32_e32 v195, 31, v194
	v_ashrrev_i32_e32 v185, 31, v184
	v_lshl_add_u64 v[130:131], v[194:195], 4, s[76:77]
	v_lshl_add_u64 v[134:135], v[184:185], 4, s[76:77]
	global_load_dwordx4 v[206:209], v[130:131], off
	v_or_b32_e32 v192, 48, v194
	global_load_dwordx4 v[134:137], v[134:135], off
	v_or_b32_e32 v130, 16, v194
	v_ashrrev_i32_e32 v131, 31, v130
	v_lshl_add_u64 v[130:131], v[130:131], 4, s[76:77]
	global_load_dwordx4 v[214:217], v[130:131], off
	v_or_b32_e32 v130, 32, v194
	v_ashrrev_i32_e32 v131, 31, v130
	v_lshl_add_u64 v[130:131], v[130:131], 4, s[76:77]
	v_ashrrev_i32_e32 v193, 31, v192
	global_load_dwordx4 v[218:221], v[130:131], off
	v_lshl_add_u64 v[130:131], v[192:193], 4, s[76:77]
	global_load_dwordx4 v[222:225], v[130:131], off
	v_add_u32_e32 v190, 0x80, v194
	v_ashrrev_i32_e32 v191, 31, v190
	v_add_u32_e32 v188, 0x90, v194
	v_lshl_add_u64 v[130:131], v[190:191], 4, s[76:77]
	v_ashrrev_i32_e32 v189, 31, v188
	global_load_dwordx4 v[138:141], v[130:131], off
	v_lshl_add_u64 v[130:131], v[188:189], 4, s[76:77]
	global_load_dwordx4 v[142:145], v[130:131], off
	v_add_u32_e32 v186, 0xa0, v194
	v_ashrrev_i32_e32 v187, 31, v186
	v_lshl_add_u64 v[130:131], v[186:187], 4, s[76:77]
	global_load_dwordx4 v[130:133], v[130:131], off
	s_mov_b32 s0, 0x358637bd
	v_mov_b64_e32 v[202:203], s[0:1]
	s_mov_b64 s[16:17], s[12:13]
	s_mov_b64 s[14:15], s[10:11]
	s_waitcnt vmcnt(0)
	v_mov_b32_e32 v163, v206
	v_mov_b32_e32 v165, v208
	v_mov_b32_e32 v162, v214
	v_mov_b32_e32 v206, v215
	v_pk_add_f32 v[162:163], v[162:163], v[206:207]
	v_mov_b32_e32 v164, v216
	v_pk_add_f32 v[162:163], v[164:165], v[162:163]
	v_mov_b32_e32 v208, v217
	v_pk_add_f32 v[162:163], v[208:209], v[162:163]
	v_mov_b32_e32 v164, v224
	v_pk_fma_f32 v[162:163], v[162:163], s[72:73], v[202:203] op_sel_hi:[1,0,0]
	v_mov_b32_e32 v165, v220
	v_mul_f32_e32 v8, 0x4b800000, v163
	v_cmp_gt_f32_e64 s[4:5], s94, v163
	v_cmp_gt_f32_e32 vcc, s94, v162
	v_mov_b32_e32 v220, v225
	v_cndmask_b32_e64 v8, v163, v8, s[4:5]
	v_rsq_f32_e32 v8, v8
	s_nop 0
	v_mul_f32_e32 v163, 0x45800000, v8
	v_cndmask_b32_e64 v198, v8, v163, s[4:5]
	v_mul_f32_e32 v8, 0x4b800000, v162
	v_cndmask_b32_e32 v8, v162, v8, vcc
	v_rsq_f32_e32 v8, v8
	v_mov_b32_e32 v163, v218
	v_mov_b32_e32 v218, v223
	v_pk_mul_f32 v[128:129], v[128:129], v[198:199] op_sel_hi:[1,0]
	v_mul_f32_e32 v162, 0x45800000, v8
	v_cndmask_b32_e32 v8, v8, v162, vcc
	v_mov_b32_e32 v162, v222
	v_pk_add_f32 v[162:163], v[162:163], v[218:219]
	v_pk_mul_f32 v[126:127], v[126:127], v[198:199] op_sel_hi:[1,0]
	v_pk_add_f32 v[162:163], v[164:165], v[162:163]
	v_pk_mul_f32 v[122:123], v[122:123], v[198:199] op_sel_hi:[1,0]
	v_pk_add_f32 v[162:163], v[220:221], v[162:163]
	v_pk_mul_f32 v[120:121], v[120:121], v[198:199] op_sel_hi:[1,0]
	v_pk_fma_f32 v[162:163], v[162:163], s[72:73], v[202:203] op_sel_hi:[1,0,0]
	v_pk_mul_f32 v[118:119], v[118:119], v[198:199] op_sel_hi:[1,0]
; template <class Epi>
; DEVI void gemm_phase(LAS unsigned char* lds, const Gemm g, const Epi& E) {
;     ...
;                     const int r = row0 + ai * HALF + m * 16; float rs = 1.f, part = 0.f;
;                     if constexpr (Epi::RS) rs = rsv[ai * 4 + m];
;                     if constexpr (Epi::PAIR) E.pair8(cur.b, r, cur.pn * HALF + wc * 32 + 8 * fq, acc[ai][0][m][0] * rs, acc[ai][0][m][1] * rs, acc[ai][1][m][0] * rs, acc[ai][1][m][1] * rs);
;                     else
; #pragma unroll
;                     for (int bj = 0; bj < 2; ++bj) {
;                         const int c = col0 + bj * HALF; f32x4 v0 = acc[ai][bj][m][0], v1 = acc[ai][bj][m][1];
;                         if constexpr (Epi::RS) { v0 = v0 * rs; v1 = v1 * rs; }
;                         if constexpr (Epi::PRE) part += E.frag_pre8(cur.b, r, c, v0, v1, pre[mm][bj][0], pre[mm][bj][1]);
;                         else if constexpr (Epi::PERM) E.frag8(cur.b, r, c, v0, v1);
;                         else { E.frag(cur.b, r, c, v0); E.frag(cur.b, r, c + 16, v1); }
	v_mul_f32_e32 v164, 0x4b800000, v163
	v_cmp_gt_f32_e64 s[4:5], s94, v163
	v_cmp_gt_f32_e32 vcc, s94, v162
	v_pk_mul_f32 v[110:111], v[110:111], v[198:199] op_sel_hi:[1,0]
	v_cndmask_b32_e64 v163, v163, v164, s[4:5]
	v_rsq_f32_e32 v163, v163
	v_cvt_pk_bf16_f32 v118, v118, v119
	v_cvt_pk_bf16_f32 v119, v120, v121
	v_cvt_pk_bf16_f32 v120, v110, v111
	v_mul_f32_e32 v164, 0x45800000, v163
	v_cndmask_b32_e64 v200, v163, v164, s[4:5]
	v_mul_f32_e32 v163, 0x4b800000, v162
	v_cndmask_b32_e32 v162, v162, v163, vcc
	v_rsq_f32_e32 v162, v162
	v_pk_mul_f32 v[112:113], v[112:113], v[198:199] op_sel_hi:[1,0]
	v_pk_mul_f32 v[114:115], v[114:115], v[8:9] op_sel_hi:[1,0]
	v_cvt_pk_bf16_f32 v121, v112, v113
	v_mul_f32_e32 v163, 0x45800000, v162
	v_cndmask_b32_e32 v196, v162, v163, vcc
	v_mov_b32_e32 v162, v142
	v_mov_b32_e32 v163, v138
	v_mov_b32_e32 v138, v143
	v_pk_add_f32 v[138:139], v[162:163], v[138:139]
	v_mov_b32_e32 v142, v144
	v_mov_b32_e32 v143, v140
	v_pk_add_f32 v[138:139], v[142:143], v[138:139]
	v_mov_b32_e32 v140, v145
	v_pk_add_f32 v[138:139], v[140:141], v[138:139]
	v_mov_b32_e32 v142, v134
	v_pk_fma_f32 v[140:141], v[138:139], s[72:73], v[202:203] op_sel_hi:[1,0,0]
	v_mov_b32_e32 v143, v130
	v_mul_f32_e32 v138, 0x4b800000, v141
	v_cmp_gt_f32_e64 s[4:5], s94, v141
	v_mov_b32_e32 v130, v135
	v_pk_add_f32 v[130:131], v[142:143], v[130:131]
	v_cndmask_b32_e64 v138, v141, v138, s[4:5]
	v_rsq_f32_e32 v138, v138
	v_mov_b32_e32 v134, v136
	v_mov_b32_e32 v135, v132
	v_pk_add_f32 v[130:131], v[134:135], v[130:131]
	v_mov_b32_e32 v132, v137
	v_pk_add_f32 v[130:131], v[132:133], v[130:131]
	v_mul_f32_e32 v139, 0x45800000, v138
	v_pk_fma_f32 v[130:131], v[130:131], s[72:73], v[202:203] op_sel_hi:[1,0,0]
	v_cmp_gt_f32_e32 vcc, s94, v140
	v_cndmask_b32_e64 v138, v138, v139, s[4:5]
	v_mul_f32_e32 v139, 0x4b800000, v140
	v_mul_f32_e32 v132, 0x4b800000, v131
	v_cmp_gt_f32_e64 s[4:5], s94, v131
	v_cndmask_b32_e32 v139, v140, v139, vcc
	v_rsq_f32_e32 v139, v139
	v_cndmask_b32_e64 v131, v131, v132, s[4:5]
	v_rsq_f32_e32 v131, v131
	v_pk_mul_f32 v[136:137], v[124:125], v[198:199] op_sel_hi:[1,0]
	v_mul_f32_e32 v140, 0x45800000, v139
	v_cndmask_b32_e32 v140, v139, v140, vcc
	v_mul_f32_e32 v132, 0x45800000, v131
	v_cmp_gt_f32_e32 vcc, s94, v130
	v_cndmask_b32_e64 v132, v131, v132, s[4:5]
	v_mul_f32_e32 v131, 0x4b800000, v130
	v_cndmask_b32_e32 v130, v130, v131, vcc
	v_rsq_f32_e32 v130, v130
	v_cvt_pk_bf16_f32 v125, v128, v129
	v_ashrrev_i32_e32 v134, 5, v194
	v_ashrrev_i32_e32 v135, 31, v134
	v_mul_f32_e32 v131, 0x45800000, v130
	v_cndmask_b32_e32 v130, v130, v131, vcc
	v_lshl_or_b32 v131, s84, 8, v201
	v_ashrrev_i32_e32 v128, 4, v131
	v_ashrrev_i32_e32 v129, 31, v128
	v_cvt_pk_bf16_f32 v124, v126, v127
	v_cvt_pk_bf16_f32 v126, v122, v123
	v_lshlrev_b64 v[122:123], 10, v[128:129]
	v_or_b32_e32 v110, 8, v128
	v_cvt_pk_bf16_f32 v127, v136, v137
	v_lshl_add_u64 v[136:137], v[122:123], 0, v[134:135]
	v_ashrrev_i32_e32 v111, 31, v110
	v_mad_u64_u32 v[142:143], s[0:1], v136, s34, v[178:179]
	v_lshlrev_b64 v[110:111], 10, v[110:111]
	v_mad_i32_i24 v143, v137, s34, v143
	v_lshl_add_u64 v[112:113], v[110:111], 0, v[134:135]
	global_store_dwordx4 v[142:143], v[124:127], off
	v_pk_mul_f32 v[100:101], v[100:101], v[8:9] op_sel_hi:[1,0]
	v_pk_mul_f32 v[98:99], v[98:99], v[8:9] op_sel_hi:[1,0]
	v_mad_u64_u32 v[124:125], s[0:1], v112, s34, v[178:179]
	v_mad_i32_i24 v125, v113, s34, v125
	v_pk_mul_f32 v[112:113], v[116:117], v[8:9] op_sel_hi:[1,0]
	v_pk_mul_f32 v[116:117], v[108:109], v[8:9] op_sel_hi:[1,0]
	v_pk_mul_f32 v[108:109], v[106:107], v[8:9] op_sel_hi:[1,0]
	v_cvt_pk_bf16_f32 v106, v114, v115
	v_cvt_pk_bf16_f32 v107, v112, v113
	v_cvt_pk_bf16_f32 v108, v108, v109
	v_cvt_pk_bf16_f32 v109, v116, v117
	global_store_dwordx4 v[142:143], v[106:109], off offset:512
	v_pk_mul_f32 v[94:95], v[94:95], v[200:201] op_sel_hi:[1,0]
	v_pk_mul_f32 v[96:97], v[96:97], v[200:201] op_sel_hi:[1,0]
	v_pk_mul_f32 v[106:107], v[92:93], v[8:9] op_sel_hi:[1,0]
	v_pk_mul_f32 v[92:93], v[90:91], v[8:9] op_sel_hi:[1,0]
	v_cvt_pk_bf16_f32 v90, v98, v99
	v_cvt_pk_bf16_f32 v91, v100, v101
	v_cvt_pk_bf16_f32 v92, v92, v93
	v_cvt_pk_bf16_f32 v93, v106, v107
	v_or_b32_e32 v98, 1, v134
	global_store_dwordx4 v[124:125], v[90:93], off offset:512
	v_ashrrev_i32_e32 v99, 31, v98
	v_pk_mul_f32 v[86:87], v[86:87], v[200:201] op_sel_hi:[1,0]
	v_pk_mul_f32 v[92:93], v[104:105], v[200:201] op_sel_hi:[1,0]
	v_pk_mul_f32 v[90:91], v[102:103], v[200:201] op_sel_hi:[1,0]
	v_pk_mul_f32 v[88:89], v[88:89], v[200:201] op_sel_hi:[1,0]
	v_cvt_pk_bf16_f32 v90, v90, v91
	v_cvt_pk_bf16_f32 v91, v92, v93
	v_cvt_pk_bf16_f32 v92, v94, v95
	v_lshl_add_u64 v[94:95], v[122:123], 0, v[98:99]
	v_cvt_pk_bf16_f32 v93, v96, v97
	v_mad_u64_u32 v[96:97], s[0:1], v94, s34, v[178:179]
	v_mad_i32_i24 v97, v95, s34, v97
	global_store_dwordx4 v[96:97], v[90:93], off
	v_lshlrev_b32_e32 v8, 5, v192
	v_and_b32_e32 v8, 0x3e0, v8
	v_pk_mul_f32 v[90:91], v[80:81], v[200:201] op_sel_hi:[1,0]
	v_pk_mul_f32 v[80:81], v[78:79], v[200:201] op_sel_hi:[1,0]
	v_cvt_pk_bf16_f32 v78, v86, v87
	v_lshl_add_u64 v[86:87], v[110:111], 0, v[98:99]
	v_cvt_pk_bf16_f32 v79, v88, v89
	v_mad_u64_u32 v[88:89], s[0:1], v86, s34, v[178:179]
	v_cvt_pk_bf16_f32 v80, v80, v81
	v_cvt_pk_bf16_f32 v81, v90, v91
	v_mad_i32_i24 v89, v87, s34, v89
	global_store_dwordx4 v[88:89], v[78:81], off
	v_pk_mul_f32 v[82:83], v[82:83], v[196:197] op_sel_hi:[1,0]
	v_pk_mul_f32 v[84:85], v[84:85], v[196:197] op_sel_hi:[1,0]
	v_ashrrev_i32_e32 v78, 5, v192
	v_ashrrev_i32_e32 v79, 31, v78
	v_lshl_add_u64 v[80:81], v[176:177], 0, v[8:9]
	v_pk_mul_f32 v[86:87], v[76:77], v[196:197] op_sel_hi:[1,0]
; template <class Epi>
; DEVI void gemm_phase(LAS unsigned char* lds, const Gemm g, const Epi& E) {
;     ...
;                     const int r = row0 + ai * HALF + m * 16; float rs = 1.f, part = 0.f;
;                     if constexpr (Epi::RS) rs = rsv[ai * 4 + m];
;                     if constexpr (Epi::PAIR) E.pair8(cur.b, r, cur.pn * HALF + wc * 32 + 8 * fq, acc[ai][0][m][0] * rs, acc[ai][0][m][1] * rs, acc[ai][1][m][0] * rs, acc[ai][1][m][1] * rs);
;                     else
; #pragma unroll
;                     for (int bj = 0; bj < 2; ++bj) {
;                         const int c = col0 + bj * HALF; f32x4 v0 = acc[ai][bj][m][0], v1 = acc[ai][bj][m][1];
;                         if constexpr (Epi::RS) { v0 = v0 * rs; v1 = v1 * rs; }
;                         if constexpr (Epi::PRE) part += E.frag_pre8(cur.b, r, c, v0, v1, pre[mm][bj][0], pre[mm][bj][1]);
;                         else if constexpr (Epi::PERM) E.frag8(cur.b, r, c, v0, v1);
;                         else { E.frag(cur.b, r, c, v0); E.frag(cur.b, r, c + 16, v1); }
	v_pk_mul_f32 v[76:77], v[74:75], v[196:197] op_sel_hi:[1,0]
	v_cvt_pk_bf16_f32 v74, v82, v83
	v_lshl_add_u64 v[82:83], v[122:123], 0, v[78:79]
	v_cvt_pk_bf16_f32 v75, v84, v85
	v_mad_u64_u32 v[84:85], s[0:1], v82, s34, v[80:81]
	v_cvt_pk_bf16_f32 v76, v76, v77
	v_cvt_pk_bf16_f32 v77, v86, v87
	v_mad_i32_i24 v85, v83, s34, v85
	v_pk_mul_f32 v[54:55], v[54:55], v[196:197] op_sel_hi:[1,0]
	global_store_dwordx4 v[124:125], v[118:121], off
	global_store_dwordx4 v[84:85], v[74:77], off
	v_pk_mul_f32 v[56:57], v[56:57], v[196:197] op_sel_hi:[1,0]
	v_lshlrev_b32_e32 v8, 5, v188
	v_pk_mul_f32 v[74:75], v[36:37], v[196:197] op_sel_hi:[1,0]
	v_pk_mul_f32 v[36:37], v[34:35], v[196:197] op_sel_hi:[1,0]
	v_cvt_pk_bf16_f32 v34, v54, v55
	v_lshl_add_u64 v[54:55], v[110:111], 0, v[78:79]
	v_cvt_pk_bf16_f32 v35, v56, v57
	v_mad_u64_u32 v[56:57], s[0:1], v54, s34, v[80:81]
	v_cvt_pk_bf16_f32 v36, v36, v37
	v_cvt_pk_bf16_f32 v37, v74, v75
	v_mad_i32_i24 v57, v55, s34, v57
	v_ashrrev_i32_e32 v54, 5, v190
	global_store_dwordx4 v[56:57], v[34:37], off
	v_ashrrev_i32_e32 v55, 31, v54
	v_pk_mul_f32 v[56:57], v[64:65], v[138:139] op_sel_hi:[1,0]
	v_pk_mul_f32 v[36:37], v[60:61], v[138:139] op_sel_hi:[1,0]
	v_pk_mul_f32 v[34:35], v[58:59], v[138:139] op_sel_hi:[1,0]
	v_pk_mul_f32 v[58:59], v[62:63], v[138:139] op_sel_hi:[1,0]
	v_cvt_pk_bf16_f32 v34, v34, v35
	v_cvt_pk_bf16_f32 v35, v36, v37
	v_cvt_pk_bf16_f32 v37, v56, v57
	v_lshl_add_u64 v[56:57], v[122:123], 0, v[54:55]
	v_cvt_pk_bf16_f32 v36, v58, v59
	v_mad_u64_u32 v[58:59], s[0:1], v56, s34, v[178:179]
	v_mad_i32_i24 v59, v57, s34, v59
	global_store_dwordx4 v[58:59], v[34:37], off
	v_pk_mul_f32 v[56:57], v[72:73], v[138:139] op_sel_hi:[1,0]
	v_lshl_add_u64 v[54:55], v[110:111], 0, v[54:55]
	v_pk_mul_f32 v[36:37], v[68:69], v[138:139] op_sel_hi:[1,0]
	v_pk_mul_f32 v[34:35], v[66:67], v[138:139] op_sel_hi:[1,0]
	v_pk_mul_f32 v[58:59], v[70:71], v[138:139] op_sel_hi:[1,0]
	v_cvt_pk_bf16_f32 v34, v34, v35
	v_cvt_pk_bf16_f32 v35, v36, v37
	v_cvt_pk_bf16_f32 v37, v56, v57
	v_mad_u64_u32 v[56:57], s[0:1], v54, s34, v[178:179]
	v_cvt_pk_bf16_f32 v36, v58, v59
	v_mad_i32_i24 v57, v55, s34, v57
	v_ashrrev_i32_e32 v54, 5, v188
	global_store_dwordx4 v[56:57], v[34:37], off
	v_ashrrev_i32_e32 v55, 31, v54
	v_and_b32_e32 v8, 0x3e0, v8
	v_pk_mul_f32 v[36:37], v[40:41], v[140:141] op_sel_hi:[1,0]
	v_pk_mul_f32 v[34:35], v[38:39], v[140:141] op_sel_hi:[1,0]
	v_pk_mul_f32 v[38:39], v[44:45], v[140:141] op_sel_hi:[1,0]
	v_lshl_add_u64 v[56:57], v[176:177], 0, v[8:9]
	v_pk_mul_f32 v[40:41], v[42:43], v[140:141] op_sel_hi:[1,0]
	v_cvt_pk_bf16_f32 v34, v34, v35
	v_cvt_pk_bf16_f32 v35, v36, v37
	v_cvt_pk_bf16_f32 v37, v38, v39
	v_lshl_add_u64 v[38:39], v[122:123], 0, v[54:55]
	v_cvt_pk_bf16_f32 v36, v40, v41
	v_mad_u64_u32 v[40:41], s[0:1], v38, s34, v[56:57]
	v_mad_i32_i24 v41, v39, s34, v41
	global_store_dwordx4 v[40:41], v[34:37], off
	v_pk_mul_f32 v[38:39], v[52:53], v[140:141] op_sel_hi:[1,0]
	v_pk_mul_f32 v[40:41], v[50:51], v[140:141] op_sel_hi:[1,0]
	v_pk_mul_f32 v[36:37], v[48:49], v[140:141] op_sel_hi:[1,0]
	v_pk_mul_f32 v[34:35], v[46:47], v[140:141] op_sel_hi:[1,0]
	v_pk_mul_f32 v[20:21], v[20:21], v[132:133] op_sel_hi:[1,0]
	v_cvt_pk_bf16_f32 v34, v34, v35
	v_cvt_pk_bf16_f32 v35, v36, v37
	v_cvt_pk_bf16_f32 v37, v38, v39
	v_lshl_add_u64 v[38:39], v[110:111], 0, v[54:55]
	v_cvt_pk_bf16_f32 v36, v40, v41
	v_mad_u64_u32 v[40:41], s[0:1], v38, s34, v[56:57]
	v_mad_i32_i24 v41, v39, s34, v41
	global_store_dwordx4 v[40:41], v[34:37], off
	v_pk_mul_f32 v[18:19], v[18:19], v[132:133] op_sel_hi:[1,0]
	v_pk_mul_f32 v[22:23], v[22:23], v[132:133] op_sel_hi:[1,0]
	v_ashrrev_i32_e32 v34, 5, v186
	v_ashrrev_i32_e32 v35, 31, v34
	v_pk_mul_f32 v[24:25], v[24:25], v[132:133] op_sel_hi:[1,0]
	v_cvt_pk_bf16_f32 v18, v18, v19
	v_cvt_pk_bf16_f32 v19, v20, v21
	v_cvt_pk_bf16_f32 v20, v22, v23
	v_lshl_add_u64 v[22:23], v[122:123], 0, v[34:35]
	v_cvt_pk_bf16_f32 v21, v24, v25
	v_mad_u64_u32 v[24:25], s[0:1], v22, s34, v[178:179]
	v_mad_i32_i24 v25, v23, s34, v25
	global_store_dwordx4 v[24:25], v[18:21], off
	v_pk_mul_f32 v[22:23], v[32:33], v[132:133] op_sel_hi:[1,0]
	v_pk_mul_f32 v[24:25], v[30:31], v[132:133] op_sel_hi:[1,0]
	v_pk_mul_f32 v[20:21], v[28:29], v[132:133] op_sel_hi:[1,0]
	v_pk_mul_f32 v[18:19], v[26:27], v[132:133] op_sel_hi:[1,0]
	v_lshlrev_b32_e32 v8, 5, v184
	v_cvt_pk_bf16_f32 v18, v18, v19
	v_cvt_pk_bf16_f32 v19, v20, v21
	v_cvt_pk_bf16_f32 v21, v22, v23
	v_lshl_add_u64 v[22:23], v[110:111], 0, v[34:35]
	v_cvt_pk_bf16_f32 v20, v24, v25
	v_mad_u64_u32 v[24:25], s[0:1], v22, s34, v[178:179]
	v_mad_i32_i24 v25, v23, s34, v25
	global_store_dwordx4 v[24:25], v[18:21], off
	v_and_b32_e32 v8, 0x3e0, v8
	v_pk_mul_f32 v[2:3], v[2:3], v[130:131] op_sel_hi:[1,0]
	v_ashrrev_i32_e32 v18, 5, v184
	v_ashrrev_i32_e32 v19, 31, v18
	v_pk_mul_f32 v[0:1], v[0:1], v[130:131] op_sel_hi:[1,0]
	v_pk_mul_f32 v[4:5], v[4:5], v[130:131] op_sel_hi:[1,0]
	v_lshl_add_u64 v[20:21], v[176:177], 0, v[8:9]
	v_pk_mul_f32 v[6:7], v[6:7], v[130:131] op_sel_hi:[1,0]
	v_cvt_pk_bf16_f32 v0, v0, v1
	v_cvt_pk_bf16_f32 v1, v2, v3
	v_cvt_pk_bf16_f32 v2, v4, v5
	v_lshl_add_u64 v[4:5], v[122:123], 0, v[18:19]
	v_cvt_pk_bf16_f32 v3, v6, v7
	v_mad_u64_u32 v[6:7], s[0:1], v4, s34, v[20:21]
	v_mad_i32_i24 v7, v5, s34, v7
	global_store_dwordx4 v[6:7], v[0:3], off
	v_pk_mul_f32 v[4:5], v[16:17], v[130:131] op_sel_hi:[1,0]
	v_pk_mul_f32 v[6:7], v[14:15], v[130:131] op_sel_hi:[1,0]
	v_pk_mul_f32 v[2:3], v[12:13], v[130:131] op_sel_hi:[1,0]
	v_pk_mul_f32 v[0:1], v[10:11], v[130:131] op_sel_hi:[1,0]
	s_and_b64 vcc, exec, s[2:3]
	v_cvt_pk_bf16_f32 v0, v0, v1
	v_cvt_pk_bf16_f32 v1, v2, v3
	v_cvt_pk_bf16_f32 v3, v4, v5
	v_lshl_add_u64 v[4:5], v[110:111], 0, v[18:19]
	v_cvt_pk_bf16_f32 v2, v6, v7
	v_mad_u64_u32 v[6:7], s[0:1], v4, s34, v[20:21]
	v_mad_i32_i24 v7, v5, s34, v7
	s_mov_b32 s84, s8
	s_mov_b32 s4, s6
	global_store_dwordx4 v[6:7], v[0:3], off
	s_cbranch_vccz .LBB0_1000
	s_waitcnt vmcnt(0)
	s_cmpk_gt_u32 s46, 0xff
	s_cbranch_scc1 .LBB0_1011
	s_barrier

; #define PG8_STAGE(bufoff, gbase, voff) do { _Pragma("unroll") for (int _i = 0; _i < 2; ++_i) \
;         __builtin_amdgcn_global_load_lds((const unsigned*)((const char*)(gbase) + (voff)[_i]), (LAS unsigned*)(lds + (bufoff) + ldsw + _i * 8192), 16, 0, 0); } while (0)
; #define PG8_LDA(dst, b, h) do { _Pragma("unroll") for (int m = 0; m < 4; ++m) _Pragma("unroll") for (int k = 0; k < 2; ++k) dst[m][k] = *(const LAS bf16x8*)(lds + PG8_SA(b, h) + aoff + m * 2048 + k * 1024); } while (0)
; #define PG8_LDB(dst, b, h) do { _Pragma("unroll") for (int n = 0; n < 2; ++n) _Pragma("unroll") for (int k = 0; k < 2; ++k) dst[n][k] = *(const LAS bf16x8*)(lds + PG8_SB(b, h) + boff + n * 2048 + k * 1024); } while (0)
; template <class Epi>
; DEVI void gemm_phase(LAS unsigned char* lds, const Gemm g, const Epi& E) {
;     ...
;             const bool last = (t == nt - 2);
;             const char* a1 = cA + (size_t)(t + 1) * kstep;
;             const char* a2 = last ? nA : cA + (size_t)(t + 2) * kstep; const char* b2 = last ? nB : cB + (size_t)(t + 2) * kstep;
;             const char* a3 = a2 + kstep; const char* b3 = b2 + kstep;
;             PG8_LDB(B0, 0, 0); PG8_SCHED; PG8_LDA(At, 0, 0); PG8_STAGE(PG8_SA(1, 1), a1 + hstepA, voffA);
;             PG8_WAIT_L(8); PG8_BAR; PG8_WAIT_L(0); PG8_MMA(0, 0, At, B0); PG8_BAR; PG8_SCHED;
;             PG8_LDB(B1, 0, 1); PG8_STAGE(PG8_SB(0, 0), b2, voffB);
;             PG8_BAR; PG8_WAIT_L(0); PG8_MMA(0, 1, At, B1); PG8_BAR;
;             PG8_LDA(At, 0, 1); PG8_STAGE(PG8_SA(0, 0), a2, voffA);
;             PG8_BAR; PG8_WAIT_L(0); PG8_MMA(1, 0, At, B0); PG8_BAR; PG8_SCHED;
;             PG8_STAGE(PG8_SB(0, 1), b2 + hstepB, voffB);
;             PG8_WAIT_V(6); PG8_BAR; PG8_MMA(1, 1, At, B1); PG8_BAR;
;             PG8_LDB(B0, 1, 0); PG8_SCHED; PG8_LDA(At, 1, 0); PG8_STAGE(PG8_SA(0, 1), a2 + hstepA, voffA);
;             PG8_WAIT_L(8); PG8_BAR; PG8_WAIT_L(0); PG8_MMA(0, 0, At, B0); PG8_BAR; PG8_SCHED;
;             PG8_LDB(B1, 1, 1); PG8_STAGE(PG8_SB(1, 0), b3, voffB);
;             PG8_BAR; PG8_WAIT_L(0); PG8_MMA(0, 1, At, B1); PG8_BAR;
;             PG8_LDA(At, 1, 1); PG8_STAGE(PG8_SA(1, 0), a3, voffA);
;             PG8_BAR; PG8_WAIT_L(0); PG8_MMA(1, 0, At, B0); PG8_BAR; PG8_SCHED;
;             PG8_STAGE(PG8_SB(1, 1), b3 + hstepB, voffB);
;             PG8_WAIT_V(6); PG8_BAR; PG8_MMA(1, 1, At, B1); PG8_BAR;
.LBB0_1127:
	s_add_u32 s14, s12, 0x100
	s_addc_u32 s15, s13, 0
	s_add_i32 s48, 0, 0x10000
	v_add_u32_e32 v81, s48, v79
	ds_read_b128 v[82:85], v81
	ds_read_b128 v[86:89], v81 offset:1024
	ds_read_b128 v[90:93], v81 offset:2048
	ds_read_b128 v[94:97], v81 offset:3072
	s_cmp_eq_u32 s47, 4
	s_cselect_b32 s37, s9, s15
	s_cselect_b32 s36, s8, s14
	s_cselect_b32 s17, s11, s7
	s_cselect_b32 s16, s10, s5
	s_add_i32 m0, s18, 0xc000
	ds_read_b128 v[98:101], v80
	ds_read_b128 v[102:105], v80 offset:1024
	ds_read_b128 v[106:109], v80 offset:2048
	ds_read_b128 v[110:113], v80 offset:3072
	ds_read_b128 v[114:117], v80 offset:4096
	ds_read_b128 v[118:121], v80 offset:5120
	ds_read_b128 v[122:125], v80 offset:6144
	ds_read_b128 v[126:129], v80 offset:7168
	global_load_lds_dwordx4 v74, s[12:13]
	s_add_i32 m0, s18, 0xe000
	s_nop 0
	global_load_lds_dwordx4 v76, s[12:13]
	s_waitcnt lgkmcnt(8)
	s_barrier
	s_waitcnt lgkmcnt(0)
	v_mfma_f32_16x16x32_bf16 v[62:65], v[82:85], v[98:101], v[62:65]
	v_mfma_f32_16x16x32_bf16 v[58:61], v[90:93], v[98:101], v[58:61]
	v_mfma_f32_16x16x32_bf16 v[54:57], v[82:85], v[106:109], v[54:57]
	v_mfma_f32_16x16x32_bf16 v[50:53], v[90:93], v[106:109], v[50:53]
	v_mfma_f32_16x16x32_bf16 v[46:49], v[82:85], v[114:117], v[46:49]
	v_mfma_f32_16x16x32_bf16 v[42:45], v[90:93], v[114:117], v[42:45]
	v_mfma_f32_16x16x32_bf16 v[38:41], v[82:85], v[122:125], v[38:41]
	v_mfma_f32_16x16x32_bf16 v[34:37], v[90:93], v[122:125], v[34:37]
	v_mfma_f32_16x16x32_bf16 v[62:65], v[86:89], v[102:105], v[62:65]
	v_mfma_f32_16x16x32_bf16 v[58:61], v[94:97], v[102:105], v[58:61]
	v_mfma_f32_16x16x32_bf16 v[54:57], v[86:89], v[110:113], v[54:57]
	v_mfma_f32_16x16x32_bf16 v[50:53], v[94:97], v[110:113], v[50:53]
	v_mfma_f32_16x16x32_bf16 v[46:49], v[86:89], v[118:121], v[46:49]
	v_mfma_f32_16x16x32_bf16 v[42:45], v[94:97], v[118:121], v[42:45]
	v_mfma_f32_16x16x32_bf16 v[38:41], v[86:89], v[126:129], v[38:41]
	v_mfma_f32_16x16x32_bf16 v[34:37], v[94:97], v[126:129], v[34:37]
	s_barrier
	s_add_i32 s12, s48, s1
	v_lshl_add_u64 v[130:131], s[16:17], 0, v[70:71]
	s_mov_b32 m0, s12
	v_lshl_add_u64 v[132:133], s[16:17], 0, v[66:67]
	global_load_lds_dwordx4 v[130:131], off
	s_add_i32 m0, s12, 0x2000
	s_nop 0
	global_load_lds_dwordx4 v[132:133], off
	s_barrier
	s_waitcnt lgkmcnt(0)
	s_mov_b32 m0, s18
	v_lshl_add_u64 v[134:135], s[36:37], 0, v[72:73]
	s_barrier
	ds_read_b128 v[98:101], v80 offset:16384
	ds_read_b128 v[102:105], v80 offset:17408
	ds_read_b128 v[106:109], v80 offset:18432
	ds_read_b128 v[110:113], v80 offset:19456
	ds_read_b128 v[114:117], v80 offset:20480
	ds_read_b128 v[118:121], v80 offset:21504
	ds_read_b128 v[122:125], v80 offset:22528
	ds_read_b128 v[126:129], v80 offset:23552
	global_load_lds_dwordx4 v[134:135], off
	s_mov_b32 m0, s19
	v_lshl_add_u64 v[136:137], s[36:37], 0, v[68:69]
	global_load_lds_dwordx4 v[136:137], off
	s_barrier
	s_waitcnt lgkmcnt(0)
	v_mfma_f32_16x16x32_bf16 v[30:33], v[82:85], v[98:101], v[30:33]
	v_mfma_f32_16x16x32_bf16 v[26:29], v[90:93], v[98:101], v[26:29]
	v_mfma_f32_16x16x32_bf16 v[22:25], v[82:85], v[106:109], v[22:25]
	v_mfma_f32_16x16x32_bf16 v[18:21], v[90:93], v[106:109], v[18:21]
	v_mfma_f32_16x16x32_bf16 v[14:17], v[82:85], v[114:117], v[14:17]
	v_mfma_f32_16x16x32_bf16 v[10:13], v[90:93], v[114:117], v[10:13]
	v_mfma_f32_16x16x32_bf16 v[4:7], v[82:85], v[122:125], v[4:7]
	v_mfma_f32_16x16x32_bf16 v[0:3], v[90:93], v[122:125], v[0:3]
	v_mfma_f32_16x16x32_bf16 v[30:33], v[86:89], v[102:105], v[30:33]
	v_mfma_f32_16x16x32_bf16 v[26:29], v[94:97], v[102:105], v[26:29]
	v_mfma_f32_16x16x32_bf16 v[22:25], v[86:89], v[110:113], v[22:25]
	v_mfma_f32_16x16x32_bf16 v[18:21], v[94:97], v[110:113], v[18:21]
	v_mfma_f32_16x16x32_bf16 v[14:17], v[86:89], v[118:121], v[14:17]
	v_mfma_f32_16x16x32_bf16 v[10:13], v[94:97], v[118:121], v[10:13]
	v_mfma_f32_16x16x32_bf16 v[4:7], v[86:89], v[126:129], v[4:7]
	v_mfma_f32_16x16x32_bf16 v[0:3], v[94:97], v[126:129], v[0:3]
	s_barrier
	s_add_u32 s12, s16, 0x20000
	s_addc_u32 s13, s17, 0
	s_mov_b32 m0, s26
	s_nop 0
	global_load_lds_dwordx4 v70, s[12:13]
	s_mov_b32 m0, s27
	s_nop 0
	global_load_lds_dwordx4 v66, s[12:13]
	s_waitcnt vmcnt(6)
	s_barrier
	s_add_i32 s48, 0, 0x18000
	v_add_u32_e32 v81, s48, v79
	s_barrier
	ds_read_b128 v[82:85], v81
	ds_read_b128 v[86:89], v81 offset:1024
	ds_read_b128 v[90:93], v81 offset:2048
	ds_read_b128 v[94:97], v81 offset:3072
	s_add_u32 s12, s36, 0x28000
	s_addc_u32 s13, s37, 0
	s_mov_b32 m0, s38
	ds_read_b128 v[98:101], v80 offset:32768
	ds_read_b128 v[102:105], v80 offset:33792
	ds_read_b128 v[106:109], v80 offset:34816
	ds_read_b128 v[110:113], v80 offset:35840
	ds_read_b128 v[114:117], v80 offset:36864
	ds_read_b128 v[118:121], v80 offset:37888
	ds_read_b128 v[122:125], v80 offset:38912
	ds_read_b128 v[126:129], v80 offset:39936
	global_load_lds_dwordx4 v72, s[12:13]
	s_mov_b32 m0, s39
	s_nop 0
	global_load_lds_dwordx4 v68, s[12:13]
	s_waitcnt lgkmcnt(8)
	s_barrier
	s_waitcnt lgkmcnt(0)
	v_mfma_f32_16x16x32_bf16 v[62:65], v[82:85], v[98:101], v[62:65]
	v_mfma_f32_16x16x32_bf16 v[58:61], v[90:93], v[98:101], v[58:61]
	v_mfma_f32_16x16x32_bf16 v[54:57], v[82:85], v[106:109], v[54:57]
	v_mfma_f32_16x16x32_bf16 v[50:53], v[90:93], v[106:109], v[50:53]
	v_mfma_f32_16x16x32_bf16 v[46:49], v[82:85], v[114:117], v[46:49]
	v_mfma_f32_16x16x32_bf16 v[42:45], v[90:93], v[114:117], v[42:45]
	v_mfma_f32_16x16x32_bf16 v[38:41], v[82:85], v[122:125], v[38:41]
	v_mfma_f32_16x16x32_bf16 v[34:37], v[90:93], v[122:125], v[34:37]
	v_mfma_f32_16x16x32_bf16 v[62:65], v[86:89], v[102:105], v[62:65]
	v_mfma_f32_16x16x32_bf16 v[58:61], v[94:97], v[102:105], v[58:61]
	v_mfma_f32_16x16x32_bf16 v[54:57], v[86:89], v[110:113], v[54:57]
	v_mfma_f32_16x16x32_bf16 v[50:53], v[94:97], v[110:113], v[50:53]
	v_mfma_f32_16x16x32_bf16 v[46:49], v[86:89], v[118:121], v[46:49]
	v_mfma_f32_16x16x32_bf16 v[42:45], v[94:97], v[118:121], v[42:45]
	v_mfma_f32_16x16x32_bf16 v[38:41], v[86:89], v[126:129], v[38:41]
	v_mfma_f32_16x16x32_bf16 v[34:37], v[94:97], v[126:129], v[34:37]
	s_barrier
; #define PG8_STAGE(bufoff, gbase, voff) do { _Pragma("unroll") for (int _i = 0; _i < 2; ++_i) \
;         __builtin_amdgcn_global_load_lds((const unsigned*)((const char*)(gbase) + (voff)[_i]), (LAS unsigned*)(lds + (bufoff) + ldsw + _i * 8192), 16, 0, 0); } while (0)
; #define PG8_MMA(ai, bj, At, Bt) do { __builtin_amdgcn_s_setprio(1); _Pragma("unroll") for (int m = 0; m < 4; ++m) _Pragma("unroll") for (int n = 0; n < 2; ++n) _Pragma("unroll") for (int k = 0; k < 2; ++k) \
;         acc[ai][bj][m][n] = __builtin_amdgcn_mfma_f32_16x16x32_bf16(Bt[n][k], At[m][k], acc[ai][bj][m][n], 0, 0, 0); __builtin_amdgcn_s_setprio(0); } while (0)
; #define PG8_WAIT_V(n) asm volatile("s_waitcnt vmcnt(" #n ")" ::: "memory")
; #define PG8_WAIT_L(n) asm volatile("s_waitcnt lgkmcnt(" #n ")" ::: "memory")
; #define PG8_BAR __builtin_amdgcn_s_barrier()
; #define PG8_SCHED __builtin_amdgcn_sched_barrier(0)
; template <class Epi>
; DEVI void gemm_phase(LAS unsigned char* lds, const Gemm g, const Epi& E) {
;     ...
;             PG8_BAR; PG8_WAIT_L(0); PG8_MMA(1, 0, At, B0); PG8_BAR; PG8_SCHED;
;             PG8_STAGE(PG8_SB(1, 1), b3 + hstepB, voffB);
;             PG8_WAIT_V(6); PG8_BAR; PG8_MMA(1, 1, At, B1); PG8_BAR;
;         }
	s_add_i32 s12, s48, s1
	s_mov_b32 m0, s12
	v_lshl_add_u64 v[98:99], v[130:131], 0, s[70:71]
	global_load_lds_dwordx4 v[98:99], off
	s_add_i32 m0, s12, 0x2000
	v_lshl_add_u64 v[98:99], v[132:133], 0, s[70:71]
	global_load_lds_dwordx4 v[98:99], off
	s_barrier
	s_waitcnt lgkmcnt(0)
	s_mov_b32 m0, s41
	v_lshl_add_u64 v[130:131], v[134:135], 0, s[70:71]
	s_barrier
	ds_read_b128 v[98:101], v80 offset:49152
	ds_read_b128 v[102:105], v80 offset:50176
	ds_read_b128 v[106:109], v80 offset:51200
	ds_read_b128 v[110:113], v80 offset:52224
	ds_read_b128 v[114:117], v80 offset:53248
	ds_read_b128 v[118:121], v80 offset:54272
	ds_read_b128 v[122:125], v80 offset:55296
	ds_read_b128 v[126:129], v80 offset:56320
	global_load_lds_dwordx4 v[130:131], off
	s_mov_b32 m0, s42
	v_lshl_add_u64 v[130:131], v[136:137], 0, s[70:71]
	global_load_lds_dwordx4 v[130:131], off
	s_barrier
	s_waitcnt lgkmcnt(0)
	v_mfma_f32_16x16x32_bf16 v[30:33], v[82:85], v[98:101], v[30:33]
	v_mfma_f32_16x16x32_bf16 v[26:29], v[90:93], v[98:101], v[26:29]
	v_mfma_f32_16x16x32_bf16 v[22:25], v[82:85], v[106:109], v[22:25]
	v_mfma_f32_16x16x32_bf16 v[18:21], v[90:93], v[106:109], v[18:21]
	v_mfma_f32_16x16x32_bf16 v[14:17], v[82:85], v[114:117], v[14:17]
	v_mfma_f32_16x16x32_bf16 v[10:13], v[90:93], v[114:117], v[10:13]
	v_mfma_f32_16x16x32_bf16 v[4:7], v[82:85], v[122:125], v[4:7]
	v_mfma_f32_16x16x32_bf16 v[0:3], v[90:93], v[122:125], v[0:3]
	v_mfma_f32_16x16x32_bf16 v[30:33], v[86:89], v[102:105], v[30:33]
	v_mfma_f32_16x16x32_bf16 v[26:29], v[94:97], v[102:105], v[26:29]
	v_mfma_f32_16x16x32_bf16 v[22:25], v[86:89], v[110:113], v[22:25]
	v_mfma_f32_16x16x32_bf16 v[18:21], v[94:97], v[110:113], v[18:21]
	v_mfma_f32_16x16x32_bf16 v[14:17], v[86:89], v[118:121], v[14:17]
	v_mfma_f32_16x16x32_bf16 v[10:13], v[94:97], v[118:121], v[10:13]
	v_mfma_f32_16x16x32_bf16 v[4:7], v[86:89], v[126:129], v[4:7]
	v_mfma_f32_16x16x32_bf16 v[0:3], v[94:97], v[126:129], v[0:3]
	s_barrier
	s_add_u32 s12, s16, 0x20080
	s_addc_u32 s13, s17, 0
	s_mov_b32 m0, s43
	s_nop 0
	global_load_lds_dwordx4 v70, s[12:13]
	s_mov_b32 m0, s44
	s_nop 0
	global_load_lds_dwordx4 v66, s[12:13]
	s_waitcnt vmcnt(6)
	s_barrier
	s_add_i32 s47, s47, 2
	s_add_u32 s5, s5, 0x100
	s_addc_u32 s7, s7, 0
	s_cmp_gt_u32 s47, 5
	s_mov_b64 s[12:13], s[14:15]
	s_barrier
	s_cbranch_scc0 .LBB0_1127
	s_setprio 0
	s_ashr_i32 s5, s4, 31
	v_lshl_add_u32 v82, s40, 8, v78
	s_lshl_b64 s[4:5], s[4:5], 19
	v_readlane_b32 s7, v253, 50
	s_add_u32 s4, s7, s4
	v_readlane_b32 s7, v253, 51
	v_ashrrev_i32_e32 v83, 31, v82
	s_addc_u32 s5, s7, s5
	v_lshlrev_b64 v[84:85], 9, v[82:83]
	v_lshl_add_u64 v[84:85], s[4:5], 0, v[84:85]
	v_lshl_add_u64 v[84:85], v[84:85], 0, v[8:9]
	global_store_dwordx4 v[84:85], v[62:65], off
	global_store_dwordx4 v[84:85], v[58:61], off offset:64
	s_mov_b32 s40, s46
	s_mov_b64 s[14:15], s[10:11]
	v_or_b32_e32 v58, 16, v82
	v_ashrrev_i32_e32 v59, 31, v58
	v_lshlrev_b64 v[58:59], 9, v[58:59]
	v_lshl_add_u64 v[58:59], s[4:5], 0, v[58:59]
	v_lshl_add_u64 v[58:59], v[58:59], 0, v[8:9]
	global_store_dwordx4 v[58:59], v[54:57], off
	global_store_dwordx4 v[58:59], v[50:53], off offset:64
	s_mov_b64 s[12:13], s[8:9]
	s_nop 0
	v_or_b32_e32 v50, 32, v82
	v_ashrrev_i32_e32 v51, 31, v50
	v_lshlrev_b64 v[50:51], 9, v[50:51]
	v_lshl_add_u64 v[50:51], s[4:5], 0, v[50:51]
	v_lshl_add_u64 v[50:51], v[50:51], 0, v[8:9]
	global_store_dwordx4 v[50:51], v[46:49], off
	global_store_dwordx4 v[50:51], v[42:45], off offset:64
	s_nop 1
	v_or_b32_e32 v42, 48, v82
	v_ashrrev_i32_e32 v43, 31, v42
	v_lshlrev_b64 v[42:43], 9, v[42:43]
	v_lshl_add_u64 v[42:43], s[4:5], 0, v[42:43]
	v_lshl_add_u64 v[42:43], v[42:43], 0, v[8:9]
	s_mov_b64 s[4:5], 0x10000
	global_store_dwordx4 v[42:43], v[38:41], off
	global_store_dwordx4 v[42:43], v[34:37], off offset:64
	s_nop 1
	v_lshl_add_u64 v[34:35], v[84:85], 0, s[4:5]
	s_mov_b32 s4, 0x10000
	v_add_co_u32_e32 v36, vcc, s4, v84
	s_mov_b64 s[4:5], 0x12000
	s_nop 0
	v_addc_co_u32_e32 v37, vcc, 0, v85, vcc
	global_store_dwordx4 v[36:37], v[30:33], off
	global_store_dwordx4 v[34:35], v[26:29], off offset:64
	s_nop 1
	v_lshl_add_u64 v[26:27], v[84:85], 0, s[4:5]
	s_mov_b32 s4, 0x12000
	v_add_co_u32_e32 v28, vcc, s4, v84
	s_mov_b64 s[4:5], 0x14000
	s_nop 0
	v_addc_co_u32_e32 v29, vcc, 0, v85, vcc
	global_store_dwordx4 v[28:29], v[22:25], off
	global_store_dwordx4 v[26:27], v[18:21], off offset:64
	s_nop 1
	v_add_co_u32_e32 v20, vcc, 0x14000, v84
	v_lshl_add_u64 v[18:19], v[84:85], 0, s[4:5]
	s_nop 0
	v_addc_co_u32_e32 v21, vcc, 0, v85, vcc
	global_store_dwordx4 v[20:21], v[14:17], off
	global_store_dwordx4 v[18:19], v[10:13], off offset:64
	s_mov_b64 s[4:5], 0x16000
	s_nop 0
	v_add_co_u32_e32 v12, vcc, 0x16000, v84
	v_lshl_add_u64 v[10:11], v[84:85], 0, s[4:5]
	s_nop 0
	v_addc_co_u32_e32 v13, vcc, 0, v85, vcc
	s_and_b64 vcc, exec, s[2:3]
	s_mov_b32 s4, s6
	global_store_dwordx4 v[12:13], v[4:7], off
	global_store_dwordx4 v[10:11], v[0:3], off offset:64
	s_cbranch_vccz .LBB0_1122
	s_branch .LBB0_1131

; #define PG8_STAGE(bufoff, gbase, voff) do { _Pragma("unroll") for (int _i = 0; _i < 2; ++_i) \
;         __builtin_amdgcn_global_load_lds((const unsigned*)((const char*)(gbase) + (voff)[_i]), (LAS unsigned*)(lds + (bufoff) + ldsw + _i * 8192), 16, 0, 0); } while (0)
; #define PG8_LDA(dst, b, h) do { _Pragma("unroll") for (int m = 0; m < 4; ++m) _Pragma("unroll") for (int k = 0; k < 2; ++k) dst[m][k] = *(const LAS bf16x8*)(lds + PG8_SA(b, h) + aoff + m * 2048 + k * 1024); } while (0)
; #define PG8_LDB(dst, b, h) do { _Pragma("unroll") for (int n = 0; n < 2; ++n) _Pragma("unroll") for (int k = 0; k < 2; ++k) dst[n][k] = *(const LAS bf16x8*)(lds + PG8_SB(b, h) + boff + n * 2048 + k * 1024); } while (0)
; #define PG8_MMA(ai, bj, At, Bt) do { __builtin_amdgcn_s_setprio(1); _Pragma("unroll") for (int m = 0; m < 4; ++m) _Pragma("unroll") for (int n = 0; n < 2; ++n) _Pragma("unroll") for (int k = 0; k < 2; ++k) \
;         acc[ai][bj][m][n] = __builtin_amdgcn_mfma_f32_16x16x32_bf16(Bt[n][k], At[m][k], acc[ai][bj][m][n], 0, 0, 0); __builtin_amdgcn_s_setprio(0); } while (0)
; #define PG8_WAIT_V(n) asm volatile("s_waitcnt vmcnt(" #n ")" ::: "memory")
; #define PG8_WAIT_L(n) asm volatile("s_waitcnt lgkmcnt(" #n ")" ::: "memory")
; #define PG8_BAR __builtin_amdgcn_s_barrier()
; #define PG8_SCHED __builtin_amdgcn_sched_barrier(0)
; template <class Epi>
; DEVI void gemm_phase(LAS unsigned char* lds, const Gemm g, const Epi& E) {
;     ...
;             const bool last = (t == nt - 2);
;             const char* a1 = cA + (size_t)(t + 1) * kstep;
;             const char* a2 = last ? nA : cA + (size_t)(t + 2) * kstep; const char* b2 = last ? nB : cB + (size_t)(t + 2) * kstep;
;             const char* a3 = a2 + kstep; const char* b3 = b2 + kstep;
;             PG8_LDB(B0, 0, 0); PG8_SCHED; PG8_LDA(At, 0, 0); PG8_STAGE(PG8_SA(1, 1), a1 + hstepA, voffA);
;             PG8_WAIT_L(8); PG8_BAR; PG8_WAIT_L(0); PG8_MMA(0, 0, At, B0); PG8_BAR; PG8_SCHED;
;             PG8_LDB(B1, 0, 1); PG8_STAGE(PG8_SB(0, 0), b2, voffB);
;             PG8_BAR; PG8_WAIT_L(0); PG8_MMA(0, 1, At, B1); PG8_BAR;
;             PG8_LDA(At, 0, 1); PG8_STAGE(PG8_SA(0, 0), a2, voffA);
;             PG8_BAR; PG8_WAIT_L(0); PG8_MMA(1, 0, At, B0); PG8_BAR; PG8_SCHED;
;             PG8_STAGE(PG8_SB(0, 1), b2 + hstepB, voffB);
;             PG8_WAIT_V(6); PG8_BAR; PG8_MMA(1, 1, At, B1); PG8_BAR;
.LBB0_1278:
	s_add_u32 s12, s10, 0x100
	s_addc_u32 s13, s11, 0
	s_add_i32 s38, 0, 0x10000
	v_add_u32_e32 v146, s38, v149
	ds_read_b128 v[142:145], v146
	ds_read_b128 v[176:179], v146 offset:1024
	ds_read_b128 v[180:183], v146 offset:2048
	ds_read_b128 v[184:187], v146 offset:3072
	s_cmp_eq_u32 s27, 6
	s_cselect_b32 s17, s5, s13
	s_cselect_b32 s16, s4, s12
	s_cselect_b32 s15, s7, s26
	s_cselect_b32 s14, s6, s19
	s_add_i32 m0, s46, 0xc000
	ds_read_b128 v[188:191], v151
	ds_read_b128 v[192:195], v151 offset:1024
	ds_read_b128 v[196:199], v151 offset:2048
	ds_read_b128 v[200:203], v151 offset:3072
	ds_read_b128 v[204:207], v151 offset:4096
	ds_read_b128 v[214:217], v151 offset:5120
	ds_read_b128 v[218:221], v151 offset:6144
	ds_read_b128 v[222:225], v151 offset:7168
	global_load_lds_dwordx4 v138, s[10:11]
	s_add_i32 m0, s46, 0xe000
	s_nop 0
	global_load_lds_dwordx4 v140, s[10:11]
	s_waitcnt lgkmcnt(8)
	s_barrier
	s_waitcnt lgkmcnt(0)
	v_mfma_f32_16x16x32_bf16 v[126:129], v[142:145], v[188:191], v[126:129]
	v_mfma_f32_16x16x32_bf16 v[122:125], v[180:183], v[188:191], v[122:125]
	v_mfma_f32_16x16x32_bf16 v[110:113], v[142:145], v[196:199], v[110:113]
	v_mfma_f32_16x16x32_bf16 v[106:109], v[180:183], v[196:199], v[106:109]
	v_mfma_f32_16x16x32_bf16 v[94:97], v[142:145], v[204:207], v[94:97]
	v_mfma_f32_16x16x32_bf16 v[90:93], v[180:183], v[204:207], v[90:93]
	v_mfma_f32_16x16x32_bf16 v[78:81], v[142:145], v[218:221], v[78:81]
	v_mfma_f32_16x16x32_bf16 v[74:77], v[180:183], v[218:221], v[74:77]
	v_mfma_f32_16x16x32_bf16 v[126:129], v[176:179], v[192:195], v[126:129]
	v_mfma_f32_16x16x32_bf16 v[122:125], v[184:187], v[192:195], v[122:125]
	v_mfma_f32_16x16x32_bf16 v[110:113], v[176:179], v[200:203], v[110:113]
	v_mfma_f32_16x16x32_bf16 v[106:109], v[184:187], v[200:203], v[106:109]
	v_mfma_f32_16x16x32_bf16 v[94:97], v[176:179], v[214:217], v[94:97]
	v_mfma_f32_16x16x32_bf16 v[90:93], v[184:187], v[214:217], v[90:93]
	v_mfma_f32_16x16x32_bf16 v[78:81], v[176:179], v[222:225], v[78:81]
	v_mfma_f32_16x16x32_bf16 v[74:77], v[184:187], v[222:225], v[74:77]
	s_barrier
	s_add_i32 s39, 0, 0x14000
	v_add_u32_e32 v146, s39, v149
	s_add_i32 s10, s38, s37
	ds_read_b128 v[226:229], v146
	ds_read_b128 v[230:233], v146 offset:1024
	ds_read_b128 v[234:237], v146 offset:2048
	ds_read_b128 v[238:241], v146 offset:3072
	v_lshl_add_u64 v[146:147], s[14:15], 0, v[8:9]
	s_mov_b32 m0, s10
	v_lshl_add_u64 v[152:153], s[14:15], 0, v[130:131]
	global_load_lds_dwordx4 v[146:147], off
	s_add_i32 m0, s10, 0x2000
	s_nop 0
	global_load_lds_dwordx4 v[152:153], off
	s_barrier
	s_waitcnt lgkmcnt(0)
	v_mfma_f32_16x16x32_bf16 v[118:121], v[226:229], v[188:191], v[118:121]
	v_mfma_f32_16x16x32_bf16 v[114:117], v[234:237], v[188:191], v[114:117]
	v_mfma_f32_16x16x32_bf16 v[102:105], v[226:229], v[196:199], v[102:105]
	v_mfma_f32_16x16x32_bf16 v[98:101], v[234:237], v[196:199], v[98:101]
	v_mfma_f32_16x16x32_bf16 v[86:89], v[226:229], v[204:207], v[86:89]
	v_mfma_f32_16x16x32_bf16 v[82:85], v[234:237], v[204:207], v[82:85]
	v_mfma_f32_16x16x32_bf16 v[70:73], v[226:229], v[218:221], v[70:73]
	v_mfma_f32_16x16x32_bf16 v[66:69], v[234:237], v[218:221], v[66:69]
	v_mfma_f32_16x16x32_bf16 v[118:121], v[230:233], v[192:195], v[118:121]
	v_mfma_f32_16x16x32_bf16 v[114:117], v[238:241], v[192:195], v[114:117]
	v_mfma_f32_16x16x32_bf16 v[102:105], v[230:233], v[200:203], v[102:105]
	v_mfma_f32_16x16x32_bf16 v[98:101], v[238:241], v[200:203], v[98:101]
	v_mfma_f32_16x16x32_bf16 v[86:89], v[230:233], v[214:217], v[86:89]
	v_mfma_f32_16x16x32_bf16 v[82:85], v[238:241], v[214:217], v[82:85]
	v_mfma_f32_16x16x32_bf16 v[70:73], v[230:233], v[222:225], v[70:73]
	v_mfma_f32_16x16x32_bf16 v[66:69], v[238:241], v[222:225], v[66:69]
	s_mov_b32 m0, s46
	v_lshl_add_u64 v[162:163], s[16:17], 0, v[134:135]
	s_barrier
	ds_read_b128 v[188:191], v151 offset:16384
	ds_read_b128 v[192:195], v151 offset:17408
	ds_read_b128 v[196:199], v151 offset:18432
	ds_read_b128 v[200:203], v151 offset:19456
	ds_read_b128 v[204:207], v151 offset:20480
	ds_read_b128 v[214:217], v151 offset:21504
	ds_read_b128 v[218:221], v151 offset:22528
	ds_read_b128 v[222:225], v151 offset:23552
	global_load_lds_dwordx4 v[162:163], off
	s_mov_b32 m0, s47
	v_lshl_add_u64 v[164:165], s[16:17], 0, v[132:133]
	global_load_lds_dwordx4 v[164:165], off
	s_barrier
	s_waitcnt lgkmcnt(0)
	v_mfma_f32_16x16x32_bf16 v[62:65], v[142:145], v[188:191], v[62:65]
	v_mfma_f32_16x16x32_bf16 v[58:61], v[180:183], v[188:191], v[58:61]
	v_mfma_f32_16x16x32_bf16 v[46:49], v[142:145], v[196:199], v[46:49]
	v_mfma_f32_16x16x32_bf16 v[42:45], v[180:183], v[196:199], v[42:45]
	v_mfma_f32_16x16x32_bf16 v[30:33], v[142:145], v[204:207], v[30:33]
	v_mfma_f32_16x16x32_bf16 v[26:29], v[180:183], v[204:207], v[26:29]
	v_mfma_f32_16x16x32_bf16 v[14:17], v[142:145], v[218:221], v[14:17]
	v_mfma_f32_16x16x32_bf16 v[10:13], v[180:183], v[218:221], v[10:13]
	v_mfma_f32_16x16x32_bf16 v[62:65], v[176:179], v[192:195], v[62:65]
	v_mfma_f32_16x16x32_bf16 v[58:61], v[184:187], v[192:195], v[58:61]
	v_mfma_f32_16x16x32_bf16 v[46:49], v[176:179], v[200:203], v[46:49]
	v_mfma_f32_16x16x32_bf16 v[42:45], v[184:187], v[200:203], v[42:45]
	v_mfma_f32_16x16x32_bf16 v[30:33], v[176:179], v[214:217], v[30:33]
	v_mfma_f32_16x16x32_bf16 v[26:29], v[184:187], v[214:217], v[26:29]
	v_mfma_f32_16x16x32_bf16 v[14:17], v[176:179], v[222:225], v[14:17]
	v_mfma_f32_16x16x32_bf16 v[10:13], v[184:187], v[222:225], v[10:13]
	s_barrier
	s_add_u32 s10, s14, 0x28000
	s_addc_u32 s11, s15, 0
	s_add_i32 s38, s39, s37
	s_mov_b32 m0, s38
	s_nop 0
	global_load_lds_dwordx4 v8, s[10:11]
	s_add_i32 m0, s38, 0x2000
	s_nop 0
	global_load_lds_dwordx4 v130, s[10:11]
	s_waitcnt vmcnt(6)
	s_barrier
; #define PG8_STAGE(bufoff, gbase, voff) do { _Pragma("unroll") for (int _i = 0; _i < 2; ++_i) \
;         __builtin_amdgcn_global_load_lds((const unsigned*)((const char*)(gbase) + (voff)[_i]), (LAS unsigned*)(lds + (bufoff) + ldsw + _i * 8192), 16, 0, 0); } while (0)
; #define PG8_LDA(dst, b, h) do { _Pragma("unroll") for (int m = 0; m < 4; ++m) _Pragma("unroll") for (int k = 0; k < 2; ++k) dst[m][k] = *(const LAS bf16x8*)(lds + PG8_SA(b, h) + aoff + m * 2048 + k * 1024); } while (0)
; #define PG8_LDB(dst, b, h) do { _Pragma("unroll") for (int n = 0; n < 2; ++n) _Pragma("unroll") for (int k = 0; k < 2; ++k) dst[n][k] = *(const LAS bf16x8*)(lds + PG8_SB(b, h) + boff + n * 2048 + k * 1024); } while (0)
; #define PG8_MMA(ai, bj, At, Bt) do { __builtin_amdgcn_s_setprio(1); _Pragma("unroll") for (int m = 0; m < 4; ++m) _Pragma("unroll") for (int n = 0; n < 2; ++n) _Pragma("unroll") for (int k = 0; k < 2; ++k) \
;         acc[ai][bj][m][n] = __builtin_amdgcn_mfma_f32_16x16x32_bf16(Bt[n][k], At[m][k], acc[ai][bj][m][n], 0, 0, 0); __builtin_amdgcn_s_setprio(0); } while (0)
; #define PG8_WAIT_V(n) asm volatile("s_waitcnt vmcnt(" #n ")" ::: "memory")
; #define PG8_WAIT_L(n) asm volatile("s_waitcnt lgkmcnt(" #n ")" ::: "memory")
; #define PG8_BAR __builtin_amdgcn_s_barrier()
; #define PG8_SCHED __builtin_amdgcn_sched_barrier(0)
; template <class Epi>
; DEVI void gemm_phase(LAS unsigned char* lds, const Gemm g, const Epi& E) {
;     ...
;             PG8_WAIT_V(6); PG8_BAR; PG8_MMA(1, 1, At, B1); PG8_BAR;
;             PG8_LDB(B0, 1, 0); PG8_SCHED; PG8_LDA(At, 1, 0); PG8_STAGE(PG8_SA(0, 1), a2 + hstepA, voffA);
;             PG8_WAIT_L(8); PG8_BAR; PG8_WAIT_L(0); PG8_MMA(0, 0, At, B0); PG8_BAR; PG8_SCHED;
;             PG8_LDB(B1, 1, 1); PG8_STAGE(PG8_SB(1, 0), b3, voffB);
;             PG8_BAR; PG8_WAIT_L(0); PG8_MMA(0, 1, At, B1); PG8_BAR;
;             PG8_LDA(At, 1, 1); PG8_STAGE(PG8_SA(1, 0), a3, voffA);
	v_mfma_f32_16x16x32_bf16 v[54:57], v[226:229], v[188:191], v[54:57]
	v_mfma_f32_16x16x32_bf16 v[50:53], v[234:237], v[188:191], v[50:53]
	v_mfma_f32_16x16x32_bf16 v[38:41], v[226:229], v[196:199], v[38:41]
	v_mfma_f32_16x16x32_bf16 v[34:37], v[234:237], v[196:199], v[34:37]
	v_mfma_f32_16x16x32_bf16 v[22:25], v[226:229], v[204:207], v[22:25]
	v_mfma_f32_16x16x32_bf16 v[18:21], v[234:237], v[204:207], v[18:21]
	v_mfma_f32_16x16x32_bf16 v[4:7], v[226:229], v[218:221], v[4:7]
	v_mfma_f32_16x16x32_bf16 v[0:3], v[234:237], v[218:221], v[0:3]
	v_mfma_f32_16x16x32_bf16 v[54:57], v[230:233], v[192:195], v[54:57]
	v_mfma_f32_16x16x32_bf16 v[50:53], v[238:241], v[192:195], v[50:53]
	v_mfma_f32_16x16x32_bf16 v[38:41], v[230:233], v[200:203], v[38:41]
	v_mfma_f32_16x16x32_bf16 v[34:37], v[238:241], v[200:203], v[34:37]
	v_mfma_f32_16x16x32_bf16 v[22:25], v[230:233], v[214:217], v[22:25]
	v_mfma_f32_16x16x32_bf16 v[18:21], v[238:241], v[214:217], v[18:21]
	v_mfma_f32_16x16x32_bf16 v[4:7], v[230:233], v[222:225], v[4:7]
	v_mfma_f32_16x16x32_bf16 v[0:3], v[238:241], v[222:225], v[0:3]
	s_add_i32 s38, 0, 0x18000
	v_add_u32_e32 v184, s38, v149
	s_barrier
	ds_read_b128 v[142:145], v184
	ds_read_b128 v[176:179], v184 offset:1024
	ds_read_b128 v[180:183], v184 offset:2048
	ds_read_b128 v[184:187], v184 offset:3072
	s_add_u32 s10, s16, 0x28000
	s_addc_u32 s11, s17, 0
	s_mov_b32 m0, s66
	ds_read_b128 v[188:191], v151 offset:32768
	ds_read_b128 v[192:195], v151 offset:33792
	ds_read_b128 v[196:199], v151 offset:34816
	ds_read_b128 v[200:203], v151 offset:35840
	ds_read_b128 v[204:207], v151 offset:36864
	ds_read_b128 v[214:217], v151 offset:37888
	ds_read_b128 v[218:221], v151 offset:38912
	ds_read_b128 v[222:225], v151 offset:39936
	global_load_lds_dwordx4 v134, s[10:11]
	s_mov_b32 m0, s68
	s_nop 0
	global_load_lds_dwordx4 v132, s[10:11]
	s_waitcnt lgkmcnt(8)
	s_barrier
	s_waitcnt lgkmcnt(0)
	v_mfma_f32_16x16x32_bf16 v[126:129], v[142:145], v[188:191], v[126:129]
	v_mfma_f32_16x16x32_bf16 v[122:125], v[180:183], v[188:191], v[122:125]
	v_mfma_f32_16x16x32_bf16 v[110:113], v[142:145], v[196:199], v[110:113]
	v_mfma_f32_16x16x32_bf16 v[106:109], v[180:183], v[196:199], v[106:109]
	v_mfma_f32_16x16x32_bf16 v[94:97], v[142:145], v[204:207], v[94:97]
	v_mfma_f32_16x16x32_bf16 v[90:93], v[180:183], v[204:207], v[90:93]
	v_mfma_f32_16x16x32_bf16 v[78:81], v[142:145], v[218:221], v[78:81]
	v_mfma_f32_16x16x32_bf16 v[74:77], v[180:183], v[218:221], v[74:77]
	v_mfma_f32_16x16x32_bf16 v[126:129], v[176:179], v[192:195], v[126:129]
	v_mfma_f32_16x16x32_bf16 v[122:125], v[184:187], v[192:195], v[122:125]
	v_mfma_f32_16x16x32_bf16 v[110:113], v[176:179], v[200:203], v[110:113]
	v_mfma_f32_16x16x32_bf16 v[106:109], v[184:187], v[200:203], v[106:109]
	v_mfma_f32_16x16x32_bf16 v[94:97], v[176:179], v[214:217], v[94:97]
	v_mfma_f32_16x16x32_bf16 v[90:93], v[184:187], v[214:217], v[90:93]
	v_mfma_f32_16x16x32_bf16 v[78:81], v[176:179], v[222:225], v[78:81]
	v_mfma_f32_16x16x32_bf16 v[74:77], v[184:187], v[222:225], v[74:77]
	s_barrier
	s_add_i32 s16, 0, 0x1c000
	s_add_i32 s10, s38, s37
	v_add_u32_e32 v208, s16, v149
	v_lshl_add_u64 v[146:147], v[146:147], 0, s[70:71]
	s_mov_b32 m0, s10
	ds_read_b128 v[226:229], v208
	ds_read_b128 v[230:233], v208 offset:1024
	ds_read_b128 v[234:237], v208 offset:2048
	ds_read_b128 v[238:241], v208 offset:3072
	global_load_lds_dwordx4 v[146:147], off
	s_add_i32 m0, s10, 0x2000
	v_lshl_add_u64 v[146:147], v[152:153], 0, s[70:71]
	global_load_lds_dwordx4 v[146:147], off
	s_barrier
	s_waitcnt lgkmcnt(0)
	v_mfma_f32_16x16x32_bf16 v[118:121], v[226:229], v[188:191], v[118:121]
	v_mfma_f32_16x16x32_bf16 v[114:117], v[234:237], v[188:191], v[114:117]
	v_mfma_f32_16x16x32_bf16 v[102:105], v[226:229], v[196:199], v[102:105]
	v_mfma_f32_16x16x32_bf16 v[98:101], v[234:237], v[196:199], v[98:101]
	v_mfma_f32_16x16x32_bf16 v[86:89], v[226:229], v[204:207], v[86:89]
	v_mfma_f32_16x16x32_bf16 v[82:85], v[234:237], v[204:207], v[82:85]
	v_mfma_f32_16x16x32_bf16 v[70:73], v[226:229], v[218:221], v[70:73]
	v_mfma_f32_16x16x32_bf16 v[66:69], v[234:237], v[218:221], v[66:69]
	v_mfma_f32_16x16x32_bf16 v[118:121], v[230:233], v[192:195], v[118:121]
	v_mfma_f32_16x16x32_bf16 v[114:117], v[238:241], v[192:195], v[114:117]
	v_mfma_f32_16x16x32_bf16 v[102:105], v[230:233], v[200:203], v[102:105]
	v_mfma_f32_16x16x32_bf16 v[98:101], v[238:241], v[200:203], v[98:101]
	v_mfma_f32_16x16x32_bf16 v[86:89], v[230:233], v[214:217], v[86:89]
	v_mfma_f32_16x16x32_bf16 v[82:85], v[238:241], v[214:217], v[82:85]
	v_mfma_f32_16x16x32_bf16 v[70:73], v[230:233], v[222:225], v[70:73]
	v_mfma_f32_16x16x32_bf16 v[66:69], v[238:241], v[222:225], v[66:69]
	s_mov_b32 m0, s69
	v_lshl_add_u64 v[146:147], v[162:163], 0, s[70:71]
	s_barrier
	ds_read_b128 v[188:191], v151 offset:49152
	ds_read_b128 v[192:195], v151 offset:50176
	ds_read_b128 v[196:199], v151 offset:51200
	ds_read_b128 v[200:203], v151 offset:52224
	ds_read_b128 v[204:207], v151 offset:53248
	ds_read_b128 v[214:217], v151 offset:54272
	ds_read_b128 v[218:221], v151 offset:55296
	ds_read_b128 v[222:225], v151 offset:56320
	global_load_lds_dwordx4 v[146:147], off
	s_mov_b32 m0, s80
	v_lshl_add_u64 v[146:147], v[164:165], 0, s[70:71]
	global_load_lds_dwordx4 v[146:147], off
	s_barrier
; #define PG8_STAGE(bufoff, gbase, voff) do { _Pragma("unroll") for (int _i = 0; _i < 2; ++_i) \
;         __builtin_amdgcn_global_load_lds((const unsigned*)((const char*)(gbase) + (voff)[_i]), (LAS unsigned*)(lds + (bufoff) + ldsw + _i * 8192), 16, 0, 0); } while (0)
; #define PG8_MMA(ai, bj, At, Bt) do { __builtin_amdgcn_s_setprio(1); _Pragma("unroll") for (int m = 0; m < 4; ++m) _Pragma("unroll") for (int n = 0; n < 2; ++n) _Pragma("unroll") for (int k = 0; k < 2; ++k) \
;         acc[ai][bj][m][n] = __builtin_amdgcn_mfma_f32_16x16x32_bf16(Bt[n][k], At[m][k], acc[ai][bj][m][n], 0, 0, 0); __builtin_amdgcn_s_setprio(0); } while (0)
; #define PG8_WAIT_V(n) asm volatile("s_waitcnt vmcnt(" #n ")" ::: "memory")
; #define PG8_WAIT_L(n) asm volatile("s_waitcnt lgkmcnt(" #n ")" ::: "memory")
; #define PG8_BAR __builtin_amdgcn_s_barrier()
; #define PG8_SCHED __builtin_amdgcn_sched_barrier(0)
; template <class Epi>
; DEVI void gemm_phase(LAS unsigned char* lds, const Gemm g, const Epi& E) {
;     ...
;             PG8_BAR; PG8_WAIT_L(0); PG8_MMA(1, 0, At, B0); PG8_BAR; PG8_SCHED;
;             PG8_STAGE(PG8_SB(1, 1), b3 + hstepB, voffB);
;             PG8_WAIT_V(6); PG8_BAR; PG8_MMA(1, 1, At, B1); PG8_BAR;
;         }
	s_waitcnt lgkmcnt(0)
	v_mfma_f32_16x16x32_bf16 v[62:65], v[142:145], v[188:191], v[62:65]
	v_mfma_f32_16x16x32_bf16 v[58:61], v[180:183], v[188:191], v[58:61]
	v_mfma_f32_16x16x32_bf16 v[46:49], v[142:145], v[196:199], v[46:49]
	v_mfma_f32_16x16x32_bf16 v[42:45], v[180:183], v[196:199], v[42:45]
	v_mfma_f32_16x16x32_bf16 v[30:33], v[142:145], v[204:207], v[30:33]
	v_mfma_f32_16x16x32_bf16 v[26:29], v[180:183], v[204:207], v[26:29]
	v_mfma_f32_16x16x32_bf16 v[14:17], v[142:145], v[218:221], v[14:17]
	v_mfma_f32_16x16x32_bf16 v[10:13], v[180:183], v[218:221], v[10:13]
	v_mfma_f32_16x16x32_bf16 v[62:65], v[176:179], v[192:195], v[62:65]
	v_mfma_f32_16x16x32_bf16 v[58:61], v[184:187], v[192:195], v[58:61]
	v_mfma_f32_16x16x32_bf16 v[46:49], v[176:179], v[200:203], v[46:49]
	v_mfma_f32_16x16x32_bf16 v[42:45], v[184:187], v[200:203], v[42:45]
	v_mfma_f32_16x16x32_bf16 v[30:33], v[176:179], v[214:217], v[30:33]
	v_mfma_f32_16x16x32_bf16 v[26:29], v[184:187], v[214:217], v[26:29]
	v_mfma_f32_16x16x32_bf16 v[14:17], v[176:179], v[222:225], v[14:17]
	v_mfma_f32_16x16x32_bf16 v[10:13], v[184:187], v[222:225], v[10:13]
	s_barrier
	s_add_u32 s10, s14, 0x28080
	s_addc_u32 s11, s15, 0
	s_add_i32 s14, s16, s37
	s_mov_b32 m0, s14
	s_nop 0
	global_load_lds_dwordx4 v8, s[10:11]
	s_add_i32 m0, s14, 0x2000
	s_nop 0
	global_load_lds_dwordx4 v130, s[10:11]
	s_waitcnt vmcnt(6)
	s_barrier
	v_mfma_f32_16x16x32_bf16 v[54:57], v[226:229], v[188:191], v[54:57]
	v_mfma_f32_16x16x32_bf16 v[50:53], v[234:237], v[188:191], v[50:53]
	v_mfma_f32_16x16x32_bf16 v[38:41], v[226:229], v[196:199], v[38:41]
	v_mfma_f32_16x16x32_bf16 v[34:37], v[234:237], v[196:199], v[34:37]
	v_mfma_f32_16x16x32_bf16 v[22:25], v[226:229], v[204:207], v[22:25]
	v_mfma_f32_16x16x32_bf16 v[18:21], v[234:237], v[204:207], v[18:21]
	v_mfma_f32_16x16x32_bf16 v[4:7], v[226:229], v[218:221], v[4:7]
	v_mfma_f32_16x16x32_bf16 v[0:3], v[234:237], v[218:221], v[0:3]
	v_mfma_f32_16x16x32_bf16 v[54:57], v[230:233], v[192:195], v[54:57]
	v_mfma_f32_16x16x32_bf16 v[50:53], v[238:241], v[192:195], v[50:53]
	v_mfma_f32_16x16x32_bf16 v[38:41], v[230:233], v[200:203], v[38:41]
	v_mfma_f32_16x16x32_bf16 v[34:37], v[238:241], v[200:203], v[34:37]
	v_mfma_f32_16x16x32_bf16 v[22:25], v[230:233], v[214:217], v[22:25]
	v_mfma_f32_16x16x32_bf16 v[18:21], v[238:241], v[214:217], v[18:21]
	v_mfma_f32_16x16x32_bf16 v[4:7], v[230:233], v[222:225], v[4:7]
	v_mfma_f32_16x16x32_bf16 v[0:3], v[238:241], v[222:225], v[0:3]
	s_add_i32 s27, s27, 2
	s_add_u32 s19, s19, 0x100
	s_addc_u32 s26, s26, 0
	s_cmp_gt_u32 s27, 7
	s_mov_b64 s[10:11], s[12:13]
	s_barrier
	s_cbranch_scc0 .LBB0_1278
	s_setprio 0
	v_lshl_add_u32 v144, s18, 8, v148
	v_ashrrev_i32_e32 v145, 31, v144
	v_lshlrev_b64 v[142:143], 16, v[144:145]
	v_mul_f32_e32 v145, 0x3d372713, v126
	v_mul_f32_e32 v145, v126, v145
	v_fma_f32 v145, v126, v145, v126
	v_mul_f32_e32 v145, 0x3f4c422a, v145
	v_add_f32_e32 v145, v145, v145
	v_mul_f32_e32 v145, 0xbfb8aa3b, v145
	v_exp_f32_e32 v145, v145
	v_lshl_or_b32 v164, s1, 8, v150
	s_lshl_b32 s0, s0, 4
	s_ashr_i32 s1, s0, 31
	v_add_f32_e32 v145, 1.0, v145
	v_rcp_f32_e32 v152, v145
	v_mul_f32_e32 v145, 0x3d372713, v122
	v_mul_f32_e32 v145, v122, v145
	v_fma_f32 v145, v122, v145, v122
	v_mul_f32_e32 v145, 0x3f4c422a, v145
	v_add_f32_e32 v145, v145, v145
	v_mul_f32_e32 v145, 0xbfb8aa3b, v145
	v_exp_f32_e32 v145, v145
	v_lshl_add_u64 v[146:147], s[0:1], 1, v[136:137]
	v_lshl_add_u64 v[142:143], v[146:147], 0, v[142:143]
	s_mov_b64 s[0:1], 0x800000
	v_add_f32_e32 v145, 1.0, v145
	v_rcp_f32_e32 v162, v145
	v_mul_f32_e32 v145, 0x3d372713, v127
	v_mul_f32_e32 v145, v127, v145
	v_fma_f32 v145, v127, v145, v127
	v_mul_f32_e32 v145, 0x3f4c422a, v145
	v_add_f32_e32 v145, v145, v145
	v_mul_f32_e32 v145, 0xbfb8aa3b, v145
	v_exp_f32_e32 v145, v145
	s_and_b64 vcc, exec, s[2:3]
	s_mov_b32 s18, s82
	s_mov_b64 s[12:13], s[6:7]
	v_add_f32_e32 v145, 1.0, v145
	v_rcp_f32_e32 v153, v145
	v_mul_f32_e32 v145, 0x3d372713, v123
	v_mul_f32_e32 v145, v123, v145
	v_fma_f32 v145, v123, v145, v123
	v_mul_f32_e32 v145, 0x3f4c422a, v145
	v_add_f32_e32 v145, v145, v145
	v_mul_f32_e32 v145, 0xbfb8aa3b, v145
	v_exp_f32_e32 v145, v145
	v_pk_mul_f32 v[126:127], v[126:127], v[152:153]
	s_mov_b64 s[10:11], s[4:5]
	v_add_f32_e32 v145, 1.0, v145
	v_rcp_f32_e32 v163, v145
	v_mul_f32_e32 v145, 0x3d372713, v128
	v_mul_f32_e32 v145, v128, v145
	v_fma_f32 v145, v128, v145, v128
	v_mul_f32_e32 v145, 0x3f4c422a, v145
	v_add_f32_e32 v145, v145, v145
	v_mul_f32_e32 v145, 0xbfb8aa3b, v145
	v_exp_f32_e32 v145, v145
	v_pk_mul_f32 v[122:123], v[122:123], v[162:163]
	v_add_f32_e32 v145, 1.0, v145
	v_rcp_f32_e32 v152, v145
	v_mul_f32_e32 v145, 0x3d372713, v124
	v_mul_f32_e32 v145, v124, v145
	v_fma_f32 v145, v124, v145, v124
	v_mul_f32_e32 v145, 0x3f4c422a, v145
	v_add_f32_e32 v145, v145, v145
	v_mul_f32_e32 v145, 0xbfb8aa3b, v145
	v_exp_f32_e32 v145, v145
	s_nop 0
	v_add_f32_e32 v145, 1.0, v145
	v_rcp_f32_e32 v162, v145
	v_mul_f32_e32 v145, 0x3d372713, v129
	v_mul_f32_e32 v145, v129, v145
	v_fma_f32 v145, v129, v145, v129
	v_mul_f32_e32 v145, 0x3f4c422a, v145
	v_add_f32_e32 v145, v145, v145
	v_mul_f32_e32 v145, 0xbfb8aa3b, v145
	v_exp_f32_e32 v145, v145
	s_nop 0
	v_add_f32_e32 v145, 1.0, v145
	v_rcp_f32_e32 v153, v145
	v_mul_f32_e32 v145, 0x3d372713, v125
	v_mul_f32_e32 v145, v125, v145
	v_fma_f32 v145, v125, v145, v125
	v_mul_f32_e32 v145, 0x3f4c422a, v145
	v_add_f32_e32 v145, v145, v145
	v_mul_f32_e32 v145, 0xbfb8aa3b, v145
	v_exp_f32_e32 v145, v145
	v_pk_mul_f32 v[128:129], v[128:129], v[152:153]
	v_add_f32_e32 v145, 1.0, v145
	v_rcp_f32_e32 v163, v145
	s_nop 0
	v_pk_mul_f32 v[152:153], v[124:125], v[162:163]
; DEVI float sigmoidf_(float x) { return __builtin_amdgcn_rcpf(1.f + __expf(-x)); }
; DEVI float siluf_(float x) { return x * __builtin_amdgcn_rcpf(1.f + __expf(-x)); }
; DEVI float logsigf_(float x) { return fminf(x, 0.f) - __logf(1.f + __expf(-fabsf(x))); }
	v_cvt_pk_bf16_f32 v125, v128, v129
	v_ashrrev_i32_e32 v128, 4, v164
	v_ashrrev_i32_e32 v129, 31, v128
	v_cvt_pk_bf16_f32 v124, v126, v127
	v_cvt_pk_bf16_f32 v126, v122, v123
	v_lshlrev_b64 v[122:123], 11, v[128:129]
	v_cvt_pk_bf16_f32 v127, v152, v153
	v_lshl_add_u64 v[152:153], v[142:143], 0, v[122:123]
	global_store_dwordx4 v[152:153], v[124:127], off
	s_nop 1
	v_mul_f32_e32 v125, 0x3d372713, v114
	v_mul_f32_e32 v125, v114, v125
	v_fma_f32 v125, v114, v125, v114
	v_mul_f32_e32 v125, 0x3f4c422a, v125
	v_add_f32_e32 v125, v125, v125
	v_mul_f32_e32 v125, 0xbfb8aa3b, v125
	v_exp_f32_e32 v125, v125
	v_mul_f32_e32 v124, 0x3d372713, v118
	v_mul_f32_e32 v124, v118, v124
	v_fma_f32 v124, v118, v124, v118
	v_add_f32_e32 v125, 1.0, v125
	v_rcp_f32_e32 v126, v125
	v_mul_f32_e32 v125, 0x3d372713, v119
	v_mul_f32_e32 v125, v119, v125
	v_fma_f32 v125, v119, v125, v119
	v_mul_f32_e32 v124, 0x3f4c422a, v124
	v_mul_f32_e32 v125, 0x3f4c422a, v125
	v_add_f32_e32 v124, v124, v124
	v_add_f32_e32 v125, v125, v125
	v_mul_f32_e32 v124, 0xbfb8aa3b, v124
	v_mul_f32_e32 v125, 0xbfb8aa3b, v125
	v_exp_f32_e32 v124, v124
	v_exp_f32_e32 v125, v125
	v_add_f32_e32 v124, 1.0, v124
	v_add_f32_e32 v125, 1.0, v125
	v_rcp_f32_e32 v124, v124
	v_rcp_f32_e32 v125, v125
	s_nop 0
	v_pk_mul_f32 v[118:119], v[118:119], v[124:125]
	v_mul_f32_e32 v124, 0x3d372713, v115
	v_mul_f32_e32 v124, v115, v124
	v_fma_f32 v124, v115, v124, v115
	v_mul_f32_e32 v124, 0x3f4c422a, v124
	v_add_f32_e32 v124, v124, v124
	v_mul_f32_e32 v125, 0x3d372713, v116
	v_mul_f32_e32 v124, 0xbfb8aa3b, v124
	v_mul_f32_e32 v125, v116, v125
	v_exp_f32_e32 v124, v124
	v_fma_f32 v125, v116, v125, v116
	v_mul_f32_e32 v125, 0x3f4c422a, v125
	v_add_f32_e32 v125, v125, v125
	v_mul_f32_e32 v125, 0xbfb8aa3b, v125
	v_add_f32_e32 v124, 1.0, v124
	v_exp_f32_e32 v125, v125
	v_rcp_f32_e32 v127, v124
	v_mul_f32_e32 v124, 0x3d372713, v120
	v_mul_f32_e32 v124, v120, v124
	v_add_f32_e32 v125, 1.0, v125
	v_pk_mul_f32 v[114:115], v[114:115], v[126:127]
	v_rcp_f32_e32 v126, v125
	v_mul_f32_e32 v125, 0x3d372713, v121
	v_mul_f32_e32 v125, v121, v125
	v_fma_f32 v124, v120, v124, v120
	v_fma_f32 v125, v121, v125, v121
	v_mul_f32_e32 v124, 0x3f4c422a, v124
	v_mul_f32_e32 v125, 0x3f4c422a, v125
	v_add_f32_e32 v124, v124, v124
	v_add_f32_e32 v125, v125, v125
	v_mul_f32_e32 v124, 0xbfb8aa3b, v124
	v_mul_f32_e32 v125, 0xbfb8aa3b, v125
	v_exp_f32_e32 v124, v124
	v_exp_f32_e32 v125, v125
	v_add_f32_e32 v124, 1.0, v124
	v_add_f32_e32 v125, 1.0, v125
	v_rcp_f32_e32 v124, v124
	v_rcp_f32_e32 v125, v125
	s_nop 0
	v_pk_mul_f32 v[120:121], v[120:121], v[124:125]
	v_mul_f32_e32 v124, 0x3d372713, v117
	v_mul_f32_e32 v124, v117, v124
	v_fma_f32 v124, v117, v124, v117
	v_mul_f32_e32 v124, 0x3f4c422a, v124
	v_add_f32_e32 v124, v124, v124
	v_mul_f32_e32 v124, 0xbfb8aa3b, v124
	v_exp_f32_e32 v124, v124
	s_nop 0
	v_add_f32_e32 v124, 1.0, v124
	v_rcp_f32_e32 v127, v124
	s_nop 0
	v_pk_mul_f32 v[124:125], v[116:117], v[126:127]
	v_cvt_pk_bf16_f32 v116, v118, v119
	v_cvt_pk_bf16_f32 v118, v114, v115
	v_or_b32_e32 v114, 8, v128
	v_ashrrev_i32_e32 v115, 31, v114
	v_lshlrev_b64 v[114:115], 11, v[114:115]
	v_cvt_pk_bf16_f32 v117, v120, v121
	v_cvt_pk_bf16_f32 v119, v124, v125
	v_lshl_add_u64 v[120:121], v[142:143], 0, v[114:115]
	global_store_dwordx4 v[120:121], v[116:119], off
	s_nop 1
	v_mul_f32_e32 v119, 0x3d372713, v106
	v_mul_f32_e32 v119, v106, v119
	v_fma_f32 v119, v106, v119, v106
	v_mul_f32_e32 v119, 0x3f4c422a, v119
	v_add_f32_e32 v119, v119, v119
	v_mul_f32_e32 v119, 0xbfb8aa3b, v119
	v_exp_f32_e32 v119, v119
	v_mul_f32_e32 v118, 0x3d372713, v110
	v_mul_f32_e32 v118, v110, v118
	v_fma_f32 v118, v110, v118, v110
	v_add_f32_e32 v119, 1.0, v119
	v_rcp_f32_e32 v120, v119
	v_mul_f32_e32 v119, 0x3d372713, v111
	v_mul_f32_e32 v119, v111, v119
	v_fma_f32 v119, v111, v119, v111
	v_mul_f32_e32 v118, 0x3f4c422a, v118
	v_mul_f32_e32 v119, 0x3f4c422a, v119
	v_add_f32_e32 v118, v118, v118
	v_add_f32_e32 v119, v119, v119
	v_mul_f32_e32 v118, 0xbfb8aa3b, v118
	v_mul_f32_e32 v119, 0xbfb8aa3b, v119
	v_exp_f32_e32 v118, v118
	v_exp_f32_e32 v119, v119
	v_or_b32_e32 v116, 16, v144
	v_ashrrev_i32_e32 v117, 31, v116
	v_add_f32_e32 v118, 1.0, v118
	v_add_f32_e32 v119, 1.0, v119
	v_rcp_f32_e32 v118, v118
	v_rcp_f32_e32 v119, v119
	v_lshlrev_b64 v[116:117], 16, v[116:117]
	v_lshl_add_u64 v[116:117], v[146:147], 0, v[116:117]
	v_pk_mul_f32 v[110:111], v[110:111], v[118:119]
	v_mul_f32_e32 v118, 0x3d372713, v107
	v_mul_f32_e32 v118, v107, v118
	v_fma_f32 v118, v107, v118, v107
	v_mul_f32_e32 v118, 0x3f4c422a, v118
	v_add_f32_e32 v118, v118, v118
	v_mul_f32_e32 v118, 0xbfb8aa3b, v118
	v_exp_f32_e32 v118, v118
	s_nop 0
	v_add_f32_e32 v118, 1.0, v118
	v_rcp_f32_e32 v121, v118
	s_nop 0
	v_pk_mul_f32 v[118:119], v[106:107], v[120:121]
	v_mul_f32_e32 v107, 0x3d372713, v108
	v_mul_f32_e32 v107, v108, v107
	v_fma_f32 v107, v108, v107, v108
	v_mul_f32_e32 v107, 0x3f4c422a, v107
	v_add_f32_e32 v107, v107, v107
	v_mul_f32_e32 v107, 0xbfb8aa3b, v107
	v_exp_f32_e32 v107, v107
	v_mul_f32_e32 v106, 0x3d372713, v112
	v_mul_f32_e32 v106, v112, v106
	v_fma_f32 v106, v112, v106, v112
	v_add_f32_e32 v107, 1.0, v107
	v_rcp_f32_e32 v120, v107
	v_mul_f32_e32 v107, 0x3d372713, v113
	v_mul_f32_e32 v107, v113, v107
	v_fma_f32 v107, v113, v107, v113
	v_mul_f32_e32 v106, 0x3f4c422a, v106
	v_mul_f32_e32 v107, 0x3f4c422a, v107
	v_add_f32_e32 v106, v106, v106
	v_add_f32_e32 v107, v107, v107
	v_mul_f32_e32 v106, 0xbfb8aa3b, v106
	v_mul_f32_e32 v107, 0xbfb8aa3b, v107
	v_exp_f32_e32 v106, v106
	v_exp_f32_e32 v107, v107
	v_add_f32_e32 v106, 1.0, v106
	v_add_f32_e32 v107, 1.0, v107
	v_rcp_f32_e32 v106, v106
; DEVI float sigmoidf_(float x) { return __builtin_amdgcn_rcpf(1.f + __expf(-x)); }
; DEVI float siluf_(float x) { return x * __builtin_amdgcn_rcpf(1.f + __expf(-x)); }
; DEVI float logsigf_(float x) { return fminf(x, 0.f) - __logf(1.f + __expf(-fabsf(x))); }
	v_rcp_f32_e32 v107, v107
	s_nop 0
	v_pk_mul_f32 v[112:113], v[112:113], v[106:107]
	v_mul_f32_e32 v106, 0x3d372713, v109
	v_mul_f32_e32 v106, v109, v106
	v_fma_f32 v106, v109, v106, v109
	v_mul_f32_e32 v106, 0x3f4c422a, v106
	v_add_f32_e32 v106, v106, v106
	v_mul_f32_e32 v106, 0xbfb8aa3b, v106
	v_exp_f32_e32 v106, v106
	v_cvt_pk_bf16_f32 v107, v112, v113
	v_add_f32_e32 v106, 1.0, v106
	v_rcp_f32_e32 v121, v106
	v_cvt_pk_bf16_f32 v106, v110, v111
	v_lshl_add_u64 v[110:111], v[116:117], 0, v[122:123]
	v_pk_mul_f32 v[120:121], v[108:109], v[120:121]
	v_cvt_pk_bf16_f32 v108, v118, v119
	v_cvt_pk_bf16_f32 v109, v120, v121
	global_store_dwordx4 v[110:111], v[106:109], off
	s_nop 1
	v_mul_f32_e32 v107, 0x3d372713, v98
	v_mul_f32_e32 v107, v98, v107
	v_fma_f32 v107, v98, v107, v98
	v_mul_f32_e32 v107, 0x3f4c422a, v107
	v_add_f32_e32 v107, v107, v107
	v_mul_f32_e32 v107, 0xbfb8aa3b, v107
	v_exp_f32_e32 v107, v107
	v_mul_f32_e32 v106, 0x3d372713, v102
	v_mul_f32_e32 v106, v102, v106
	v_fma_f32 v106, v102, v106, v102
	v_add_f32_e32 v107, 1.0, v107
	v_rcp_f32_e32 v108, v107
	v_mul_f32_e32 v107, 0x3d372713, v103
	v_mul_f32_e32 v107, v103, v107
	v_fma_f32 v107, v103, v107, v103
	v_mul_f32_e32 v106, 0x3f4c422a, v106
	v_mul_f32_e32 v107, 0x3f4c422a, v107
	v_add_f32_e32 v106, v106, v106
	v_add_f32_e32 v107, v107, v107
	v_mul_f32_e32 v106, 0xbfb8aa3b, v106
	v_mul_f32_e32 v107, 0xbfb8aa3b, v107
	v_exp_f32_e32 v106, v106
	v_exp_f32_e32 v107, v107
	v_add_f32_e32 v106, 1.0, v106
	v_add_f32_e32 v107, 1.0, v107
	v_rcp_f32_e32 v106, v106
	v_rcp_f32_e32 v107, v107
	s_nop 0
	v_pk_mul_f32 v[102:103], v[102:103], v[106:107]
	v_mul_f32_e32 v106, 0x3d372713, v99
	v_mul_f32_e32 v106, v99, v106
	v_fma_f32 v106, v99, v106, v99
	v_mul_f32_e32 v106, 0x3f4c422a, v106
	v_add_f32_e32 v106, v106, v106
	v_mul_f32_e32 v106, 0xbfb8aa3b, v106
	v_exp_f32_e32 v106, v106
	s_nop 0
	v_add_f32_e32 v106, 1.0, v106
	v_rcp_f32_e32 v109, v106
	s_nop 0
	v_pk_mul_f32 v[106:107], v[98:99], v[108:109]
	v_mul_f32_e32 v99, 0x3d372713, v100
	v_mul_f32_e32 v99, v100, v99
	v_fma_f32 v99, v100, v99, v100
	v_mul_f32_e32 v99, 0x3f4c422a, v99
	v_add_f32_e32 v99, v99, v99
	v_mul_f32_e32 v99, 0xbfb8aa3b, v99
	v_exp_f32_e32 v99, v99
	v_mul_f32_e32 v98, 0x3d372713, v104
	v_mul_f32_e32 v98, v104, v98
	v_fma_f32 v98, v104, v98, v104
	v_add_f32_e32 v99, 1.0, v99
	v_rcp_f32_e32 v108, v99
	v_mul_f32_e32 v99, 0x3d372713, v105
	v_mul_f32_e32 v99, v105, v99
	v_fma_f32 v99, v105, v99, v105
	v_mul_f32_e32 v98, 0x3f4c422a, v98
	v_mul_f32_e32 v99, 0x3f4c422a, v99
	v_add_f32_e32 v98, v98, v98
	v_add_f32_e32 v99, v99, v99
	v_mul_f32_e32 v98, 0xbfb8aa3b, v98
	v_mul_f32_e32 v99, 0xbfb8aa3b, v99
	v_exp_f32_e32 v98, v98
	v_exp_f32_e32 v99, v99
	v_add_f32_e32 v98, 1.0, v98
	v_add_f32_e32 v99, 1.0, v99
	v_rcp_f32_e32 v98, v98
	v_rcp_f32_e32 v99, v99
	s_nop 0
	v_pk_mul_f32 v[104:105], v[104:105], v[98:99]
	v_mul_f32_e32 v98, 0x3d372713, v101
	v_mul_f32_e32 v98, v101, v98
	v_fma_f32 v98, v101, v98, v101
	v_mul_f32_e32 v98, 0x3f4c422a, v98
	v_add_f32_e32 v98, v98, v98
	v_mul_f32_e32 v98, 0xbfb8aa3b, v98
	v_exp_f32_e32 v98, v98
	v_cvt_pk_bf16_f32 v99, v104, v105
	v_add_f32_e32 v98, 1.0, v98
	v_rcp_f32_e32 v109, v98
	v_cvt_pk_bf16_f32 v98, v102, v103
	v_lshl_add_u64 v[102:103], v[116:117], 0, v[114:115]
	v_pk_mul_f32 v[108:109], v[100:101], v[108:109]
	v_cvt_pk_bf16_f32 v100, v106, v107
	v_cvt_pk_bf16_f32 v101, v108, v109
	global_store_dwordx4 v[102:103], v[98:101], off
	s_nop 1
	v_mul_f32_e32 v101, 0x3d372713, v90
	v_mul_f32_e32 v101, v90, v101
	v_fma_f32 v101, v90, v101, v90
	v_mul_f32_e32 v101, 0x3f4c422a, v101
	v_add_f32_e32 v101, v101, v101
	v_mul_f32_e32 v101, 0xbfb8aa3b, v101
	v_exp_f32_e32 v101, v101
	v_mul_f32_e32 v100, 0x3d372713, v94
	v_mul_f32_e32 v100, v94, v100
	v_fma_f32 v100, v94, v100, v94
	v_add_f32_e32 v101, 1.0, v101
	v_rcp_f32_e32 v102, v101
	v_mul_f32_e32 v101, 0x3d372713, v95
	v_mul_f32_e32 v101, v95, v101
	v_fma_f32 v101, v95, v101, v95
	v_mul_f32_e32 v100, 0x3f4c422a, v100
	v_mul_f32_e32 v101, 0x3f4c422a, v101
	v_add_f32_e32 v100, v100, v100
	v_add_f32_e32 v101, v101, v101
	v_mul_f32_e32 v100, 0xbfb8aa3b, v100
	v_mul_f32_e32 v101, 0xbfb8aa3b, v101
	v_exp_f32_e32 v100, v100
	v_exp_f32_e32 v101, v101
	v_or_b32_e32 v98, 32, v144
	v_ashrrev_i32_e32 v99, 31, v98
	v_add_f32_e32 v100, 1.0, v100
	v_add_f32_e32 v101, 1.0, v101
	v_rcp_f32_e32 v100, v100
	v_rcp_f32_e32 v101, v101
	v_lshlrev_b64 v[98:99], 16, v[98:99]
	v_lshl_add_u64 v[98:99], v[146:147], 0, v[98:99]
	v_pk_mul_f32 v[94:95], v[94:95], v[100:101]
	v_mul_f32_e32 v100, 0x3d372713, v91
	v_mul_f32_e32 v100, v91, v100
	v_fma_f32 v100, v91, v100, v91
	v_mul_f32_e32 v100, 0x3f4c422a, v100
	v_add_f32_e32 v100, v100, v100
	v_mul_f32_e32 v100, 0xbfb8aa3b, v100
	v_exp_f32_e32 v100, v100
	s_nop 0
	v_add_f32_e32 v100, 1.0, v100
	v_rcp_f32_e32 v103, v100
	s_nop 0
	v_pk_mul_f32 v[100:101], v[90:91], v[102:103]
	v_mul_f32_e32 v91, 0x3d372713, v92
	v_mul_f32_e32 v91, v92, v91
	v_fma_f32 v91, v92, v91, v92
	v_mul_f32_e32 v91, 0x3f4c422a, v91
	v_add_f32_e32 v91, v91, v91
	v_mul_f32_e32 v91, 0xbfb8aa3b, v91
	v_exp_f32_e32 v91, v91
	v_mul_f32_e32 v90, 0x3d372713, v96
	v_mul_f32_e32 v90, v96, v90
	v_fma_f32 v90, v96, v90, v96
	v_add_f32_e32 v91, 1.0, v91
	v_rcp_f32_e32 v102, v91
	v_mul_f32_e32 v91, 0x3d372713, v97
	v_mul_f32_e32 v91, v97, v91
	v_fma_f32 v91, v97, v91, v97
	v_mul_f32_e32 v90, 0x3f4c422a, v90
	v_mul_f32_e32 v91, 0x3f4c422a, v91
	v_add_f32_e32 v90, v90, v90
	v_add_f32_e32 v91, v91, v91
	v_mul_f32_e32 v90, 0xbfb8aa3b, v90
	v_mul_f32_e32 v91, 0xbfb8aa3b, v91
	v_exp_f32_e32 v90, v90
	v_exp_f32_e32 v91, v91
	v_add_f32_e32 v90, 1.0, v90
	v_add_f32_e32 v91, 1.0, v91
; DEVI float sigmoidf_(float x) { return __builtin_amdgcn_rcpf(1.f + __expf(-x)); }
; DEVI float siluf_(float x) { return x * __builtin_amdgcn_rcpf(1.f + __expf(-x)); }
; DEVI float logsigf_(float x) { return fminf(x, 0.f) - __logf(1.f + __expf(-fabsf(x))); }
	v_rcp_f32_e32 v90, v90
	v_rcp_f32_e32 v91, v91
	s_nop 0
	v_pk_mul_f32 v[96:97], v[96:97], v[90:91]
	v_mul_f32_e32 v90, 0x3d372713, v93
	v_mul_f32_e32 v90, v93, v90
	v_fma_f32 v90, v93, v90, v93
	v_mul_f32_e32 v90, 0x3f4c422a, v90
	v_add_f32_e32 v90, v90, v90
	v_mul_f32_e32 v90, 0xbfb8aa3b, v90
	v_exp_f32_e32 v90, v90
	v_cvt_pk_bf16_f32 v91, v96, v97
	v_add_f32_e32 v90, 1.0, v90
	v_rcp_f32_e32 v103, v90
	v_cvt_pk_bf16_f32 v90, v94, v95
	v_lshl_add_u64 v[94:95], v[98:99], 0, v[122:123]
	v_pk_mul_f32 v[102:103], v[92:93], v[102:103]
	v_cvt_pk_bf16_f32 v92, v100, v101
	v_cvt_pk_bf16_f32 v93, v102, v103
	global_store_dwordx4 v[94:95], v[90:93], off
	s_nop 1
	v_mul_f32_e32 v91, 0x3d372713, v82
	v_mul_f32_e32 v91, v82, v91
	v_fma_f32 v91, v82, v91, v82
	v_mul_f32_e32 v91, 0x3f4c422a, v91
	v_add_f32_e32 v91, v91, v91
	v_mul_f32_e32 v91, 0xbfb8aa3b, v91
	v_exp_f32_e32 v91, v91
	v_mul_f32_e32 v90, 0x3d372713, v86
	v_mul_f32_e32 v90, v86, v90
	v_fma_f32 v90, v86, v90, v86
	v_add_f32_e32 v91, 1.0, v91
	v_rcp_f32_e32 v92, v91
	v_mul_f32_e32 v91, 0x3d372713, v87
	v_mul_f32_e32 v91, v87, v91
	v_fma_f32 v91, v87, v91, v87
	v_mul_f32_e32 v90, 0x3f4c422a, v90
	v_mul_f32_e32 v91, 0x3f4c422a, v91
	v_add_f32_e32 v90, v90, v90
	v_add_f32_e32 v91, v91, v91
	v_mul_f32_e32 v90, 0xbfb8aa3b, v90
	v_mul_f32_e32 v91, 0xbfb8aa3b, v91
	v_exp_f32_e32 v90, v90
	v_exp_f32_e32 v91, v91
	v_add_f32_e32 v90, 1.0, v90
	v_add_f32_e32 v91, 1.0, v91
	v_rcp_f32_e32 v90, v90
	v_rcp_f32_e32 v91, v91
	s_nop 0
	v_pk_mul_f32 v[86:87], v[86:87], v[90:91]
	v_mul_f32_e32 v90, 0x3d372713, v83
	v_mul_f32_e32 v90, v83, v90
	v_fma_f32 v90, v83, v90, v83
	v_mul_f32_e32 v90, 0x3f4c422a, v90
	v_add_f32_e32 v90, v90, v90
	v_mul_f32_e32 v90, 0xbfb8aa3b, v90
	v_exp_f32_e32 v90, v90
	s_nop 0
	v_add_f32_e32 v90, 1.0, v90
	v_rcp_f32_e32 v93, v90
	s_nop 0
	v_pk_mul_f32 v[90:91], v[82:83], v[92:93]
	v_mul_f32_e32 v83, 0x3d372713, v84
	v_mul_f32_e32 v83, v84, v83
	v_fma_f32 v83, v84, v83, v84
	v_mul_f32_e32 v83, 0x3f4c422a, v83
	v_add_f32_e32 v83, v83, v83
	v_mul_f32_e32 v83, 0xbfb8aa3b, v83
	v_exp_f32_e32 v83, v83
	v_mul_f32_e32 v82, 0x3d372713, v88
	v_mul_f32_e32 v82, v88, v82
	v_fma_f32 v82, v88, v82, v88
	v_add_f32_e32 v83, 1.0, v83
	v_rcp_f32_e32 v92, v83
	v_mul_f32_e32 v83, 0x3d372713, v89
	v_mul_f32_e32 v83, v89, v83
	v_fma_f32 v83, v89, v83, v89
	v_mul_f32_e32 v82, 0x3f4c422a, v82
	v_mul_f32_e32 v83, 0x3f4c422a, v83
	v_add_f32_e32 v82, v82, v82
	v_add_f32_e32 v83, v83, v83
	v_mul_f32_e32 v82, 0xbfb8aa3b, v82
	v_mul_f32_e32 v83, 0xbfb8aa3b, v83
	v_exp_f32_e32 v82, v82
	v_exp_f32_e32 v83, v83
	v_add_f32_e32 v82, 1.0, v82
	v_add_f32_e32 v83, 1.0, v83
	v_rcp_f32_e32 v82, v82
	v_rcp_f32_e32 v83, v83
	s_nop 0
	v_pk_mul_f32 v[88:89], v[88:89], v[82:83]
	v_mul_f32_e32 v82, 0x3d372713, v85
	v_mul_f32_e32 v82, v85, v82
	v_fma_f32 v82, v85, v82, v85
	v_mul_f32_e32 v82, 0x3f4c422a, v82
	v_add_f32_e32 v82, v82, v82
	v_mul_f32_e32 v82, 0xbfb8aa3b, v82
	v_exp_f32_e32 v82, v82
	v_cvt_pk_bf16_f32 v83, v88, v89
	v_add_f32_e32 v82, 1.0, v82
	v_rcp_f32_e32 v93, v82
	v_cvt_pk_bf16_f32 v82, v86, v87
	v_lshl_add_u64 v[86:87], v[98:99], 0, v[114:115]
	v_pk_mul_f32 v[92:93], v[84:85], v[92:93]
	v_cvt_pk_bf16_f32 v84, v90, v91
	v_cvt_pk_bf16_f32 v85, v92, v93
	global_store_dwordx4 v[86:87], v[82:85], off
	s_nop 1
	v_mul_f32_e32 v85, 0x3d372713, v74
	v_mul_f32_e32 v85, v74, v85
	v_fma_f32 v85, v74, v85, v74
	v_mul_f32_e32 v85, 0x3f4c422a, v85
	v_add_f32_e32 v85, v85, v85
	v_mul_f32_e32 v85, 0xbfb8aa3b, v85
	v_exp_f32_e32 v85, v85
	v_mul_f32_e32 v84, 0x3d372713, v78
	v_mul_f32_e32 v84, v78, v84
	v_fma_f32 v84, v78, v84, v78
	v_add_f32_e32 v85, 1.0, v85
	v_rcp_f32_e32 v86, v85
	v_mul_f32_e32 v85, 0x3d372713, v79
	v_mul_f32_e32 v85, v79, v85
	v_fma_f32 v85, v79, v85, v79
	v_mul_f32_e32 v84, 0x3f4c422a, v84
	v_mul_f32_e32 v85, 0x3f4c422a, v85
	v_add_f32_e32 v84, v84, v84
	v_add_f32_e32 v85, v85, v85
	v_mul_f32_e32 v84, 0xbfb8aa3b, v84
	v_mul_f32_e32 v85, 0xbfb8aa3b, v85
	v_exp_f32_e32 v84, v84
	v_exp_f32_e32 v85, v85
	v_or_b32_e32 v82, 48, v144
	v_ashrrev_i32_e32 v83, 31, v82
	v_add_f32_e32 v84, 1.0, v84
	v_add_f32_e32 v85, 1.0, v85
	v_rcp_f32_e32 v84, v84
	v_rcp_f32_e32 v85, v85
	v_lshlrev_b64 v[82:83], 16, v[82:83]
	v_lshl_add_u64 v[82:83], v[146:147], 0, v[82:83]
	v_pk_mul_f32 v[78:79], v[78:79], v[84:85]
	v_mul_f32_e32 v84, 0x3d372713, v75
	v_mul_f32_e32 v84, v75, v84
	v_fma_f32 v84, v75, v84, v75
	v_mul_f32_e32 v84, 0x3f4c422a, v84
	v_add_f32_e32 v84, v84, v84
	v_mul_f32_e32 v84, 0xbfb8aa3b, v84
	v_exp_f32_e32 v84, v84
	s_nop 0
	v_add_f32_e32 v84, 1.0, v84
	v_rcp_f32_e32 v87, v84
	s_nop 0
	v_pk_mul_f32 v[84:85], v[74:75], v[86:87]
	v_mul_f32_e32 v75, 0x3d372713, v76
	v_mul_f32_e32 v75, v76, v75
	v_fma_f32 v75, v76, v75, v76
	v_mul_f32_e32 v75, 0x3f4c422a, v75
	v_add_f32_e32 v75, v75, v75
	v_mul_f32_e32 v75, 0xbfb8aa3b, v75
	v_exp_f32_e32 v75, v75
	v_mul_f32_e32 v74, 0x3d372713, v80
	v_mul_f32_e32 v74, v80, v74
	v_fma_f32 v74, v80, v74, v80
	v_add_f32_e32 v75, 1.0, v75
	v_rcp_f32_e32 v86, v75
	v_mul_f32_e32 v75, 0x3d372713, v81
	v_mul_f32_e32 v75, v81, v75
	v_fma_f32 v75, v81, v75, v81
	v_mul_f32_e32 v74, 0x3f4c422a, v74
	v_mul_f32_e32 v75, 0x3f4c422a, v75
	v_add_f32_e32 v74, v74, v74
	v_add_f32_e32 v75, v75, v75
	v_mul_f32_e32 v74, 0xbfb8aa3b, v74
	v_mul_f32_e32 v75, 0xbfb8aa3b, v75
	v_exp_f32_e32 v74, v74
	v_exp_f32_e32 v75, v75
	v_add_f32_e32 v74, 1.0, v74
	v_add_f32_e32 v75, 1.0, v75
	v_rcp_f32_e32 v74, v74
	v_rcp_f32_e32 v75, v75
	s_nop 0
	v_pk_mul_f32 v[80:81], v[80:81], v[74:75]
	v_mul_f32_e32 v74, 0x3d372713, v77
	v_mul_f32_e32 v74, v77, v74
	v_fma_f32 v74, v77, v74, v77
	v_mul_f32_e32 v74, 0x3f4c422a, v74
; DEVI float sigmoidf_(float x) { return __builtin_amdgcn_rcpf(1.f + __expf(-x)); }
; DEVI float siluf_(float x) { return x * __builtin_amdgcn_rcpf(1.f + __expf(-x)); }
; DEVI float logsigf_(float x) { return fminf(x, 0.f) - __logf(1.f + __expf(-fabsf(x))); }
	v_add_f32_e32 v74, v74, v74
	v_mul_f32_e32 v74, 0xbfb8aa3b, v74
	v_exp_f32_e32 v74, v74
	v_cvt_pk_bf16_f32 v75, v80, v81
	v_add_f32_e32 v74, 1.0, v74
	v_rcp_f32_e32 v87, v74
	v_cvt_pk_bf16_f32 v74, v78, v79
	v_lshl_add_u64 v[78:79], v[82:83], 0, v[122:123]
	v_pk_mul_f32 v[86:87], v[76:77], v[86:87]
	v_cvt_pk_bf16_f32 v76, v84, v85
	v_cvt_pk_bf16_f32 v77, v86, v87
	global_store_dwordx4 v[78:79], v[74:77], off
	s_nop 1
	v_mul_f32_e32 v75, 0x3d372713, v66
	v_mul_f32_e32 v75, v66, v75
	v_fma_f32 v75, v66, v75, v66
	v_mul_f32_e32 v75, 0x3f4c422a, v75
	v_add_f32_e32 v75, v75, v75
	v_mul_f32_e32 v75, 0xbfb8aa3b, v75
	v_exp_f32_e32 v75, v75
	v_mul_f32_e32 v74, 0x3d372713, v70
	v_mul_f32_e32 v74, v70, v74
	v_fma_f32 v74, v70, v74, v70
	v_add_f32_e32 v75, 1.0, v75
	v_rcp_f32_e32 v76, v75
	v_mul_f32_e32 v75, 0x3d372713, v71
	v_mul_f32_e32 v75, v71, v75
	v_fma_f32 v75, v71, v75, v71
	v_mul_f32_e32 v74, 0x3f4c422a, v74
	v_mul_f32_e32 v75, 0x3f4c422a, v75
	v_add_f32_e32 v74, v74, v74
	v_add_f32_e32 v75, v75, v75
	v_mul_f32_e32 v74, 0xbfb8aa3b, v74
	v_mul_f32_e32 v75, 0xbfb8aa3b, v75
	v_exp_f32_e32 v74, v74
	v_exp_f32_e32 v75, v75
	v_add_f32_e32 v74, 1.0, v74
	v_add_f32_e32 v75, 1.0, v75
	v_rcp_f32_e32 v74, v74
	v_rcp_f32_e32 v75, v75
	s_nop 0
	v_pk_mul_f32 v[70:71], v[70:71], v[74:75]
	v_mul_f32_e32 v74, 0x3d372713, v67
	v_mul_f32_e32 v74, v67, v74
	v_fma_f32 v74, v67, v74, v67
	v_mul_f32_e32 v74, 0x3f4c422a, v74
	v_add_f32_e32 v74, v74, v74
	v_mul_f32_e32 v74, 0xbfb8aa3b, v74
	v_exp_f32_e32 v74, v74
	s_nop 0
	v_add_f32_e32 v74, 1.0, v74
	v_rcp_f32_e32 v77, v74
	s_nop 0
	v_pk_mul_f32 v[74:75], v[66:67], v[76:77]
	v_mul_f32_e32 v67, 0x3d372713, v68
	v_mul_f32_e32 v67, v68, v67
	v_fma_f32 v67, v68, v67, v68
	v_mul_f32_e32 v67, 0x3f4c422a, v67
	v_add_f32_e32 v67, v67, v67
	v_mul_f32_e32 v67, 0xbfb8aa3b, v67
	v_exp_f32_e32 v67, v67
	v_mul_f32_e32 v66, 0x3d372713, v72
	v_mul_f32_e32 v66, v72, v66
	v_fma_f32 v66, v72, v66, v72
	v_add_f32_e32 v67, 1.0, v67
	v_rcp_f32_e32 v76, v67
	v_mul_f32_e32 v67, 0x3d372713, v73
	v_mul_f32_e32 v67, v73, v67
	v_fma_f32 v67, v73, v67, v73
	v_mul_f32_e32 v66, 0x3f4c422a, v66
	v_mul_f32_e32 v67, 0x3f4c422a, v67
	v_add_f32_e32 v66, v66, v66
	v_add_f32_e32 v67, v67, v67
	v_mul_f32_e32 v66, 0xbfb8aa3b, v66
	v_mul_f32_e32 v67, 0xbfb8aa3b, v67
	v_exp_f32_e32 v66, v66
	v_exp_f32_e32 v67, v67
	v_add_f32_e32 v66, 1.0, v66
	v_add_f32_e32 v67, 1.0, v67
	v_rcp_f32_e32 v66, v66
	v_rcp_f32_e32 v67, v67
	s_nop 0
	v_pk_mul_f32 v[72:73], v[72:73], v[66:67]
	v_mul_f32_e32 v66, 0x3d372713, v69
	v_mul_f32_e32 v66, v69, v66
	v_fma_f32 v66, v69, v66, v69
	v_mul_f32_e32 v66, 0x3f4c422a, v66
	v_add_f32_e32 v66, v66, v66
	v_mul_f32_e32 v66, 0xbfb8aa3b, v66
	v_exp_f32_e32 v66, v66
	v_cvt_pk_bf16_f32 v67, v72, v73
	v_add_f32_e32 v66, 1.0, v66
	v_rcp_f32_e32 v77, v66
	v_cvt_pk_bf16_f32 v66, v70, v71
	v_lshl_add_u64 v[70:71], v[82:83], 0, v[114:115]
	v_pk_mul_f32 v[76:77], v[68:69], v[76:77]
	v_cvt_pk_bf16_f32 v68, v74, v75
	v_cvt_pk_bf16_f32 v69, v76, v77
	global_store_dwordx4 v[70:71], v[66:69], off
	s_nop 1
	v_mul_f32_e32 v69, 0x3d372713, v58
	v_mul_f32_e32 v69, v58, v69
	v_fma_f32 v69, v58, v69, v58
	v_mul_f32_e32 v69, 0x3f4c422a, v69
	v_add_f32_e32 v69, v69, v69
	v_mul_f32_e32 v69, 0xbfb8aa3b, v69
	v_exp_f32_e32 v69, v69
	v_mul_f32_e32 v68, 0x3d372713, v62
	v_mul_f32_e32 v68, v62, v68
	v_fma_f32 v68, v62, v68, v62
	v_add_f32_e32 v69, 1.0, v69
	v_rcp_f32_e32 v70, v69
	v_mul_f32_e32 v69, 0x3d372713, v63
	v_mul_f32_e32 v69, v63, v69
	v_fma_f32 v69, v63, v69, v63
	v_mul_f32_e32 v68, 0x3f4c422a, v68
	v_mul_f32_e32 v69, 0x3f4c422a, v69
	v_add_f32_e32 v68, v68, v68
	v_add_f32_e32 v69, v69, v69
	v_mul_f32_e32 v68, 0xbfb8aa3b, v68
	v_mul_f32_e32 v69, 0xbfb8aa3b, v69
	v_exp_f32_e32 v68, v68
	v_exp_f32_e32 v69, v69
	v_lshl_add_u64 v[66:67], v[142:143], 0, s[0:1]
	s_mov_b64 s[0:1], 0x900000
	v_add_f32_e32 v68, 1.0, v68
	v_add_f32_e32 v69, 1.0, v69
	v_rcp_f32_e32 v68, v68
	v_rcp_f32_e32 v69, v69
	s_nop 0
	v_pk_mul_f32 v[62:63], v[62:63], v[68:69]
	v_mul_f32_e32 v68, 0x3d372713, v59
	v_mul_f32_e32 v68, v59, v68
	v_fma_f32 v68, v59, v68, v59
	v_mul_f32_e32 v68, 0x3f4c422a, v68
	v_add_f32_e32 v68, v68, v68
	v_mul_f32_e32 v68, 0xbfb8aa3b, v68
	v_exp_f32_e32 v68, v68
	s_nop 0
	v_add_f32_e32 v68, 1.0, v68
	v_rcp_f32_e32 v71, v68
	s_nop 0
	v_pk_mul_f32 v[68:69], v[58:59], v[70:71]
	v_mul_f32_e32 v59, 0x3d372713, v60
	v_mul_f32_e32 v59, v60, v59
	v_fma_f32 v59, v60, v59, v60
	v_mul_f32_e32 v59, 0x3f4c422a, v59
	v_add_f32_e32 v59, v59, v59
	v_mul_f32_e32 v59, 0xbfb8aa3b, v59
	v_exp_f32_e32 v59, v59
	v_mul_f32_e32 v58, 0x3d372713, v64
	v_mul_f32_e32 v58, v64, v58
	v_fma_f32 v58, v64, v58, v64
	v_add_f32_e32 v59, 1.0, v59
	v_rcp_f32_e32 v70, v59
	v_mul_f32_e32 v59, 0x3d372713, v65
	v_mul_f32_e32 v59, v65, v59
	v_fma_f32 v59, v65, v59, v65
	v_mul_f32_e32 v58, 0x3f4c422a, v58
	v_mul_f32_e32 v59, 0x3f4c422a, v59
	v_add_f32_e32 v58, v58, v58
	v_add_f32_e32 v59, v59, v59
	v_mul_f32_e32 v58, 0xbfb8aa3b, v58
	v_mul_f32_e32 v59, 0xbfb8aa3b, v59
	v_exp_f32_e32 v58, v58
	v_exp_f32_e32 v59, v59
	v_add_f32_e32 v58, 1.0, v58
	v_add_f32_e32 v59, 1.0, v59
	v_rcp_f32_e32 v58, v58
	v_rcp_f32_e32 v59, v59
	s_nop 0
	v_pk_mul_f32 v[64:65], v[64:65], v[58:59]
	v_mul_f32_e32 v58, 0x3d372713, v61
	v_mul_f32_e32 v58, v61, v58
	v_fma_f32 v58, v61, v58, v61
	v_mul_f32_e32 v58, 0x3f4c422a, v58
	v_add_f32_e32 v58, v58, v58
	v_mul_f32_e32 v58, 0xbfb8aa3b, v58
	v_exp_f32_e32 v58, v58
	v_cvt_pk_bf16_f32 v59, v64, v65
	v_add_f32_e32 v58, 1.0, v58
	v_rcp_f32_e32 v71, v58
	v_cvt_pk_bf16_f32 v58, v62, v63
	v_lshl_add_u64 v[62:63], v[66:67], 0, v[122:123]
	v_pk_mul_f32 v[70:71], v[60:61], v[70:71]
; DEVI float sigmoidf_(float x) { return __builtin_amdgcn_rcpf(1.f + __expf(-x)); }
; DEVI float siluf_(float x) { return x * __builtin_amdgcn_rcpf(1.f + __expf(-x)); }
; DEVI float logsigf_(float x) { return fminf(x, 0.f) - __logf(1.f + __expf(-fabsf(x))); }
	v_cvt_pk_bf16_f32 v60, v68, v69
	v_cvt_pk_bf16_f32 v61, v70, v71
	global_store_dwordx4 v[62:63], v[58:61], off
	s_nop 1
	v_mul_f32_e32 v59, 0x3d372713, v50
	v_mul_f32_e32 v59, v50, v59
	v_fma_f32 v59, v50, v59, v50
	v_mul_f32_e32 v59, 0x3f4c422a, v59
	v_add_f32_e32 v59, v59, v59
	v_mul_f32_e32 v59, 0xbfb8aa3b, v59
	v_exp_f32_e32 v59, v59
	v_mul_f32_e32 v58, 0x3d372713, v54
	v_mul_f32_e32 v58, v54, v58
	v_fma_f32 v58, v54, v58, v54
	v_add_f32_e32 v59, 1.0, v59
	v_rcp_f32_e32 v60, v59
	v_mul_f32_e32 v59, 0x3d372713, v55
	v_mul_f32_e32 v59, v55, v59
	v_fma_f32 v59, v55, v59, v55
	v_mul_f32_e32 v58, 0x3f4c422a, v58
	v_mul_f32_e32 v59, 0x3f4c422a, v59
	v_add_f32_e32 v58, v58, v58
	v_add_f32_e32 v59, v59, v59
	v_mul_f32_e32 v58, 0xbfb8aa3b, v58
	v_mul_f32_e32 v59, 0xbfb8aa3b, v59
	v_exp_f32_e32 v58, v58
	v_exp_f32_e32 v59, v59
	v_add_f32_e32 v58, 1.0, v58
	v_add_f32_e32 v59, 1.0, v59
	v_rcp_f32_e32 v58, v58
	v_rcp_f32_e32 v59, v59
	s_nop 0
	v_pk_mul_f32 v[54:55], v[54:55], v[58:59]
	v_mul_f32_e32 v58, 0x3d372713, v51
	v_mul_f32_e32 v58, v51, v58
	v_fma_f32 v58, v51, v58, v51
	v_mul_f32_e32 v58, 0x3f4c422a, v58
	v_add_f32_e32 v58, v58, v58
	v_mul_f32_e32 v58, 0xbfb8aa3b, v58
	v_exp_f32_e32 v58, v58
	s_nop 0
	v_add_f32_e32 v58, 1.0, v58
	v_rcp_f32_e32 v61, v58
	s_nop 0
	v_pk_mul_f32 v[58:59], v[50:51], v[60:61]
	v_mul_f32_e32 v51, 0x3d372713, v52
	v_mul_f32_e32 v51, v52, v51
	v_fma_f32 v51, v52, v51, v52
	v_mul_f32_e32 v51, 0x3f4c422a, v51
	v_add_f32_e32 v51, v51, v51
	v_mul_f32_e32 v51, 0xbfb8aa3b, v51
	v_exp_f32_e32 v51, v51
	v_mul_f32_e32 v50, 0x3d372713, v56
	v_mul_f32_e32 v50, v56, v50
	v_fma_f32 v50, v56, v50, v56
	v_add_f32_e32 v51, 1.0, v51
	v_rcp_f32_e32 v60, v51
	v_mul_f32_e32 v51, 0x3d372713, v57
	v_mul_f32_e32 v51, v57, v51
	v_fma_f32 v51, v57, v51, v57
	v_mul_f32_e32 v50, 0x3f4c422a, v50
	v_mul_f32_e32 v51, 0x3f4c422a, v51
	v_add_f32_e32 v50, v50, v50
	v_add_f32_e32 v51, v51, v51
	v_mul_f32_e32 v50, 0xbfb8aa3b, v50
	v_mul_f32_e32 v51, 0xbfb8aa3b, v51
	v_exp_f32_e32 v50, v50
	v_exp_f32_e32 v51, v51
	v_add_f32_e32 v50, 1.0, v50
	v_add_f32_e32 v51, 1.0, v51
	v_rcp_f32_e32 v50, v50
	v_rcp_f32_e32 v51, v51
	s_nop 0
	v_pk_mul_f32 v[56:57], v[56:57], v[50:51]
	v_mul_f32_e32 v50, 0x3d372713, v53
	v_mul_f32_e32 v50, v53, v50
	v_fma_f32 v50, v53, v50, v53
	v_mul_f32_e32 v50, 0x3f4c422a, v50
	v_add_f32_e32 v50, v50, v50
	v_mul_f32_e32 v50, 0xbfb8aa3b, v50
	v_exp_f32_e32 v50, v50
	v_cvt_pk_bf16_f32 v51, v56, v57
	v_add_f32_e32 v50, 1.0, v50
	v_rcp_f32_e32 v61, v50
	v_cvt_pk_bf16_f32 v50, v54, v55
	v_lshl_add_u64 v[54:55], v[66:67], 0, v[114:115]
	v_pk_mul_f32 v[60:61], v[52:53], v[60:61]
	v_cvt_pk_bf16_f32 v52, v58, v59
	v_cvt_pk_bf16_f32 v53, v60, v61
	global_store_dwordx4 v[54:55], v[50:53], off
	s_nop 1
	v_mul_f32_e32 v53, 0x3d372713, v42
	v_mul_f32_e32 v53, v42, v53
	v_fma_f32 v53, v42, v53, v42
	v_mul_f32_e32 v53, 0x3f4c422a, v53
	v_add_f32_e32 v53, v53, v53
	v_mul_f32_e32 v53, 0xbfb8aa3b, v53
	v_exp_f32_e32 v53, v53
	v_mul_f32_e32 v52, 0x3d372713, v46
	v_mul_f32_e32 v52, v46, v52
	v_fma_f32 v52, v46, v52, v46
	v_add_f32_e32 v53, 1.0, v53
	v_rcp_f32_e32 v54, v53
	v_mul_f32_e32 v53, 0x3d372713, v47
	v_mul_f32_e32 v53, v47, v53
	v_fma_f32 v53, v47, v53, v47
	v_mul_f32_e32 v52, 0x3f4c422a, v52
	v_mul_f32_e32 v53, 0x3f4c422a, v53
	v_add_f32_e32 v52, v52, v52
	v_add_f32_e32 v53, v53, v53
	v_mul_f32_e32 v52, 0xbfb8aa3b, v52
	v_mul_f32_e32 v53, 0xbfb8aa3b, v53
	v_exp_f32_e32 v52, v52
	v_exp_f32_e32 v53, v53
	v_lshl_add_u64 v[50:51], v[142:143], 0, s[0:1]
	s_mov_b64 s[0:1], 0xa00000
	v_add_f32_e32 v52, 1.0, v52
	v_add_f32_e32 v53, 1.0, v53
	v_rcp_f32_e32 v52, v52
	v_rcp_f32_e32 v53, v53
	s_nop 0
	v_pk_mul_f32 v[46:47], v[46:47], v[52:53]
	v_mul_f32_e32 v52, 0x3d372713, v43
	v_mul_f32_e32 v52, v43, v52
	v_fma_f32 v52, v43, v52, v43
	v_mul_f32_e32 v52, 0x3f4c422a, v52
	v_add_f32_e32 v52, v52, v52
	v_mul_f32_e32 v52, 0xbfb8aa3b, v52
	v_exp_f32_e32 v52, v52
	s_nop 0
	v_add_f32_e32 v52, 1.0, v52
	v_rcp_f32_e32 v55, v52
	s_nop 0
	v_pk_mul_f32 v[52:53], v[42:43], v[54:55]
	v_mul_f32_e32 v43, 0x3d372713, v44
	v_mul_f32_e32 v43, v44, v43
	v_fma_f32 v43, v44, v43, v44
	v_mul_f32_e32 v43, 0x3f4c422a, v43
	v_add_f32_e32 v43, v43, v43
	v_mul_f32_e32 v43, 0xbfb8aa3b, v43
	v_exp_f32_e32 v43, v43
	v_mul_f32_e32 v42, 0x3d372713, v48
	v_mul_f32_e32 v42, v48, v42
	v_fma_f32 v42, v48, v42, v48
	v_add_f32_e32 v43, 1.0, v43
	v_rcp_f32_e32 v54, v43
	v_mul_f32_e32 v43, 0x3d372713, v49
	v_mul_f32_e32 v43, v49, v43
	v_fma_f32 v43, v49, v43, v49
	v_mul_f32_e32 v42, 0x3f4c422a, v42
	v_mul_f32_e32 v43, 0x3f4c422a, v43
	v_add_f32_e32 v42, v42, v42
	v_add_f32_e32 v43, v43, v43
	v_mul_f32_e32 v42, 0xbfb8aa3b, v42
	v_mul_f32_e32 v43, 0xbfb8aa3b, v43
	v_exp_f32_e32 v42, v42
	v_exp_f32_e32 v43, v43
	v_add_f32_e32 v42, 1.0, v42
	v_add_f32_e32 v43, 1.0, v43
	v_rcp_f32_e32 v42, v42
	v_rcp_f32_e32 v43, v43
	s_nop 0
	v_pk_mul_f32 v[48:49], v[48:49], v[42:43]
	v_mul_f32_e32 v42, 0x3d372713, v45
	v_mul_f32_e32 v42, v45, v42
	v_fma_f32 v42, v45, v42, v45
	v_mul_f32_e32 v42, 0x3f4c422a, v42
	v_add_f32_e32 v42, v42, v42
	v_mul_f32_e32 v42, 0xbfb8aa3b, v42
	v_exp_f32_e32 v42, v42
	v_cvt_pk_bf16_f32 v43, v48, v49
	v_add_f32_e32 v42, 1.0, v42
	v_rcp_f32_e32 v55, v42
	v_cvt_pk_bf16_f32 v42, v46, v47
	v_lshl_add_u64 v[46:47], v[50:51], 0, v[122:123]
	v_pk_mul_f32 v[54:55], v[44:45], v[54:55]
	v_cvt_pk_bf16_f32 v44, v52, v53
	v_cvt_pk_bf16_f32 v45, v54, v55
	global_store_dwordx4 v[46:47], v[42:45], off
	s_nop 1
	v_mul_f32_e32 v43, 0x3d372713, v34
	v_mul_f32_e32 v43, v34, v43
	v_fma_f32 v43, v34, v43, v34
	v_mul_f32_e32 v43, 0x3f4c422a, v43
	v_add_f32_e32 v43, v43, v43
	v_mul_f32_e32 v43, 0xbfb8aa3b, v43
; DEVI float sigmoidf_(float x) { return __builtin_amdgcn_rcpf(1.f + __expf(-x)); }
; DEVI float siluf_(float x) { return x * __builtin_amdgcn_rcpf(1.f + __expf(-x)); }
; DEVI float logsigf_(float x) { return fminf(x, 0.f) - __logf(1.f + __expf(-fabsf(x))); }
	v_exp_f32_e32 v43, v43
	v_mul_f32_e32 v42, 0x3d372713, v38
	v_mul_f32_e32 v42, v38, v42
	v_fma_f32 v42, v38, v42, v38
	v_add_f32_e32 v43, 1.0, v43
	v_rcp_f32_e32 v44, v43
	v_mul_f32_e32 v43, 0x3d372713, v39
	v_mul_f32_e32 v43, v39, v43
	v_fma_f32 v43, v39, v43, v39
	v_mul_f32_e32 v42, 0x3f4c422a, v42
	v_mul_f32_e32 v43, 0x3f4c422a, v43
	v_add_f32_e32 v42, v42, v42
	v_add_f32_e32 v43, v43, v43
	v_mul_f32_e32 v42, 0xbfb8aa3b, v42
	v_mul_f32_e32 v43, 0xbfb8aa3b, v43
	v_exp_f32_e32 v42, v42
	v_exp_f32_e32 v43, v43
	v_add_f32_e32 v42, 1.0, v42
	v_add_f32_e32 v43, 1.0, v43
	v_rcp_f32_e32 v42, v42
	v_rcp_f32_e32 v43, v43
	s_nop 0
	v_pk_mul_f32 v[38:39], v[38:39], v[42:43]
	v_mul_f32_e32 v42, 0x3d372713, v35
	v_mul_f32_e32 v42, v35, v42
	v_fma_f32 v42, v35, v42, v35
	v_mul_f32_e32 v42, 0x3f4c422a, v42
	v_add_f32_e32 v42, v42, v42
	v_mul_f32_e32 v42, 0xbfb8aa3b, v42
	v_exp_f32_e32 v42, v42
	s_nop 0
	v_add_f32_e32 v42, 1.0, v42
	v_rcp_f32_e32 v45, v42
	s_nop 0
	v_pk_mul_f32 v[42:43], v[34:35], v[44:45]
	v_mul_f32_e32 v35, 0x3d372713, v36
	v_mul_f32_e32 v35, v36, v35
	v_fma_f32 v35, v36, v35, v36
	v_mul_f32_e32 v35, 0x3f4c422a, v35
	v_add_f32_e32 v35, v35, v35
	v_mul_f32_e32 v35, 0xbfb8aa3b, v35
	v_exp_f32_e32 v35, v35
	v_mul_f32_e32 v34, 0x3d372713, v40
	v_mul_f32_e32 v34, v40, v34
	v_fma_f32 v34, v40, v34, v40
	v_add_f32_e32 v35, 1.0, v35
	v_rcp_f32_e32 v44, v35
	v_mul_f32_e32 v35, 0x3d372713, v41
	v_mul_f32_e32 v35, v41, v35
	v_fma_f32 v35, v41, v35, v41
	v_mul_f32_e32 v34, 0x3f4c422a, v34
	v_mul_f32_e32 v35, 0x3f4c422a, v35
	v_add_f32_e32 v34, v34, v34
	v_add_f32_e32 v35, v35, v35
	v_mul_f32_e32 v34, 0xbfb8aa3b, v34
	v_mul_f32_e32 v35, 0xbfb8aa3b, v35
	v_exp_f32_e32 v34, v34
	v_exp_f32_e32 v35, v35
	v_add_f32_e32 v34, 1.0, v34
	v_add_f32_e32 v35, 1.0, v35
	v_rcp_f32_e32 v34, v34
	v_rcp_f32_e32 v35, v35
	s_nop 0
	v_pk_mul_f32 v[40:41], v[40:41], v[34:35]
	v_mul_f32_e32 v34, 0x3d372713, v37
	v_mul_f32_e32 v34, v37, v34
	v_fma_f32 v34, v37, v34, v37
	v_mul_f32_e32 v34, 0x3f4c422a, v34
	v_add_f32_e32 v34, v34, v34
	v_mul_f32_e32 v34, 0xbfb8aa3b, v34
	v_exp_f32_e32 v34, v34
	v_cvt_pk_bf16_f32 v35, v40, v41
	v_add_f32_e32 v34, 1.0, v34
	v_rcp_f32_e32 v45, v34
	v_cvt_pk_bf16_f32 v34, v38, v39
	v_lshl_add_u64 v[38:39], v[50:51], 0, v[114:115]
	v_pk_mul_f32 v[44:45], v[36:37], v[44:45]
	v_cvt_pk_bf16_f32 v36, v42, v43
	v_cvt_pk_bf16_f32 v37, v44, v45
	global_store_dwordx4 v[38:39], v[34:37], off
	s_nop 1
	v_mul_f32_e32 v37, 0x3d372713, v26
	v_mul_f32_e32 v37, v26, v37
	v_fma_f32 v37, v26, v37, v26
	v_mul_f32_e32 v37, 0x3f4c422a, v37
	v_add_f32_e32 v37, v37, v37
	v_mul_f32_e32 v37, 0xbfb8aa3b, v37
	v_exp_f32_e32 v37, v37
	v_mul_f32_e32 v36, 0x3d372713, v30
	v_mul_f32_e32 v36, v30, v36
	v_fma_f32 v36, v30, v36, v30
	v_add_f32_e32 v37, 1.0, v37
	v_rcp_f32_e32 v38, v37
	v_mul_f32_e32 v37, 0x3d372713, v31
	v_mul_f32_e32 v37, v31, v37
	v_fma_f32 v37, v31, v37, v31
	v_mul_f32_e32 v36, 0x3f4c422a, v36
	v_mul_f32_e32 v37, 0x3f4c422a, v37
	v_add_f32_e32 v36, v36, v36
	v_add_f32_e32 v37, v37, v37
	v_mul_f32_e32 v36, 0xbfb8aa3b, v36
	v_mul_f32_e32 v37, 0xbfb8aa3b, v37
	v_exp_f32_e32 v36, v36
	v_exp_f32_e32 v37, v37
	v_lshl_add_u64 v[34:35], v[142:143], 0, s[0:1]
	s_mov_b64 s[0:1], 0xb00000
	v_add_f32_e32 v36, 1.0, v36
	v_add_f32_e32 v37, 1.0, v37
	v_rcp_f32_e32 v36, v36
	v_rcp_f32_e32 v37, v37
	s_nop 0
	v_pk_mul_f32 v[30:31], v[30:31], v[36:37]
	v_mul_f32_e32 v36, 0x3d372713, v27
	v_mul_f32_e32 v36, v27, v36
	v_fma_f32 v36, v27, v36, v27
	v_mul_f32_e32 v36, 0x3f4c422a, v36
	v_add_f32_e32 v36, v36, v36
	v_mul_f32_e32 v36, 0xbfb8aa3b, v36
	v_exp_f32_e32 v36, v36
	s_nop 0
	v_add_f32_e32 v36, 1.0, v36
	v_rcp_f32_e32 v39, v36
	s_nop 0
	v_pk_mul_f32 v[36:37], v[26:27], v[38:39]
	v_mul_f32_e32 v27, 0x3d372713, v28
	v_mul_f32_e32 v27, v28, v27
	v_fma_f32 v27, v28, v27, v28
	v_mul_f32_e32 v27, 0x3f4c422a, v27
	v_add_f32_e32 v27, v27, v27
	v_mul_f32_e32 v27, 0xbfb8aa3b, v27
	v_exp_f32_e32 v27, v27
	v_mul_f32_e32 v26, 0x3d372713, v32
	v_mul_f32_e32 v26, v32, v26
	v_fma_f32 v26, v32, v26, v32
	v_add_f32_e32 v27, 1.0, v27
	v_rcp_f32_e32 v38, v27
	v_mul_f32_e32 v27, 0x3d372713, v33
	v_mul_f32_e32 v27, v33, v27
	v_fma_f32 v27, v33, v27, v33
	v_mul_f32_e32 v26, 0x3f4c422a, v26
	v_mul_f32_e32 v27, 0x3f4c422a, v27
	v_add_f32_e32 v26, v26, v26
	v_add_f32_e32 v27, v27, v27
	v_mul_f32_e32 v26, 0xbfb8aa3b, v26
	v_mul_f32_e32 v27, 0xbfb8aa3b, v27
	v_exp_f32_e32 v26, v26
	v_exp_f32_e32 v27, v27
	v_add_f32_e32 v26, 1.0, v26
	v_add_f32_e32 v27, 1.0, v27
	v_rcp_f32_e32 v26, v26
	v_rcp_f32_e32 v27, v27
	s_nop 0
	v_pk_mul_f32 v[32:33], v[32:33], v[26:27]
	v_mul_f32_e32 v26, 0x3d372713, v29
	v_mul_f32_e32 v26, v29, v26
	v_fma_f32 v26, v29, v26, v29
	v_mul_f32_e32 v26, 0x3f4c422a, v26
	v_add_f32_e32 v26, v26, v26
	v_mul_f32_e32 v26, 0xbfb8aa3b, v26
	v_exp_f32_e32 v26, v26
	v_cvt_pk_bf16_f32 v27, v32, v33
	v_add_f32_e32 v26, 1.0, v26
	v_rcp_f32_e32 v39, v26
	v_cvt_pk_bf16_f32 v26, v30, v31
	v_lshl_add_u64 v[30:31], v[34:35], 0, v[122:123]
	v_pk_mul_f32 v[38:39], v[28:29], v[38:39]
	v_cvt_pk_bf16_f32 v28, v36, v37
	v_cvt_pk_bf16_f32 v29, v38, v39
	global_store_dwordx4 v[30:31], v[26:29], off
	s_nop 1
	v_mul_f32_e32 v27, 0x3d372713, v18
	v_mul_f32_e32 v27, v18, v27
	v_fma_f32 v27, v18, v27, v18
	v_mul_f32_e32 v27, 0x3f4c422a, v27
	v_add_f32_e32 v27, v27, v27
	v_mul_f32_e32 v27, 0xbfb8aa3b, v27
	v_exp_f32_e32 v27, v27
	v_mul_f32_e32 v26, 0x3d372713, v22
	v_mul_f32_e32 v26, v22, v26
	v_fma_f32 v26, v22, v26, v22
	v_add_f32_e32 v27, 1.0, v27
	v_rcp_f32_e32 v28, v27
	v_mul_f32_e32 v27, 0x3d372713, v23
	v_mul_f32_e32 v27, v23, v27
	v_fma_f32 v27, v23, v27, v23
	v_mul_f32_e32 v26, 0x3f4c422a, v26
; DEVI float sigmoidf_(float x) { return __builtin_amdgcn_rcpf(1.f + __expf(-x)); }
; DEVI float siluf_(float x) { return x * __builtin_amdgcn_rcpf(1.f + __expf(-x)); }
; DEVI float logsigf_(float x) { return fminf(x, 0.f) - __logf(1.f + __expf(-fabsf(x))); }
	v_mul_f32_e32 v27, 0x3f4c422a, v27
	v_add_f32_e32 v26, v26, v26
	v_add_f32_e32 v27, v27, v27
	v_mul_f32_e32 v26, 0xbfb8aa3b, v26
	v_mul_f32_e32 v27, 0xbfb8aa3b, v27
	v_exp_f32_e32 v26, v26
	v_exp_f32_e32 v27, v27
	v_add_f32_e32 v26, 1.0, v26
	v_add_f32_e32 v27, 1.0, v27
	v_rcp_f32_e32 v26, v26
	v_rcp_f32_e32 v27, v27
	s_nop 0
	v_pk_mul_f32 v[22:23], v[22:23], v[26:27]
	v_mul_f32_e32 v26, 0x3d372713, v19
	v_mul_f32_e32 v26, v19, v26
	v_fma_f32 v26, v19, v26, v19
	v_mul_f32_e32 v26, 0x3f4c422a, v26
	v_add_f32_e32 v26, v26, v26
	v_mul_f32_e32 v26, 0xbfb8aa3b, v26
	v_exp_f32_e32 v26, v26
	s_nop 0
	v_add_f32_e32 v26, 1.0, v26
	v_rcp_f32_e32 v29, v26
	s_nop 0
	v_pk_mul_f32 v[26:27], v[18:19], v[28:29]
	v_mul_f32_e32 v19, 0x3d372713, v20
	v_mul_f32_e32 v19, v20, v19
	v_fma_f32 v19, v20, v19, v20
	v_mul_f32_e32 v19, 0x3f4c422a, v19
	v_add_f32_e32 v19, v19, v19
	v_mul_f32_e32 v19, 0xbfb8aa3b, v19
	v_exp_f32_e32 v19, v19
	v_mul_f32_e32 v18, 0x3d372713, v24
	v_mul_f32_e32 v18, v24, v18
	v_fma_f32 v18, v24, v18, v24
	v_add_f32_e32 v19, 1.0, v19
	v_rcp_f32_e32 v28, v19
	v_mul_f32_e32 v19, 0x3d372713, v25
	v_mul_f32_e32 v19, v25, v19
	v_fma_f32 v19, v25, v19, v25
	v_mul_f32_e32 v18, 0x3f4c422a, v18
	v_mul_f32_e32 v19, 0x3f4c422a, v19
	v_add_f32_e32 v18, v18, v18
	v_add_f32_e32 v19, v19, v19
	v_mul_f32_e32 v18, 0xbfb8aa3b, v18
	v_mul_f32_e32 v19, 0xbfb8aa3b, v19
	v_exp_f32_e32 v18, v18
	v_exp_f32_e32 v19, v19
	v_add_f32_e32 v18, 1.0, v18
	v_add_f32_e32 v19, 1.0, v19
	v_rcp_f32_e32 v18, v18
	v_rcp_f32_e32 v19, v19
	s_nop 0
	v_pk_mul_f32 v[24:25], v[24:25], v[18:19]
	v_mul_f32_e32 v18, 0x3d372713, v21
	v_mul_f32_e32 v18, v21, v18
	v_fma_f32 v18, v21, v18, v21
	v_mul_f32_e32 v18, 0x3f4c422a, v18
	v_add_f32_e32 v18, v18, v18
	v_mul_f32_e32 v18, 0xbfb8aa3b, v18
	v_exp_f32_e32 v18, v18
	v_cvt_pk_bf16_f32 v19, v24, v25
	v_add_f32_e32 v18, 1.0, v18
	v_rcp_f32_e32 v29, v18
	v_cvt_pk_bf16_f32 v18, v22, v23
	v_lshl_add_u64 v[22:23], v[34:35], 0, v[114:115]
	v_pk_mul_f32 v[28:29], v[20:21], v[28:29]
	v_cvt_pk_bf16_f32 v20, v26, v27
	v_cvt_pk_bf16_f32 v21, v28, v29
	global_store_dwordx4 v[22:23], v[18:21], off
	s_nop 1
	v_mul_f32_e32 v21, 0x3d372713, v10
	v_mul_f32_e32 v21, v10, v21
	v_fma_f32 v21, v10, v21, v10
	v_mul_f32_e32 v21, 0x3f4c422a, v21
	v_add_f32_e32 v21, v21, v21
	v_mul_f32_e32 v21, 0xbfb8aa3b, v21
	v_exp_f32_e32 v21, v21
	v_mul_f32_e32 v20, 0x3d372713, v14
	v_mul_f32_e32 v20, v14, v20
	v_fma_f32 v20, v14, v20, v14
	v_add_f32_e32 v21, 1.0, v21
	v_rcp_f32_e32 v22, v21
	v_mul_f32_e32 v21, 0x3d372713, v15
	v_mul_f32_e32 v21, v15, v21
	v_fma_f32 v21, v15, v21, v15
	v_mul_f32_e32 v20, 0x3f4c422a, v20
	v_mul_f32_e32 v21, 0x3f4c422a, v21
	v_add_f32_e32 v20, v20, v20
	v_add_f32_e32 v21, v21, v21
	v_mul_f32_e32 v20, 0xbfb8aa3b, v20
	v_mul_f32_e32 v21, 0xbfb8aa3b, v21
	v_exp_f32_e32 v20, v20
	v_exp_f32_e32 v21, v21
	v_lshl_add_u64 v[18:19], v[142:143], 0, s[0:1]
	s_mov_b32 s0, s8
	v_add_f32_e32 v20, 1.0, v20
	v_add_f32_e32 v21, 1.0, v21
	v_rcp_f32_e32 v20, v20
	v_rcp_f32_e32 v21, v21
	s_mov_b32 s1, s9
	v_pk_mul_f32 v[14:15], v[14:15], v[20:21]
	v_mul_f32_e32 v20, 0x3d372713, v11
	v_mul_f32_e32 v20, v11, v20
	v_fma_f32 v20, v11, v20, v11
	v_mul_f32_e32 v20, 0x3f4c422a, v20
	v_add_f32_e32 v20, v20, v20
	v_mul_f32_e32 v20, 0xbfb8aa3b, v20
	v_exp_f32_e32 v20, v20
	s_nop 0
	v_add_f32_e32 v20, 1.0, v20
	v_rcp_f32_e32 v23, v20
	s_nop 0
	v_pk_mul_f32 v[20:21], v[10:11], v[22:23]
	v_mul_f32_e32 v11, 0x3d372713, v12
	v_mul_f32_e32 v11, v12, v11
	v_fma_f32 v11, v12, v11, v12
	v_mul_f32_e32 v11, 0x3f4c422a, v11
	v_add_f32_e32 v11, v11, v11
	v_mul_f32_e32 v11, 0xbfb8aa3b, v11
	v_exp_f32_e32 v11, v11
	v_mul_f32_e32 v10, 0x3d372713, v16
	v_mul_f32_e32 v10, v16, v10
	v_fma_f32 v10, v16, v10, v16
; #define PG8_WAIT_V(n) asm volatile("s_waitcnt vmcnt(" #n ")" ::: "memory")
; #define PG8_BAR __builtin_amdgcn_s_barrier()
; template <class Epi>
; DEVI void gemm_phase(LAS unsigned char* lds, const Gemm g, const Epi& E) {
;     ...
;     }
;     PG8_WAIT_V(0);
;     if (wr == 0) PG8_BAR;
;     PG8_BAR;
	v_add_f32_e32 v11, 1.0, v11
	v_rcp_f32_e32 v22, v11
	v_mul_f32_e32 v11, 0x3d372713, v17
	v_mul_f32_e32 v11, v17, v11
	v_fma_f32 v11, v17, v11, v17
	v_mul_f32_e32 v10, 0x3f4c422a, v10
	v_mul_f32_e32 v11, 0x3f4c422a, v11
	v_add_f32_e32 v10, v10, v10
	v_add_f32_e32 v11, v11, v11
	v_mul_f32_e32 v10, 0xbfb8aa3b, v10
	v_mul_f32_e32 v11, 0xbfb8aa3b, v11
	v_exp_f32_e32 v10, v10
	v_exp_f32_e32 v11, v11
	v_add_f32_e32 v10, 1.0, v10
	v_add_f32_e32 v11, 1.0, v11
	v_rcp_f32_e32 v10, v10
	v_rcp_f32_e32 v11, v11
	s_nop 0
	v_pk_mul_f32 v[16:17], v[16:17], v[10:11]
	v_mul_f32_e32 v10, 0x3d372713, v13
	v_mul_f32_e32 v10, v13, v10
	v_fma_f32 v10, v13, v10, v13
	v_mul_f32_e32 v10, 0x3f4c422a, v10
	v_add_f32_e32 v10, v10, v10
	v_mul_f32_e32 v10, 0xbfb8aa3b, v10
	v_exp_f32_e32 v10, v10
	v_cvt_pk_bf16_f32 v11, v16, v17
	v_add_f32_e32 v10, 1.0, v10
	v_rcp_f32_e32 v23, v10
	v_cvt_pk_bf16_f32 v10, v14, v15
	v_lshl_add_u64 v[14:15], v[18:19], 0, v[122:123]
	v_pk_mul_f32 v[22:23], v[12:13], v[22:23]
	v_cvt_pk_bf16_f32 v12, v20, v21
	v_cvt_pk_bf16_f32 v13, v22, v23
	global_store_dwordx4 v[14:15], v[10:13], off
	s_nop 1
	v_mul_f32_e32 v11, 0x3d372713, v0
	v_mul_f32_e32 v11, v0, v11
	v_fma_f32 v11, v0, v11, v0
	v_mul_f32_e32 v11, 0x3f4c422a, v11
	v_add_f32_e32 v11, v11, v11
	v_mul_f32_e32 v11, 0xbfb8aa3b, v11
	v_exp_f32_e32 v11, v11
	v_mul_f32_e32 v10, 0x3d372713, v4
	v_mul_f32_e32 v10, v4, v10
	v_fma_f32 v10, v4, v10, v4
	v_add_f32_e32 v11, 1.0, v11
	v_rcp_f32_e32 v12, v11
	v_mul_f32_e32 v11, 0x3d372713, v5
	v_mul_f32_e32 v11, v5, v11
	v_fma_f32 v11, v5, v11, v5
	v_mul_f32_e32 v10, 0x3f4c422a, v10
	v_mul_f32_e32 v11, 0x3f4c422a, v11
	v_add_f32_e32 v10, v10, v10
	v_add_f32_e32 v11, v11, v11
	v_mul_f32_e32 v10, 0xbfb8aa3b, v10
	v_mul_f32_e32 v11, 0xbfb8aa3b, v11
	v_exp_f32_e32 v10, v10
	v_exp_f32_e32 v11, v11
	v_add_f32_e32 v10, 1.0, v10
	v_add_f32_e32 v11, 1.0, v11
	v_rcp_f32_e32 v10, v10
	v_rcp_f32_e32 v11, v11
	s_nop 0
	v_pk_mul_f32 v[4:5], v[4:5], v[10:11]
	v_mul_f32_e32 v10, 0x3d372713, v1
	v_mul_f32_e32 v10, v1, v10
	v_fma_f32 v10, v1, v10, v1
	v_mul_f32_e32 v10, 0x3f4c422a, v10
	v_add_f32_e32 v10, v10, v10
	v_mul_f32_e32 v10, 0xbfb8aa3b, v10
	v_exp_f32_e32 v10, v10
	s_nop 0
	v_add_f32_e32 v10, 1.0, v10
	v_rcp_f32_e32 v13, v10
	s_nop 0
	v_pk_mul_f32 v[10:11], v[0:1], v[12:13]
	v_mul_f32_e32 v1, 0x3d372713, v2
	v_mul_f32_e32 v1, v2, v1
	v_fma_f32 v1, v2, v1, v2
	v_mul_f32_e32 v1, 0x3f4c422a, v1
	v_add_f32_e32 v1, v1, v1
	v_mul_f32_e32 v1, 0xbfb8aa3b, v1
	v_exp_f32_e32 v1, v1
	v_mul_f32_e32 v0, 0x3d372713, v6
	v_mul_f32_e32 v0, v6, v0
	v_fma_f32 v0, v6, v0, v6
	v_add_f32_e32 v1, 1.0, v1
	v_rcp_f32_e32 v12, v1
	v_mul_f32_e32 v1, 0x3d372713, v7
	v_mul_f32_e32 v1, v7, v1
	v_fma_f32 v1, v7, v1, v7
	v_mul_f32_e32 v0, 0x3f4c422a, v0
	v_mul_f32_e32 v1, 0x3f4c422a, v1
	v_add_f32_e32 v0, v0, v0
	v_add_f32_e32 v1, v1, v1
	v_mul_f32_e32 v0, 0xbfb8aa3b, v0
	v_mul_f32_e32 v1, 0xbfb8aa3b, v1
	v_exp_f32_e32 v0, v0
	v_exp_f32_e32 v1, v1
	v_add_f32_e32 v0, 1.0, v0
	v_add_f32_e32 v1, 1.0, v1
	v_rcp_f32_e32 v0, v0
	v_rcp_f32_e32 v1, v1
	s_nop 0
	v_pk_mul_f32 v[6:7], v[6:7], v[0:1]
	v_mul_f32_e32 v0, 0x3d372713, v3
	v_mul_f32_e32 v0, v3, v0
	v_fma_f32 v0, v3, v0, v3
	v_mul_f32_e32 v0, 0x3f4c422a, v0
	v_add_f32_e32 v0, v0, v0
	v_mul_f32_e32 v0, 0xbfb8aa3b, v0
	v_exp_f32_e32 v0, v0
	v_cvt_pk_bf16_f32 v1, v6, v7
	v_add_f32_e32 v0, 1.0, v0
	v_rcp_f32_e32 v13, v0
	v_cvt_pk_bf16_f32 v0, v4, v5
	v_lshl_add_u64 v[4:5], v[18:19], 0, v[114:115]
	v_pk_mul_f32 v[12:13], v[2:3], v[12:13]
	v_cvt_pk_bf16_f32 v2, v10, v11
	v_cvt_pk_bf16_f32 v3, v12, v13
	global_store_dwordx4 v[4:5], v[0:3], off
	s_cbranch_vccz .LBB0_1271
	s_waitcnt vmcnt(0)
	s_cmpk_gt_u32 s36, 0xff
	s_cbranch_scc1 .LBB0_1282
	s_barrier

; #define PG8_STAGE(bufoff, gbase, voff) do { _Pragma("unroll") for (int _i = 0; _i < 2; ++_i) \
;         __builtin_amdgcn_global_load_lds((const unsigned*)((const char*)(gbase) + (voff)[_i]), (LAS unsigned*)(lds + (bufoff) + ldsw + _i * 8192), 16, 0, 0); } while (0)
; #define PG8_LDA(dst, b, h) do { _Pragma("unroll") for (int m = 0; m < 4; ++m) _Pragma("unroll") for (int k = 0; k < 2; ++k) dst[m][k] = *(const LAS bf16x8*)(lds + PG8_SA(b, h) + aoff + m * 2048 + k * 1024); } while (0)
; #define PG8_WAIT_V(n) asm volatile("s_waitcnt vmcnt(" #n ")" ::: "memory")
; #define PG8_WAIT_L(n) asm volatile("s_waitcnt lgkmcnt(" #n ")" ::: "memory")
; template <class Epi>
; DEVI void gemm_phase(LAS unsigned char* lds, const Gemm g, const Epi& E) {
;     ...
;         for (int t = 0; t < nt; t += 2) {
;             const bool last = (t == nt - 2);
;             const char* a1 = cA + (size_t)(t + 1) * kstep;
;             const char* a2 = last ? nA : cA + (size_t)(t + 2) * kstep; const char* b2 = last ? nB : cB + (size_t)(t + 2) * kstep;
;             const char* a3 = a2 + kstep; const char* b3 = b2 + kstep;
;             PG8_LDB(B0, 0, 0); PG8_SCHED; PG8_LDA(At, 0, 0); PG8_STAGE(PG8_SA(1, 1), a1 + hstepA, voffA);
;             PG8_WAIT_L(8); PG8_BAR; PG8_WAIT_L(0); PG8_MMA(0, 0, At, B0); PG8_BAR; PG8_SCHED;
;             PG8_LDB(B1, 0, 1); PG8_STAGE(PG8_SB(0, 0), b2, voffB);
;             PG8_BAR; PG8_WAIT_L(0); PG8_MMA(0, 1, At, B1); PG8_BAR;
;             PG8_LDA(At, 0, 1); PG8_STAGE(PG8_SA(0, 0), a2, voffA);
;             PG8_BAR; PG8_WAIT_L(0); PG8_MMA(1, 0, At, B0); PG8_BAR; PG8_SCHED;
;             PG8_STAGE(PG8_SB(0, 1), b2 + hstepB, voffB);
;             PG8_WAIT_V(6); PG8_BAR; PG8_MMA(1, 1, At, B1); PG8_BAR;
;             PG8_LDB(B0, 1, 0); PG8_SCHED; PG8_LDA(At, 1, 0); PG8_STAGE(PG8_SA(0, 1), a2 + hstepA, voffA);
;             PG8_WAIT_L(8); PG8_BAR; PG8_WAIT_L(0); PG8_MMA(0, 0, At, B0); PG8_BAR; PG8_SCHED;
;             PG8_LDB(B1, 1, 1); PG8_STAGE(PG8_SB(1, 0), b3, voffB);
;             PG8_BAR; PG8_WAIT_L(0); PG8_MMA(0, 1, At, B1); PG8_BAR;
;             PG8_LDA(At, 1, 1); PG8_STAGE(PG8_SA(1, 0), a3, voffA);
;             PG8_BAR; PG8_WAIT_L(0); PG8_MMA(1, 0, At, B0); PG8_BAR; PG8_SCHED;
;             PG8_STAGE(PG8_SB(1, 1), b3 + hstepB, voffB);
;             PG8_WAIT_V(6); PG8_BAR; PG8_MMA(1, 1, At, B1); PG8_BAR;
;         }
.LBB0_1346:
	s_add_u32 s14, s12, 0xfffc0080
	s_addc_u32 s15, s13, -1
	s_add_i32 s38, 0, 0x10000
	v_add_u32_e32 v152, s38, v185
	ds_read_b128 v[114:117], v152
	ds_read_b128 v[126:129], v152 offset:1024
	ds_read_b128 v[130:133], v152 offset:2048
	ds_read_b128 v[176:179], v152 offset:3072
	s_cmp_eq_u32 s27, 12
	s_cselect_b32 s17, s1, s15
	s_cselect_b32 s16, s3, s14
	s_cselect_b32 s15, s5, s26
	s_cselect_b32 s14, s18, s19
	s_add_i32 m0, s11, 0xc000
	ds_read_b128 v[180:183], v187
	ds_read_b128 v[188:191], v187 offset:1024
	ds_read_b128 v[192:195], v187 offset:2048
	ds_read_b128 v[196:199], v187 offset:3072
	ds_read_b128 v[200:203], v187 offset:4096
	ds_read_b128 v[204:207], v187 offset:5120
	ds_read_b128 v[214:217], v187 offset:6144
	ds_read_b128 v[218:221], v187 offset:7168
	global_load_lds_dwordx4 v148, s[12:13]
	s_add_i32 m0, s11, 0xe000
	s_nop 0
	global_load_lds_dwordx4 v150, s[12:13]
	s_waitcnt lgkmcnt(8)
	s_barrier
	s_waitcnt lgkmcnt(0)
	v_mfma_f32_16x16x32_bf16 v[138:141], v[114:117], v[180:183], v[138:141]
	v_mfma_f32_16x16x32_bf16 v[134:137], v[130:133], v[180:183], v[134:137]
	v_mfma_f32_16x16x32_bf16 v[110:113], v[114:117], v[192:195], v[110:113]
	v_mfma_f32_16x16x32_bf16 v[106:109], v[130:133], v[192:195], v[106:109]
	v_mfma_f32_16x16x32_bf16 v[94:97], v[114:117], v[200:203], v[94:97]
	v_mfma_f32_16x16x32_bf16 v[90:93], v[130:133], v[200:203], v[90:93]
	v_mfma_f32_16x16x32_bf16 v[78:81], v[114:117], v[214:217], v[78:81]
	v_mfma_f32_16x16x32_bf16 v[74:77], v[130:133], v[214:217], v[74:77]
	v_mfma_f32_16x16x32_bf16 v[138:141], v[126:129], v[188:191], v[138:141]
	v_mfma_f32_16x16x32_bf16 v[134:137], v[176:179], v[188:191], v[134:137]
	v_mfma_f32_16x16x32_bf16 v[110:113], v[126:129], v[196:199], v[110:113]
	v_mfma_f32_16x16x32_bf16 v[106:109], v[176:179], v[196:199], v[106:109]
	v_mfma_f32_16x16x32_bf16 v[94:97], v[126:129], v[204:207], v[94:97]
	v_mfma_f32_16x16x32_bf16 v[90:93], v[176:179], v[204:207], v[90:93]
	v_mfma_f32_16x16x32_bf16 v[78:81], v[126:129], v[218:221], v[78:81]
	v_mfma_f32_16x16x32_bf16 v[74:77], v[176:179], v[218:221], v[74:77]
	s_barrier
	s_add_i32 s40, 0, 0x14000
	v_add_u32_e32 v152, s40, v185
	s_add_i32 s38, s38, s47
	ds_read_b128 v[222:225], v152
	ds_read_b128 v[226:229], v152 offset:1024
	ds_read_b128 v[230:233], v152 offset:2048
	ds_read_b128 v[234:237], v152 offset:3072
	v_lshl_add_u64 v[152:153], s[14:15], 0, v[8:9]
	s_mov_b32 m0, s38
	v_lshl_add_u64 v[162:163], s[14:15], 0, v[146:147]
	global_load_lds_dwordx4 v[152:153], off
	s_add_i32 m0, s38, 0x2000
	s_nop 0
	global_load_lds_dwordx4 v[162:163], off
	s_barrier
	s_waitcnt lgkmcnt(0)
	v_mfma_f32_16x16x32_bf16 v[122:125], v[222:225], v[180:183], v[122:125]
	v_mfma_f32_16x16x32_bf16 v[118:121], v[230:233], v[180:183], v[118:121]
	v_mfma_f32_16x16x32_bf16 v[102:105], v[222:225], v[192:195], v[102:105]
	v_mfma_f32_16x16x32_bf16 v[98:101], v[230:233], v[192:195], v[98:101]
	v_mfma_f32_16x16x32_bf16 v[86:89], v[222:225], v[200:203], v[86:89]
	v_mfma_f32_16x16x32_bf16 v[82:85], v[230:233], v[200:203], v[82:85]
	v_mfma_f32_16x16x32_bf16 v[70:73], v[222:225], v[214:217], v[70:73]
	v_mfma_f32_16x16x32_bf16 v[66:69], v[230:233], v[214:217], v[66:69]
	v_mfma_f32_16x16x32_bf16 v[122:125], v[226:229], v[188:191], v[122:125]
	v_mfma_f32_16x16x32_bf16 v[118:121], v[234:237], v[188:191], v[118:121]
	v_mfma_f32_16x16x32_bf16 v[102:105], v[226:229], v[196:199], v[102:105]
	v_mfma_f32_16x16x32_bf16 v[98:101], v[234:237], v[196:199], v[98:101]
	v_mfma_f32_16x16x32_bf16 v[86:89], v[226:229], v[204:207], v[86:89]
	v_mfma_f32_16x16x32_bf16 v[82:85], v[234:237], v[204:207], v[82:85]
	v_mfma_f32_16x16x32_bf16 v[70:73], v[226:229], v[218:221], v[70:73]
	v_mfma_f32_16x16x32_bf16 v[66:69], v[234:237], v[218:221], v[66:69]
	s_mov_b32 m0, s11
	v_lshl_add_u64 v[164:165], s[16:17], 0, v[142:143]
	s_barrier
	ds_read_b128 v[180:183], v187 offset:16384
	ds_read_b128 v[188:191], v187 offset:17408
	ds_read_b128 v[192:195], v187 offset:18432
	ds_read_b128 v[196:199], v187 offset:19456
	ds_read_b128 v[200:203], v187 offset:20480
	ds_read_b128 v[204:207], v187 offset:21504
	ds_read_b128 v[214:217], v187 offset:22528
	ds_read_b128 v[218:221], v187 offset:23552
	global_load_lds_dwordx4 v[164:165], off
	s_mov_b32 m0, s66
	v_lshl_add_u64 v[208:209], s[16:17], 0, v[144:145]
	global_load_lds_dwordx4 v[208:209], off
	s_barrier
	s_waitcnt lgkmcnt(0)
	v_mfma_f32_16x16x32_bf16 v[62:65], v[114:117], v[180:183], v[62:65]
	v_mfma_f32_16x16x32_bf16 v[58:61], v[130:133], v[180:183], v[58:61]
	v_mfma_f32_16x16x32_bf16 v[46:49], v[114:117], v[192:195], v[46:49]
	v_mfma_f32_16x16x32_bf16 v[42:45], v[130:133], v[192:195], v[42:45]
	v_mfma_f32_16x16x32_bf16 v[30:33], v[114:117], v[200:203], v[30:33]
	v_mfma_f32_16x16x32_bf16 v[26:29], v[130:133], v[200:203], v[26:29]
	v_mfma_f32_16x16x32_bf16 v[14:17], v[114:117], v[214:217], v[14:17]
	v_mfma_f32_16x16x32_bf16 v[10:13], v[130:133], v[214:217], v[10:13]
	v_mfma_f32_16x16x32_bf16 v[62:65], v[126:129], v[188:191], v[62:65]
	v_mfma_f32_16x16x32_bf16 v[58:61], v[176:179], v[188:191], v[58:61]
	v_mfma_f32_16x16x32_bf16 v[46:49], v[126:129], v[196:199], v[46:49]
	v_mfma_f32_16x16x32_bf16 v[42:45], v[176:179], v[196:199], v[42:45]
	v_mfma_f32_16x16x32_bf16 v[30:33], v[126:129], v[204:207], v[30:33]
	v_mfma_f32_16x16x32_bf16 v[26:29], v[176:179], v[204:207], v[26:29]
	v_mfma_f32_16x16x32_bf16 v[14:17], v[126:129], v[218:221], v[14:17]
	v_mfma_f32_16x16x32_bf16 v[10:13], v[176:179], v[218:221], v[10:13]
	s_barrier
	s_add_u32 s38, s14, 0x40000
	s_addc_u32 s39, s15, 0
	s_add_i32 s40, s40, s47
	s_mov_b32 m0, s40
	s_nop 0
	global_load_lds_dwordx4 v8, s[38:39]
	s_add_i32 m0, s40, 0x2000
	s_nop 0
	global_load_lds_dwordx4 v146, s[38:39]
	s_waitcnt vmcnt(6)
	s_barrier
; #define PG8_STAGE(bufoff, gbase, voff) do { _Pragma("unroll") for (int _i = 0; _i < 2; ++_i) \
;         __builtin_amdgcn_global_load_lds((const unsigned*)((const char*)(gbase) + (voff)[_i]), (LAS unsigned*)(lds + (bufoff) + ldsw + _i * 8192), 16, 0, 0); } while (0)
; #define PG8_LDA(dst, b, h) do { _Pragma("unroll") for (int m = 0; m < 4; ++m) _Pragma("unroll") for (int k = 0; k < 2; ++k) dst[m][k] = *(const LAS bf16x8*)(lds + PG8_SA(b, h) + aoff + m * 2048 + k * 1024); } while (0)
; #define PG8_WAIT_V(n) asm volatile("s_waitcnt vmcnt(" #n ")" ::: "memory")
; #define PG8_WAIT_L(n) asm volatile("s_waitcnt lgkmcnt(" #n ")" ::: "memory")
; template <class Epi>
; DEVI void gemm_phase(LAS unsigned char* lds, const Gemm g, const Epi& E) {
;     ...
;         for (int t = 0; t < nt; t += 2) {
;             const bool last = (t == nt - 2);
;             const char* a1 = cA + (size_t)(t + 1) * kstep;
;             const char* a2 = last ? nA : cA + (size_t)(t + 2) * kstep; const char* b2 = last ? nB : cB + (size_t)(t + 2) * kstep;
;             const char* a3 = a2 + kstep; const char* b3 = b2 + kstep;
;             PG8_LDB(B0, 0, 0); PG8_SCHED; PG8_LDA(At, 0, 0); PG8_STAGE(PG8_SA(1, 1), a1 + hstepA, voffA);
;             PG8_WAIT_L(8); PG8_BAR; PG8_WAIT_L(0); PG8_MMA(0, 0, At, B0); PG8_BAR; PG8_SCHED;
;             PG8_LDB(B1, 0, 1); PG8_STAGE(PG8_SB(0, 0), b2, voffB);
;             PG8_BAR; PG8_WAIT_L(0); PG8_MMA(0, 1, At, B1); PG8_BAR;
;             PG8_LDA(At, 0, 1); PG8_STAGE(PG8_SA(0, 0), a2, voffA);
;             PG8_BAR; PG8_WAIT_L(0); PG8_MMA(1, 0, At, B0); PG8_BAR; PG8_SCHED;
;             PG8_STAGE(PG8_SB(0, 1), b2 + hstepB, voffB);
;             PG8_WAIT_V(6); PG8_BAR; PG8_MMA(1, 1, At, B1); PG8_BAR;
;             PG8_LDB(B0, 1, 0); PG8_SCHED; PG8_LDA(At, 1, 0); PG8_STAGE(PG8_SA(0, 1), a2 + hstepA, voffA);
;             PG8_WAIT_L(8); PG8_BAR; PG8_WAIT_L(0); PG8_MMA(0, 0, At, B0); PG8_BAR; PG8_SCHED;
;             PG8_LDB(B1, 1, 1); PG8_STAGE(PG8_SB(1, 0), b3, voffB);
;             PG8_BAR; PG8_WAIT_L(0); PG8_MMA(0, 1, At, B1); PG8_BAR;
;             PG8_LDA(At, 1, 1); PG8_STAGE(PG8_SA(1, 0), a3, voffA);
;             PG8_BAR; PG8_WAIT_L(0); PG8_MMA(1, 0, At, B0); PG8_BAR; PG8_SCHED;
;             PG8_STAGE(PG8_SB(1, 1), b3 + hstepB, voffB);
;             PG8_WAIT_V(6); PG8_BAR; PG8_MMA(1, 1, At, B1); PG8_BAR;
;         }
	v_mfma_f32_16x16x32_bf16 v[54:57], v[222:225], v[180:183], v[54:57]
	v_mfma_f32_16x16x32_bf16 v[50:53], v[230:233], v[180:183], v[50:53]
	v_mfma_f32_16x16x32_bf16 v[38:41], v[222:225], v[192:195], v[38:41]
	v_mfma_f32_16x16x32_bf16 v[34:37], v[230:233], v[192:195], v[34:37]
	v_mfma_f32_16x16x32_bf16 v[22:25], v[222:225], v[200:203], v[22:25]
	v_mfma_f32_16x16x32_bf16 v[18:21], v[230:233], v[200:203], v[18:21]
	v_mfma_f32_16x16x32_bf16 v[4:7], v[222:225], v[214:217], v[4:7]
	v_mfma_f32_16x16x32_bf16 v[0:3], v[230:233], v[214:217], v[0:3]
	v_mfma_f32_16x16x32_bf16 v[54:57], v[226:229], v[188:191], v[54:57]
	v_mfma_f32_16x16x32_bf16 v[50:53], v[234:237], v[188:191], v[50:53]
	v_mfma_f32_16x16x32_bf16 v[38:41], v[226:229], v[196:199], v[38:41]
	v_mfma_f32_16x16x32_bf16 v[34:37], v[234:237], v[196:199], v[34:37]
	v_mfma_f32_16x16x32_bf16 v[22:25], v[226:229], v[204:207], v[22:25]
	v_mfma_f32_16x16x32_bf16 v[18:21], v[234:237], v[204:207], v[18:21]
	v_mfma_f32_16x16x32_bf16 v[4:7], v[226:229], v[218:221], v[4:7]
	v_mfma_f32_16x16x32_bf16 v[0:3], v[234:237], v[218:221], v[0:3]
	s_add_i32 s38, 0, 0x18000
	v_add_u32_e32 v176, s38, v185
	s_barrier
	ds_read_b128 v[114:117], v176
	ds_read_b128 v[126:129], v176 offset:1024
	ds_read_b128 v[130:133], v176 offset:2048
	ds_read_b128 v[176:179], v176 offset:3072
	s_add_u32 s16, s16, 0x40000
	s_addc_u32 s17, s17, 0
	s_mov_b32 m0, s68
	ds_read_b128 v[180:183], v187 offset:32768
	ds_read_b128 v[188:191], v187 offset:33792
	ds_read_b128 v[192:195], v187 offset:34816
	ds_read_b128 v[196:199], v187 offset:35840
	ds_read_b128 v[200:203], v187 offset:36864
	ds_read_b128 v[204:207], v187 offset:37888
	ds_read_b128 v[214:217], v187 offset:38912
	ds_read_b128 v[218:221], v187 offset:39936
	global_load_lds_dwordx4 v142, s[16:17]
	s_mov_b32 m0, s69
	s_nop 0
	global_load_lds_dwordx4 v144, s[16:17]
	s_waitcnt lgkmcnt(8)
	s_barrier
	s_waitcnt lgkmcnt(0)
	v_mfma_f32_16x16x32_bf16 v[138:141], v[114:117], v[180:183], v[138:141]
	v_mfma_f32_16x16x32_bf16 v[134:137], v[130:133], v[180:183], v[134:137]
	v_mfma_f32_16x16x32_bf16 v[110:113], v[114:117], v[192:195], v[110:113]
	v_mfma_f32_16x16x32_bf16 v[106:109], v[130:133], v[192:195], v[106:109]
	v_mfma_f32_16x16x32_bf16 v[94:97], v[114:117], v[200:203], v[94:97]
	v_mfma_f32_16x16x32_bf16 v[90:93], v[130:133], v[200:203], v[90:93]
	v_mfma_f32_16x16x32_bf16 v[78:81], v[114:117], v[214:217], v[78:81]
	v_mfma_f32_16x16x32_bf16 v[74:77], v[130:133], v[214:217], v[74:77]
	v_mfma_f32_16x16x32_bf16 v[138:141], v[126:129], v[188:191], v[138:141]
	v_mfma_f32_16x16x32_bf16 v[134:137], v[176:179], v[188:191], v[134:137]
	v_mfma_f32_16x16x32_bf16 v[110:113], v[126:129], v[196:199], v[110:113]
	v_mfma_f32_16x16x32_bf16 v[106:109], v[176:179], v[196:199], v[106:109]
	v_mfma_f32_16x16x32_bf16 v[94:97], v[126:129], v[204:207], v[94:97]
	v_mfma_f32_16x16x32_bf16 v[90:93], v[176:179], v[204:207], v[90:93]
	v_mfma_f32_16x16x32_bf16 v[78:81], v[126:129], v[218:221], v[78:81]
	v_mfma_f32_16x16x32_bf16 v[74:77], v[176:179], v[218:221], v[74:77]
	s_barrier
	s_add_i32 s16, 0, 0x1c000
	s_add_i32 s17, s38, s47
	v_add_u32_e32 v213, s16, v185
	v_lshl_add_u64 v[152:153], v[152:153], 0, s[70:71]
	s_mov_b32 m0, s17
	ds_read_b128 v[222:225], v213
	ds_read_b128 v[226:229], v213 offset:1024
	ds_read_b128 v[230:233], v213 offset:2048
	ds_read_b128 v[234:237], v213 offset:3072
	global_load_lds_dwordx4 v[152:153], off
	s_add_i32 m0, s17, 0x2000
	v_lshl_add_u64 v[152:153], v[162:163], 0, s[70:71]
	global_load_lds_dwordx4 v[152:153], off
	s_barrier
	s_waitcnt lgkmcnt(0)
	v_mfma_f32_16x16x32_bf16 v[122:125], v[222:225], v[180:183], v[122:125]
	v_mfma_f32_16x16x32_bf16 v[118:121], v[230:233], v[180:183], v[118:121]
	v_mfma_f32_16x16x32_bf16 v[102:105], v[222:225], v[192:195], v[102:105]
	v_mfma_f32_16x16x32_bf16 v[98:101], v[230:233], v[192:195], v[98:101]
	v_mfma_f32_16x16x32_bf16 v[86:89], v[222:225], v[200:203], v[86:89]
	v_mfma_f32_16x16x32_bf16 v[82:85], v[230:233], v[200:203], v[82:85]
	v_mfma_f32_16x16x32_bf16 v[70:73], v[222:225], v[214:217], v[70:73]
	v_mfma_f32_16x16x32_bf16 v[66:69], v[230:233], v[214:217], v[66:69]
	v_mfma_f32_16x16x32_bf16 v[122:125], v[226:229], v[188:191], v[122:125]
	v_mfma_f32_16x16x32_bf16 v[118:121], v[234:237], v[188:191], v[118:121]
	v_mfma_f32_16x16x32_bf16 v[102:105], v[226:229], v[196:199], v[102:105]
	v_mfma_f32_16x16x32_bf16 v[98:101], v[234:237], v[196:199], v[98:101]
	v_mfma_f32_16x16x32_bf16 v[86:89], v[226:229], v[204:207], v[86:89]
	v_mfma_f32_16x16x32_bf16 v[82:85], v[234:237], v[204:207], v[82:85]
	v_mfma_f32_16x16x32_bf16 v[70:73], v[226:229], v[218:221], v[70:73]
	v_mfma_f32_16x16x32_bf16 v[66:69], v[234:237], v[218:221], v[66:69]
	s_mov_b32 m0, s80
	v_lshl_add_u64 v[152:153], v[164:165], 0, s[70:71]
	s_barrier
	ds_read_b128 v[180:183], v187 offset:49152
	ds_read_b128 v[188:191], v187 offset:50176
	ds_read_b128 v[192:195], v187 offset:51200
	ds_read_b128 v[196:199], v187 offset:52224
	ds_read_b128 v[200:203], v187 offset:53248
	ds_read_b128 v[204:207], v187 offset:54272
	ds_read_b128 v[214:217], v187 offset:55296
	ds_read_b128 v[218:221], v187 offset:56320
	global_load_lds_dwordx4 v[152:153], off
	s_mov_b32 m0, s81
	v_lshl_add_u64 v[152:153], v[208:209], 0, s[70:71]
	global_load_lds_dwordx4 v[152:153], off
	s_barrier
; #define PG8_STAGE(bufoff, gbase, voff) do { _Pragma("unroll") for (int _i = 0; _i < 2; ++_i) \
;         __builtin_amdgcn_global_load_lds((const unsigned*)((const char*)(gbase) + (voff)[_i]), (LAS unsigned*)(lds + (bufoff) + ldsw + _i * 8192), 16, 0, 0); } while (0)
; #define PG8_BAR __builtin_amdgcn_s_barrier()
; template <class Epi>
; DEVI void gemm_phase(LAS unsigned char* lds, const Gemm g, const Epi& E) {
;     ...
;         for (int t = 0; t < nt; t += 2) {
;             const bool last = (t == nt - 2);
;             const char* a1 = cA + (size_t)(t + 1) * kstep;
;             const char* a2 = last ? nA : cA + (size_t)(t + 2) * kstep; const char* b2 = last ? nB : cB + (size_t)(t + 2) * kstep;
;             const char* a3 = a2 + kstep; const char* b3 = b2 + kstep;
;             PG8_LDB(B0, 0, 0); PG8_SCHED; PG8_LDA(At, 0, 0); PG8_STAGE(PG8_SA(1, 1), a1 + hstepA, voffA);
;             PG8_WAIT_L(8); PG8_BAR; PG8_WAIT_L(0); PG8_MMA(0, 0, At, B0); PG8_BAR; PG8_SCHED;
;             PG8_LDB(B1, 0, 1); PG8_STAGE(PG8_SB(0, 0), b2, voffB);
;             PG8_BAR; PG8_WAIT_L(0); PG8_MMA(0, 1, At, B1); PG8_BAR;
;             PG8_LDA(At, 0, 1); PG8_STAGE(PG8_SA(0, 0), a2, voffA);
;             PG8_BAR; PG8_WAIT_L(0); PG8_MMA(1, 0, At, B0); PG8_BAR; PG8_SCHED;
;             PG8_STAGE(PG8_SB(0, 1), b2 + hstepB, voffB);
;             PG8_WAIT_V(6); PG8_BAR; PG8_MMA(1, 1, At, B1); PG8_BAR;
;             PG8_LDB(B0, 1, 0); PG8_SCHED; PG8_LDA(At, 1, 0); PG8_STAGE(PG8_SA(0, 1), a2 + hstepA, voffA);
;             PG8_WAIT_L(8); PG8_BAR; PG8_WAIT_L(0); PG8_MMA(0, 0, At, B0); PG8_BAR; PG8_SCHED;
;             PG8_LDB(B1, 1, 1); PG8_STAGE(PG8_SB(1, 0), b3, voffB);
;             PG8_BAR; PG8_WAIT_L(0); PG8_MMA(0, 1, At, B1); PG8_BAR;
;             PG8_LDA(At, 1, 1); PG8_STAGE(PG8_SA(1, 0), a3, voffA);
;             PG8_BAR; PG8_WAIT_L(0); PG8_MMA(1, 0, At, B0); PG8_BAR; PG8_SCHED;
;             PG8_STAGE(PG8_SB(1, 1), b3 + hstepB, voffB);
;             PG8_WAIT_V(6); PG8_BAR; PG8_MMA(1, 1, At, B1); PG8_BAR;
;         }
;     ...
;                 if constexpr (Epi::PRE) {
; #pragma unroll
;                     for (int m = 0; m < 2; ++m)
; #pragma unroll
;                         for (int bj = 0; bj < 2; ++bj)
; #pragma unroll
;                             for (int n = 0; n < 2; ++n) pre[m][bj][n] = E.load(row0 + ai * HALF + (m0 + m) * 16, col0 + bj * HALF + n * NST);
	s_waitcnt lgkmcnt(0)
	v_mfma_f32_16x16x32_bf16 v[62:65], v[114:117], v[180:183], v[62:65]
	v_mfma_f32_16x16x32_bf16 v[58:61], v[130:133], v[180:183], v[58:61]
	v_mfma_f32_16x16x32_bf16 v[46:49], v[114:117], v[192:195], v[46:49]
	v_mfma_f32_16x16x32_bf16 v[42:45], v[130:133], v[192:195], v[42:45]
	v_mfma_f32_16x16x32_bf16 v[30:33], v[114:117], v[200:203], v[30:33]
	v_mfma_f32_16x16x32_bf16 v[26:29], v[130:133], v[200:203], v[26:29]
	v_mfma_f32_16x16x32_bf16 v[14:17], v[114:117], v[214:217], v[14:17]
	v_mfma_f32_16x16x32_bf16 v[10:13], v[130:133], v[214:217], v[10:13]
	v_mfma_f32_16x16x32_bf16 v[62:65], v[126:129], v[188:191], v[62:65]
	v_mfma_f32_16x16x32_bf16 v[58:61], v[176:179], v[188:191], v[58:61]
	v_mfma_f32_16x16x32_bf16 v[46:49], v[126:129], v[196:199], v[46:49]
	v_mfma_f32_16x16x32_bf16 v[42:45], v[176:179], v[196:199], v[42:45]
	v_mfma_f32_16x16x32_bf16 v[30:33], v[126:129], v[204:207], v[30:33]
	v_mfma_f32_16x16x32_bf16 v[26:29], v[176:179], v[204:207], v[26:29]
	v_mfma_f32_16x16x32_bf16 v[14:17], v[126:129], v[218:221], v[14:17]
	v_mfma_f32_16x16x32_bf16 v[10:13], v[176:179], v[218:221], v[10:13]
	s_barrier
	s_add_u32 s14, s14, 0x40080
	s_addc_u32 s15, s15, 0
	s_add_i32 s16, s16, s47
	s_mov_b32 m0, s16
	s_nop 0
	global_load_lds_dwordx4 v8, s[14:15]
	s_add_i32 m0, s16, 0x2000
	s_nop 0
	global_load_lds_dwordx4 v146, s[14:15]
	s_waitcnt vmcnt(6)
	s_barrier
	v_mfma_f32_16x16x32_bf16 v[54:57], v[222:225], v[180:183], v[54:57]
	v_mfma_f32_16x16x32_bf16 v[50:53], v[230:233], v[180:183], v[50:53]
	v_mfma_f32_16x16x32_bf16 v[38:41], v[222:225], v[192:195], v[38:41]
	v_mfma_f32_16x16x32_bf16 v[34:37], v[230:233], v[192:195], v[34:37]
	v_mfma_f32_16x16x32_bf16 v[22:25], v[222:225], v[200:203], v[22:25]
	v_mfma_f32_16x16x32_bf16 v[18:21], v[230:233], v[200:203], v[18:21]
	v_mfma_f32_16x16x32_bf16 v[4:7], v[222:225], v[214:217], v[4:7]
	v_mfma_f32_16x16x32_bf16 v[0:3], v[230:233], v[214:217], v[0:3]
	v_mfma_f32_16x16x32_bf16 v[54:57], v[226:229], v[188:191], v[54:57]
	v_mfma_f32_16x16x32_bf16 v[50:53], v[234:237], v[188:191], v[50:53]
	v_mfma_f32_16x16x32_bf16 v[38:41], v[226:229], v[196:199], v[38:41]
	v_mfma_f32_16x16x32_bf16 v[34:37], v[234:237], v[196:199], v[34:37]
	v_mfma_f32_16x16x32_bf16 v[22:25], v[226:229], v[204:207], v[22:25]
	v_mfma_f32_16x16x32_bf16 v[18:21], v[234:237], v[204:207], v[18:21]
	v_mfma_f32_16x16x32_bf16 v[4:7], v[226:229], v[218:221], v[4:7]
	v_mfma_f32_16x16x32_bf16 v[0:3], v[234:237], v[218:221], v[0:3]
	s_add_i32 s27, s27, 2
	s_add_u32 s12, s12, 0x100
	s_addc_u32 s13, s13, 0
	s_add_u32 s19, s19, 0x100
	s_addc_u32 s26, s26, 0
	s_cmp_gt_u32 s27, 13
	s_barrier
	s_cbranch_scc0 .LBB0_1346
	s_setprio 0
	v_lshl_add_u32 v180, s10, 8, v184
	v_lshl_or_b32 v152, s0, 8, v186
	v_ashrrev_i32_e32 v181, 31, v180
	v_lshlrev_b64 v[178:179], 11, v[180:181]
	v_ashrrev_i32_e32 v153, 31, v152
	v_lshl_add_u64 v[114:115], s[24:25], 0, v[178:179]
	v_lshlrev_b64 v[176:177], 1, v[152:153]
	v_lshl_add_u64 v[114:115], v[114:115], 0, v[176:177]
	global_load_dwordx4 v[188:191], v[114:115], off
	global_load_dwordx4 v[130:133], v[114:115], off offset:256
	v_or_b32_e32 v114, 16, v180
	v_ashrrev_i32_e32 v115, 31, v114
	v_lshlrev_b64 v[182:183], 11, v[114:115]
	v_readlane_b32 s48, v251, 40
	v_lshl_add_u64 v[114:115], s[24:25], 0, v[182:183]
	v_readlane_b32 s54, v251, 46
	v_readlane_b32 s55, v251, 47
	v_lshl_add_u64 v[114:115], v[114:115], 0, v[176:177]
	global_load_dwordx4 v[126:129], v[114:115], off
	s_nop 0
	global_load_dwordx4 v[114:117], v[114:115], off offset:256
	v_lshl_add_u64 v[152:153], v[152:153], 2, s[54:55]
	global_load_dwordx4 v[214:217], v[152:153], off
	global_load_dwordx4 v[218:221], v[152:153], off offset:16
	global_load_dwordx4 v[222:225], v[152:153], off offset:512
	global_load_dwordx4 v[226:229], v[152:153], off offset:528
	s_mov_b64 s[0:1], 0x40000
	v_readlane_b32 s52, v251, 44
	v_readlane_b32 s56, v251, 48
	v_readlane_b32 s57, v251, 49
	v_readlane_b32 s58, v251, 50
	v_readlane_b32 s59, v251, 51
	v_readlane_b32 s60, v251, 52
	v_readlane_b32 s61, v251, 53
	v_readlane_b32 s62, v251, 54
	v_readlane_b32 s63, v251, 55
	s_and_b64 vcc, exec, s[36:37]
	s_mov_b32 s10, s2
	s_mov_b64 s[14:15], s[8:9]
	s_mov_b64 s[12:13], s[6:7]
	s_mov_b64 s[56:57], s[42:43]
	s_mov_b64 s[58:59], s[44:45]
	s_mov_b32 s60, s41
	s_mov_b32 s61, s83
	s_mov_b32 s62, s84
	s_mov_b32 s63, s85
	v_readlane_b32 s55, v254, 0
	s_movk_i32 s52, 0x110
	v_readlane_b32 s49, v251, 41
	v_readlane_b32 s50, v251, 42
	v_readlane_b32 s51, v251, 43
	v_readlane_b32 s53, v251, 45
	v_readlane_b32 s40, v254, 1
	s_waitcnt vmcnt(0)
; DEVI float bf2f(u16 b) { return __uint_as_float(((unsigned)b) << 16); }
;     DEVI f32x4 load(int r, int c) const { const bf16x4 y = *(const bf16x4*)(Y + (size_t)r * DM + c); return (f32x4){bf2f((u16)y[0]), bf2f((u16)y[1]), bf2f((u16)y[2]), bf2f((u16)y[3])}; }
	v_and_b32_e32 v163, 0xffff0000, v188
	v_lshlrev_b32_e32 v162, 16, v188
	v_add_f32_e32 v134, v134, v218
	v_add_f32_e32 v138, v138, v214
	v_add_f32_e32 v139, v139, v215
	v_mul_f32_e32 v138, 0xbfb8aa3b, v138
	v_mul_f32_e32 v139, 0xbfb8aa3b, v139
	v_add_f32_e32 v135, v135, v219
	v_exp_f32_e32 v138, v138
	v_mul_f32_e32 v134, 0xbfb8aa3b, v134
	v_exp_f32_e32 v139, v139
	v_mul_f32_e32 v135, 0xbfb8aa3b, v135
	v_exp_f32_e32 v134, v134
	v_exp_f32_e32 v135, v135
	v_add_f32_e32 v138, 1.0, v138
	v_add_f32_e32 v139, 1.0, v139
	v_rcp_f32_e32 v138, v138
	v_add_f32_e32 v134, 1.0, v134
	v_rcp_f32_e32 v139, v139
	v_add_f32_e32 v135, 1.0, v135
	v_rcp_f32_e32 v134, v134
	v_rcp_f32_e32 v135, v135
	v_pk_mul_f32 v[138:139], v[138:139], v[162:163]
	v_and_b32_e32 v163, 0xffff0000, v190
	v_lshlrev_b32_e32 v162, 16, v190
	v_pk_mul_f32 v[162:163], v[134:135], v[162:163]
	v_add_f32_e32 v135, v136, v220
	v_mul_f32_e32 v135, 0xbfb8aa3b, v135
	v_exp_f32_e32 v135, v135
	v_add_f32_e32 v134, v140, v216
	v_mul_f32_e32 v134, 0xbfb8aa3b, v134
	v_exp_f32_e32 v134, v134
	v_add_f32_e32 v135, 1.0, v135
	v_rcp_f32_e32 v136, v135
	v_add_f32_e32 v135, v141, v217
	v_mul_f32_e32 v135, 0xbfb8aa3b, v135
	v_exp_f32_e32 v135, v135
	v_add_f32_e32 v134, 1.0, v134
	v_rcp_f32_e32 v134, v134
	v_and_b32_e32 v141, 0xffff0000, v189
	v_add_f32_e32 v135, 1.0, v135
	v_rcp_f32_e32 v135, v135
	v_lshlrev_b32_e32 v140, 16, v189
	v_pk_mul_f32 v[140:141], v[134:135], v[140:141]
	v_add_f32_e32 v134, v137, v221
	v_mul_f32_e32 v134, 0xbfb8aa3b, v134
	v_exp_f32_e32 v134, v134
	v_and_b32_e32 v135, 0xffff0000, v191
	v_add_f32_e32 v134, 1.0, v134
	v_rcp_f32_e32 v137, v134
	v_lshlrev_b32_e32 v134, 16, v191
	v_pk_mul_f32 v[164:165], v[136:137], v[134:135]
	v_cvt_pk_bf16_f32 v134, v138, v139
	v_lshl_add_u64 v[138:139], s[64:65], 0, v[178:179]
	v_cvt_pk_bf16_f32 v135, v140, v141
	v_cvt_pk_bf16_f32 v136, v162, v163
	v_cvt_pk_bf16_f32 v137, v164, v165
	v_lshl_add_u64 v[138:139], v[138:139], 0, v[176:177]
	global_store_dwordx4 v[138:139], v[134:137], off
	s_nop 0
	v_and_b32_e32 v141, 0xffff0000, v130
	v_lshlrev_b32_e32 v140, 16, v130
	v_lshlrev_b32_e32 v130, 16, v133
	v_add_f32_e32 v118, v118, v226
	v_add_f32_e32 v119, v119, v227
	v_add_f32_e32 v122, v122, v222
	v_mul_f32_e32 v118, 0xbfb8aa3b, v118
	v_add_f32_e32 v123, v123, v223
	v_mul_f32_e32 v119, 0xbfb8aa3b, v119
	v_add_f32_e32 v124, v124, v224
	v_add_f32_e32 v120, v120, v228
	v_add_f32_e32 v125, v125, v225
	v_add_f32_e32 v121, v121, v229
	v_mul_f32_e32 v122, 0xbfb8aa3b, v122
	v_exp_f32_e32 v118, v118
	v_mul_f32_e32 v123, 0xbfb8aa3b, v123
	v_exp_f32_e32 v119, v119
	v_mul_f32_e32 v124, 0xbfb8aa3b, v124
	v_mul_f32_e32 v120, 0xbfb8aa3b, v120
	v_mul_f32_e32 v125, 0xbfb8aa3b, v125
	v_mul_f32_e32 v121, 0xbfb8aa3b, v121
	v_exp_f32_e32 v122, v122
	v_exp_f32_e32 v123, v123
	v_exp_f32_e32 v124, v124
	v_exp_f32_e32 v120, v120
	v_exp_f32_e32 v125, v125
	v_exp_f32_e32 v121, v121
	v_add_f32_e32 v118, 1.0, v118
	v_add_f32_e32 v119, 1.0, v119
	v_add_f32_e32 v122, 1.0, v122
	v_rcp_f32_e32 v118, v118
	v_add_f32_e32 v123, 1.0, v123
	v_rcp_f32_e32 v119, v119
	v_add_f32_e32 v124, 1.0, v124
	v_add_f32_e32 v120, 1.0, v120
	v_add_f32_e32 v125, 1.0, v125
	v_add_f32_e32 v121, 1.0, v121
	v_rcp_f32_e32 v122, v122
	v_rcp_f32_e32 v123, v123
	v_rcp_f32_e32 v124, v124
	v_rcp_f32_e32 v120, v120
	v_rcp_f32_e32 v125, v125
	v_rcp_f32_e32 v121, v121
	v_and_b32_e32 v135, 0xffff0000, v132
	v_lshlrev_b32_e32 v134, 16, v132
	v_pk_mul_f32 v[118:119], v[118:119], v[134:135]
	v_and_b32_e32 v135, 0xffff0000, v131
	v_lshlrev_b32_e32 v134, 16, v131
	v_and_b32_e32 v131, 0xffff0000, v133
	v_pk_mul_f32 v[122:123], v[122:123], v[140:141]
	v_pk_mul_f32 v[124:125], v[124:125], v[134:135]
	v_pk_mul_f32 v[130:131], v[120:121], v[130:131]
	v_cvt_pk_bf16_f32 v120, v122, v123
	v_cvt_pk_bf16_f32 v121, v124, v125
	v_cvt_pk_bf16_f32 v122, v118, v119
	v_cvt_pk_bf16_f32 v123, v130, v131
	global_store_dwordx4 v[138:139], v[120:123], off offset:256
	s_nop 0
	v_add_f32_e32 v106, v106, v218
	v_add_f32_e32 v107, v107, v219
	v_mul_f32_e32 v106, 0xbfb8aa3b, v106
	v_mul_f32_e32 v107, 0xbfb8aa3b, v107
	v_exp_f32_e32 v106, v106
	v_exp_f32_e32 v107, v107
	v_and_b32_e32 v119, 0xffff0000, v128
	v_lshlrev_b32_e32 v118, 16, v128
	v_add_f32_e32 v106, 1.0, v106
	v_add_f32_e32 v107, 1.0, v107
	v_rcp_f32_e32 v106, v106
	v_rcp_f32_e32 v107, v107
	v_add_f32_e32 v110, v110, v214
	v_add_f32_e32 v111, v111, v215
	v_mul_f32_e32 v110, 0xbfb8aa3b, v110
	v_pk_mul_f32 v[118:119], v[106:107], v[118:119]
	v_add_f32_e32 v107, v108, v220
	v_mul_f32_e32 v107, 0xbfb8aa3b, v107
	v_exp_f32_e32 v107, v107
	v_add_f32_e32 v106, v112, v216
	v_mul_f32_e32 v106, 0xbfb8aa3b, v106
	v_exp_f32_e32 v106, v106
	v_add_f32_e32 v107, 1.0, v107
	v_rcp_f32_e32 v108, v107
	v_add_f32_e32 v107, v113, v217
	v_mul_f32_e32 v107, 0xbfb8aa3b, v107
	v_exp_f32_e32 v107, v107
	v_add_f32_e32 v106, 1.0, v106
	v_rcp_f32_e32 v106, v106
	v_and_b32_e32 v113, 0xffff0000, v127
	v_add_f32_e32 v107, 1.0, v107
	v_rcp_f32_e32 v107, v107
	v_lshlrev_b32_e32 v112, 16, v127
	v_mul_f32_e32 v111, 0xbfb8aa3b, v111
	v_exp_f32_e32 v110, v110
	v_pk_mul_f32 v[112:113], v[106:107], v[112:113]
	v_add_f32_e32 v106, v109, v221
	v_exp_f32_e32 v111, v111
	v_mul_f32_e32 v106, 0xbfb8aa3b, v106
	v_exp_f32_e32 v106, v106
	v_add_f32_e32 v110, 1.0, v110
	v_add_f32_e32 v111, 1.0, v111
	v_rcp_f32_e32 v110, v110
	v_rcp_f32_e32 v111, v111
	v_add_f32_e32 v106, 1.0, v106
	v_rcp_f32_e32 v109, v106
	v_and_b32_e32 v123, 0xffff0000, v126
	v_lshlrev_b32_e32 v122, 16, v126
	v_pk_mul_f32 v[110:111], v[110:111], v[122:123]
	v_and_b32_e32 v107, 0xffff0000, v129
	v_lshlrev_b32_e32 v106, 16, v129
	v_pk_mul_f32 v[120:121], v[108:109], v[106:107]
; DEVI float bf2f(u16 b) { return __uint_as_float(((unsigned)b) << 16); }
; template <class Epi>
; DEVI void gemm_phase(LAS unsigned char* lds, const Gemm g, const Epi& E) {
;     ...
;                 if constexpr (Epi::PRE) {
; #pragma unroll
;                     for (int m = 0; m < 2; ++m)
; #pragma unroll
;                         for (int bj = 0; bj < 2; ++bj)
; #pragma unroll
;                             for (int n = 0; n < 2; ++n) pre[m][bj][n] = E.load(row0 + ai * HALF + (m0 + m) * 16, col0 + bj * HALF + n * NST);
;                 }
; #pragma unroll
;                 for (int mm = 0; mm < 2; ++mm) {
;                     const int m = m0 + mm;
;                     const int r = row0 + ai * HALF + m * 16; float rs = 1.f, part = 0.f;
;                     if constexpr (Epi::RS) rs = rsv[ai * 4 + m];
;                     if constexpr (Epi::PAIR) E.pair8(cur.b, r, cur.pn * HALF + wc * 32 + 8 * fq, acc[ai][0][m][0] * rs, acc[ai][0][m][1] * rs, acc[ai][1][m][0] * rs, acc[ai][1][m][1] * rs);
;                     else
; #pragma unroll
;                     for (int bj = 0; bj < 2; ++bj) {
;                         const int c = col0 + bj * HALF; f32x4 v0 = acc[ai][bj][m][0], v1 = acc[ai][bj][m][1];
;                         if constexpr (Epi::RS) { v0 = v0 * rs; v1 = v1 * rs; }
;                         if constexpr (Epi::PRE) part += E.frag_pre8(cur.b, r, c, v0, v1, pre[mm][bj][0], pre[mm][bj][1]);
;                         else if constexpr (Epi::PERM) E.frag8(cur.b, r, c, v0, v1);
;                         else { E.frag(cur.b, r, c, v0); E.frag(cur.b, r, c + 16, v1); }
;     DEVI f32x4 load(int r, int c) const { const bf16x4 y = *(const bf16x4*)(Y + (size_t)r * DM + c); return (f32x4){bf2f((u16)y[0]), bf2f((u16)y[1]), bf2f((u16)y[2]), bf2f((u16)y[3])}; }
	v_cvt_pk_bf16_f32 v106, v110, v111
	v_lshl_add_u64 v[110:111], s[64:65], 0, v[182:183]
	v_cvt_pk_bf16_f32 v107, v112, v113
	v_cvt_pk_bf16_f32 v108, v118, v119
	v_cvt_pk_bf16_f32 v109, v120, v121
	v_lshl_add_u64 v[110:111], v[110:111], 0, v[176:177]
	global_store_dwordx4 v[110:111], v[106:109], off
	s_nop 0
	v_and_b32_e32 v113, 0xffff0000, v114
	v_lshlrev_b32_e32 v112, 16, v114
	v_add_f32_e32 v98, v98, v226
	v_add_f32_e32 v99, v99, v227
	v_mul_f32_e32 v98, 0xbfb8aa3b, v98
	v_mul_f32_e32 v99, 0xbfb8aa3b, v99
	v_exp_f32_e32 v98, v98
	v_exp_f32_e32 v99, v99
	v_and_b32_e32 v107, 0xffff0000, v116
	v_lshlrev_b32_e32 v106, 16, v116
	v_add_f32_e32 v98, 1.0, v98
	v_add_f32_e32 v99, 1.0, v99
	v_rcp_f32_e32 v98, v98
	v_rcp_f32_e32 v99, v99
	v_add_f32_e32 v102, v102, v222
	v_add_f32_e32 v103, v103, v223
	v_mul_f32_e32 v102, 0xbfb8aa3b, v102
	v_pk_mul_f32 v[106:107], v[98:99], v[106:107]
	v_add_f32_e32 v99, v100, v228
	v_mul_f32_e32 v99, 0xbfb8aa3b, v99
	v_exp_f32_e32 v99, v99
	v_add_f32_e32 v98, v104, v224
	v_mul_f32_e32 v98, 0xbfb8aa3b, v98
	v_exp_f32_e32 v98, v98
	v_add_f32_e32 v99, 1.0, v99
	v_rcp_f32_e32 v100, v99
	v_add_f32_e32 v99, v105, v225
	v_mul_f32_e32 v99, 0xbfb8aa3b, v99
	v_exp_f32_e32 v99, v99
	v_add_f32_e32 v98, 1.0, v98
	v_rcp_f32_e32 v98, v98
	v_and_b32_e32 v105, 0xffff0000, v115
	v_add_f32_e32 v99, 1.0, v99
	v_rcp_f32_e32 v99, v99
	v_lshlrev_b32_e32 v104, 16, v115
	v_mul_f32_e32 v103, 0xbfb8aa3b, v103
	v_exp_f32_e32 v102, v102
	v_pk_mul_f32 v[104:105], v[98:99], v[104:105]
	v_add_f32_e32 v98, v101, v229
	v_mul_f32_e32 v98, 0xbfb8aa3b, v98
	v_exp_f32_e32 v103, v103
	v_exp_f32_e32 v98, v98
	v_add_f32_e32 v102, 1.0, v102
	v_rcp_f32_e32 v102, v102
	v_add_f32_e32 v103, 1.0, v103
	v_add_f32_e32 v98, 1.0, v98
	v_rcp_f32_e32 v103, v103
	v_rcp_f32_e32 v101, v98
	v_and_b32_e32 v99, 0xffff0000, v117
	v_lshlrev_b32_e32 v98, 16, v117
	v_pk_mul_f32 v[102:103], v[102:103], v[112:113]
	v_pk_mul_f32 v[108:109], v[100:101], v[98:99]
	v_cvt_pk_bf16_f32 v98, v102, v103
	v_cvt_pk_bf16_f32 v99, v104, v105
	v_cvt_pk_bf16_f32 v100, v106, v107
	v_cvt_pk_bf16_f32 v101, v108, v109
	global_store_dwordx4 v[110:111], v[98:101], off offset:256
	s_nop 1
	v_or_b32_e32 v98, 32, v180
	v_ashrrev_i32_e32 v99, 31, v98
	v_lshlrev_b64 v[120:121], 11, v[98:99]
	v_lshl_add_u64 v[98:99], s[24:25], 0, v[120:121]
	v_lshl_add_u64 v[98:99], v[98:99], 0, v[176:177]
	global_load_dwordx4 v[110:113], v[98:99], off
	global_load_dwordx4 v[106:109], v[98:99], off offset:256
	v_or_b32_e32 v98, 48, v180
	v_ashrrev_i32_e32 v99, 31, v98
	v_lshlrev_b64 v[118:119], 11, v[98:99]
	v_lshl_add_u64 v[98:99], s[24:25], 0, v[118:119]
	v_lshl_add_u64 v[98:99], v[98:99], 0, v[176:177]
	global_load_dwordx4 v[102:105], v[98:99], off
	s_nop 0
	global_load_dwordx4 v[98:101], v[98:99], off offset:256
	s_nop 0
	s_waitcnt vmcnt(0)
	v_add_f32_e32 v90, v90, v218
	v_add_f32_e32 v91, v91, v219
	v_mul_f32_e32 v90, 0xbfb8aa3b, v90
	v_mul_f32_e32 v91, 0xbfb8aa3b, v91
	v_exp_f32_e32 v90, v90
	v_exp_f32_e32 v91, v91
	v_and_b32_e32 v115, 0xffff0000, v112
	v_lshlrev_b32_e32 v114, 16, v112
	v_add_f32_e32 v90, 1.0, v90
	v_add_f32_e32 v91, 1.0, v91
	v_rcp_f32_e32 v90, v90
	v_rcp_f32_e32 v91, v91
	v_add_f32_e32 v94, v94, v214
	v_add_f32_e32 v95, v95, v215
	v_mul_f32_e32 v94, 0xbfb8aa3b, v94
	v_pk_mul_f32 v[114:115], v[90:91], v[114:115]
	v_add_f32_e32 v91, v92, v220
	v_mul_f32_e32 v91, 0xbfb8aa3b, v91
	v_exp_f32_e32 v91, v91
	v_add_f32_e32 v90, v96, v216
	v_mul_f32_e32 v90, 0xbfb8aa3b, v90
	v_exp_f32_e32 v90, v90
	v_add_f32_e32 v91, 1.0, v91
	v_rcp_f32_e32 v92, v91
	v_add_f32_e32 v91, v97, v217
	v_mul_f32_e32 v91, 0xbfb8aa3b, v91
	v_exp_f32_e32 v91, v91
	v_add_f32_e32 v90, 1.0, v90
	v_rcp_f32_e32 v90, v90
	v_and_b32_e32 v97, 0xffff0000, v111
	v_add_f32_e32 v91, 1.0, v91
	v_rcp_f32_e32 v91, v91
	v_lshlrev_b32_e32 v96, 16, v111
	v_mul_f32_e32 v95, 0xbfb8aa3b, v95
	v_exp_f32_e32 v94, v94
	v_pk_mul_f32 v[96:97], v[90:91], v[96:97]
	v_add_f32_e32 v90, v93, v221
	v_exp_f32_e32 v95, v95
	v_mul_f32_e32 v90, 0xbfb8aa3b, v90
	v_exp_f32_e32 v90, v90
	v_add_f32_e32 v94, 1.0, v94
	v_add_f32_e32 v95, 1.0, v95
	v_rcp_f32_e32 v94, v94
	v_rcp_f32_e32 v95, v95
	v_add_f32_e32 v90, 1.0, v90
	v_rcp_f32_e32 v93, v90
	v_and_b32_e32 v123, 0xffff0000, v110
	v_lshlrev_b32_e32 v122, 16, v110
	v_pk_mul_f32 v[94:95], v[94:95], v[122:123]
	v_and_b32_e32 v91, 0xffff0000, v113
	v_lshlrev_b32_e32 v90, 16, v113
	v_pk_mul_f32 v[110:111], v[92:93], v[90:91]
	v_cvt_pk_bf16_f32 v90, v94, v95
	v_lshl_add_u64 v[94:95], s[64:65], 0, v[120:121]
	v_cvt_pk_bf16_f32 v91, v96, v97
	v_cvt_pk_bf16_f32 v92, v114, v115
	v_cvt_pk_bf16_f32 v93, v110, v111
	v_lshl_add_u64 v[94:95], v[94:95], 0, v[176:177]
	global_store_dwordx4 v[94:95], v[90:93], off
	s_nop 0
	v_and_b32_e32 v97, 0xffff0000, v106
	v_lshlrev_b32_e32 v96, 16, v106
	v_add_f32_e32 v82, v82, v226
	v_add_f32_e32 v83, v83, v227
	v_mul_f32_e32 v82, 0xbfb8aa3b, v82
	v_mul_f32_e32 v83, 0xbfb8aa3b, v83
	v_add_f32_e32 v88, v88, v224
	v_add_f32_e32 v89, v89, v225
	v_add_f32_e32 v86, v86, v222
	v_exp_f32_e32 v82, v82
	v_add_f32_e32 v87, v87, v223
	v_exp_f32_e32 v83, v83
	v_mul_f32_e32 v88, 0xbfb8aa3b, v88
	v_add_f32_e32 v84, v84, v228
	v_mul_f32_e32 v89, 0xbfb8aa3b, v89
	v_add_f32_e32 v85, v85, v229
	v_mul_f32_e32 v86, 0xbfb8aa3b, v86
	v_mul_f32_e32 v87, 0xbfb8aa3b, v87
	v_exp_f32_e32 v88, v88
	v_mul_f32_e32 v84, 0xbfb8aa3b, v84
	v_exp_f32_e32 v89, v89
	v_mul_f32_e32 v85, 0xbfb8aa3b, v85
	v_exp_f32_e32 v86, v86
	v_exp_f32_e32 v87, v87
	v_exp_f32_e32 v84, v84
	v_exp_f32_e32 v85, v85
	v_add_f32_e32 v82, 1.0, v82
	v_add_f32_e32 v83, 1.0, v83
	v_rcp_f32_e32 v82, v82
	v_rcp_f32_e32 v83, v83
	v_add_f32_e32 v88, 1.0, v88
; DEVI float bf2f(u16 b) { return __uint_as_float(((unsigned)b) << 16); }
; template <class Epi>
; DEVI void gemm_phase(LAS unsigned char* lds, const Gemm g, const Epi& E) {
;     ...
;                 if constexpr (Epi::PRE) {
; #pragma unroll
;                     for (int m = 0; m < 2; ++m)
; #pragma unroll
;                         for (int bj = 0; bj < 2; ++bj)
; #pragma unroll
;                             for (int n = 0; n < 2; ++n) pre[m][bj][n] = E.load(row0 + ai * HALF + (m0 + m) * 16, col0 + bj * HALF + n * NST);
;                 }
; #pragma unroll
;                 for (int mm = 0; mm < 2; ++mm) {
;                     const int m = m0 + mm;
;                     const int r = row0 + ai * HALF + m * 16; float rs = 1.f, part = 0.f;
;                     if constexpr (Epi::RS) rs = rsv[ai * 4 + m];
;                     if constexpr (Epi::PAIR) E.pair8(cur.b, r, cur.pn * HALF + wc * 32 + 8 * fq, acc[ai][0][m][0] * rs, acc[ai][0][m][1] * rs, acc[ai][1][m][0] * rs, acc[ai][1][m][1] * rs);
;                     else
; #pragma unroll
;                     for (int bj = 0; bj < 2; ++bj) {
;                         const int c = col0 + bj * HALF; f32x4 v0 = acc[ai][bj][m][0], v1 = acc[ai][bj][m][1];
;                         if constexpr (Epi::RS) { v0 = v0 * rs; v1 = v1 * rs; }
;                         if constexpr (Epi::PRE) part += E.frag_pre8(cur.b, r, c, v0, v1, pre[mm][bj][0], pre[mm][bj][1]);
;                         else if constexpr (Epi::PERM) E.frag8(cur.b, r, c, v0, v1);
;                         else { E.frag(cur.b, r, c, v0); E.frag(cur.b, r, c + 16, v1); }
;     DEVI f32x4 load(int r, int c) const { const bf16x4 y = *(const bf16x4*)(Y + (size_t)r * DM + c); return (f32x4){bf2f((u16)y[0]), bf2f((u16)y[1]), bf2f((u16)y[2]), bf2f((u16)y[3])}; }
	v_add_f32_e32 v89, 1.0, v89
	v_add_f32_e32 v86, 1.0, v86
	v_add_f32_e32 v87, 1.0, v87
	v_rcp_f32_e32 v88, v88
	v_add_f32_e32 v84, 1.0, v84
	v_rcp_f32_e32 v89, v89
	v_add_f32_e32 v85, 1.0, v85
	v_rcp_f32_e32 v86, v86
	v_rcp_f32_e32 v87, v87
	v_rcp_f32_e32 v84, v84
	v_rcp_f32_e32 v85, v85
	v_and_b32_e32 v91, 0xffff0000, v108
	v_lshlrev_b32_e32 v90, 16, v108
	v_pk_mul_f32 v[82:83], v[82:83], v[90:91]
	v_and_b32_e32 v91, 0xffff0000, v107
	v_lshlrev_b32_e32 v90, 16, v107
	v_pk_mul_f32 v[88:89], v[88:89], v[90:91]
	v_and_b32_e32 v91, 0xffff0000, v109
	v_lshlrev_b32_e32 v90, 16, v109
	v_pk_mul_f32 v[86:87], v[86:87], v[96:97]
	v_pk_mul_f32 v[90:91], v[84:85], v[90:91]
	v_cvt_pk_bf16_f32 v84, v86, v87
	v_cvt_pk_bf16_f32 v85, v88, v89
	v_cvt_pk_bf16_f32 v86, v82, v83
	v_cvt_pk_bf16_f32 v87, v90, v91
	global_store_dwordx4 v[94:95], v[84:87], off offset:256
	s_nop 0
	v_add_f32_e32 v74, v74, v218
	v_add_f32_e32 v75, v75, v219
	v_mul_f32_e32 v74, 0xbfb8aa3b, v74
	v_mul_f32_e32 v75, 0xbfb8aa3b, v75
	v_exp_f32_e32 v74, v74
	v_exp_f32_e32 v75, v75
	v_and_b32_e32 v83, 0xffff0000, v104
	v_lshlrev_b32_e32 v82, 16, v104
	v_add_f32_e32 v74, 1.0, v74
	v_add_f32_e32 v75, 1.0, v75
	v_rcp_f32_e32 v74, v74
	v_rcp_f32_e32 v75, v75
	v_add_f32_e32 v78, v78, v214
	v_add_f32_e32 v79, v79, v215
	v_mul_f32_e32 v78, 0xbfb8aa3b, v78
	v_pk_mul_f32 v[82:83], v[74:75], v[82:83]
	v_add_f32_e32 v75, v76, v220
	v_mul_f32_e32 v75, 0xbfb8aa3b, v75
	v_exp_f32_e32 v75, v75
	v_add_f32_e32 v74, v80, v216
	v_mul_f32_e32 v74, 0xbfb8aa3b, v74
	v_exp_f32_e32 v74, v74
	v_add_f32_e32 v75, 1.0, v75
	v_rcp_f32_e32 v76, v75
	v_add_f32_e32 v75, v81, v217
	v_mul_f32_e32 v75, 0xbfb8aa3b, v75
	v_exp_f32_e32 v75, v75
	v_add_f32_e32 v74, 1.0, v74
	v_rcp_f32_e32 v74, v74
	v_and_b32_e32 v81, 0xffff0000, v103
	v_add_f32_e32 v75, 1.0, v75
	v_rcp_f32_e32 v75, v75
	v_lshlrev_b32_e32 v80, 16, v103
	v_mul_f32_e32 v79, 0xbfb8aa3b, v79
	v_exp_f32_e32 v78, v78
	v_pk_mul_f32 v[80:81], v[74:75], v[80:81]
	v_add_f32_e32 v74, v77, v221
	v_exp_f32_e32 v79, v79
	v_mul_f32_e32 v74, 0xbfb8aa3b, v74
	v_exp_f32_e32 v74, v74
	v_add_f32_e32 v78, 1.0, v78
	v_add_f32_e32 v79, 1.0, v79
	v_rcp_f32_e32 v78, v78
	v_rcp_f32_e32 v79, v79
	v_add_f32_e32 v74, 1.0, v74
	v_rcp_f32_e32 v77, v74
	v_and_b32_e32 v87, 0xffff0000, v102
	v_lshlrev_b32_e32 v86, 16, v102
	v_pk_mul_f32 v[78:79], v[78:79], v[86:87]
	v_and_b32_e32 v75, 0xffff0000, v105
	v_lshlrev_b32_e32 v74, 16, v105
	v_pk_mul_f32 v[84:85], v[76:77], v[74:75]
	v_cvt_pk_bf16_f32 v74, v78, v79
	v_lshl_add_u64 v[78:79], s[64:65], 0, v[118:119]
	v_cvt_pk_bf16_f32 v75, v80, v81
	v_cvt_pk_bf16_f32 v76, v82, v83
	v_cvt_pk_bf16_f32 v77, v84, v85
	v_lshl_add_u64 v[78:79], v[78:79], 0, v[176:177]
	global_store_dwordx4 v[78:79], v[74:77], off
	s_nop 0
	v_lshl_add_u64 v[88:89], v[178:179], 0, s[0:1]
	s_mov_b64 s[0:1], 0x48000
	v_lshl_add_u64 v[86:87], v[178:179], 0, s[0:1]
	s_mov_b64 s[0:1], 0x50000
	v_add_f32_e32 v66, v66, v226
	v_add_f32_e32 v67, v67, v227
	v_mul_f32_e32 v66, 0xbfb8aa3b, v66
	v_mul_f32_e32 v67, 0xbfb8aa3b, v67
	v_exp_f32_e32 v66, v66
	v_exp_f32_e32 v67, v67
	v_and_b32_e32 v75, 0xffff0000, v100
	v_lshlrev_b32_e32 v74, 16, v100
	v_add_f32_e32 v66, 1.0, v66
	v_add_f32_e32 v67, 1.0, v67
	v_rcp_f32_e32 v66, v66
	v_rcp_f32_e32 v67, v67
	v_add_f32_e32 v70, v70, v222
	v_add_f32_e32 v71, v71, v223
	v_mul_f32_e32 v70, 0xbfb8aa3b, v70
	v_pk_mul_f32 v[74:75], v[66:67], v[74:75]
	v_add_f32_e32 v67, v68, v228
	v_mul_f32_e32 v67, 0xbfb8aa3b, v67
	v_exp_f32_e32 v67, v67
	v_add_f32_e32 v66, v72, v224
	v_mul_f32_e32 v66, 0xbfb8aa3b, v66
	v_exp_f32_e32 v66, v66
	v_add_f32_e32 v67, 1.0, v67
	v_rcp_f32_e32 v68, v67
	v_add_f32_e32 v67, v73, v225
	v_mul_f32_e32 v67, 0xbfb8aa3b, v67
	v_exp_f32_e32 v67, v67
	v_add_f32_e32 v66, 1.0, v66
	v_rcp_f32_e32 v66, v66
	v_and_b32_e32 v73, 0xffff0000, v99
	v_add_f32_e32 v67, 1.0, v67
	v_rcp_f32_e32 v67, v67
	v_lshlrev_b32_e32 v72, 16, v99
	v_mul_f32_e32 v71, 0xbfb8aa3b, v71
	v_exp_f32_e32 v70, v70
	v_pk_mul_f32 v[72:73], v[66:67], v[72:73]
	v_add_f32_e32 v66, v69, v229
	v_mul_f32_e32 v66, 0xbfb8aa3b, v66
	v_exp_f32_e32 v71, v71
	v_exp_f32_e32 v66, v66
	v_add_f32_e32 v70, 1.0, v70
	v_rcp_f32_e32 v70, v70
	v_add_f32_e32 v71, 1.0, v71
	v_add_f32_e32 v66, 1.0, v66
	v_rcp_f32_e32 v71, v71
	v_rcp_f32_e32 v69, v66
	v_and_b32_e32 v81, 0xffff0000, v98
	v_lshlrev_b32_e32 v80, 16, v98
	v_and_b32_e32 v67, 0xffff0000, v101
	v_lshlrev_b32_e32 v66, 16, v101
	v_pk_mul_f32 v[70:71], v[70:71], v[80:81]
	v_pk_mul_f32 v[76:77], v[68:69], v[66:67]
	v_cvt_pk_bf16_f32 v66, v70, v71
	v_cvt_pk_bf16_f32 v67, v72, v73
	v_cvt_pk_bf16_f32 v68, v74, v75
	v_cvt_pk_bf16_f32 v69, v76, v77
	global_store_dwordx4 v[78:79], v[66:69], off offset:256
	s_nop 1
	v_lshl_add_u64 v[66:67], s[24:25], 0, v[88:89]
	v_lshl_add_u64 v[66:67], v[66:67], 0, v[176:177]
	global_load_dwordx4 v[78:81], v[66:67], off
	global_load_dwordx4 v[74:77], v[66:67], off offset:256
	v_lshl_add_u64 v[66:67], s[24:25], 0, v[86:87]
	v_lshl_add_u64 v[66:67], v[66:67], 0, v[176:177]
	global_load_dwordx4 v[70:73], v[66:67], off
	s_nop 0
	global_load_dwordx4 v[66:69], v[66:67], off offset:256
	s_nop 0
	s_waitcnt vmcnt(0)
; DEVI float bf2f(u16 b) { return __uint_as_float(((unsigned)b) << 16); }
; template <class Epi>
; DEVI void gemm_phase(LAS unsigned char* lds, const Gemm g, const Epi& E) {
;     ...
;                 if constexpr (Epi::PRE) {
; #pragma unroll
;                     for (int m = 0; m < 2; ++m)
; #pragma unroll
;                         for (int bj = 0; bj < 2; ++bj)
; #pragma unroll
;                             for (int n = 0; n < 2; ++n) pre[m][bj][n] = E.load(row0 + ai * HALF + (m0 + m) * 16, col0 + bj * HALF + n * NST);
;                 }
; #pragma unroll
;                 for (int mm = 0; mm < 2; ++mm) {
;                     const int m = m0 + mm;
;                     const int r = row0 + ai * HALF + m * 16; float rs = 1.f, part = 0.f;
;                     if constexpr (Epi::RS) rs = rsv[ai * 4 + m];
;                     if constexpr (Epi::PAIR) E.pair8(cur.b, r, cur.pn * HALF + wc * 32 + 8 * fq, acc[ai][0][m][0] * rs, acc[ai][0][m][1] * rs, acc[ai][1][m][0] * rs, acc[ai][1][m][1] * rs);
;                     else
; #pragma unroll
;                     for (int bj = 0; bj < 2; ++bj) {
;                         const int c = col0 + bj * HALF; f32x4 v0 = acc[ai][bj][m][0], v1 = acc[ai][bj][m][1];
;                         if constexpr (Epi::RS) { v0 = v0 * rs; v1 = v1 * rs; }
;                         if constexpr (Epi::PRE) part += E.frag_pre8(cur.b, r, c, v0, v1, pre[mm][bj][0], pre[mm][bj][1]);
;                         else if constexpr (Epi::PERM) E.frag8(cur.b, r, c, v0, v1);
;                         else { E.frag(cur.b, r, c, v0); E.frag(cur.b, r, c + 16, v1); }
;     DEVI f32x4 load(int r, int c) const { const bf16x4 y = *(const bf16x4*)(Y + (size_t)r * DM + c); return (f32x4){bf2f((u16)y[0]), bf2f((u16)y[1]), bf2f((u16)y[2]), bf2f((u16)y[3])}; }
	v_add_f32_e32 v58, v58, v218
	v_add_f32_e32 v59, v59, v219
	v_mul_f32_e32 v58, 0xbfb8aa3b, v58
	v_mul_f32_e32 v59, 0xbfb8aa3b, v59
	v_exp_f32_e32 v58, v58
	v_exp_f32_e32 v59, v59
	v_and_b32_e32 v83, 0xffff0000, v80
	v_lshlrev_b32_e32 v82, 16, v80
	v_add_f32_e32 v58, 1.0, v58
	v_add_f32_e32 v59, 1.0, v59
	v_rcp_f32_e32 v58, v58
	v_rcp_f32_e32 v59, v59
	v_add_f32_e32 v62, v62, v214
	v_add_f32_e32 v63, v63, v215
	v_mul_f32_e32 v62, 0xbfb8aa3b, v62
	v_pk_mul_f32 v[82:83], v[58:59], v[82:83]
	v_add_f32_e32 v59, v60, v220
	v_mul_f32_e32 v59, 0xbfb8aa3b, v59
	v_exp_f32_e32 v59, v59
	v_add_f32_e32 v58, v64, v216
	v_mul_f32_e32 v58, 0xbfb8aa3b, v58
	v_exp_f32_e32 v58, v58
	v_add_f32_e32 v59, 1.0, v59
	v_rcp_f32_e32 v60, v59
	v_add_f32_e32 v59, v65, v217
	v_mul_f32_e32 v59, 0xbfb8aa3b, v59
	v_exp_f32_e32 v59, v59
	v_add_f32_e32 v58, 1.0, v58
	v_rcp_f32_e32 v58, v58
	v_and_b32_e32 v65, 0xffff0000, v79
	v_add_f32_e32 v59, 1.0, v59
	v_rcp_f32_e32 v59, v59
	v_lshlrev_b32_e32 v64, 16, v79
	v_mul_f32_e32 v63, 0xbfb8aa3b, v63
	v_exp_f32_e32 v62, v62
	v_pk_mul_f32 v[64:65], v[58:59], v[64:65]
	v_add_f32_e32 v58, v61, v221
	v_exp_f32_e32 v63, v63
	v_mul_f32_e32 v58, 0xbfb8aa3b, v58
	v_exp_f32_e32 v58, v58
	v_add_f32_e32 v62, 1.0, v62
	v_add_f32_e32 v63, 1.0, v63
	v_rcp_f32_e32 v62, v62
	v_rcp_f32_e32 v63, v63
	v_add_f32_e32 v58, 1.0, v58
	v_rcp_f32_e32 v61, v58
	v_and_b32_e32 v91, 0xffff0000, v78
	v_lshlrev_b32_e32 v90, 16, v78
	v_pk_mul_f32 v[62:63], v[62:63], v[90:91]
	v_and_b32_e32 v59, 0xffff0000, v81
	v_lshlrev_b32_e32 v58, 16, v81
	v_pk_mul_f32 v[78:79], v[60:61], v[58:59]
	v_cvt_pk_bf16_f32 v58, v62, v63
	v_lshl_add_u64 v[62:63], s[64:65], 0, v[88:89]
	v_cvt_pk_bf16_f32 v59, v64, v65
	v_cvt_pk_bf16_f32 v60, v82, v83
	v_cvt_pk_bf16_f32 v61, v78, v79
	v_lshl_add_u64 v[62:63], v[62:63], 0, v[176:177]
	global_store_dwordx4 v[62:63], v[58:61], off
	s_nop 0
	v_and_b32_e32 v65, 0xffff0000, v74
	v_lshlrev_b32_e32 v64, 16, v74
	v_add_f32_e32 v50, v50, v226
	v_add_f32_e32 v51, v51, v227
	v_mul_f32_e32 v50, 0xbfb8aa3b, v50
	v_mul_f32_e32 v51, 0xbfb8aa3b, v51
	v_add_f32_e32 v56, v56, v224
	v_add_f32_e32 v57, v57, v225
	v_add_f32_e32 v54, v54, v222
	v_exp_f32_e32 v50, v50
	v_add_f32_e32 v55, v55, v223
	v_exp_f32_e32 v51, v51
	v_mul_f32_e32 v56, 0xbfb8aa3b, v56
	v_add_f32_e32 v52, v52, v228
	v_mul_f32_e32 v57, 0xbfb8aa3b, v57
	v_add_f32_e32 v53, v53, v229
	v_mul_f32_e32 v54, 0xbfb8aa3b, v54
	v_mul_f32_e32 v55, 0xbfb8aa3b, v55
	v_exp_f32_e32 v56, v56
	v_mul_f32_e32 v52, 0xbfb8aa3b, v52
	v_exp_f32_e32 v57, v57
	v_mul_f32_e32 v53, 0xbfb8aa3b, v53
	v_exp_f32_e32 v54, v54
	v_exp_f32_e32 v55, v55
	v_exp_f32_e32 v52, v52
	v_exp_f32_e32 v53, v53
	v_add_f32_e32 v50, 1.0, v50
	v_add_f32_e32 v51, 1.0, v51
	v_rcp_f32_e32 v50, v50
	v_rcp_f32_e32 v51, v51
	v_add_f32_e32 v56, 1.0, v56
	v_add_f32_e32 v57, 1.0, v57
	v_add_f32_e32 v54, 1.0, v54
	v_add_f32_e32 v55, 1.0, v55
	v_rcp_f32_e32 v56, v56
	v_add_f32_e32 v52, 1.0, v52
	v_rcp_f32_e32 v57, v57
	v_add_f32_e32 v53, 1.0, v53
	v_rcp_f32_e32 v54, v54
	v_rcp_f32_e32 v55, v55
	v_rcp_f32_e32 v52, v52
	v_rcp_f32_e32 v53, v53
	v_and_b32_e32 v59, 0xffff0000, v76
	v_lshlrev_b32_e32 v58, 16, v76
	v_pk_mul_f32 v[50:51], v[50:51], v[58:59]
	v_and_b32_e32 v59, 0xffff0000, v75
	v_lshlrev_b32_e32 v58, 16, v75
	v_pk_mul_f32 v[56:57], v[56:57], v[58:59]
	v_and_b32_e32 v59, 0xffff0000, v77
	v_lshlrev_b32_e32 v58, 16, v77
	v_pk_mul_f32 v[54:55], v[54:55], v[64:65]
	v_pk_mul_f32 v[58:59], v[52:53], v[58:59]
	v_cvt_pk_bf16_f32 v52, v54, v55
	v_cvt_pk_bf16_f32 v53, v56, v57
	v_cvt_pk_bf16_f32 v54, v50, v51
	v_cvt_pk_bf16_f32 v55, v58, v59
	global_store_dwordx4 v[62:63], v[52:55], off offset:256
	s_nop 0
	v_add_f32_e32 v42, v42, v218
	v_add_f32_e32 v43, v43, v219
	v_mul_f32_e32 v42, 0xbfb8aa3b, v42
	v_mul_f32_e32 v43, 0xbfb8aa3b, v43
	v_exp_f32_e32 v42, v42
	v_exp_f32_e32 v43, v43
	v_and_b32_e32 v51, 0xffff0000, v72
	v_lshlrev_b32_e32 v50, 16, v72
	v_add_f32_e32 v42, 1.0, v42
	v_add_f32_e32 v43, 1.0, v43
	v_rcp_f32_e32 v42, v42
	v_rcp_f32_e32 v43, v43
	v_add_f32_e32 v46, v46, v214
	v_add_f32_e32 v47, v47, v215
	v_mul_f32_e32 v46, 0xbfb8aa3b, v46
	v_pk_mul_f32 v[50:51], v[42:43], v[50:51]
	v_add_f32_e32 v43, v44, v220
	v_mul_f32_e32 v43, 0xbfb8aa3b, v43
	v_exp_f32_e32 v43, v43
	v_add_f32_e32 v42, v48, v216
	v_mul_f32_e32 v42, 0xbfb8aa3b, v42
	v_exp_f32_e32 v42, v42
	v_add_f32_e32 v43, 1.0, v43
	v_rcp_f32_e32 v44, v43
	v_add_f32_e32 v43, v49, v217
	v_mul_f32_e32 v43, 0xbfb8aa3b, v43
	v_exp_f32_e32 v43, v43
	v_add_f32_e32 v42, 1.0, v42
	v_rcp_f32_e32 v42, v42
	v_and_b32_e32 v49, 0xffff0000, v71
	v_add_f32_e32 v43, 1.0, v43
	v_rcp_f32_e32 v43, v43
	v_lshlrev_b32_e32 v48, 16, v71
	v_mul_f32_e32 v47, 0xbfb8aa3b, v47
	v_exp_f32_e32 v46, v46
	v_pk_mul_f32 v[48:49], v[42:43], v[48:49]
	v_add_f32_e32 v42, v45, v221
	v_exp_f32_e32 v47, v47
	v_mul_f32_e32 v42, 0xbfb8aa3b, v42
	v_exp_f32_e32 v42, v42
	v_add_f32_e32 v46, 1.0, v46
	v_add_f32_e32 v47, 1.0, v47
	v_rcp_f32_e32 v46, v46
	v_rcp_f32_e32 v47, v47
	v_add_f32_e32 v42, 1.0, v42
	v_rcp_f32_e32 v45, v42
	v_and_b32_e32 v55, 0xffff0000, v70
	v_lshlrev_b32_e32 v54, 16, v70
	v_pk_mul_f32 v[46:47], v[46:47], v[54:55]
	v_and_b32_e32 v43, 0xffff0000, v73
	v_lshlrev_b32_e32 v42, 16, v73
	v_pk_mul_f32 v[52:53], v[44:45], v[42:43]
	v_cvt_pk_bf16_f32 v42, v46, v47
	v_lshl_add_u64 v[46:47], s[64:65], 0, v[86:87]
	v_cvt_pk_bf16_f32 v43, v48, v49
	v_cvt_pk_bf16_f32 v44, v50, v51
	v_cvt_pk_bf16_f32 v45, v52, v53
	v_lshl_add_u64 v[46:47], v[46:47], 0, v[176:177]
	global_store_dwordx4 v[46:47], v[42:45], off
	s_nop 0
	v_lshl_add_u64 v[56:57], v[178:179], 0, s[0:1]
	s_mov_b64 s[0:1], 0x58000
	v_lshl_add_u64 v[54:55], v[178:179], 0, s[0:1]
; DEVI float bf2f(u16 b) { return __uint_as_float(((unsigned)b) << 16); }
; template <class Epi>
; DEVI void gemm_phase(LAS unsigned char* lds, const Gemm g, const Epi& E) {
;     ...
;                 if constexpr (Epi::PRE) {
; #pragma unroll
;                     for (int m = 0; m < 2; ++m)
; #pragma unroll
;                         for (int bj = 0; bj < 2; ++bj)
; #pragma unroll
;                             for (int n = 0; n < 2; ++n) pre[m][bj][n] = E.load(row0 + ai * HALF + (m0 + m) * 16, col0 + bj * HALF + n * NST);
;                 }
; #pragma unroll
;                 for (int mm = 0; mm < 2; ++mm) {
;                     const int m = m0 + mm;
;                     const int r = row0 + ai * HALF + m * 16; float rs = 1.f, part = 0.f;
;                     if constexpr (Epi::RS) rs = rsv[ai * 4 + m];
;                     if constexpr (Epi::PAIR) E.pair8(cur.b, r, cur.pn * HALF + wc * 32 + 8 * fq, acc[ai][0][m][0] * rs, acc[ai][0][m][1] * rs, acc[ai][1][m][0] * rs, acc[ai][1][m][1] * rs);
;                     else
; #pragma unroll
;                     for (int bj = 0; bj < 2; ++bj) {
;                         const int c = col0 + bj * HALF; f32x4 v0 = acc[ai][bj][m][0], v1 = acc[ai][bj][m][1];
;                         if constexpr (Epi::RS) { v0 = v0 * rs; v1 = v1 * rs; }
;                         if constexpr (Epi::PRE) part += E.frag_pre8(cur.b, r, c, v0, v1, pre[mm][bj][0], pre[mm][bj][1]);
;                         else if constexpr (Epi::PERM) E.frag8(cur.b, r, c, v0, v1);
;                         else { E.frag(cur.b, r, c, v0); E.frag(cur.b, r, c + 16, v1); }
;     DEVI f32x4 load(int r, int c) const { const bf16x4 y = *(const bf16x4*)(Y + (size_t)r * DM + c); return (f32x4){bf2f((u16)y[0]), bf2f((u16)y[1]), bf2f((u16)y[2]), bf2f((u16)y[3])}; }
	s_mov_b32 s0, s4
	v_add_f32_e32 v34, v34, v226
	v_add_f32_e32 v35, v35, v227
	v_mul_f32_e32 v34, 0xbfb8aa3b, v34
	v_mul_f32_e32 v35, 0xbfb8aa3b, v35
	v_exp_f32_e32 v34, v34
	v_exp_f32_e32 v35, v35
	v_and_b32_e32 v43, 0xffff0000, v68
	v_lshlrev_b32_e32 v42, 16, v68
	v_add_f32_e32 v34, 1.0, v34
	v_add_f32_e32 v35, 1.0, v35
	v_rcp_f32_e32 v34, v34
	v_rcp_f32_e32 v35, v35
	v_add_f32_e32 v38, v38, v222
	v_add_f32_e32 v39, v39, v223
	v_mul_f32_e32 v38, 0xbfb8aa3b, v38
	v_pk_mul_f32 v[42:43], v[34:35], v[42:43]
	v_add_f32_e32 v35, v36, v228
	v_mul_f32_e32 v35, 0xbfb8aa3b, v35
	v_exp_f32_e32 v35, v35
	v_add_f32_e32 v34, v40, v224
	v_mul_f32_e32 v34, 0xbfb8aa3b, v34
	v_exp_f32_e32 v34, v34
	v_add_f32_e32 v35, 1.0, v35
	v_rcp_f32_e32 v36, v35
	v_add_f32_e32 v35, v41, v225
	v_mul_f32_e32 v35, 0xbfb8aa3b, v35
	v_exp_f32_e32 v35, v35
	v_add_f32_e32 v34, 1.0, v34
	v_rcp_f32_e32 v34, v34
	v_and_b32_e32 v41, 0xffff0000, v67
	v_add_f32_e32 v35, 1.0, v35
	v_rcp_f32_e32 v35, v35
	v_lshlrev_b32_e32 v40, 16, v67
	v_mul_f32_e32 v39, 0xbfb8aa3b, v39
	v_exp_f32_e32 v38, v38
	v_pk_mul_f32 v[40:41], v[34:35], v[40:41]
	v_add_f32_e32 v34, v37, v229
	v_mul_f32_e32 v34, 0xbfb8aa3b, v34
	v_exp_f32_e32 v39, v39
	v_exp_f32_e32 v34, v34
	v_add_f32_e32 v38, 1.0, v38
	v_rcp_f32_e32 v38, v38
	v_add_f32_e32 v39, 1.0, v39
	v_add_f32_e32 v34, 1.0, v34
	v_rcp_f32_e32 v39, v39
	v_rcp_f32_e32 v37, v34
	v_and_b32_e32 v49, 0xffff0000, v66
	v_lshlrev_b32_e32 v48, 16, v66
	v_and_b32_e32 v35, 0xffff0000, v69
	v_lshlrev_b32_e32 v34, 16, v69
	v_pk_mul_f32 v[38:39], v[38:39], v[48:49]
	v_pk_mul_f32 v[44:45], v[36:37], v[34:35]
	v_cvt_pk_bf16_f32 v34, v38, v39
	v_cvt_pk_bf16_f32 v35, v40, v41
	v_cvt_pk_bf16_f32 v36, v42, v43
	v_cvt_pk_bf16_f32 v37, v44, v45
	global_store_dwordx4 v[46:47], v[34:37], off offset:256
	s_nop 1
	v_lshl_add_u64 v[34:35], s[24:25], 0, v[56:57]
	v_lshl_add_u64 v[34:35], v[34:35], 0, v[176:177]
	global_load_dwordx4 v[46:49], v[34:35], off
	global_load_dwordx4 v[42:45], v[34:35], off offset:256
	v_lshl_add_u64 v[34:35], s[24:25], 0, v[54:55]
	v_lshl_add_u64 v[34:35], v[34:35], 0, v[176:177]
	global_load_dwordx4 v[38:41], v[34:35], off
	s_nop 0
	global_load_dwordx4 v[34:37], v[34:35], off offset:256
	s_nop 0
	s_waitcnt vmcnt(0)
	v_add_f32_e32 v26, v26, v218
	v_add_f32_e32 v27, v27, v219
	v_mul_f32_e32 v26, 0xbfb8aa3b, v26
	v_mul_f32_e32 v27, 0xbfb8aa3b, v27
	v_exp_f32_e32 v26, v26
	v_exp_f32_e32 v27, v27
	v_and_b32_e32 v51, 0xffff0000, v48
	v_lshlrev_b32_e32 v50, 16, v48
	v_add_f32_e32 v26, 1.0, v26
	v_add_f32_e32 v27, 1.0, v27
	v_rcp_f32_e32 v26, v26
	v_rcp_f32_e32 v27, v27
	v_add_f32_e32 v30, v30, v214
	v_add_f32_e32 v31, v31, v215
	v_mul_f32_e32 v30, 0xbfb8aa3b, v30
	v_pk_mul_f32 v[50:51], v[26:27], v[50:51]
	v_add_f32_e32 v27, v28, v220
	v_mul_f32_e32 v27, 0xbfb8aa3b, v27
	v_exp_f32_e32 v27, v27
	v_add_f32_e32 v26, v32, v216
	v_mul_f32_e32 v26, 0xbfb8aa3b, v26
	v_exp_f32_e32 v26, v26
	v_add_f32_e32 v27, 1.0, v27
	v_rcp_f32_e32 v28, v27
	v_add_f32_e32 v27, v33, v217
	v_mul_f32_e32 v27, 0xbfb8aa3b, v27
	v_exp_f32_e32 v27, v27
	v_add_f32_e32 v26, 1.0, v26
	v_rcp_f32_e32 v26, v26
	v_and_b32_e32 v33, 0xffff0000, v47
	v_add_f32_e32 v27, 1.0, v27
	v_rcp_f32_e32 v27, v27
	v_lshlrev_b32_e32 v32, 16, v47
	v_mul_f32_e32 v31, 0xbfb8aa3b, v31
	v_exp_f32_e32 v30, v30
	v_pk_mul_f32 v[32:33], v[26:27], v[32:33]
	v_add_f32_e32 v26, v29, v221
	v_exp_f32_e32 v31, v31
	v_mul_f32_e32 v26, 0xbfb8aa3b, v26
	v_exp_f32_e32 v26, v26
	v_add_f32_e32 v30, 1.0, v30
	v_add_f32_e32 v31, 1.0, v31
	v_rcp_f32_e32 v30, v30
	v_rcp_f32_e32 v31, v31
	v_add_f32_e32 v26, 1.0, v26
	v_rcp_f32_e32 v29, v26
	v_and_b32_e32 v59, 0xffff0000, v46
	v_lshlrev_b32_e32 v58, 16, v46
	v_pk_mul_f32 v[30:31], v[30:31], v[58:59]
	v_and_b32_e32 v27, 0xffff0000, v49
	v_lshlrev_b32_e32 v26, 16, v49
	v_pk_mul_f32 v[46:47], v[28:29], v[26:27]
	v_cvt_pk_bf16_f32 v26, v30, v31
	v_lshl_add_u64 v[30:31], s[64:65], 0, v[56:57]
	v_cvt_pk_bf16_f32 v27, v32, v33
	v_cvt_pk_bf16_f32 v28, v50, v51
	v_cvt_pk_bf16_f32 v29, v46, v47
	v_lshl_add_u64 v[30:31], v[30:31], 0, v[176:177]
	global_store_dwordx4 v[30:31], v[26:29], off
	s_nop 0
	v_and_b32_e32 v33, 0xffff0000, v42
	v_lshlrev_b32_e32 v32, 16, v42
	v_add_f32_e32 v18, v18, v226
	v_add_f32_e32 v19, v19, v227
	v_mul_f32_e32 v18, 0xbfb8aa3b, v18
	v_mul_f32_e32 v19, 0xbfb8aa3b, v19
	v_add_f32_e32 v24, v24, v224
	v_add_f32_e32 v25, v25, v225
	v_add_f32_e32 v22, v22, v222
	v_exp_f32_e32 v18, v18
	v_add_f32_e32 v23, v23, v223
	v_exp_f32_e32 v19, v19
	v_mul_f32_e32 v24, 0xbfb8aa3b, v24
	v_add_f32_e32 v20, v20, v228
	v_mul_f32_e32 v25, 0xbfb8aa3b, v25
	v_add_f32_e32 v21, v21, v229
	v_mul_f32_e32 v22, 0xbfb8aa3b, v22
	v_mul_f32_e32 v23, 0xbfb8aa3b, v23
	v_exp_f32_e32 v24, v24
	v_mul_f32_e32 v20, 0xbfb8aa3b, v20
	v_exp_f32_e32 v25, v25
; #define PG8_WAIT_V(n) asm volatile("s_waitcnt vmcnt(" #n ")" ::: "memory")
; #define PG8_BAR __builtin_amdgcn_s_barrier()
;     DEVI f32x4 load(int r, int c) const { const bf16x4 y = *(const bf16x4*)(Y + (size_t)r * DM + c); return (f32x4){bf2f((u16)y[0]), bf2f((u16)y[1]), bf2f((u16)y[2]), bf2f((u16)y[3])}; }
; template <class Epi>
; DEVI void gemm_phase(LAS unsigned char* lds, const Gemm g, const Epi& E) {
;     ...
;                 if constexpr (Epi::PRE) {
; #pragma unroll
;                     for (int m = 0; m < 2; ++m)
; #pragma unroll
;                         for (int bj = 0; bj < 2; ++bj)
; #pragma unroll
;                             for (int n = 0; n < 2; ++n) pre[m][bj][n] = E.load(row0 + ai * HALF + (m0 + m) * 16, col0 + bj * HALF + n * NST);
;                 }
; #pragma unroll
;                 for (int mm = 0; mm < 2; ++mm) {
;                     const int m = m0 + mm;
;                     const int r = row0 + ai * HALF + m * 16; float rs = 1.f, part = 0.f;
;                     if constexpr (Epi::RS) rs = rsv[ai * 4 + m];
;                     if constexpr (Epi::PAIR) E.pair8(cur.b, r, cur.pn * HALF + wc * 32 + 8 * fq, acc[ai][0][m][0] * rs, acc[ai][0][m][1] * rs, acc[ai][1][m][0] * rs, acc[ai][1][m][1] * rs);
;                     else
; #pragma unroll
;                     for (int bj = 0; bj < 2; ++bj) {
;                         const int c = col0 + bj * HALF; f32x4 v0 = acc[ai][bj][m][0], v1 = acc[ai][bj][m][1];
;                         if constexpr (Epi::RS) { v0 = v0 * rs; v1 = v1 * rs; }
;                         if constexpr (Epi::PRE) part += E.frag_pre8(cur.b, r, c, v0, v1, pre[mm][bj][0], pre[mm][bj][1]);
;                         else if constexpr (Epi::PERM) E.frag8(cur.b, r, c, v0, v1);
;                         else { E.frag(cur.b, r, c, v0); E.frag(cur.b, r, c + 16, v1); }
;     ...
;         if (!has_next) break;
;     ...
;     PG8_WAIT_V(0);
;     if (wr == 0) PG8_BAR;
;     PG8_BAR;
	v_mul_f32_e32 v21, 0xbfb8aa3b, v21
	v_exp_f32_e32 v22, v22
	v_exp_f32_e32 v23, v23
	v_exp_f32_e32 v20, v20
	v_exp_f32_e32 v21, v21
	v_add_f32_e32 v18, 1.0, v18
	v_add_f32_e32 v19, 1.0, v19
	v_rcp_f32_e32 v18, v18
	v_rcp_f32_e32 v19, v19
	v_add_f32_e32 v24, 1.0, v24
	v_add_f32_e32 v25, 1.0, v25
	v_add_f32_e32 v22, 1.0, v22
	v_add_f32_e32 v23, 1.0, v23
	v_rcp_f32_e32 v24, v24
	v_add_f32_e32 v20, 1.0, v20
	v_rcp_f32_e32 v25, v25
	v_add_f32_e32 v21, 1.0, v21
	v_rcp_f32_e32 v22, v22
	v_rcp_f32_e32 v23, v23
	v_rcp_f32_e32 v20, v20
	v_rcp_f32_e32 v21, v21
	v_and_b32_e32 v27, 0xffff0000, v44
	v_lshlrev_b32_e32 v26, 16, v44
	v_pk_mul_f32 v[18:19], v[18:19], v[26:27]
	v_and_b32_e32 v27, 0xffff0000, v43
	v_lshlrev_b32_e32 v26, 16, v43
	v_pk_mul_f32 v[24:25], v[24:25], v[26:27]
	v_and_b32_e32 v27, 0xffff0000, v45
	v_lshlrev_b32_e32 v26, 16, v45
	v_pk_mul_f32 v[22:23], v[22:23], v[32:33]
	v_pk_mul_f32 v[26:27], v[20:21], v[26:27]
	v_cvt_pk_bf16_f32 v20, v22, v23
	v_cvt_pk_bf16_f32 v21, v24, v25
	v_cvt_pk_bf16_f32 v22, v18, v19
	v_cvt_pk_bf16_f32 v23, v26, v27
	global_store_dwordx4 v[30:31], v[20:23], off offset:256
	s_nop 0
	v_add_f32_e32 v10, v10, v218
	v_add_f32_e32 v11, v11, v219
	v_mul_f32_e32 v10, 0xbfb8aa3b, v10
	v_mul_f32_e32 v11, 0xbfb8aa3b, v11
	v_exp_f32_e32 v10, v10
	v_exp_f32_e32 v11, v11
	v_and_b32_e32 v19, 0xffff0000, v40
	v_lshlrev_b32_e32 v18, 16, v40
	v_add_f32_e32 v10, 1.0, v10
	v_add_f32_e32 v11, 1.0, v11
	v_rcp_f32_e32 v10, v10
	v_rcp_f32_e32 v11, v11
	v_add_f32_e32 v14, v14, v214
	v_add_f32_e32 v15, v15, v215
	v_mul_f32_e32 v14, 0xbfb8aa3b, v14
	v_pk_mul_f32 v[18:19], v[10:11], v[18:19]
	v_add_f32_e32 v11, v12, v220
	v_mul_f32_e32 v11, 0xbfb8aa3b, v11
	v_exp_f32_e32 v11, v11
	v_add_f32_e32 v10, v16, v216
	v_mul_f32_e32 v10, 0xbfb8aa3b, v10
	v_exp_f32_e32 v10, v10
	v_add_f32_e32 v11, 1.0, v11
	v_rcp_f32_e32 v12, v11
	v_add_f32_e32 v11, v17, v217
	v_mul_f32_e32 v11, 0xbfb8aa3b, v11
	v_exp_f32_e32 v11, v11
	v_add_f32_e32 v10, 1.0, v10
	v_rcp_f32_e32 v10, v10
	v_and_b32_e32 v17, 0xffff0000, v39
	v_add_f32_e32 v11, 1.0, v11
	v_rcp_f32_e32 v11, v11
	v_lshlrev_b32_e32 v16, 16, v39
	v_mul_f32_e32 v15, 0xbfb8aa3b, v15
	v_exp_f32_e32 v14, v14
	v_pk_mul_f32 v[16:17], v[10:11], v[16:17]
	v_add_f32_e32 v10, v13, v221
	v_exp_f32_e32 v15, v15
	v_mul_f32_e32 v10, 0xbfb8aa3b, v10
	v_exp_f32_e32 v10, v10
	v_add_f32_e32 v14, 1.0, v14
	v_add_f32_e32 v15, 1.0, v15
	v_rcp_f32_e32 v14, v14
	v_rcp_f32_e32 v15, v15
	v_add_f32_e32 v10, 1.0, v10
	v_rcp_f32_e32 v13, v10
	v_and_b32_e32 v23, 0xffff0000, v38
	v_lshlrev_b32_e32 v22, 16, v38
	v_pk_mul_f32 v[14:15], v[14:15], v[22:23]
	v_and_b32_e32 v11, 0xffff0000, v41
	v_lshlrev_b32_e32 v10, 16, v41
	v_pk_mul_f32 v[20:21], v[12:13], v[10:11]
	v_cvt_pk_bf16_f32 v10, v14, v15
	v_lshl_add_u64 v[14:15], s[64:65], 0, v[54:55]
	v_cvt_pk_bf16_f32 v11, v16, v17
	v_cvt_pk_bf16_f32 v12, v18, v19
	v_cvt_pk_bf16_f32 v13, v20, v21
	v_lshl_add_u64 v[14:15], v[14:15], 0, v[176:177]
	global_store_dwordx4 v[14:15], v[10:13], off
	s_nop 0
	v_add_f32_e32 v0, v0, v226
	v_add_f32_e32 v1, v1, v227
	v_mul_f32_e32 v0, 0xbfb8aa3b, v0
	v_mul_f32_e32 v1, 0xbfb8aa3b, v1
	v_exp_f32_e32 v0, v0
	v_exp_f32_e32 v1, v1
	v_and_b32_e32 v11, 0xffff0000, v36
	v_lshlrev_b32_e32 v10, 16, v36
	v_add_f32_e32 v0, 1.0, v0
	v_add_f32_e32 v1, 1.0, v1
	v_rcp_f32_e32 v0, v0
	v_rcp_f32_e32 v1, v1
	v_add_f32_e32 v4, v4, v222
	v_add_f32_e32 v5, v5, v223
	v_mul_f32_e32 v4, 0xbfb8aa3b, v4
	v_pk_mul_f32 v[10:11], v[0:1], v[10:11]
	v_add_f32_e32 v1, v2, v228
	v_mul_f32_e32 v1, 0xbfb8aa3b, v1
	v_exp_f32_e32 v1, v1
	v_add_f32_e32 v0, v6, v224
	v_mul_f32_e32 v0, 0xbfb8aa3b, v0
	v_exp_f32_e32 v0, v0
	v_add_f32_e32 v1, 1.0, v1
	v_rcp_f32_e32 v2, v1
	v_add_f32_e32 v1, v7, v225
	v_mul_f32_e32 v1, 0xbfb8aa3b, v1
	v_exp_f32_e32 v1, v1
	v_add_f32_e32 v0, 1.0, v0
	v_rcp_f32_e32 v0, v0
	v_and_b32_e32 v7, 0xffff0000, v35
	v_add_f32_e32 v1, 1.0, v1
	v_rcp_f32_e32 v1, v1
	v_lshlrev_b32_e32 v6, 16, v35
	v_mul_f32_e32 v5, 0xbfb8aa3b, v5
	v_exp_f32_e32 v4, v4
	v_pk_mul_f32 v[6:7], v[0:1], v[6:7]
	v_add_f32_e32 v0, v3, v229
	v_mul_f32_e32 v0, 0xbfb8aa3b, v0
	v_exp_f32_e32 v5, v5
	v_exp_f32_e32 v0, v0
	v_add_f32_e32 v4, 1.0, v4
	v_rcp_f32_e32 v4, v4
	v_add_f32_e32 v5, 1.0, v5
	v_add_f32_e32 v0, 1.0, v0
	v_rcp_f32_e32 v5, v5
	v_rcp_f32_e32 v3, v0
	v_and_b32_e32 v17, 0xffff0000, v34
	v_lshlrev_b32_e32 v16, 16, v34
	v_and_b32_e32 v1, 0xffff0000, v37
	v_lshlrev_b32_e32 v0, 16, v37
	v_pk_mul_f32 v[4:5], v[4:5], v[16:17]
	v_pk_mul_f32 v[12:13], v[2:3], v[0:1]
	v_cvt_pk_bf16_f32 v0, v4, v5
	v_cvt_pk_bf16_f32 v1, v6, v7
	v_cvt_pk_bf16_f32 v2, v10, v11
	v_cvt_pk_bf16_f32 v3, v12, v13
	global_store_dwordx4 v[14:15], v[0:3], off offset:256
	s_cbranch_vccz .LBB0_1339
	s_waitcnt vmcnt(0)
	s_cmpk_gt_u32 s46, 0xff
	s_cbranch_scc1 .LBB0_1350
	s_barrier

; #define PG8_STAGE(bufoff, gbase, voff) do { _Pragma("unroll") for (int _i = 0; _i < 2; ++_i) \
;         __builtin_amdgcn_global_load_lds((const unsigned*)((const char*)(gbase) + (voff)[_i]), (LAS unsigned*)(lds + (bufoff) + ldsw + _i * 8192), 16, 0, 0); } while (0)
; #define PG8_LDA(dst, b, h) do { _Pragma("unroll") for (int m = 0; m < 4; ++m) _Pragma("unroll") for (int k = 0; k < 2; ++k) dst[m][k] = *(const LAS bf16x8*)(lds + PG8_SA(b, h) + aoff + m * 2048 + k * 1024); } while (0)
; #define PG8_WAIT_V(n) asm volatile("s_waitcnt vmcnt(" #n ")" ::: "memory")
; #define PG8_WAIT_L(n) asm volatile("s_waitcnt lgkmcnt(" #n ")" ::: "memory")
; template <class Epi>
; DEVI void gemm_phase(LAS unsigned char* lds, const Gemm g, const Epi& E) {
;     ...
;         for (int t = 0; t < nt; t += 2) {
;             const bool last = (t == nt - 2);
;             const char* a1 = cA + (size_t)(t + 1) * kstep;
;             const char* a2 = last ? nA : cA + (size_t)(t + 2) * kstep; const char* b2 = last ? nB : cB + (size_t)(t + 2) * kstep;
;             const char* a3 = a2 + kstep; const char* b3 = b2 + kstep;
;             PG8_LDB(B0, 0, 0); PG8_SCHED; PG8_LDA(At, 0, 0); PG8_STAGE(PG8_SA(1, 1), a1 + hstepA, voffA);
;             PG8_WAIT_L(8); PG8_BAR; PG8_WAIT_L(0); PG8_MMA(0, 0, At, B0); PG8_BAR; PG8_SCHED;
;             PG8_LDB(B1, 0, 1); PG8_STAGE(PG8_SB(0, 0), b2, voffB);
;             PG8_BAR; PG8_WAIT_L(0); PG8_MMA(0, 1, At, B1); PG8_BAR;
;             PG8_LDA(At, 0, 1); PG8_STAGE(PG8_SA(0, 0), a2, voffA);
;             PG8_BAR; PG8_WAIT_L(0); PG8_MMA(1, 0, At, B0); PG8_BAR; PG8_SCHED;
;             PG8_STAGE(PG8_SB(0, 1), b2 + hstepB, voffB);
;             PG8_WAIT_V(6); PG8_BAR; PG8_MMA(1, 1, At, B1); PG8_BAR;
;             PG8_LDB(B0, 1, 0); PG8_SCHED; PG8_LDA(At, 1, 0); PG8_STAGE(PG8_SA(0, 1), a2 + hstepA, voffA);
;             PG8_WAIT_L(8); PG8_BAR; PG8_WAIT_L(0); PG8_MMA(0, 0, At, B0); PG8_BAR; PG8_SCHED;
;             PG8_LDB(B1, 1, 1); PG8_STAGE(PG8_SB(1, 0), b3, voffB);
;             PG8_BAR; PG8_WAIT_L(0); PG8_MMA(0, 1, At, B1); PG8_BAR;
;             PG8_LDA(At, 1, 1); PG8_STAGE(PG8_SA(1, 0), a3, voffA);
;             PG8_BAR; PG8_WAIT_L(0); PG8_MMA(1, 0, At, B0); PG8_BAR; PG8_SCHED;
;             PG8_STAGE(PG8_SB(1, 1), b3 + hstepB, voffB);
;             PG8_WAIT_V(6); PG8_BAR; PG8_MMA(1, 1, At, B1); PG8_BAR;
;         }
.LBB0_1507:
	s_add_u32 s19, s6, 0xfffc0080
	s_addc_u32 s26, s7, -1
	s_add_i32 s27, 0, 0x10000
	v_add_u32_e32 v142, s27, v199
	ds_read_b128 v[130:133], v142
	ds_read_b128 v[134:137], v142 offset:1024
	ds_read_b128 v[138:141], v142 offset:2048
	ds_read_b128 v[142:145], v142 offset:3072
	s_cmp_eq_u32 s18, 12
	s_cselect_b32 s79, s0, s26
	s_cselect_b32 s78, s1, s19
	s_cselect_b32 s69, s15, s13
	s_cselect_b32 s68, s14, s11
	s_add_i32 m0, s37, 0xc000
	ds_read_b128 v[146:149], v202
	ds_read_b128 v[150:153], v202 offset:1024
	ds_read_b128 v[186:189], v202 offset:2048
	ds_read_b128 v[190:193], v202 offset:3072
	ds_read_b128 v[194:197], v202 offset:4096
	ds_read_b128 v[204:207], v202 offset:5120
	ds_read_b128 v[214:217], v202 offset:6144
	ds_read_b128 v[218:221], v202 offset:7168
	global_load_lds_dwordx4 v182, s[6:7]
	s_add_i32 m0, s37, 0xe000
	s_nop 0
	global_load_lds_dwordx4 v184, s[6:7]
	s_waitcnt lgkmcnt(8)
	s_barrier
	s_waitcnt lgkmcnt(0)
	v_mfma_f32_16x16x32_bf16 v[126:129], v[130:133], v[146:149], v[126:129]
	v_mfma_f32_16x16x32_bf16 v[122:125], v[138:141], v[146:149], v[122:125]
	v_mfma_f32_16x16x32_bf16 v[110:113], v[130:133], v[186:189], v[110:113]
	v_mfma_f32_16x16x32_bf16 v[106:109], v[138:141], v[186:189], v[106:109]
	v_mfma_f32_16x16x32_bf16 v[94:97], v[130:133], v[194:197], v[94:97]
	v_mfma_f32_16x16x32_bf16 v[90:93], v[138:141], v[194:197], v[90:93]
	v_mfma_f32_16x16x32_bf16 v[78:81], v[130:133], v[214:217], v[78:81]
	v_mfma_f32_16x16x32_bf16 v[74:77], v[138:141], v[214:217], v[74:77]
	v_mfma_f32_16x16x32_bf16 v[126:129], v[134:137], v[150:153], v[126:129]
	v_mfma_f32_16x16x32_bf16 v[122:125], v[142:145], v[150:153], v[122:125]
	v_mfma_f32_16x16x32_bf16 v[110:113], v[134:137], v[190:193], v[110:113]
	v_mfma_f32_16x16x32_bf16 v[106:109], v[142:145], v[190:193], v[106:109]
	v_mfma_f32_16x16x32_bf16 v[94:97], v[134:137], v[204:207], v[94:97]
	v_mfma_f32_16x16x32_bf16 v[90:93], v[142:145], v[204:207], v[90:93]
	v_mfma_f32_16x16x32_bf16 v[78:81], v[134:137], v[218:221], v[78:81]
	v_mfma_f32_16x16x32_bf16 v[74:77], v[142:145], v[218:221], v[74:77]
	s_barrier
	s_add_i32 s19, 0, 0x14000
	v_add_u32_e32 v162, s19, v199
	s_add_i32 s26, s27, s80
	ds_read_b128 v[222:225], v162
	ds_read_b128 v[226:229], v162 offset:1024
	ds_read_b128 v[230:233], v162 offset:2048
	ds_read_b128 v[234:237], v162 offset:3072
	v_lshl_add_u64 v[162:163], s[68:69], 0, v[8:9]
	s_mov_b32 m0, s26
	v_lshl_add_u64 v[164:165], s[68:69], 0, v[180:181]
	global_load_lds_dwordx4 v[162:163], off
	s_add_i32 m0, s26, 0x2000
	s_nop 0
	global_load_lds_dwordx4 v[164:165], off
	s_barrier
	s_waitcnt lgkmcnt(0)
	v_mfma_f32_16x16x32_bf16 v[118:121], v[222:225], v[146:149], v[118:121]
	v_mfma_f32_16x16x32_bf16 v[114:117], v[230:233], v[146:149], v[114:117]
	v_mfma_f32_16x16x32_bf16 v[102:105], v[222:225], v[186:189], v[102:105]
	v_mfma_f32_16x16x32_bf16 v[98:101], v[230:233], v[186:189], v[98:101]
	v_mfma_f32_16x16x32_bf16 v[86:89], v[222:225], v[194:197], v[86:89]
	v_mfma_f32_16x16x32_bf16 v[82:85], v[230:233], v[194:197], v[82:85]
	v_mfma_f32_16x16x32_bf16 v[70:73], v[222:225], v[214:217], v[70:73]
	v_mfma_f32_16x16x32_bf16 v[62:65], v[230:233], v[214:217], v[62:65]
	v_mfma_f32_16x16x32_bf16 v[118:121], v[226:229], v[150:153], v[118:121]
	v_mfma_f32_16x16x32_bf16 v[114:117], v[234:237], v[150:153], v[114:117]
	v_mfma_f32_16x16x32_bf16 v[102:105], v[226:229], v[190:193], v[102:105]
	v_mfma_f32_16x16x32_bf16 v[98:101], v[234:237], v[190:193], v[98:101]
	v_mfma_f32_16x16x32_bf16 v[86:89], v[226:229], v[204:207], v[86:89]
	v_mfma_f32_16x16x32_bf16 v[82:85], v[234:237], v[204:207], v[82:85]
	v_mfma_f32_16x16x32_bf16 v[70:73], v[226:229], v[218:221], v[70:73]
	v_mfma_f32_16x16x32_bf16 v[62:65], v[234:237], v[218:221], v[62:65]
	s_mov_b32 m0, s37
	v_lshl_add_u64 v[208:209], s[78:79], 0, v[176:177]
	s_barrier
	ds_read_b128 v[146:149], v202 offset:16384
	ds_read_b128 v[150:153], v202 offset:17408
	ds_read_b128 v[186:189], v202 offset:18432
	ds_read_b128 v[190:193], v202 offset:19456
	ds_read_b128 v[194:197], v202 offset:20480
	ds_read_b128 v[204:207], v202 offset:21504
	ds_read_b128 v[214:217], v202 offset:22528
	ds_read_b128 v[218:221], v202 offset:23552
	global_load_lds_dwordx4 v[208:209], off
	s_mov_b32 m0, s47
	v_lshl_add_u64 v[238:239], s[78:79], 0, v[178:179]
	global_load_lds_dwordx4 v[238:239], off
	s_barrier
	s_waitcnt lgkmcnt(0)
	v_mfma_f32_16x16x32_bf16 v[66:69], v[130:133], v[146:149], v[66:69]
	v_mfma_f32_16x16x32_bf16 v[54:57], v[138:141], v[146:149], v[54:57]
	v_mfma_f32_16x16x32_bf16 v[46:49], v[130:133], v[186:189], v[46:49]
	v_mfma_f32_16x16x32_bf16 v[38:41], v[138:141], v[186:189], v[38:41]
	v_mfma_f32_16x16x32_bf16 v[30:33], v[130:133], v[194:197], v[30:33]
	v_mfma_f32_16x16x32_bf16 v[22:25], v[138:141], v[194:197], v[22:25]
	v_mfma_f32_16x16x32_bf16 v[14:17], v[130:133], v[214:217], v[14:17]
	v_mfma_f32_16x16x32_bf16 v[4:7], v[138:141], v[214:217], v[4:7]
	v_mfma_f32_16x16x32_bf16 v[66:69], v[134:137], v[150:153], v[66:69]
	v_mfma_f32_16x16x32_bf16 v[54:57], v[142:145], v[150:153], v[54:57]
	v_mfma_f32_16x16x32_bf16 v[46:49], v[134:137], v[190:193], v[46:49]
	v_mfma_f32_16x16x32_bf16 v[38:41], v[142:145], v[190:193], v[38:41]
	v_mfma_f32_16x16x32_bf16 v[30:33], v[134:137], v[204:207], v[30:33]
	v_mfma_f32_16x16x32_bf16 v[22:25], v[142:145], v[204:207], v[22:25]
	v_mfma_f32_16x16x32_bf16 v[14:17], v[134:137], v[218:221], v[14:17]
	v_mfma_f32_16x16x32_bf16 v[4:7], v[142:145], v[218:221], v[4:7]
	s_barrier
	s_add_u32 s26, s68, 0x40000
	s_addc_u32 s27, s69, 0
	s_add_i32 s19, s19, s80
	s_mov_b32 m0, s19
	s_nop 0
	global_load_lds_dwordx4 v8, s[26:27]
	s_add_i32 m0, s19, 0x2000
	s_nop 0
	global_load_lds_dwordx4 v180, s[26:27]
	s_waitcnt vmcnt(6)
	s_barrier
; #define PG8_STAGE(bufoff, gbase, voff) do { _Pragma("unroll") for (int _i = 0; _i < 2; ++_i) \
;         __builtin_amdgcn_global_load_lds((const unsigned*)((const char*)(gbase) + (voff)[_i]), (LAS unsigned*)(lds + (bufoff) + ldsw + _i * 8192), 16, 0, 0); } while (0)
; #define PG8_LDA(dst, b, h) do { _Pragma("unroll") for (int m = 0; m < 4; ++m) _Pragma("unroll") for (int k = 0; k < 2; ++k) dst[m][k] = *(const LAS bf16x8*)(lds + PG8_SA(b, h) + aoff + m * 2048 + k * 1024); } while (0)
; #define PG8_WAIT_V(n) asm volatile("s_waitcnt vmcnt(" #n ")" ::: "memory")
; #define PG8_WAIT_L(n) asm volatile("s_waitcnt lgkmcnt(" #n ")" ::: "memory")
; template <class Epi>
; DEVI void gemm_phase(LAS unsigned char* lds, const Gemm g, const Epi& E) {
;     ...
;         for (int t = 0; t < nt; t += 2) {
;             const bool last = (t == nt - 2);
;             const char* a1 = cA + (size_t)(t + 1) * kstep;
;             const char* a2 = last ? nA : cA + (size_t)(t + 2) * kstep; const char* b2 = last ? nB : cB + (size_t)(t + 2) * kstep;
;             const char* a3 = a2 + kstep; const char* b3 = b2 + kstep;
;             PG8_LDB(B0, 0, 0); PG8_SCHED; PG8_LDA(At, 0, 0); PG8_STAGE(PG8_SA(1, 1), a1 + hstepA, voffA);
;             PG8_WAIT_L(8); PG8_BAR; PG8_WAIT_L(0); PG8_MMA(0, 0, At, B0); PG8_BAR; PG8_SCHED;
;             PG8_LDB(B1, 0, 1); PG8_STAGE(PG8_SB(0, 0), b2, voffB);
;             PG8_BAR; PG8_WAIT_L(0); PG8_MMA(0, 1, At, B1); PG8_BAR;
;             PG8_LDA(At, 0, 1); PG8_STAGE(PG8_SA(0, 0), a2, voffA);
;             PG8_BAR; PG8_WAIT_L(0); PG8_MMA(1, 0, At, B0); PG8_BAR; PG8_SCHED;
;             PG8_STAGE(PG8_SB(0, 1), b2 + hstepB, voffB);
;             PG8_WAIT_V(6); PG8_BAR; PG8_MMA(1, 1, At, B1); PG8_BAR;
;             PG8_LDB(B0, 1, 0); PG8_SCHED; PG8_LDA(At, 1, 0); PG8_STAGE(PG8_SA(0, 1), a2 + hstepA, voffA);
;             PG8_WAIT_L(8); PG8_BAR; PG8_WAIT_L(0); PG8_MMA(0, 0, At, B0); PG8_BAR; PG8_SCHED;
;             PG8_LDB(B1, 1, 1); PG8_STAGE(PG8_SB(1, 0), b3, voffB);
;             PG8_BAR; PG8_WAIT_L(0); PG8_MMA(0, 1, At, B1); PG8_BAR;
;             PG8_LDA(At, 1, 1); PG8_STAGE(PG8_SA(1, 0), a3, voffA);
;             PG8_BAR; PG8_WAIT_L(0); PG8_MMA(1, 0, At, B0); PG8_BAR; PG8_SCHED;
;             PG8_STAGE(PG8_SB(1, 1), b3 + hstepB, voffB);
;             PG8_WAIT_V(6); PG8_BAR; PG8_MMA(1, 1, At, B1); PG8_BAR;
;         }
	v_mfma_f32_16x16x32_bf16 v[58:61], v[222:225], v[146:149], v[58:61]
	v_mfma_f32_16x16x32_bf16 v[50:53], v[230:233], v[146:149], v[50:53]
	v_mfma_f32_16x16x32_bf16 v[42:45], v[222:225], v[186:189], v[42:45]
	v_mfma_f32_16x16x32_bf16 v[34:37], v[230:233], v[186:189], v[34:37]
	v_mfma_f32_16x16x32_bf16 v[26:29], v[222:225], v[194:197], v[26:29]
	v_mfma_f32_16x16x32_bf16 v[18:21], v[230:233], v[194:197], v[18:21]
	v_mfma_f32_16x16x32_bf16 v[10:13], v[222:225], v[214:217], v[10:13]
	v_mfma_f32_16x16x32_bf16 v[0:3], v[230:233], v[214:217], v[0:3]
	v_mfma_f32_16x16x32_bf16 v[58:61], v[226:229], v[150:153], v[58:61]
	v_mfma_f32_16x16x32_bf16 v[50:53], v[234:237], v[150:153], v[50:53]
	v_mfma_f32_16x16x32_bf16 v[42:45], v[226:229], v[190:193], v[42:45]
	v_mfma_f32_16x16x32_bf16 v[34:37], v[234:237], v[190:193], v[34:37]
	v_mfma_f32_16x16x32_bf16 v[26:29], v[226:229], v[204:207], v[26:29]
	v_mfma_f32_16x16x32_bf16 v[18:21], v[234:237], v[204:207], v[18:21]
	v_mfma_f32_16x16x32_bf16 v[10:13], v[226:229], v[218:221], v[10:13]
	v_mfma_f32_16x16x32_bf16 v[0:3], v[234:237], v[218:221], v[0:3]
	s_add_i32 s19, 0, 0x18000
	v_add_u32_e32 v142, s19, v199
	s_barrier
	ds_read_b128 v[130:133], v142
	ds_read_b128 v[134:137], v142 offset:1024
	ds_read_b128 v[138:141], v142 offset:2048
	ds_read_b128 v[142:145], v142 offset:3072
	s_add_u32 s26, s78, 0x40000
	s_addc_u32 s27, s79, 0
	s_mov_b32 m0, s81
	ds_read_b128 v[146:149], v202 offset:32768
	ds_read_b128 v[150:153], v202 offset:33792
	ds_read_b128 v[186:189], v202 offset:34816
	ds_read_b128 v[190:193], v202 offset:35840
	ds_read_b128 v[194:197], v202 offset:36864
	ds_read_b128 v[204:207], v202 offset:37888
	ds_read_b128 v[214:217], v202 offset:38912
	ds_read_b128 v[218:221], v202 offset:39936
	global_load_lds_dwordx4 v176, s[26:27]
	s_mov_b32 m0, s82
	s_nop 0
	global_load_lds_dwordx4 v178, s[26:27]
	s_waitcnt lgkmcnt(8)
	s_barrier
	s_waitcnt lgkmcnt(0)
	v_mfma_f32_16x16x32_bf16 v[126:129], v[130:133], v[146:149], v[126:129]
	v_mfma_f32_16x16x32_bf16 v[122:125], v[138:141], v[146:149], v[122:125]
	v_mfma_f32_16x16x32_bf16 v[110:113], v[130:133], v[186:189], v[110:113]
	v_mfma_f32_16x16x32_bf16 v[106:109], v[138:141], v[186:189], v[106:109]
	v_mfma_f32_16x16x32_bf16 v[94:97], v[130:133], v[194:197], v[94:97]
	v_mfma_f32_16x16x32_bf16 v[90:93], v[138:141], v[194:197], v[90:93]
	v_mfma_f32_16x16x32_bf16 v[78:81], v[130:133], v[214:217], v[78:81]
	v_mfma_f32_16x16x32_bf16 v[74:77], v[138:141], v[214:217], v[74:77]
	v_mfma_f32_16x16x32_bf16 v[126:129], v[134:137], v[150:153], v[126:129]
	v_mfma_f32_16x16x32_bf16 v[122:125], v[142:145], v[150:153], v[122:125]
	v_mfma_f32_16x16x32_bf16 v[110:113], v[134:137], v[190:193], v[110:113]
	v_mfma_f32_16x16x32_bf16 v[106:109], v[142:145], v[190:193], v[106:109]
	v_mfma_f32_16x16x32_bf16 v[94:97], v[134:137], v[204:207], v[94:97]
	v_mfma_f32_16x16x32_bf16 v[90:93], v[142:145], v[204:207], v[90:93]
	v_mfma_f32_16x16x32_bf16 v[78:81], v[134:137], v[218:221], v[78:81]
	v_mfma_f32_16x16x32_bf16 v[74:77], v[142:145], v[218:221], v[74:77]
	s_barrier
	s_add_i32 s38, 0, 0x1c000
	s_add_i32 s19, s19, s80
	v_add_u32_e32 v213, s38, v199
	v_lshl_add_u64 v[162:163], v[162:163], 0, s[70:71]
	s_mov_b32 m0, s19
	ds_read_b128 v[222:225], v213
	ds_read_b128 v[226:229], v213 offset:1024
	ds_read_b128 v[230:233], v213 offset:2048
	ds_read_b128 v[234:237], v213 offset:3072
	global_load_lds_dwordx4 v[162:163], off
	s_add_i32 m0, s19, 0x2000
	v_lshl_add_u64 v[162:163], v[164:165], 0, s[70:71]
	global_load_lds_dwordx4 v[162:163], off
	s_barrier
	s_waitcnt lgkmcnt(0)
	v_mfma_f32_16x16x32_bf16 v[118:121], v[222:225], v[146:149], v[118:121]
	v_mfma_f32_16x16x32_bf16 v[114:117], v[230:233], v[146:149], v[114:117]
	v_mfma_f32_16x16x32_bf16 v[102:105], v[222:225], v[186:189], v[102:105]
	v_mfma_f32_16x16x32_bf16 v[98:101], v[230:233], v[186:189], v[98:101]
	v_mfma_f32_16x16x32_bf16 v[86:89], v[222:225], v[194:197], v[86:89]
	v_mfma_f32_16x16x32_bf16 v[82:85], v[230:233], v[194:197], v[82:85]
	v_mfma_f32_16x16x32_bf16 v[70:73], v[222:225], v[214:217], v[70:73]
	v_mfma_f32_16x16x32_bf16 v[62:65], v[230:233], v[214:217], v[62:65]
	v_mfma_f32_16x16x32_bf16 v[118:121], v[226:229], v[150:153], v[118:121]
	v_mfma_f32_16x16x32_bf16 v[114:117], v[234:237], v[150:153], v[114:117]
	v_mfma_f32_16x16x32_bf16 v[102:105], v[226:229], v[190:193], v[102:105]
	v_mfma_f32_16x16x32_bf16 v[98:101], v[234:237], v[190:193], v[98:101]
	v_mfma_f32_16x16x32_bf16 v[86:89], v[226:229], v[204:207], v[86:89]
	v_mfma_f32_16x16x32_bf16 v[82:85], v[234:237], v[204:207], v[82:85]
	v_mfma_f32_16x16x32_bf16 v[70:73], v[226:229], v[218:221], v[70:73]
	v_mfma_f32_16x16x32_bf16 v[62:65], v[234:237], v[218:221], v[62:65]
	s_mov_b32 m0, s83
	v_lshl_add_u64 v[162:163], v[208:209], 0, s[70:71]
	s_barrier
	ds_read_b128 v[146:149], v202 offset:49152
	ds_read_b128 v[150:153], v202 offset:50176
	ds_read_b128 v[186:189], v202 offset:51200
	ds_read_b128 v[190:193], v202 offset:52224
	ds_read_b128 v[194:197], v202 offset:53248
	ds_read_b128 v[204:207], v202 offset:54272
	ds_read_b128 v[214:217], v202 offset:55296
	ds_read_b128 v[218:221], v202 offset:56320
	global_load_lds_dwordx4 v[162:163], off
	s_mov_b32 m0, s84
	v_lshl_add_u64 v[162:163], v[238:239], 0, s[70:71]
	global_load_lds_dwordx4 v[162:163], off
	s_barrier
; #define PG8_STAGE(bufoff, gbase, voff) do { _Pragma("unroll") for (int _i = 0; _i < 2; ++_i) \
;         __builtin_amdgcn_global_load_lds((const unsigned*)((const char*)(gbase) + (voff)[_i]), (LAS unsigned*)(lds + (bufoff) + ldsw + _i * 8192), 16, 0, 0); } while (0)
; #define PG8_LDA(dst, b, h) do { _Pragma("unroll") for (int m = 0; m < 4; ++m) _Pragma("unroll") for (int k = 0; k < 2; ++k) dst[m][k] = *(const LAS bf16x8*)(lds + PG8_SA(b, h) + aoff + m * 2048 + k * 1024); } while (0)
; #define PG8_WAIT_V(n) asm volatile("s_waitcnt vmcnt(" #n ")" ::: "memory")
; #define PG8_WAIT_L(n) asm volatile("s_waitcnt lgkmcnt(" #n ")" ::: "memory")
; template <class Epi>
; DEVI void gemm_phase(LAS unsigned char* lds, const Gemm g, const Epi& E) {
;     ...
;         for (int t = 0; t < nt; t += 2) {
;             const bool last = (t == nt - 2);
;             const char* a1 = cA + (size_t)(t + 1) * kstep;
;             const char* a2 = last ? nA : cA + (size_t)(t + 2) * kstep; const char* b2 = last ? nB : cB + (size_t)(t + 2) * kstep;
;             const char* a3 = a2 + kstep; const char* b3 = b2 + kstep;
;             PG8_LDB(B0, 0, 0); PG8_SCHED; PG8_LDA(At, 0, 0); PG8_STAGE(PG8_SA(1, 1), a1 + hstepA, voffA);
;             PG8_WAIT_L(8); PG8_BAR; PG8_WAIT_L(0); PG8_MMA(0, 0, At, B0); PG8_BAR; PG8_SCHED;
;             PG8_LDB(B1, 0, 1); PG8_STAGE(PG8_SB(0, 0), b2, voffB);
;             PG8_BAR; PG8_WAIT_L(0); PG8_MMA(0, 1, At, B1); PG8_BAR;
;             PG8_LDA(At, 0, 1); PG8_STAGE(PG8_SA(0, 0), a2, voffA);
;             PG8_BAR; PG8_WAIT_L(0); PG8_MMA(1, 0, At, B0); PG8_BAR; PG8_SCHED;
;             PG8_STAGE(PG8_SB(0, 1), b2 + hstepB, voffB);
;             PG8_WAIT_V(6); PG8_BAR; PG8_MMA(1, 1, At, B1); PG8_BAR;
;             PG8_LDB(B0, 1, 0); PG8_SCHED; PG8_LDA(At, 1, 0); PG8_STAGE(PG8_SA(0, 1), a2 + hstepA, voffA);
;             PG8_WAIT_L(8); PG8_BAR; PG8_WAIT_L(0); PG8_MMA(0, 0, At, B0); PG8_BAR; PG8_SCHED;
;             PG8_LDB(B1, 1, 1); PG8_STAGE(PG8_SB(1, 0), b3, voffB);
;             PG8_BAR; PG8_WAIT_L(0); PG8_MMA(0, 1, At, B1); PG8_BAR;
;             PG8_LDA(At, 1, 1); PG8_STAGE(PG8_SA(1, 0), a3, voffA);
;             PG8_BAR; PG8_WAIT_L(0); PG8_MMA(1, 0, At, B0); PG8_BAR; PG8_SCHED;
;             PG8_STAGE(PG8_SB(1, 1), b3 + hstepB, voffB);
;             PG8_WAIT_V(6); PG8_BAR; PG8_MMA(1, 1, At, B1); PG8_BAR;
;         }
	s_waitcnt lgkmcnt(0)
	v_mfma_f32_16x16x32_bf16 v[66:69], v[130:133], v[146:149], v[66:69]
	v_mfma_f32_16x16x32_bf16 v[54:57], v[138:141], v[146:149], v[54:57]
	v_mfma_f32_16x16x32_bf16 v[46:49], v[130:133], v[186:189], v[46:49]
	v_mfma_f32_16x16x32_bf16 v[38:41], v[138:141], v[186:189], v[38:41]
	v_mfma_f32_16x16x32_bf16 v[30:33], v[130:133], v[194:197], v[30:33]
	v_mfma_f32_16x16x32_bf16 v[22:25], v[138:141], v[194:197], v[22:25]
	v_mfma_f32_16x16x32_bf16 v[14:17], v[130:133], v[214:217], v[14:17]
	v_mfma_f32_16x16x32_bf16 v[4:7], v[138:141], v[214:217], v[4:7]
	v_mfma_f32_16x16x32_bf16 v[66:69], v[134:137], v[150:153], v[66:69]
	v_mfma_f32_16x16x32_bf16 v[54:57], v[142:145], v[150:153], v[54:57]
	v_mfma_f32_16x16x32_bf16 v[46:49], v[134:137], v[190:193], v[46:49]
	v_mfma_f32_16x16x32_bf16 v[38:41], v[142:145], v[190:193], v[38:41]
	v_mfma_f32_16x16x32_bf16 v[30:33], v[134:137], v[204:207], v[30:33]
	v_mfma_f32_16x16x32_bf16 v[22:25], v[142:145], v[204:207], v[22:25]
	v_mfma_f32_16x16x32_bf16 v[14:17], v[134:137], v[218:221], v[14:17]
	v_mfma_f32_16x16x32_bf16 v[4:7], v[142:145], v[218:221], v[4:7]
	s_barrier
	s_add_u32 s26, s68, 0x40080
	s_addc_u32 s27, s69, 0
	s_add_i32 s19, s38, s80
	s_mov_b32 m0, s19
	s_nop 0
	global_load_lds_dwordx4 v8, s[26:27]
	s_add_i32 m0, s19, 0x2000
	s_nop 0
	global_load_lds_dwordx4 v180, s[26:27]
	s_waitcnt vmcnt(6)
	s_barrier
	v_mfma_f32_16x16x32_bf16 v[58:61], v[222:225], v[146:149], v[58:61]
	v_mfma_f32_16x16x32_bf16 v[50:53], v[230:233], v[146:149], v[50:53]
	v_mfma_f32_16x16x32_bf16 v[42:45], v[222:225], v[186:189], v[42:45]
	v_mfma_f32_16x16x32_bf16 v[34:37], v[230:233], v[186:189], v[34:37]
	v_mfma_f32_16x16x32_bf16 v[26:29], v[222:225], v[194:197], v[26:29]
	v_mfma_f32_16x16x32_bf16 v[18:21], v[230:233], v[194:197], v[18:21]
	v_mfma_f32_16x16x32_bf16 v[10:13], v[222:225], v[214:217], v[10:13]
	v_mfma_f32_16x16x32_bf16 v[0:3], v[230:233], v[214:217], v[0:3]
	v_mfma_f32_16x16x32_bf16 v[58:61], v[226:229], v[150:153], v[58:61]
	v_mfma_f32_16x16x32_bf16 v[50:53], v[234:237], v[150:153], v[50:53]
	v_mfma_f32_16x16x32_bf16 v[42:45], v[226:229], v[190:193], v[42:45]
	v_mfma_f32_16x16x32_bf16 v[34:37], v[234:237], v[190:193], v[34:37]
	v_mfma_f32_16x16x32_bf16 v[26:29], v[226:229], v[204:207], v[26:29]
	v_mfma_f32_16x16x32_bf16 v[18:21], v[234:237], v[204:207], v[18:21]
	v_mfma_f32_16x16x32_bf16 v[10:13], v[226:229], v[218:221], v[10:13]
	v_mfma_f32_16x16x32_bf16 v[0:3], v[234:237], v[218:221], v[0:3]
	s_add_i32 s18, s18, 2
	s_add_u32 s6, s6, 0x100
	s_addc_u32 s7, s7, 0
	s_add_u32 s11, s11, 0x100
	s_addc_u32 s13, s13, 0
	s_cmp_gt_u32 s18, 13
	s_barrier
	s_cbranch_scc0 .LBB0_1507
; #define LAS __attribute__((address_space(3)))
; template <class Epi>
; DEVI void gemm_phase(LAS unsigned char* lds, const Gemm g, const Epi& E) {
;     ...
;             const int row0 = cur.pm * BM + wr * 64 + fr, col0 = cur.pn * BM + wc * 32 + (Epi::PERM ? 8 : 4) * fq; constexpr int NST = Epi::PERM ? 4 : 16;
;             float rsv[8];
;             if constexpr (Epi::RS) { f32x4 q4[8];
; #pragma unroll
;                 for (int i = 0; i < 8; ++i) q4[i] = *(const f32x4*)(E.ssq_in + (size_t)(row0 + (i >> 2) * HALF + (i & 3) * 16) * 4);
; #pragma unroll
;                 for (int i = 0; i < 8; ++i) rsv[i] = rsqrtf((((q4[i][0] + q4[i][1]) + q4[i][2]) + q4[i][3]) * (1.f / DM) + 1e-6f); }
;             if constexpr (Epi::SOFTMAX) {
;                 LAS float* red = (LAS float*)(lds + 131072);
; #pragma unroll
;                 for (int ai = 0; ai < 2; ++ai)
; #pragma unroll
;                     for (int m = 0; m < 4; ++m) { const float sc = rsv[ai * 4 + m] * 0.0625f; float part = 0.f;
; #pragma unroll
;                         for (int bj = 0; bj < 2; ++bj)
; #pragma unroll
;                             for (int n = 0; n < 2; ++n)
; #pragma unroll
;                                 for (int j = 0; j < 4; ++j) { const float e = __expf(fmaxf(fminf(acc[ai][bj][m][n][j] * sc, 80.f), -80.f)); acc[ai][bj][m][n][j] = e; part += e; }
;                         part += __shfl_xor(part, 16); part += __shfl_xor(part, 32);
;                         if (fq == 0) red[(wr * 4 + wc) * 128 + ai * 64 + m * 16 + fr] = part; }
	s_setprio 0
	v_lshl_add_u32 v194, s46, 8, v198
	v_or_b32_e32 v192, 16, v194
	v_ashrrev_i32_e32 v195, 31, v194
	v_ashrrev_i32_e32 v193, 31, v192
	v_lshl_add_u64 v[130:131], v[194:195], 4, s[8:9]
	v_lshl_add_u64 v[134:135], v[192:193], 4, s[8:9]
	global_load_dwordx4 v[130:133], v[130:131], off
	v_and_b32_e32 v139, 64, v155
	global_load_dwordx4 v[134:137], v[134:135], off
	v_add_u32_e32 v138, 0x90, v194
	v_add_u32_e32 v140, 0xa0, v194
	v_add_u32_e32 v205, 64, v139
	v_ashrrev_i32_e32 v139, 31, v138
	v_ashrrev_i32_e32 v141, 31, v140
	v_lshl_add_u64 v[164:165], v[138:139], 4, s[8:9]
	v_lshl_add_u64 v[206:207], v[140:141], 4, s[8:9]
	v_xor_b32_e32 v144, 16, v155
	v_or_b32_e32 v190, 32, v194
	v_or_b32_e32 v188, 48, v194
	v_add_u32_e32 v186, 0x80, v194
	v_cmp_lt_i32_e32 vcc, v144, v205
	v_add_u32_e32 v142, 0xb0, v194
	v_ashrrev_i32_e32 v191, 31, v190
	v_ashrrev_i32_e32 v189, 31, v188
	v_ashrrev_i32_e32 v187, 31, v186
	v_cndmask_b32_e32 v146, v155, v144, vcc
	v_ashrrev_i32_e32 v143, 31, v142
	v_lshl_add_u64 v[144:145], v[190:191], 4, s[8:9]
	v_lshl_add_u64 v[150:151], v[188:189], 4, s[8:9]
	v_lshl_add_u64 v[162:163], v[186:187], 4, s[8:9]
	v_lshl_add_u64 v[208:209], v[142:143], 4, s[8:9]
	v_lshlrev_b32_e32 v204, 2, v146
	global_load_dwordx4 v[146:149], v[144:145], off
	s_nop 0
	global_load_dwordx4 v[150:153], v[150:151], off
	s_waitcnt vmcnt(0)
	v_mov_b32_e32 v139, v130
	v_mov_b32_e32 v141, v132
	v_mov_b32_e32 v138, v134
	v_mov_b32_e32 v130, v135
	v_mov_b32_e32 v140, v136
	v_pk_add_f32 v[130:131], v[138:139], v[130:131]
	v_mov_b32_e32 v132, v137
	v_pk_add_f32 v[130:131], v[140:141], v[130:131]
	s_nop 0
	v_pk_add_f32 v[130:131], v[132:133], v[130:131]
	s_nop 0
	v_pk_fma_f32 v[196:197], v[130:131], s[72:73], v[160:161] op_sel_hi:[1,0,0]
	s_nop 0
	v_mul_f32_e32 v130, 0x4b800000, v197
	v_cmp_gt_f32_e32 vcc, s94, v197
	s_nop 1
	v_cndmask_b32_e32 v130, v197, v130, vcc
	v_rsq_f32_e32 v197, v130
	global_load_dwordx4 v[138:141], v[162:163], off
	global_load_dwordx4 v[142:145], v[164:165], off
	global_load_dwordx4 v[130:133], v[206:207], off
	global_load_dwordx4 v[134:137], v[208:209], off
	v_mul_f32_e32 v162, 0x45800000, v197
	v_cndmask_b32_e32 v162, v197, v162, vcc
	v_mul_f32_e32 v162, 0x3d800000, v162
	v_mul_f32_e32 v126, v126, v162
	v_mul_f32_e32 v127, v127, v162
	v_mul_f32_e32 v124, v124, v162
	v_min_f32_e32 v126, 0x42a00000, v126
	v_mul_f32_e32 v128, v128, v162
	v_mul_f32_e32 v125, v125, v162
	v_min_f32_e32 v127, 0x42a00000, v127
	v_min_f32_e32 v124, 0x42a00000, v124
	v_max_f32_e32 v126, 0xc2a00000, v126
	v_mul_f32_e32 v129, v129, v162
	v_min_f32_e32 v128, 0x42a00000, v128
	v_min_f32_e32 v125, 0x42a00000, v125
	v_max_f32_e32 v127, 0xc2a00000, v127
	v_max_f32_e32 v124, 0xc2a00000, v124
	v_mul_f32_e32 v126, 0x3fb8aa3b, v126
	v_mul_f32_e32 v122, v122, v162
	v_min_f32_e32 v129, 0x42a00000, v129
	v_max_f32_e32 v128, 0xc2a00000, v128
	v_max_f32_e32 v125, 0xc2a00000, v125
	v_mul_f32_e32 v127, 0x3fb8aa3b, v127
	v_mul_f32_e32 v163, 0x3fb8aa3b, v124
	v_exp_f32_e32 v124, v126
	v_mul_f32_e32 v123, v123, v162
	v_min_f32_e32 v122, 0x42a00000, v122
	v_max_f32_e32 v129, 0xc2a00000, v129
	v_mul_f32_e32 v128, 0x3fb8aa3b, v128
	v_mul_f32_e32 v164, 0x3fb8aa3b, v125
	v_exp_f32_e32 v125, v127
	v_min_f32_e32 v123, 0x42a00000, v123
	v_max_f32_e32 v122, 0xc2a00000, v122
	v_mul_f32_e32 v129, 0x3fb8aa3b, v129
	v_exp_f32_e32 v128, v128
	v_max_f32_e32 v123, 0xc2a00000, v123
	v_mul_f32_e32 v122, 0x3fb8aa3b, v122
	v_exp_f32_e32 v129, v129
	v_mul_f32_e32 v118, v118, v162
	v_mul_f32_e32 v123, 0x3fb8aa3b, v123
	v_exp_f32_e32 v122, v122
	v_exp_f32_e32 v126, v163
	v_add_f32_e32 v163, 0, v124
	v_mul_f32_e32 v119, v119, v162
	v_min_f32_e32 v118, 0x42a00000, v118
	v_exp_f32_e32 v123, v123
	v_add_f32_e32 v163, v125, v163
	v_mul_f32_e32 v120, v120, v162
	v_min_f32_e32 v119, 0x42a00000, v119
	v_max_f32_e32 v118, 0xc2a00000, v118
	v_add_f32_e32 v163, v128, v163
	v_max_f32_e32 v119, 0xc2a00000, v119
	v_mul_f32_e32 v118, 0x3fb8aa3b, v118
	v_exp_f32_e32 v127, v164
	v_add_f32_e32 v163, v129, v163
	v_min_f32_e32 v120, 0x42a00000, v120
	v_mul_f32_e32 v121, v121, v162
	v_mul_f32_e32 v119, 0x3fb8aa3b, v119
	v_exp_f32_e32 v118, v118
	v_add_f32_e32 v163, v122, v163
	v_max_f32_e32 v120, 0xc2a00000, v120
	v_min_f32_e32 v121, 0x42a00000, v121
	v_mul_f32_e32 v114, v114, v162
	v_exp_f32_e32 v119, v119
	v_add_f32_e32 v163, v123, v163
	v_mul_f32_e32 v120, 0x3fb8aa3b, v120
	v_max_f32_e32 v121, 0xc2a00000, v121
	v_min_f32_e32 v114, 0x42a00000, v114
	v_mul_f32_e32 v115, v115, v162
	v_add_f32_e32 v163, v126, v163
	v_exp_f32_e32 v120, v120
	v_mul_f32_e32 v121, 0x3fb8aa3b, v121
	v_max_f32_e32 v114, 0xc2a00000, v114
	v_min_f32_e32 v115, 0x42a00000, v115
	v_mul_f32_e32 v116, v116, v162
	v_add_f32_e32 v163, v127, v163
	v_exp_f32_e32 v121, v121
	v_mul_f32_e32 v114, 0x3fb8aa3b, v114
	v_max_f32_e32 v115, 0xc2a00000, v115
	v_min_f32_e32 v116, 0x42a00000, v116
	v_mul_f32_e32 v117, v117, v162
	v_add_f32_e32 v163, v118, v163
	v_exp_f32_e32 v114, v114
	v_mul_f32_e32 v115, 0x3fb8aa3b, v115
	v_max_f32_e32 v116, 0xc2a00000, v116
	v_min_f32_e32 v117, 0x42a00000, v117
	v_add_f32_e32 v163, v119, v163
	v_exp_f32_e32 v115, v115
	v_mul_f32_e32 v116, 0x3fb8aa3b, v116
	v_max_f32_e32 v117, 0xc2a00000, v117
	v_add_f32_e32 v163, v120, v163
	v_exp_f32_e32 v116, v116
	v_mul_f32_e32 v117, 0x3fb8aa3b, v117
	v_add_f32_e32 v163, v121, v163
	v_exp_f32_e32 v117, v117
	v_add_f32_e32 v162, v114, v163
	v_add_f32_e32 v162, v115, v162
	v_add_f32_e32 v162, v116, v162
	v_add_f32_e32 v162, v117, v162
	ds_bpermute_b32 v163, v204, v162
	v_xor_b32_e32 v164, 32, v155
	v_cmp_lt_i32_e32 vcc, v164, v205
	s_waitcnt lgkmcnt(0)
	v_add_f32_e32 v205, v162, v163
	v_cndmask_b32_e32 v164, v155, v164, vcc
	v_lshlrev_b32_e32 v197, 2, v164
	ds_bpermute_b32 v206, v197, v205
	v_cmp_gt_f32_e32 vcc, s94, v196
	s_and_saveexec_b64 s[6:7], s[2:3]
	s_cbranch_execz .LBB0_1510
	s_waitcnt lgkmcnt(0)
	v_add_f32_e32 v162, v205, v206
	ds_write_b32 v201, v162

; #define PG8_STAGE(bufoff, gbase, voff) do { _Pragma("unroll") for (int _i = 0; _i < 2; ++_i) \
;         __builtin_amdgcn_global_load_lds((const unsigned*)((const char*)(gbase) + (voff)[_i]), (LAS unsigned*)(lds + (bufoff) + ldsw + _i * 8192), 16, 0, 0); } while (0)
; #define PG8_LDA(dst, b, h) do { _Pragma("unroll") for (int m = 0; m < 4; ++m) _Pragma("unroll") for (int k = 0; k < 2; ++k) dst[m][k] = *(const LAS bf16x8*)(lds + PG8_SA(b, h) + aoff + m * 2048 + k * 1024); } while (0)
; #define PG8_WAIT_V(n) asm volatile("s_waitcnt vmcnt(" #n ")" ::: "memory")
; #define PG8_WAIT_L(n) asm volatile("s_waitcnt lgkmcnt(" #n ")" ::: "memory")
; template <class Epi>
; DEVI void gemm_phase(LAS unsigned char* lds, const Gemm g, const Epi& E) {
;     ...
;         for (int t = 0; t < nt; t += 2) {
;             const bool last = (t == nt - 2);
;             const char* a1 = cA + (size_t)(t + 1) * kstep;
;             const char* a2 = last ? nA : cA + (size_t)(t + 2) * kstep; const char* b2 = last ? nB : cB + (size_t)(t + 2) * kstep;
;             const char* a3 = a2 + kstep; const char* b3 = b2 + kstep;
;             PG8_LDB(B0, 0, 0); PG8_SCHED; PG8_LDA(At, 0, 0); PG8_STAGE(PG8_SA(1, 1), a1 + hstepA, voffA);
;             PG8_WAIT_L(8); PG8_BAR; PG8_WAIT_L(0); PG8_MMA(0, 0, At, B0); PG8_BAR; PG8_SCHED;
;             PG8_LDB(B1, 0, 1); PG8_STAGE(PG8_SB(0, 0), b2, voffB);
;             PG8_BAR; PG8_WAIT_L(0); PG8_MMA(0, 1, At, B1); PG8_BAR;
;             PG8_LDA(At, 0, 1); PG8_STAGE(PG8_SA(0, 0), a2, voffA);
;             PG8_BAR; PG8_WAIT_L(0); PG8_MMA(1, 0, At, B0); PG8_BAR; PG8_SCHED;
;             PG8_STAGE(PG8_SB(0, 1), b2 + hstepB, voffB);
;             PG8_WAIT_V(6); PG8_BAR; PG8_MMA(1, 1, At, B1); PG8_BAR;
;             PG8_LDB(B0, 1, 0); PG8_SCHED; PG8_LDA(At, 1, 0); PG8_STAGE(PG8_SA(0, 1), a2 + hstepA, voffA);
;             PG8_WAIT_L(8); PG8_BAR; PG8_WAIT_L(0); PG8_MMA(0, 0, At, B0); PG8_BAR; PG8_SCHED;
;             PG8_LDB(B1, 1, 1); PG8_STAGE(PG8_SB(1, 0), b3, voffB);
;             PG8_BAR; PG8_WAIT_L(0); PG8_MMA(0, 1, At, B1); PG8_BAR;
;             PG8_LDA(At, 1, 1); PG8_STAGE(PG8_SA(1, 0), a3, voffA);
;             PG8_BAR; PG8_WAIT_L(0); PG8_MMA(1, 0, At, B0); PG8_BAR; PG8_SCHED;
;             PG8_STAGE(PG8_SB(1, 1), b3 + hstepB, voffB);
;             PG8_WAIT_V(6); PG8_BAR; PG8_MMA(1, 1, At, B1); PG8_BAR;
;         }
.LBB0_1595:
	s_add_u32 s18, s8, 0xfffc0080
	s_addc_u32 s19, s9, -1
	s_add_i32 s26, 0, 0x10000
	v_add_u32_e32 v142, s26, v191
	ds_read_b128 v[130:133], v142
	ds_read_b128 v[134:137], v142 offset:1024
	ds_read_b128 v[138:141], v142 offset:2048
	ds_read_b128 v[142:145], v142 offset:3072
	s_cmp_eq_u32 s17, 12
	s_cselect_b32 s81, s0, s19
	s_cselect_b32 s80, s1, s18
	s_cselect_b32 s79, s37, s15
	s_cselect_b32 s78, s36, s13
	s_add_i32 m0, s69, 0xc000
	ds_read_b128 v[178:181], v196
	ds_read_b128 v[182:185], v196 offset:1024
	ds_read_b128 v[186:189], v196 offset:2048
	ds_read_b128 v[198:201], v196 offset:3072
	ds_read_b128 v[202:205], v196 offset:4096
	ds_read_b128 v[206:209], v196 offset:5120
	ds_read_b128 v[214:217], v196 offset:6144
	ds_read_b128 v[218:221], v196 offset:7168
	global_load_lds_dwordx4 v152, s[8:9]
	s_add_i32 m0, s69, 0xe000
	s_nop 0
	global_load_lds_dwordx4 v176, s[8:9]
	s_waitcnt lgkmcnt(8)
	s_barrier
	s_waitcnt lgkmcnt(0)
	v_mfma_f32_16x16x32_bf16 v[126:129], v[130:133], v[178:181], v[126:129]
	v_mfma_f32_16x16x32_bf16 v[122:125], v[138:141], v[178:181], v[122:125]
	v_mfma_f32_16x16x32_bf16 v[110:113], v[130:133], v[186:189], v[110:113]
	v_mfma_f32_16x16x32_bf16 v[106:109], v[138:141], v[186:189], v[106:109]
	v_mfma_f32_16x16x32_bf16 v[94:97], v[130:133], v[202:205], v[94:97]
	v_mfma_f32_16x16x32_bf16 v[90:93], v[138:141], v[202:205], v[90:93]
	v_mfma_f32_16x16x32_bf16 v[78:81], v[130:133], v[214:217], v[78:81]
	v_mfma_f32_16x16x32_bf16 v[74:77], v[138:141], v[214:217], v[74:77]
	v_mfma_f32_16x16x32_bf16 v[126:129], v[134:137], v[182:185], v[126:129]
	v_mfma_f32_16x16x32_bf16 v[122:125], v[142:145], v[182:185], v[122:125]
	v_mfma_f32_16x16x32_bf16 v[110:113], v[134:137], v[198:201], v[110:113]
	v_mfma_f32_16x16x32_bf16 v[106:109], v[142:145], v[198:201], v[106:109]
	v_mfma_f32_16x16x32_bf16 v[94:97], v[134:137], v[206:209], v[94:97]
	v_mfma_f32_16x16x32_bf16 v[90:93], v[142:145], v[206:209], v[90:93]
	v_mfma_f32_16x16x32_bf16 v[78:81], v[134:137], v[218:221], v[78:81]
	v_mfma_f32_16x16x32_bf16 v[74:77], v[142:145], v[218:221], v[74:77]
	s_barrier
	s_add_i32 s27, 0, 0x14000
	v_add_u32_e32 v162, s27, v191
	s_add_i32 s18, s26, s82
	ds_read_b128 v[222:225], v162
	ds_read_b128 v[226:229], v162 offset:1024
	ds_read_b128 v[230:233], v162 offset:2048
	ds_read_b128 v[234:237], v162 offset:3072
	v_lshl_add_u64 v[162:163], s[78:79], 0, v[8:9]
	s_mov_b32 m0, s18
	v_lshl_add_u64 v[164:165], s[78:79], 0, v[150:151]
	global_load_lds_dwordx4 v[162:163], off
	s_add_i32 m0, s18, 0x2000
	s_nop 0
	global_load_lds_dwordx4 v[164:165], off
	s_barrier
	s_waitcnt lgkmcnt(0)
	v_mfma_f32_16x16x32_bf16 v[118:121], v[222:225], v[178:181], v[118:121]
	v_mfma_f32_16x16x32_bf16 v[114:117], v[230:233], v[178:181], v[114:117]
	v_mfma_f32_16x16x32_bf16 v[102:105], v[222:225], v[186:189], v[102:105]
	v_mfma_f32_16x16x32_bf16 v[98:101], v[230:233], v[186:189], v[98:101]
	v_mfma_f32_16x16x32_bf16 v[86:89], v[222:225], v[202:205], v[86:89]
	v_mfma_f32_16x16x32_bf16 v[82:85], v[230:233], v[202:205], v[82:85]
	v_mfma_f32_16x16x32_bf16 v[70:73], v[222:225], v[214:217], v[70:73]
	v_mfma_f32_16x16x32_bf16 v[66:69], v[230:233], v[214:217], v[66:69]
	v_mfma_f32_16x16x32_bf16 v[118:121], v[226:229], v[182:185], v[118:121]
	v_mfma_f32_16x16x32_bf16 v[114:117], v[234:237], v[182:185], v[114:117]
	v_mfma_f32_16x16x32_bf16 v[102:105], v[226:229], v[198:201], v[102:105]
	v_mfma_f32_16x16x32_bf16 v[98:101], v[234:237], v[198:201], v[98:101]
	v_mfma_f32_16x16x32_bf16 v[86:89], v[226:229], v[206:209], v[86:89]
	v_mfma_f32_16x16x32_bf16 v[82:85], v[234:237], v[206:209], v[82:85]
	v_mfma_f32_16x16x32_bf16 v[70:73], v[226:229], v[218:221], v[70:73]
	v_mfma_f32_16x16x32_bf16 v[66:69], v[234:237], v[218:221], v[66:69]
	s_mov_b32 m0, s69
	v_lshl_add_u64 v[238:239], s[80:81], 0, v[146:147]
	s_barrier
	ds_read_b128 v[178:181], v196 offset:16384
	ds_read_b128 v[182:185], v196 offset:17408
	ds_read_b128 v[186:189], v196 offset:18432
	ds_read_b128 v[198:201], v196 offset:19456
	ds_read_b128 v[202:205], v196 offset:20480
	ds_read_b128 v[206:209], v196 offset:21504
	ds_read_b128 v[214:217], v196 offset:22528
	ds_read_b128 v[218:221], v196 offset:23552
	global_load_lds_dwordx4 v[238:239], off
	s_mov_b32 m0, s83
	v_lshl_add_u64 v[240:241], s[80:81], 0, v[148:149]
	global_load_lds_dwordx4 v[240:241], off
	s_barrier
	s_waitcnt lgkmcnt(0)
	v_mfma_f32_16x16x32_bf16 v[62:65], v[130:133], v[178:181], v[62:65]
	v_mfma_f32_16x16x32_bf16 v[58:61], v[138:141], v[178:181], v[58:61]
	v_mfma_f32_16x16x32_bf16 v[46:49], v[130:133], v[186:189], v[46:49]
	v_mfma_f32_16x16x32_bf16 v[42:45], v[138:141], v[186:189], v[42:45]
	v_mfma_f32_16x16x32_bf16 v[30:33], v[130:133], v[202:205], v[30:33]
	v_mfma_f32_16x16x32_bf16 v[26:29], v[138:141], v[202:205], v[26:29]
	v_mfma_f32_16x16x32_bf16 v[14:17], v[130:133], v[214:217], v[14:17]
	v_mfma_f32_16x16x32_bf16 v[10:13], v[138:141], v[214:217], v[10:13]
	v_mfma_f32_16x16x32_bf16 v[62:65], v[134:137], v[182:185], v[62:65]
	v_mfma_f32_16x16x32_bf16 v[58:61], v[142:145], v[182:185], v[58:61]
	v_mfma_f32_16x16x32_bf16 v[46:49], v[134:137], v[198:201], v[46:49]
	v_mfma_f32_16x16x32_bf16 v[42:45], v[142:145], v[198:201], v[42:45]
	v_mfma_f32_16x16x32_bf16 v[30:33], v[134:137], v[206:209], v[30:33]
	v_mfma_f32_16x16x32_bf16 v[26:29], v[142:145], v[206:209], v[26:29]
	v_mfma_f32_16x16x32_bf16 v[14:17], v[134:137], v[218:221], v[14:17]
	v_mfma_f32_16x16x32_bf16 v[10:13], v[142:145], v[218:221], v[10:13]
	s_barrier
	s_add_u32 s18, s78, 0x40000
	s_addc_u32 s19, s79, 0
	s_add_i32 s26, s27, s82
	s_mov_b32 m0, s26
	s_nop 0
	global_load_lds_dwordx4 v8, s[18:19]
	s_add_i32 m0, s26, 0x2000
	s_nop 0
	global_load_lds_dwordx4 v150, s[18:19]
	s_waitcnt vmcnt(6)
	s_barrier
; #define PG8_STAGE(bufoff, gbase, voff) do { _Pragma("unroll") for (int _i = 0; _i < 2; ++_i) \
;         __builtin_amdgcn_global_load_lds((const unsigned*)((const char*)(gbase) + (voff)[_i]), (LAS unsigned*)(lds + (bufoff) + ldsw + _i * 8192), 16, 0, 0); } while (0)
; #define PG8_LDA(dst, b, h) do { _Pragma("unroll") for (int m = 0; m < 4; ++m) _Pragma("unroll") for (int k = 0; k < 2; ++k) dst[m][k] = *(const LAS bf16x8*)(lds + PG8_SA(b, h) + aoff + m * 2048 + k * 1024); } while (0)
; #define PG8_WAIT_V(n) asm volatile("s_waitcnt vmcnt(" #n ")" ::: "memory")
; #define PG8_WAIT_L(n) asm volatile("s_waitcnt lgkmcnt(" #n ")" ::: "memory")
; template <class Epi>
; DEVI void gemm_phase(LAS unsigned char* lds, const Gemm g, const Epi& E) {
;     ...
;         for (int t = 0; t < nt; t += 2) {
;             const bool last = (t == nt - 2);
;             const char* a1 = cA + (size_t)(t + 1) * kstep;
;             const char* a2 = last ? nA : cA + (size_t)(t + 2) * kstep; const char* b2 = last ? nB : cB + (size_t)(t + 2) * kstep;
;             const char* a3 = a2 + kstep; const char* b3 = b2 + kstep;
;             PG8_LDB(B0, 0, 0); PG8_SCHED; PG8_LDA(At, 0, 0); PG8_STAGE(PG8_SA(1, 1), a1 + hstepA, voffA);
;             PG8_WAIT_L(8); PG8_BAR; PG8_WAIT_L(0); PG8_MMA(0, 0, At, B0); PG8_BAR; PG8_SCHED;
;             PG8_LDB(B1, 0, 1); PG8_STAGE(PG8_SB(0, 0), b2, voffB);
;             PG8_BAR; PG8_WAIT_L(0); PG8_MMA(0, 1, At, B1); PG8_BAR;
;             PG8_LDA(At, 0, 1); PG8_STAGE(PG8_SA(0, 0), a2, voffA);
;             PG8_BAR; PG8_WAIT_L(0); PG8_MMA(1, 0, At, B0); PG8_BAR; PG8_SCHED;
;             PG8_STAGE(PG8_SB(0, 1), b2 + hstepB, voffB);
;             PG8_WAIT_V(6); PG8_BAR; PG8_MMA(1, 1, At, B1); PG8_BAR;
;             PG8_LDB(B0, 1, 0); PG8_SCHED; PG8_LDA(At, 1, 0); PG8_STAGE(PG8_SA(0, 1), a2 + hstepA, voffA);
;             PG8_WAIT_L(8); PG8_BAR; PG8_WAIT_L(0); PG8_MMA(0, 0, At, B0); PG8_BAR; PG8_SCHED;
;             PG8_LDB(B1, 1, 1); PG8_STAGE(PG8_SB(1, 0), b3, voffB);
;             PG8_BAR; PG8_WAIT_L(0); PG8_MMA(0, 1, At, B1); PG8_BAR;
;             PG8_LDA(At, 1, 1); PG8_STAGE(PG8_SA(1, 0), a3, voffA);
;             PG8_BAR; PG8_WAIT_L(0); PG8_MMA(1, 0, At, B0); PG8_BAR; PG8_SCHED;
;             PG8_STAGE(PG8_SB(1, 1), b3 + hstepB, voffB);
;             PG8_WAIT_V(6); PG8_BAR; PG8_MMA(1, 1, At, B1); PG8_BAR;
;         }
	v_mfma_f32_16x16x32_bf16 v[54:57], v[222:225], v[178:181], v[54:57]
	v_mfma_f32_16x16x32_bf16 v[50:53], v[230:233], v[178:181], v[50:53]
	v_mfma_f32_16x16x32_bf16 v[38:41], v[222:225], v[186:189], v[38:41]
	v_mfma_f32_16x16x32_bf16 v[34:37], v[230:233], v[186:189], v[34:37]
	v_mfma_f32_16x16x32_bf16 v[22:25], v[222:225], v[202:205], v[22:25]
	v_mfma_f32_16x16x32_bf16 v[18:21], v[230:233], v[202:205], v[18:21]
	v_mfma_f32_16x16x32_bf16 v[4:7], v[222:225], v[214:217], v[4:7]
	v_mfma_f32_16x16x32_bf16 v[0:3], v[230:233], v[214:217], v[0:3]
	v_mfma_f32_16x16x32_bf16 v[54:57], v[226:229], v[182:185], v[54:57]
	v_mfma_f32_16x16x32_bf16 v[50:53], v[234:237], v[182:185], v[50:53]
	v_mfma_f32_16x16x32_bf16 v[38:41], v[226:229], v[198:201], v[38:41]
	v_mfma_f32_16x16x32_bf16 v[34:37], v[234:237], v[198:201], v[34:37]
	v_mfma_f32_16x16x32_bf16 v[22:25], v[226:229], v[206:209], v[22:25]
	v_mfma_f32_16x16x32_bf16 v[18:21], v[234:237], v[206:209], v[18:21]
	v_mfma_f32_16x16x32_bf16 v[4:7], v[226:229], v[218:221], v[4:7]
	v_mfma_f32_16x16x32_bf16 v[0:3], v[234:237], v[218:221], v[0:3]
	s_add_i32 s26, 0, 0x18000
	v_add_u32_e32 v142, s26, v191
	s_barrier
	ds_read_b128 v[130:133], v142
	ds_read_b128 v[134:137], v142 offset:1024
	ds_read_b128 v[138:141], v142 offset:2048
	ds_read_b128 v[142:145], v142 offset:3072
	s_add_u32 s18, s80, 0x40000
	s_addc_u32 s19, s81, 0
	s_mov_b32 m0, s84
	ds_read_b128 v[178:181], v196 offset:32768
	ds_read_b128 v[182:185], v196 offset:33792
	ds_read_b128 v[186:189], v196 offset:34816
	ds_read_b128 v[198:201], v196 offset:35840
	ds_read_b128 v[202:205], v196 offset:36864
	ds_read_b128 v[206:209], v196 offset:37888
	ds_read_b128 v[214:217], v196 offset:38912
	ds_read_b128 v[218:221], v196 offset:39936
	global_load_lds_dwordx4 v146, s[18:19]
	s_mov_b32 m0, s85
	s_nop 0
	global_load_lds_dwordx4 v148, s[18:19]
	s_waitcnt lgkmcnt(8)
	s_barrier
	s_waitcnt lgkmcnt(0)
	v_mfma_f32_16x16x32_bf16 v[126:129], v[130:133], v[178:181], v[126:129]
	v_mfma_f32_16x16x32_bf16 v[122:125], v[138:141], v[178:181], v[122:125]
	v_mfma_f32_16x16x32_bf16 v[110:113], v[130:133], v[186:189], v[110:113]
	v_mfma_f32_16x16x32_bf16 v[106:109], v[138:141], v[186:189], v[106:109]
	v_mfma_f32_16x16x32_bf16 v[94:97], v[130:133], v[202:205], v[94:97]
	v_mfma_f32_16x16x32_bf16 v[90:93], v[138:141], v[202:205], v[90:93]
	v_mfma_f32_16x16x32_bf16 v[78:81], v[130:133], v[214:217], v[78:81]
	v_mfma_f32_16x16x32_bf16 v[74:77], v[138:141], v[214:217], v[74:77]
	v_mfma_f32_16x16x32_bf16 v[126:129], v[134:137], v[182:185], v[126:129]
	v_mfma_f32_16x16x32_bf16 v[122:125], v[142:145], v[182:185], v[122:125]
	v_mfma_f32_16x16x32_bf16 v[110:113], v[134:137], v[198:201], v[110:113]
	v_mfma_f32_16x16x32_bf16 v[106:109], v[142:145], v[198:201], v[106:109]
	v_mfma_f32_16x16x32_bf16 v[94:97], v[134:137], v[206:209], v[94:97]
	v_mfma_f32_16x16x32_bf16 v[90:93], v[142:145], v[206:209], v[90:93]
	v_mfma_f32_16x16x32_bf16 v[78:81], v[134:137], v[218:221], v[78:81]
	v_mfma_f32_16x16x32_bf16 v[74:77], v[142:145], v[218:221], v[74:77]
	s_barrier
	s_add_i32 s27, 0, 0x1c000
	s_add_i32 s18, s26, s82
	v_add_u32_e32 v197, s27, v191
	v_lshl_add_u64 v[162:163], v[162:163], 0, s[70:71]
	s_mov_b32 m0, s18
	ds_read_b128 v[222:225], v197
	ds_read_b128 v[226:229], v197 offset:1024
	ds_read_b128 v[230:233], v197 offset:2048
	ds_read_b128 v[234:237], v197 offset:3072
	global_load_lds_dwordx4 v[162:163], off
	s_add_i32 m0, s18, 0x2000
	v_lshl_add_u64 v[162:163], v[164:165], 0, s[70:71]
	global_load_lds_dwordx4 v[162:163], off
	s_barrier
	s_waitcnt lgkmcnt(0)
	v_mfma_f32_16x16x32_bf16 v[118:121], v[222:225], v[178:181], v[118:121]
	v_mfma_f32_16x16x32_bf16 v[114:117], v[230:233], v[178:181], v[114:117]
	v_mfma_f32_16x16x32_bf16 v[102:105], v[222:225], v[186:189], v[102:105]
	v_mfma_f32_16x16x32_bf16 v[98:101], v[230:233], v[186:189], v[98:101]
	v_mfma_f32_16x16x32_bf16 v[86:89], v[222:225], v[202:205], v[86:89]
	v_mfma_f32_16x16x32_bf16 v[82:85], v[230:233], v[202:205], v[82:85]
	v_mfma_f32_16x16x32_bf16 v[70:73], v[222:225], v[214:217], v[70:73]
	v_mfma_f32_16x16x32_bf16 v[66:69], v[230:233], v[214:217], v[66:69]
	v_mfma_f32_16x16x32_bf16 v[118:121], v[226:229], v[182:185], v[118:121]
	v_mfma_f32_16x16x32_bf16 v[114:117], v[234:237], v[182:185], v[114:117]
	v_mfma_f32_16x16x32_bf16 v[102:105], v[226:229], v[198:201], v[102:105]
	v_mfma_f32_16x16x32_bf16 v[98:101], v[234:237], v[198:201], v[98:101]
	v_mfma_f32_16x16x32_bf16 v[86:89], v[226:229], v[206:209], v[86:89]
	v_mfma_f32_16x16x32_bf16 v[82:85], v[234:237], v[206:209], v[82:85]
	v_mfma_f32_16x16x32_bf16 v[70:73], v[226:229], v[218:221], v[70:73]
	v_mfma_f32_16x16x32_bf16 v[66:69], v[234:237], v[218:221], v[66:69]
	s_mov_b32 m0, s86
	v_lshl_add_u64 v[162:163], v[238:239], 0, s[70:71]
	s_barrier
	ds_read_b128 v[178:181], v196 offset:49152
	ds_read_b128 v[182:185], v196 offset:50176
	ds_read_b128 v[186:189], v196 offset:51200
	ds_read_b128 v[198:201], v196 offset:52224
	ds_read_b128 v[202:205], v196 offset:53248
	ds_read_b128 v[206:209], v196 offset:54272
	ds_read_b128 v[214:217], v196 offset:55296
	ds_read_b128 v[218:221], v196 offset:56320
	global_load_lds_dwordx4 v[162:163], off
	s_mov_b32 m0, s87
	v_lshl_add_u64 v[162:163], v[240:241], 0, s[70:71]
	global_load_lds_dwordx4 v[162:163], off
	s_barrier
; #define PG8_BAR __builtin_amdgcn_s_barrier()
; template <class Epi>
; DEVI void gemm_phase(LAS unsigned char* lds, const Gemm g, const Epi& E) {
;     ...
;         for (int t = 0; t < nt; t += 2) {
;             const bool last = (t == nt - 2);
;             const char* a1 = cA + (size_t)(t + 1) * kstep;
;             const char* a2 = last ? nA : cA + (size_t)(t + 2) * kstep; const char* b2 = last ? nB : cB + (size_t)(t + 2) * kstep;
;             const char* a3 = a2 + kstep; const char* b3 = b2 + kstep;
;             PG8_LDB(B0, 0, 0); PG8_SCHED; PG8_LDA(At, 0, 0); PG8_STAGE(PG8_SA(1, 1), a1 + hstepA, voffA);
;             PG8_WAIT_L(8); PG8_BAR; PG8_WAIT_L(0); PG8_MMA(0, 0, At, B0); PG8_BAR; PG8_SCHED;
;             PG8_LDB(B1, 0, 1); PG8_STAGE(PG8_SB(0, 0), b2, voffB);
;             PG8_BAR; PG8_WAIT_L(0); PG8_MMA(0, 1, At, B1); PG8_BAR;
;             PG8_LDA(At, 0, 1); PG8_STAGE(PG8_SA(0, 0), a2, voffA);
;             PG8_BAR; PG8_WAIT_L(0); PG8_MMA(1, 0, At, B0); PG8_BAR; PG8_SCHED;
;             PG8_STAGE(PG8_SB(0, 1), b2 + hstepB, voffB);
;             PG8_WAIT_V(6); PG8_BAR; PG8_MMA(1, 1, At, B1); PG8_BAR;
;             PG8_LDB(B0, 1, 0); PG8_SCHED; PG8_LDA(At, 1, 0); PG8_STAGE(PG8_SA(0, 1), a2 + hstepA, voffA);
;             PG8_WAIT_L(8); PG8_BAR; PG8_WAIT_L(0); PG8_MMA(0, 0, At, B0); PG8_BAR; PG8_SCHED;
;             PG8_LDB(B1, 1, 1); PG8_STAGE(PG8_SB(1, 0), b3, voffB);
;             PG8_BAR; PG8_WAIT_L(0); PG8_MMA(0, 1, At, B1); PG8_BAR;
;             PG8_LDA(At, 1, 1); PG8_STAGE(PG8_SA(1, 0), a3, voffA);
;             PG8_BAR; PG8_WAIT_L(0); PG8_MMA(1, 0, At, B0); PG8_BAR; PG8_SCHED;
;             PG8_STAGE(PG8_SB(1, 1), b3 + hstepB, voffB);
;             PG8_WAIT_V(6); PG8_BAR; PG8_MMA(1, 1, At, B1); PG8_BAR;
;         }
;     ...
;                 if constexpr (Epi::PRE) {
; #pragma unroll
;                     for (int m = 0; m < 2; ++m)
; #pragma unroll
;                         for (int bj = 0; bj < 2; ++bj)
; #pragma unroll
;                             for (int n = 0; n < 2; ++n) pre[m][bj][n] = E.load(row0 + ai * HALF + (m0 + m) * 16, col0 + bj * HALF + n * NST);
;                 }
; #pragma unroll
;                 for (int mm = 0; mm < 2; ++mm) {
;                     const int m = m0 + mm;
;                     const int r = row0 + ai * HALF + m * 16; float rs = 1.f, part = 0.f;
;                     if constexpr (Epi::RS) rs = rsv[ai * 4 + m];
	s_waitcnt lgkmcnt(0)
	v_mfma_f32_16x16x32_bf16 v[62:65], v[130:133], v[178:181], v[62:65]
	v_mfma_f32_16x16x32_bf16 v[58:61], v[138:141], v[178:181], v[58:61]
	v_mfma_f32_16x16x32_bf16 v[46:49], v[130:133], v[186:189], v[46:49]
	v_mfma_f32_16x16x32_bf16 v[42:45], v[138:141], v[186:189], v[42:45]
	v_mfma_f32_16x16x32_bf16 v[30:33], v[130:133], v[202:205], v[30:33]
	v_mfma_f32_16x16x32_bf16 v[26:29], v[138:141], v[202:205], v[26:29]
	v_mfma_f32_16x16x32_bf16 v[14:17], v[130:133], v[214:217], v[14:17]
	v_mfma_f32_16x16x32_bf16 v[10:13], v[138:141], v[214:217], v[10:13]
	v_mfma_f32_16x16x32_bf16 v[62:65], v[134:137], v[182:185], v[62:65]
	v_mfma_f32_16x16x32_bf16 v[58:61], v[142:145], v[182:185], v[58:61]
	v_mfma_f32_16x16x32_bf16 v[46:49], v[134:137], v[198:201], v[46:49]
	v_mfma_f32_16x16x32_bf16 v[42:45], v[142:145], v[198:201], v[42:45]
	v_mfma_f32_16x16x32_bf16 v[30:33], v[134:137], v[206:209], v[30:33]
	v_mfma_f32_16x16x32_bf16 v[26:29], v[142:145], v[206:209], v[26:29]
	v_mfma_f32_16x16x32_bf16 v[14:17], v[134:137], v[218:221], v[14:17]
	v_mfma_f32_16x16x32_bf16 v[10:13], v[142:145], v[218:221], v[10:13]
	s_barrier
	s_add_u32 s18, s78, 0x40080
	s_addc_u32 s19, s79, 0
	s_add_i32 s26, s27, s82
	s_mov_b32 m0, s26
	s_nop 0
	global_load_lds_dwordx4 v8, s[18:19]
	s_add_i32 m0, s26, 0x2000
	s_nop 0
	global_load_lds_dwordx4 v150, s[18:19]
	s_waitcnt vmcnt(6)
	s_barrier
	v_mfma_f32_16x16x32_bf16 v[54:57], v[222:225], v[178:181], v[54:57]
	v_mfma_f32_16x16x32_bf16 v[50:53], v[230:233], v[178:181], v[50:53]
	v_mfma_f32_16x16x32_bf16 v[38:41], v[222:225], v[186:189], v[38:41]
	v_mfma_f32_16x16x32_bf16 v[34:37], v[230:233], v[186:189], v[34:37]
	v_mfma_f32_16x16x32_bf16 v[22:25], v[222:225], v[202:205], v[22:25]
	v_mfma_f32_16x16x32_bf16 v[18:21], v[230:233], v[202:205], v[18:21]
	v_mfma_f32_16x16x32_bf16 v[4:7], v[222:225], v[214:217], v[4:7]
	v_mfma_f32_16x16x32_bf16 v[0:3], v[230:233], v[214:217], v[0:3]
	v_mfma_f32_16x16x32_bf16 v[54:57], v[226:229], v[182:185], v[54:57]
	v_mfma_f32_16x16x32_bf16 v[50:53], v[234:237], v[182:185], v[50:53]
	v_mfma_f32_16x16x32_bf16 v[38:41], v[226:229], v[198:201], v[38:41]
	v_mfma_f32_16x16x32_bf16 v[34:37], v[234:237], v[198:201], v[34:37]
	v_mfma_f32_16x16x32_bf16 v[22:25], v[226:229], v[206:209], v[22:25]
	v_mfma_f32_16x16x32_bf16 v[18:21], v[234:237], v[206:209], v[18:21]
	v_mfma_f32_16x16x32_bf16 v[4:7], v[226:229], v[218:221], v[4:7]
	v_mfma_f32_16x16x32_bf16 v[0:3], v[234:237], v[218:221], v[0:3]
	s_add_i32 s17, s17, 2
	s_add_u32 s8, s8, 0x100
	s_addc_u32 s9, s9, 0
	s_add_u32 s13, s13, 0x100
	s_addc_u32 s15, s15, 0
	s_cmp_gt_u32 s17, 13
	s_barrier
	s_cbranch_scc0 .LBB0_1595
	s_setprio 0
	s_lshl_b32 s0, s68, 8
	v_add_u32_e32 v182, s0, v190
	v_lshl_or_b32 v180, s12, 8, v195
	v_ashrrev_i32_e32 v183, 31, v182
	v_lshlrev_b64 v[130:131], 12, v[182:183]
	v_ashrrev_i32_e32 v181, 31, v180
	v_lshl_add_u64 v[130:131], s[30:31], 0, v[130:131]
	v_lshlrev_b64 v[184:185], 2, v[180:181]
	v_lshl_add_u64 v[162:163], v[130:131], 0, v[184:185]
	global_load_dwordx4 v[200:203], v[162:163], off
	global_load_dwordx4 v[204:207], v[162:163], off offset:16
	global_load_dwordx4 v[214:217], v[162:163], off offset:512
	global_load_dwordx4 v[218:221], v[162:163], off offset:528
	v_or_b32_e32 v188, 16, v182
	v_ashrrev_i32_e32 v189, 31, v188
	v_lshlrev_b64 v[130:131], 12, v[188:189]
	v_lshl_add_u64 v[130:131], s[30:31], 0, v[130:131]
	v_lshl_add_u64 v[186:187], v[130:131], 0, v[184:185]
	global_load_dwordx4 v[138:141], v[186:187], off offset:16
	global_load_dwordx4 v[142:145], v[186:187], off
	global_load_dwordx4 v[130:133], v[186:187], off offset:528
	global_load_dwordx4 v[134:137], v[186:187], off offset:512
	v_and_b32_e32 v165, 64, v155
	v_xor_b32_e32 v164, 16, v155
	v_add_u32_e32 v165, 64, v165
	v_xor_b32_e32 v179, 32, v155
	v_cmp_lt_i32_e32 vcc, v164, v165
	v_or_b32_e32 v178, 0x80, v180
	s_waitcnt vmcnt(0)
	v_pk_add_f32 v[128:129], v[128:129], v[202:203]
	v_cndmask_b32_e32 v164, v155, v164, vcc
	v_cmp_lt_i32_e32 vcc, v179, v165
	v_lshlrev_b32_e32 v198, 2, v164
	v_pk_add_f32 v[126:127], v[126:127], v[200:201]
	v_cndmask_b32_e32 v165, v155, v179, vcc
	v_lshlrev_b32_e32 v197, 2, v165
	v_lshlrev_b64 v[164:165], 10, v[182:183]
	v_pk_add_f32 v[124:125], v[124:125], v[206:207]
	v_pk_add_f32 v[122:123], v[122:123], v[204:205]
	v_pk_add_f32 v[120:121], v[120:121], v[216:217]
	v_pk_add_f32 v[118:119], v[118:119], v[214:215]
	v_pk_add_f32 v[202:203], v[116:117], v[220:221]
	v_pk_add_f32 v[200:201], v[114:115], v[218:219]
	v_lshl_add_u64 v[208:209], v[164:165], 0, v[180:181]
	global_store_dwordx4 v[162:163], v[126:129], off
	global_store_dwordx4 v[162:163], v[122:125], off offset:16
	v_cvt_pk_bf16_f32 v114, v126, v127
	v_cvt_pk_bf16_f32 v115, v128, v129
	v_cvt_pk_bf16_f32 v116, v122, v123
	v_cvt_pk_bf16_f32 v117, v124, v125
	v_mul_f32_e32 v127, v127, v127
	v_mul_f32_e32 v129, v129, v129
	v_mul_f32_e32 v123, v123, v123
	v_mul_f32_e32 v125, v125, v125
	v_mul_f32_e32 v183, v119, v119
	v_mul_f32_e32 v199, v121, v121
	v_mul_f32_e32 v204, v201, v201
	v_mul_f32_e32 v205, v203, v203
	v_lshl_add_u64 v[208:209], v[208:209], 1, s[24:25]
	v_fmac_f32_e32 v127, v126, v126
	v_fmac_f32_e32 v129, v128, v128
	v_fmac_f32_e32 v123, v122, v122
	v_fmac_f32_e32 v125, v124, v124
	v_fmac_f32_e32 v183, v118, v118
	v_fmac_f32_e32 v199, v120, v120
	v_fmac_f32_e32 v204, v200, v200
	v_fmac_f32_e32 v205, v202, v202
	global_store_dwordx4 v[208:209], v[114:117], off
	v_ashrrev_i32_e32 v179, 31, v178
	v_lshl_add_u64 v[164:165], v[164:165], 0, v[178:179]
	v_add_f32_e32 v114, v127, v129
	v_add_f32_e32 v115, v123, v125
	v_add_f32_e32 v116, v183, v199
	v_add_f32_e32 v117, v204, v205
	v_add_f32_e32 v114, v114, v115
	v_add_f32_e32 v115, v116, v117
	v_add_f32_e32 v114, v114, v115
	ds_bpermute_b32 v115, v198, v114
	global_store_dwordx4 v[162:163], v[118:121], off offset:512
	global_store_dwordx4 v[162:163], v[200:203], off offset:528
	v_cvt_pk_bf16_f32 v116, v118, v119
	v_cvt_pk_bf16_f32 v117, v120, v121
	v_cvt_pk_bf16_f32 v118, v200, v201
	s_waitcnt lgkmcnt(0)
	v_add_f32_e32 v114, v114, v115
	ds_bpermute_b32 v115, v197, v114
	v_cvt_pk_bf16_f32 v119, v202, v203
	v_lshl_add_u64 v[120:121], v[164:165], 1, s[24:25]
	global_store_dwordx4 v[120:121], v[116:119], off
	s_and_saveexec_b64 s[8:9], s[2:3]
	s_cbranch_execz .LBB0_1598
	s_waitcnt lgkmcnt(0)
	v_add_f32_e32 v114, v114, v115
	ds_write_b32 v192, v114

; #define PG8_STAGE(bufoff, gbase, voff) do { _Pragma("unroll") for (int _i = 0; _i < 2; ++_i) \
;         __builtin_amdgcn_global_load_lds((const unsigned*)((const char*)(gbase) + (voff)[_i]), (LAS unsigned*)(lds + (bufoff) + ldsw + _i * 8192), 16, 0, 0); } while (0)
; #define PG8_LDA(dst, b, h) do { _Pragma("unroll") for (int m = 0; m < 4; ++m) _Pragma("unroll") for (int k = 0; k < 2; ++k) dst[m][k] = *(const LAS bf16x8*)(lds + PG8_SA(b, h) + aoff + m * 2048 + k * 1024); } while (0)
; #define PG8_WAIT_V(n) asm volatile("s_waitcnt vmcnt(" #n ")" ::: "memory")
; #define PG8_WAIT_L(n) asm volatile("s_waitcnt lgkmcnt(" #n ")" ::: "memory")
; template <class Epi>
; DEVI void gemm_phase(LAS unsigned char* lds, const Gemm g, const Epi& E) {
;     ...
;         for (int t = 0; t < nt; t += 2) {
;             const bool last = (t == nt - 2);
;             const char* a1 = cA + (size_t)(t + 1) * kstep;
;             const char* a2 = last ? nA : cA + (size_t)(t + 2) * kstep; const char* b2 = last ? nB : cB + (size_t)(t + 2) * kstep;
;             const char* a3 = a2 + kstep; const char* b3 = b2 + kstep;
;             PG8_LDB(B0, 0, 0); PG8_SCHED; PG8_LDA(At, 0, 0); PG8_STAGE(PG8_SA(1, 1), a1 + hstepA, voffA);
;             PG8_WAIT_L(8); PG8_BAR; PG8_WAIT_L(0); PG8_MMA(0, 0, At, B0); PG8_BAR; PG8_SCHED;
;             PG8_LDB(B1, 0, 1); PG8_STAGE(PG8_SB(0, 0), b2, voffB);
;             PG8_BAR; PG8_WAIT_L(0); PG8_MMA(0, 1, At, B1); PG8_BAR;
;             PG8_LDA(At, 0, 1); PG8_STAGE(PG8_SA(0, 0), a2, voffA);
;             PG8_BAR; PG8_WAIT_L(0); PG8_MMA(1, 0, At, B0); PG8_BAR; PG8_SCHED;
;             PG8_STAGE(PG8_SB(0, 1), b2 + hstepB, voffB);
;             PG8_WAIT_V(6); PG8_BAR; PG8_MMA(1, 1, At, B1); PG8_BAR;
;             PG8_LDB(B0, 1, 0); PG8_SCHED; PG8_LDA(At, 1, 0); PG8_STAGE(PG8_SA(0, 1), a2 + hstepA, voffA);
;             PG8_WAIT_L(8); PG8_BAR; PG8_WAIT_L(0); PG8_MMA(0, 0, At, B0); PG8_BAR; PG8_SCHED;
;             PG8_LDB(B1, 1, 1); PG8_STAGE(PG8_SB(1, 0), b3, voffB);
;             PG8_BAR; PG8_WAIT_L(0); PG8_MMA(0, 1, At, B1); PG8_BAR;
;             PG8_LDA(At, 1, 1); PG8_STAGE(PG8_SA(1, 0), a3, voffA);
;             PG8_BAR; PG8_WAIT_L(0); PG8_MMA(1, 0, At, B0); PG8_BAR; PG8_SCHED;
;             PG8_STAGE(PG8_SB(1, 1), b3 + hstepB, voffB);
;             PG8_WAIT_V(6); PG8_BAR; PG8_MMA(1, 1, At, B1); PG8_BAR;
;         }
.LBB0_1672:
	s_add_u32 s26, s16, 0xfffc0080
	s_addc_u32 s27, s17, -1
	s_add_i32 s38, 0, 0x10000
	v_add_u32_e32 v142, s38, v197
	ds_read_b128 v[130:133], v142
	ds_read_b128 v[134:137], v142 offset:1024
	ds_read_b128 v[138:141], v142 offset:2048
	ds_read_b128 v[142:145], v142 offset:3072
	s_cmp_eq_u32 s19, 12
	s_cselect_b32 s47, s0, s27
	s_cselect_b32 s46, s1, s26
	s_cselect_b32 s37, s5, s18
	s_cselect_b32 s36, s7, s9
	s_add_i32 m0, s79, 0xc000
	ds_read_b128 v[178:181], v201
	ds_read_b128 v[182:185], v201 offset:1024
	ds_read_b128 v[186:189], v201 offset:2048
	ds_read_b128 v[202:205], v201 offset:3072
	ds_read_b128 v[206:209], v201 offset:4096
	ds_read_b128 v[214:217], v201 offset:5120
	ds_read_b128 v[218:221], v201 offset:6144
	ds_read_b128 v[222:225], v201 offset:7168
	global_load_lds_dwordx4 v152, s[16:17]
	s_add_i32 m0, s79, 0xe000
	s_nop 0
	global_load_lds_dwordx4 v176, s[16:17]
	s_waitcnt lgkmcnt(8)
	s_barrier
	s_waitcnt lgkmcnt(0)
	v_mfma_f32_16x16x32_bf16 v[126:129], v[130:133], v[178:181], v[126:129]
	v_mfma_f32_16x16x32_bf16 v[122:125], v[138:141], v[178:181], v[122:125]
	v_mfma_f32_16x16x32_bf16 v[110:113], v[130:133], v[186:189], v[110:113]
	v_mfma_f32_16x16x32_bf16 v[106:109], v[138:141], v[186:189], v[106:109]
	v_mfma_f32_16x16x32_bf16 v[94:97], v[130:133], v[206:209], v[94:97]
	v_mfma_f32_16x16x32_bf16 v[90:93], v[138:141], v[206:209], v[90:93]
	v_mfma_f32_16x16x32_bf16 v[78:81], v[130:133], v[218:221], v[78:81]
	v_mfma_f32_16x16x32_bf16 v[74:77], v[138:141], v[218:221], v[74:77]
	v_mfma_f32_16x16x32_bf16 v[126:129], v[134:137], v[182:185], v[126:129]
	v_mfma_f32_16x16x32_bf16 v[122:125], v[142:145], v[182:185], v[122:125]
	v_mfma_f32_16x16x32_bf16 v[110:113], v[134:137], v[202:205], v[110:113]
	v_mfma_f32_16x16x32_bf16 v[106:109], v[142:145], v[202:205], v[106:109]
	v_mfma_f32_16x16x32_bf16 v[94:97], v[134:137], v[214:217], v[94:97]
	v_mfma_f32_16x16x32_bf16 v[90:93], v[142:145], v[214:217], v[90:93]
	v_mfma_f32_16x16x32_bf16 v[78:81], v[134:137], v[222:225], v[78:81]
	v_mfma_f32_16x16x32_bf16 v[74:77], v[142:145], v[222:225], v[74:77]
	s_barrier
	s_add_i32 s39, 0, 0x14000
	v_add_u32_e32 v162, s39, v197
	s_add_i32 s26, s38, s78
	ds_read_b128 v[226:229], v162
	ds_read_b128 v[230:233], v162 offset:1024
	ds_read_b128 v[234:237], v162 offset:2048
	ds_read_b128 v[238:241], v162 offset:3072
	v_lshl_add_u64 v[162:163], s[36:37], 0, v[8:9]
	s_mov_b32 m0, s26
	v_lshl_add_u64 v[164:165], s[36:37], 0, v[146:147]
	global_load_lds_dwordx4 v[162:163], off
	s_add_i32 m0, s26, 0x2000
	s_nop 0
	global_load_lds_dwordx4 v[164:165], off
	s_barrier
	s_waitcnt lgkmcnt(0)
	v_mfma_f32_16x16x32_bf16 v[118:121], v[226:229], v[178:181], v[118:121]
	v_mfma_f32_16x16x32_bf16 v[114:117], v[234:237], v[178:181], v[114:117]
	v_mfma_f32_16x16x32_bf16 v[102:105], v[226:229], v[186:189], v[102:105]
	v_mfma_f32_16x16x32_bf16 v[98:101], v[234:237], v[186:189], v[98:101]
	v_mfma_f32_16x16x32_bf16 v[86:89], v[226:229], v[206:209], v[86:89]
	v_mfma_f32_16x16x32_bf16 v[82:85], v[234:237], v[206:209], v[82:85]
	v_mfma_f32_16x16x32_bf16 v[70:73], v[226:229], v[218:221], v[70:73]
	v_mfma_f32_16x16x32_bf16 v[66:69], v[234:237], v[218:221], v[66:69]
	v_mfma_f32_16x16x32_bf16 v[118:121], v[230:233], v[182:185], v[118:121]
	v_mfma_f32_16x16x32_bf16 v[114:117], v[238:241], v[182:185], v[114:117]
	v_mfma_f32_16x16x32_bf16 v[102:105], v[230:233], v[202:205], v[102:105]
	v_mfma_f32_16x16x32_bf16 v[98:101], v[238:241], v[202:205], v[98:101]
	v_mfma_f32_16x16x32_bf16 v[86:89], v[230:233], v[214:217], v[86:89]
	v_mfma_f32_16x16x32_bf16 v[82:85], v[238:241], v[214:217], v[82:85]
	v_mfma_f32_16x16x32_bf16 v[70:73], v[230:233], v[222:225], v[70:73]
	v_mfma_f32_16x16x32_bf16 v[66:69], v[238:241], v[222:225], v[66:69]
	s_mov_b32 m0, s79
	v_lshl_add_u64 v[190:191], s[46:47], 0, v[150:151]
	s_barrier
	ds_read_b128 v[178:181], v201 offset:16384
	ds_read_b128 v[182:185], v201 offset:17408
	ds_read_b128 v[186:189], v201 offset:18432
	ds_read_b128 v[202:205], v201 offset:19456
	ds_read_b128 v[206:209], v201 offset:20480
	ds_read_b128 v[214:217], v201 offset:21504
	ds_read_b128 v[218:221], v201 offset:22528
	ds_read_b128 v[222:225], v201 offset:23552
	global_load_lds_dwordx4 v[190:191], off
	s_mov_b32 m0, s80
	v_lshl_add_u64 v[194:195], s[46:47], 0, v[148:149]
	global_load_lds_dwordx4 v[194:195], off
	s_barrier
	s_waitcnt lgkmcnt(0)
	v_mfma_f32_16x16x32_bf16 v[50:53], v[130:133], v[178:181], v[50:53]
	v_mfma_f32_16x16x32_bf16 v[54:57], v[138:141], v[178:181], v[54:57]
	v_mfma_f32_16x16x32_bf16 v[34:37], v[130:133], v[186:189], v[34:37]
	v_mfma_f32_16x16x32_bf16 v[38:41], v[138:141], v[186:189], v[38:41]
	v_mfma_f32_16x16x32_bf16 v[18:21], v[130:133], v[206:209], v[18:21]
	v_mfma_f32_16x16x32_bf16 v[22:25], v[138:141], v[206:209], v[22:25]
	v_mfma_f32_16x16x32_bf16 v[0:3], v[130:133], v[218:221], v[0:3]
	v_mfma_f32_16x16x32_bf16 v[4:7], v[138:141], v[218:221], v[4:7]
	v_mfma_f32_16x16x32_bf16 v[50:53], v[134:137], v[182:185], v[50:53]
	v_mfma_f32_16x16x32_bf16 v[54:57], v[142:145], v[182:185], v[54:57]
	v_mfma_f32_16x16x32_bf16 v[34:37], v[134:137], v[202:205], v[34:37]
	v_mfma_f32_16x16x32_bf16 v[38:41], v[142:145], v[202:205], v[38:41]
	v_mfma_f32_16x16x32_bf16 v[18:21], v[134:137], v[214:217], v[18:21]
	v_mfma_f32_16x16x32_bf16 v[22:25], v[142:145], v[214:217], v[22:25]
	v_mfma_f32_16x16x32_bf16 v[0:3], v[134:137], v[222:225], v[0:3]
	v_mfma_f32_16x16x32_bf16 v[4:7], v[142:145], v[222:225], v[4:7]
	s_barrier
	s_add_u32 s26, s36, 0x40000
	s_addc_u32 s27, s37, 0
	s_add_i32 s38, s39, s78
	s_mov_b32 m0, s38
	s_nop 0
	global_load_lds_dwordx4 v8, s[26:27]
	s_add_i32 m0, s38, 0x2000
	s_nop 0
	global_load_lds_dwordx4 v146, s[26:27]
	s_waitcnt vmcnt(6)
	s_barrier
; #define PG8_STAGE(bufoff, gbase, voff) do { _Pragma("unroll") for (int _i = 0; _i < 2; ++_i) \
;         __builtin_amdgcn_global_load_lds((const unsigned*)((const char*)(gbase) + (voff)[_i]), (LAS unsigned*)(lds + (bufoff) + ldsw + _i * 8192), 16, 0, 0); } while (0)
; #define PG8_LDA(dst, b, h) do { _Pragma("unroll") for (int m = 0; m < 4; ++m) _Pragma("unroll") for (int k = 0; k < 2; ++k) dst[m][k] = *(const LAS bf16x8*)(lds + PG8_SA(b, h) + aoff + m * 2048 + k * 1024); } while (0)
; #define PG8_WAIT_V(n) asm volatile("s_waitcnt vmcnt(" #n ")" ::: "memory")
; #define PG8_WAIT_L(n) asm volatile("s_waitcnt lgkmcnt(" #n ")" ::: "memory")
; template <class Epi>
; DEVI void gemm_phase(LAS unsigned char* lds, const Gemm g, const Epi& E) {
;     ...
;         for (int t = 0; t < nt; t += 2) {
;             const bool last = (t == nt - 2);
;             const char* a1 = cA + (size_t)(t + 1) * kstep;
;             const char* a2 = last ? nA : cA + (size_t)(t + 2) * kstep; const char* b2 = last ? nB : cB + (size_t)(t + 2) * kstep;
;             const char* a3 = a2 + kstep; const char* b3 = b2 + kstep;
;             PG8_LDB(B0, 0, 0); PG8_SCHED; PG8_LDA(At, 0, 0); PG8_STAGE(PG8_SA(1, 1), a1 + hstepA, voffA);
;             PG8_WAIT_L(8); PG8_BAR; PG8_WAIT_L(0); PG8_MMA(0, 0, At, B0); PG8_BAR; PG8_SCHED;
;             PG8_LDB(B1, 0, 1); PG8_STAGE(PG8_SB(0, 0), b2, voffB);
;             PG8_BAR; PG8_WAIT_L(0); PG8_MMA(0, 1, At, B1); PG8_BAR;
;             PG8_LDA(At, 0, 1); PG8_STAGE(PG8_SA(0, 0), a2, voffA);
;             PG8_BAR; PG8_WAIT_L(0); PG8_MMA(1, 0, At, B0); PG8_BAR; PG8_SCHED;
;             PG8_STAGE(PG8_SB(0, 1), b2 + hstepB, voffB);
;             PG8_WAIT_V(6); PG8_BAR; PG8_MMA(1, 1, At, B1); PG8_BAR;
;             PG8_LDB(B0, 1, 0); PG8_SCHED; PG8_LDA(At, 1, 0); PG8_STAGE(PG8_SA(0, 1), a2 + hstepA, voffA);
;             PG8_WAIT_L(8); PG8_BAR; PG8_WAIT_L(0); PG8_MMA(0, 0, At, B0); PG8_BAR; PG8_SCHED;
;             PG8_LDB(B1, 1, 1); PG8_STAGE(PG8_SB(1, 0), b3, voffB);
;             PG8_BAR; PG8_WAIT_L(0); PG8_MMA(0, 1, At, B1); PG8_BAR;
;             PG8_LDA(At, 1, 1); PG8_STAGE(PG8_SA(1, 0), a3, voffA);
;             PG8_BAR; PG8_WAIT_L(0); PG8_MMA(1, 0, At, B0); PG8_BAR; PG8_SCHED;
;             PG8_STAGE(PG8_SB(1, 1), b3 + hstepB, voffB);
;             PG8_WAIT_V(6); PG8_BAR; PG8_MMA(1, 1, At, B1); PG8_BAR;
;         }
	v_mfma_f32_16x16x32_bf16 v[58:61], v[226:229], v[178:181], v[58:61]
	v_mfma_f32_16x16x32_bf16 v[62:65], v[234:237], v[178:181], v[62:65]
	v_mfma_f32_16x16x32_bf16 v[42:45], v[226:229], v[186:189], v[42:45]
	v_mfma_f32_16x16x32_bf16 v[46:49], v[234:237], v[186:189], v[46:49]
	v_mfma_f32_16x16x32_bf16 v[26:29], v[226:229], v[206:209], v[26:29]
	v_mfma_f32_16x16x32_bf16 v[30:33], v[234:237], v[206:209], v[30:33]
	v_mfma_f32_16x16x32_bf16 v[10:13], v[226:229], v[218:221], v[10:13]
	v_mfma_f32_16x16x32_bf16 v[14:17], v[234:237], v[218:221], v[14:17]
	v_mfma_f32_16x16x32_bf16 v[58:61], v[230:233], v[182:185], v[58:61]
	v_mfma_f32_16x16x32_bf16 v[62:65], v[238:241], v[182:185], v[62:65]
	v_mfma_f32_16x16x32_bf16 v[42:45], v[230:233], v[202:205], v[42:45]
	v_mfma_f32_16x16x32_bf16 v[46:49], v[238:241], v[202:205], v[46:49]
	v_mfma_f32_16x16x32_bf16 v[26:29], v[230:233], v[214:217], v[26:29]
	v_mfma_f32_16x16x32_bf16 v[30:33], v[238:241], v[214:217], v[30:33]
	v_mfma_f32_16x16x32_bf16 v[10:13], v[230:233], v[222:225], v[10:13]
	v_mfma_f32_16x16x32_bf16 v[14:17], v[238:241], v[222:225], v[14:17]
	s_add_i32 s38, 0, 0x18000
	v_add_u32_e32 v142, s38, v197
	s_barrier
	ds_read_b128 v[130:133], v142
	ds_read_b128 v[134:137], v142 offset:1024
	ds_read_b128 v[138:141], v142 offset:2048
	ds_read_b128 v[142:145], v142 offset:3072
	s_add_u32 s26, s46, 0x40000
	s_addc_u32 s27, s47, 0
	s_mov_b32 m0, s81
	ds_read_b128 v[178:181], v201 offset:32768
	ds_read_b128 v[182:185], v201 offset:33792
	ds_read_b128 v[186:189], v201 offset:34816
	ds_read_b128 v[202:205], v201 offset:35840
	ds_read_b128 v[206:209], v201 offset:36864
	ds_read_b128 v[214:217], v201 offset:37888
	ds_read_b128 v[218:221], v201 offset:38912
	ds_read_b128 v[222:225], v201 offset:39936
	global_load_lds_dwordx4 v150, s[26:27]
	s_mov_b32 m0, s82
	s_nop 0
	global_load_lds_dwordx4 v148, s[26:27]
	s_waitcnt lgkmcnt(8)
	s_barrier
	s_waitcnt lgkmcnt(0)
	v_mfma_f32_16x16x32_bf16 v[126:129], v[130:133], v[178:181], v[126:129]
	v_mfma_f32_16x16x32_bf16 v[122:125], v[138:141], v[178:181], v[122:125]
	v_mfma_f32_16x16x32_bf16 v[110:113], v[130:133], v[186:189], v[110:113]
	v_mfma_f32_16x16x32_bf16 v[106:109], v[138:141], v[186:189], v[106:109]
	v_mfma_f32_16x16x32_bf16 v[94:97], v[130:133], v[206:209], v[94:97]
	v_mfma_f32_16x16x32_bf16 v[90:93], v[138:141], v[206:209], v[90:93]
	v_mfma_f32_16x16x32_bf16 v[78:81], v[130:133], v[218:221], v[78:81]
	v_mfma_f32_16x16x32_bf16 v[74:77], v[138:141], v[218:221], v[74:77]
	v_mfma_f32_16x16x32_bf16 v[126:129], v[134:137], v[182:185], v[126:129]
	v_mfma_f32_16x16x32_bf16 v[122:125], v[142:145], v[182:185], v[122:125]
	v_mfma_f32_16x16x32_bf16 v[110:113], v[134:137], v[202:205], v[110:113]
	v_mfma_f32_16x16x32_bf16 v[106:109], v[142:145], v[202:205], v[106:109]
	v_mfma_f32_16x16x32_bf16 v[94:97], v[134:137], v[214:217], v[94:97]
	v_mfma_f32_16x16x32_bf16 v[90:93], v[142:145], v[214:217], v[90:93]
	v_mfma_f32_16x16x32_bf16 v[78:81], v[134:137], v[222:225], v[78:81]
	v_mfma_f32_16x16x32_bf16 v[74:77], v[142:145], v[222:225], v[74:77]
	s_barrier
	s_add_i32 s39, 0, 0x1c000
	s_add_i32 s26, s38, s78
	v_add_u32_e32 v192, s39, v197
	v_lshl_add_u64 v[162:163], v[162:163], 0, s[70:71]
	s_mov_b32 m0, s26
	ds_read_b128 v[226:229], v192
	ds_read_b128 v[230:233], v192 offset:1024
	ds_read_b128 v[234:237], v192 offset:2048
	ds_read_b128 v[238:241], v192 offset:3072
	global_load_lds_dwordx4 v[162:163], off
	s_add_i32 m0, s26, 0x2000
	v_lshl_add_u64 v[162:163], v[164:165], 0, s[70:71]
	global_load_lds_dwordx4 v[162:163], off
	s_barrier
	s_waitcnt lgkmcnt(0)
	v_mfma_f32_16x16x32_bf16 v[118:121], v[226:229], v[178:181], v[118:121]
	v_mfma_f32_16x16x32_bf16 v[114:117], v[234:237], v[178:181], v[114:117]
	v_mfma_f32_16x16x32_bf16 v[102:105], v[226:229], v[186:189], v[102:105]
	v_mfma_f32_16x16x32_bf16 v[98:101], v[234:237], v[186:189], v[98:101]
	v_mfma_f32_16x16x32_bf16 v[86:89], v[226:229], v[206:209], v[86:89]
	v_mfma_f32_16x16x32_bf16 v[82:85], v[234:237], v[206:209], v[82:85]
	v_mfma_f32_16x16x32_bf16 v[70:73], v[226:229], v[218:221], v[70:73]
	v_mfma_f32_16x16x32_bf16 v[66:69], v[234:237], v[218:221], v[66:69]
	v_mfma_f32_16x16x32_bf16 v[118:121], v[230:233], v[182:185], v[118:121]
	v_mfma_f32_16x16x32_bf16 v[114:117], v[238:241], v[182:185], v[114:117]
	v_mfma_f32_16x16x32_bf16 v[102:105], v[230:233], v[202:205], v[102:105]
	v_mfma_f32_16x16x32_bf16 v[98:101], v[238:241], v[202:205], v[98:101]
	v_mfma_f32_16x16x32_bf16 v[86:89], v[230:233], v[214:217], v[86:89]
	v_mfma_f32_16x16x32_bf16 v[82:85], v[238:241], v[214:217], v[82:85]
	v_mfma_f32_16x16x32_bf16 v[70:73], v[230:233], v[222:225], v[70:73]
	v_mfma_f32_16x16x32_bf16 v[66:69], v[238:241], v[222:225], v[66:69]
	s_mov_b32 m0, s83
	v_lshl_add_u64 v[162:163], v[190:191], 0, s[70:71]
	s_barrier
	ds_read_b128 v[178:181], v201 offset:49152
	ds_read_b128 v[182:185], v201 offset:50176
	ds_read_b128 v[186:189], v201 offset:51200
	ds_read_b128 v[202:205], v201 offset:52224
	ds_read_b128 v[206:209], v201 offset:53248
	ds_read_b128 v[214:217], v201 offset:54272
	ds_read_b128 v[218:221], v201 offset:55296
	ds_read_b128 v[222:225], v201 offset:56320
	global_load_lds_dwordx4 v[162:163], off
	s_mov_b32 m0, s84
	v_lshl_add_u64 v[162:163], v[194:195], 0, s[70:71]
	global_load_lds_dwordx4 v[162:163], off
	s_barrier
; #define PG8_STAGE(bufoff, gbase, voff) do { _Pragma("unroll") for (int _i = 0; _i < 2; ++_i) \
;         __builtin_amdgcn_global_load_lds((const unsigned*)((const char*)(gbase) + (voff)[_i]), (LAS unsigned*)(lds + (bufoff) + ldsw + _i * 8192), 16, 0, 0); } while (0)
; #define PG8_BAR __builtin_amdgcn_s_barrier()
; template <class Epi>
; DEVI void gemm_phase(LAS unsigned char* lds, const Gemm g, const Epi& E) {
;     ...
;         for (int t = 0; t < nt; t += 2) {
;             const bool last = (t == nt - 2);
;             const char* a1 = cA + (size_t)(t + 1) * kstep;
;             const char* a2 = last ? nA : cA + (size_t)(t + 2) * kstep; const char* b2 = last ? nB : cB + (size_t)(t + 2) * kstep;
;             const char* a3 = a2 + kstep; const char* b3 = b2 + kstep;
;             PG8_LDB(B0, 0, 0); PG8_SCHED; PG8_LDA(At, 0, 0); PG8_STAGE(PG8_SA(1, 1), a1 + hstepA, voffA);
;             PG8_WAIT_L(8); PG8_BAR; PG8_WAIT_L(0); PG8_MMA(0, 0, At, B0); PG8_BAR; PG8_SCHED;
;             PG8_LDB(B1, 0, 1); PG8_STAGE(PG8_SB(0, 0), b2, voffB);
;             PG8_BAR; PG8_WAIT_L(0); PG8_MMA(0, 1, At, B1); PG8_BAR;
;             PG8_LDA(At, 0, 1); PG8_STAGE(PG8_SA(0, 0), a2, voffA);
;             PG8_BAR; PG8_WAIT_L(0); PG8_MMA(1, 0, At, B0); PG8_BAR; PG8_SCHED;
;             PG8_STAGE(PG8_SB(0, 1), b2 + hstepB, voffB);
;             PG8_WAIT_V(6); PG8_BAR; PG8_MMA(1, 1, At, B1); PG8_BAR;
;             PG8_LDB(B0, 1, 0); PG8_SCHED; PG8_LDA(At, 1, 0); PG8_STAGE(PG8_SA(0, 1), a2 + hstepA, voffA);
;             PG8_WAIT_L(8); PG8_BAR; PG8_WAIT_L(0); PG8_MMA(0, 0, At, B0); PG8_BAR; PG8_SCHED;
;             PG8_LDB(B1, 1, 1); PG8_STAGE(PG8_SB(1, 0), b3, voffB);
;             PG8_BAR; PG8_WAIT_L(0); PG8_MMA(0, 1, At, B1); PG8_BAR;
;             PG8_LDA(At, 1, 1); PG8_STAGE(PG8_SA(1, 0), a3, voffA);
;             PG8_BAR; PG8_WAIT_L(0); PG8_MMA(1, 0, At, B0); PG8_BAR; PG8_SCHED;
;             PG8_STAGE(PG8_SB(1, 1), b3 + hstepB, voffB);
;             PG8_WAIT_V(6); PG8_BAR; PG8_MMA(1, 1, At, B1); PG8_BAR;
;         }
;     ...
;             if constexpr (Epi::RS) { f32x4 q4[8];
; #pragma unroll
;                 for (int i = 0; i < 8; ++i) q4[i] = *(const f32x4*)(E.ssq_in + (size_t)(row0 + (i >> 2) * HALF + (i & 3) * 16) * 4);
; #pragma unroll
;                 for (int i = 0; i < 8; ++i) rsv[i] = rsqrtf((((q4[i][0] + q4[i][1]) + q4[i][2]) + q4[i][3]) * (1.f / DM) + 1e-6f); }
	s_waitcnt lgkmcnt(0)
	v_mfma_f32_16x16x32_bf16 v[50:53], v[130:133], v[178:181], v[50:53]
	v_mfma_f32_16x16x32_bf16 v[54:57], v[138:141], v[178:181], v[54:57]
	v_mfma_f32_16x16x32_bf16 v[34:37], v[130:133], v[186:189], v[34:37]
	v_mfma_f32_16x16x32_bf16 v[38:41], v[138:141], v[186:189], v[38:41]
	v_mfma_f32_16x16x32_bf16 v[18:21], v[130:133], v[206:209], v[18:21]
	v_mfma_f32_16x16x32_bf16 v[22:25], v[138:141], v[206:209], v[22:25]
	v_mfma_f32_16x16x32_bf16 v[0:3], v[130:133], v[218:221], v[0:3]
	v_mfma_f32_16x16x32_bf16 v[4:7], v[138:141], v[218:221], v[4:7]
	v_mfma_f32_16x16x32_bf16 v[50:53], v[134:137], v[182:185], v[50:53]
	v_mfma_f32_16x16x32_bf16 v[54:57], v[142:145], v[182:185], v[54:57]
	v_mfma_f32_16x16x32_bf16 v[34:37], v[134:137], v[202:205], v[34:37]
	v_mfma_f32_16x16x32_bf16 v[38:41], v[142:145], v[202:205], v[38:41]
	v_mfma_f32_16x16x32_bf16 v[18:21], v[134:137], v[214:217], v[18:21]
	v_mfma_f32_16x16x32_bf16 v[22:25], v[142:145], v[214:217], v[22:25]
	v_mfma_f32_16x16x32_bf16 v[0:3], v[134:137], v[222:225], v[0:3]
	v_mfma_f32_16x16x32_bf16 v[4:7], v[142:145], v[222:225], v[4:7]
	s_barrier
	s_add_u32 s26, s36, 0x40080
	s_addc_u32 s27, s37, 0
	s_add_i32 s36, s39, s78
	s_mov_b32 m0, s36
	s_nop 0
	global_load_lds_dwordx4 v8, s[26:27]
	s_add_i32 m0, s36, 0x2000
	s_nop 0
	global_load_lds_dwordx4 v146, s[26:27]
	s_waitcnt vmcnt(6)
	s_barrier
	v_mfma_f32_16x16x32_bf16 v[58:61], v[226:229], v[178:181], v[58:61]
	v_mfma_f32_16x16x32_bf16 v[62:65], v[234:237], v[178:181], v[62:65]
	v_mfma_f32_16x16x32_bf16 v[42:45], v[226:229], v[186:189], v[42:45]
	v_mfma_f32_16x16x32_bf16 v[46:49], v[234:237], v[186:189], v[46:49]
	v_mfma_f32_16x16x32_bf16 v[26:29], v[226:229], v[206:209], v[26:29]
	v_mfma_f32_16x16x32_bf16 v[30:33], v[234:237], v[206:209], v[30:33]
	v_mfma_f32_16x16x32_bf16 v[10:13], v[226:229], v[218:221], v[10:13]
	v_mfma_f32_16x16x32_bf16 v[14:17], v[234:237], v[218:221], v[14:17]
	v_mfma_f32_16x16x32_bf16 v[58:61], v[230:233], v[182:185], v[58:61]
	v_mfma_f32_16x16x32_bf16 v[62:65], v[238:241], v[182:185], v[62:65]
	v_mfma_f32_16x16x32_bf16 v[42:45], v[230:233], v[202:205], v[42:45]
	v_mfma_f32_16x16x32_bf16 v[46:49], v[238:241], v[202:205], v[46:49]
	v_mfma_f32_16x16x32_bf16 v[26:29], v[230:233], v[214:217], v[26:29]
	v_mfma_f32_16x16x32_bf16 v[30:33], v[238:241], v[214:217], v[30:33]
	v_mfma_f32_16x16x32_bf16 v[10:13], v[230:233], v[222:225], v[10:13]
	v_mfma_f32_16x16x32_bf16 v[14:17], v[238:241], v[222:225], v[14:17]
	s_add_i32 s19, s19, 2
	s_add_u32 s16, s16, 0x100
	s_addc_u32 s17, s17, 0
	s_add_u32 s9, s9, 0x100
	s_addc_u32 s18, s18, 0
	s_cmp_gt_u32 s19, 13
	s_barrier
	s_cbranch_scc0 .LBB0_1672
	s_setprio 0
	v_lshl_add_u32 v194, s4, 8, v193
	v_add_u32_e32 v178, 0xb0, v194
	v_ashrrev_i32_e32 v195, 31, v194
	v_or_b32_e32 v190, 16, v194
	v_ashrrev_i32_e32 v179, 31, v178
	v_lshl_add_u64 v[130:131], v[194:195], 4, s[10:11]
	v_ashrrev_i32_e32 v191, 31, v190
	v_lshl_add_u64 v[134:135], v[178:179], 4, s[10:11]
	global_load_dwordx4 v[202:205], v[130:131], off
	v_or_b32_e32 v188, 32, v194
	global_load_dwordx4 v[134:137], v[134:135], off
	v_lshl_add_u64 v[130:131], v[190:191], 4, s[10:11]
	global_load_dwordx4 v[206:209], v[130:131], off
	v_ashrrev_i32_e32 v189, 31, v188
	v_or_b32_e32 v186, 48, v194
	v_lshl_add_u64 v[130:131], v[188:189], 4, s[10:11]
	v_ashrrev_i32_e32 v187, 31, v186
	global_load_dwordx4 v[214:217], v[130:131], off
	v_lshl_add_u64 v[130:131], v[186:187], 4, s[10:11]
	global_load_dwordx4 v[218:221], v[130:131], off
	v_add_u32_e32 v184, 0x80, v194
	v_ashrrev_i32_e32 v185, 31, v184
	v_add_u32_e32 v182, 0x90, v194
	v_lshl_add_u64 v[130:131], v[184:185], 4, s[10:11]
	v_ashrrev_i32_e32 v183, 31, v182
	global_load_dwordx4 v[138:141], v[130:131], off
	v_lshl_add_u64 v[130:131], v[182:183], 4, s[10:11]
	v_add_u32_e32 v180, 0xa0, v194
	global_load_dwordx4 v[142:145], v[130:131], off
	v_ashrrev_i32_e32 v181, 31, v180
	v_lshl_add_u64 v[130:131], v[180:181], 4, s[10:11]
	global_load_dwordx4 v[130:133], v[130:131], off
	s_mov_b32 s0, 0x358637bd
	s_mov_b64 s[36:37], s[14:15]
	s_mov_b64 s[16:17], s[12:13]
	s_waitcnt vmcnt(0)
	v_mov_b32_e32 v163, v202
	v_mov_b32_e32 v165, v204
	v_mov_b32_e32 v162, v206
	v_mov_b32_e32 v202, v207
	v_pk_add_f32 v[162:163], v[162:163], v[202:203]
	v_mov_b32_e32 v164, v208
	v_pk_add_f32 v[162:163], v[164:165], v[162:163]
	v_mov_b32_e32 v204, v209
	v_pk_add_f32 v[162:163], v[204:205], v[162:163]
	v_mov_b64_e32 v[202:203], s[0:1]
	v_pk_fma_f32 v[162:163], v[162:163], s[72:73], v[202:203] op_sel_hi:[1,0,0]
	v_mov_b32_e32 v165, v216
	v_mul_f32_e32 v164, 0x4b800000, v163
	v_cmp_gt_f32_e64 s[4:5], s94, v163
	v_cmp_gt_f32_e32 vcc, s94, v162
	v_mov_b32_e32 v216, v221
	v_cndmask_b32_e64 v163, v163, v164, s[4:5]
	v_rsq_f32_e32 v163, v163
	s_nop 0
	v_mul_f32_e32 v164, 0x45800000, v163
	v_cndmask_b32_e64 v200, v163, v164, s[4:5]
	v_mul_f32_e32 v163, 0x4b800000, v162
	v_cndmask_b32_e32 v162, v162, v163, vcc
	v_rsq_f32_e32 v162, v162
	v_mov_b32_e32 v164, v220
	v_pk_mul_f32 v[126:127], v[126:127], v[200:201] op_sel_hi:[1,0]
	v_pk_mul_f32 v[122:123], v[122:123], v[200:201] op_sel_hi:[1,0]
	v_mul_f32_e32 v163, 0x45800000, v162
	v_cndmask_b32_e32 v198, v162, v163, vcc
	v_mov_b32_e32 v162, v218
	v_mov_b32_e32 v163, v214
	v_mov_b32_e32 v214, v219
	v_pk_add_f32 v[162:163], v[162:163], v[214:215]
	v_pk_mul_f32 v[118:119], v[118:119], v[200:201] op_sel_hi:[1,0]
	v_pk_add_f32 v[162:163], v[164:165], v[162:163]
	v_pk_mul_f32 v[124:125], v[124:125], v[200:201] op_sel_hi:[1,0]
	v_pk_add_f32 v[162:163], v[216:217], v[162:163]
	v_pk_mul_f32 v[114:115], v[114:115], v[200:201] op_sel_hi:[1,0]
	v_pk_fma_f32 v[162:163], v[162:163], s[72:73], v[202:203] op_sel_hi:[1,0,0]
; template <class Epi>
; DEVI void gemm_phase(LAS unsigned char* lds, const Gemm g, const Epi& E) {
;     ...
; #pragma unroll
;                 for (int mm = 0; mm < 2; ++mm) {
;                     const int m = m0 + mm;
;                     const int r = row0 + ai * HALF + m * 16; float rs = 1.f, part = 0.f;
;                     if constexpr (Epi::RS) rs = rsv[ai * 4 + m];
;                     if constexpr (Epi::PAIR) E.pair8(cur.b, r, cur.pn * HALF + wc * 32 + 8 * fq, acc[ai][0][m][0] * rs, acc[ai][0][m][1] * rs, acc[ai][1][m][0] * rs, acc[ai][1][m][1] * rs);
	v_pk_mul_f32 v[128:129], v[128:129], v[200:201] op_sel_hi:[1,0]
	v_mul_f32_e32 v164, 0x4b800000, v163
	v_cmp_gt_f32_e64 s[4:5], s94, v163
	v_cmp_gt_f32_e32 vcc, s94, v162
	v_pk_mul_f32 v[120:121], v[120:121], v[200:201] op_sel_hi:[1,0]
	v_cndmask_b32_e64 v163, v163, v164, s[4:5]
	v_rsq_f32_e32 v163, v163
	v_pk_mul_f32 v[116:117], v[116:117], v[200:201] op_sel_hi:[1,0]
	v_pk_mul_f32 v[106:107], v[106:107], v[198:199] op_sel_hi:[1,0]
	v_pk_mul_f32 v[110:111], v[110:111], v[198:199] op_sel_hi:[1,0]
	v_mul_f32_e32 v164, 0x45800000, v163
	v_cndmask_b32_e64 v196, v163, v164, s[4:5]
	v_mul_f32_e32 v163, 0x4b800000, v162
	v_cndmask_b32_e32 v162, v162, v163, vcc
	v_rsq_f32_e32 v162, v162
	v_pk_mul_f32 v[102:103], v[102:103], v[198:199] op_sel_hi:[1,0]
	v_pk_mul_f32 v[108:109], v[108:109], v[198:199] op_sel_hi:[1,0]
	v_pk_mul_f32 v[98:99], v[98:99], v[198:199] op_sel_hi:[1,0]
	v_mul_f32_e32 v163, 0x45800000, v162
	v_cndmask_b32_e32 v192, v162, v163, vcc
	v_mov_b32_e32 v162, v142
	v_mov_b32_e32 v163, v138
	v_mov_b32_e32 v138, v143
	v_pk_add_f32 v[138:139], v[162:163], v[138:139]
	v_mov_b32_e32 v142, v144
	v_mov_b32_e32 v143, v140
	v_pk_add_f32 v[138:139], v[142:143], v[138:139]
	v_mov_b32_e32 v142, v134
	v_mov_b32_e32 v143, v130
	v_mov_b32_e32 v130, v135
	v_pk_add_f32 v[130:131], v[142:143], v[130:131]
	v_mov_b32_e32 v134, v136
	v_mov_b32_e32 v135, v132
	v_pk_add_f32 v[130:131], v[134:135], v[130:131]
	v_mov_b32_e32 v132, v137
	v_pk_add_f32 v[130:131], v[132:133], v[130:131]
	v_mul_f32_e32 v133, 0xbfb8aa3b, v126
	v_exp_f32_e32 v133, v133
	v_mov_b32_e32 v140, v145
	v_pk_add_f32 v[138:139], v[140:141], v[138:139]
	v_pk_fma_f32 v[130:131], v[130:131], s[72:73], v[202:203] op_sel_hi:[1,0,0]
	v_add_f32_e32 v133, 1.0, v133
	v_rcp_f32_e32 v136, v133
	v_mul_f32_e32 v133, 0xbfb8aa3b, v122
	v_exp_f32_e32 v133, v133
	v_pk_fma_f32 v[138:139], v[138:139], s[72:73], v[202:203] op_sel_hi:[1,0,0]
	v_mul_f32_e32 v132, 0x4b800000, v131
	v_mul_f32_e32 v140, 0x4b800000, v139
	v_add_f32_e32 v133, 1.0, v133
	v_rcp_f32_e32 v142, v133
	v_mul_f32_e32 v133, 0xbfb8aa3b, v127
	v_exp_f32_e32 v133, v133
	v_cmp_gt_f32_e64 s[4:5], s94, v139
	v_cmp_gt_f32_e32 vcc, s94, v138
	v_pk_mul_f32 v[112:113], v[112:113], v[198:199] op_sel_hi:[1,0]
	v_add_f32_e32 v133, 1.0, v133
	v_rcp_f32_e32 v137, v133
	v_cndmask_b32_e64 v139, v139, v140, s[4:5]
	v_rsq_f32_e32 v139, v139
	v_pk_mul_f32 v[104:105], v[104:105], v[198:199] op_sel_hi:[1,0]
	v_pk_mul_f32 v[126:127], v[126:127], v[136:137]
	v_pk_mul_f32 v[100:101], v[100:101], v[198:199] op_sel_hi:[1,0]
	v_pk_mul_f32 v[118:119], v[118:119], v[126:127]
	v_mul_f32_e32 v126, 0xbfb8aa3b, v123
	v_exp_f32_e32 v126, v126
	v_mul_f32_e32 v140, 0x45800000, v139
	v_cndmask_b32_e64 v140, v139, v140, s[4:5]
	v_mul_f32_e32 v139, 0x4b800000, v138
	v_add_f32_e32 v126, 1.0, v126
	v_rcp_f32_e32 v143, v126
	v_cmp_gt_f32_e64 s[4:5], s94, v131
	v_cndmask_b32_e32 v138, v138, v139, vcc
	v_rsq_f32_e32 v138, v138
	v_pk_mul_f32 v[122:123], v[122:123], v[142:143]
	v_cndmask_b32_e64 v131, v131, v132, s[4:5]
	v_pk_mul_f32 v[122:123], v[114:115], v[122:123]
	v_mul_f32_e32 v115, 0xbfb8aa3b, v124
	v_exp_f32_e32 v115, v115
	v_mul_f32_e32 v114, 0xbfb8aa3b, v128
	v_exp_f32_e32 v114, v114
	v_rsq_f32_e32 v131, v131
	v_add_f32_e32 v115, 1.0, v115
	v_rcp_f32_e32 v126, v115
	v_mul_f32_e32 v115, 0xbfb8aa3b, v129
	v_exp_f32_e32 v115, v115
	v_add_f32_e32 v114, 1.0, v114
	v_rcp_f32_e32 v114, v114
	v_mul_f32_e32 v139, 0x45800000, v138
	v_add_f32_e32 v115, 1.0, v115
	v_rcp_f32_e32 v115, v115
	v_mul_f32_e32 v132, 0x45800000, v131
	v_cndmask_b32_e32 v138, v138, v139, vcc
	v_cmp_gt_f32_e32 vcc, s94, v130
	v_pk_mul_f32 v[114:115], v[128:129], v[114:115]
	v_cndmask_b32_e64 v134, v131, v132, s[4:5]
	v_pk_mul_f32 v[120:121], v[120:121], v[114:115]
	v_mul_f32_e32 v114, 0xbfb8aa3b, v125
	v_exp_f32_e32 v114, v114
	v_mul_f32_e32 v131, 0x4b800000, v130
	v_cndmask_b32_e32 v130, v130, v131, vcc
	v_rsq_f32_e32 v130, v130
	v_add_f32_e32 v114, 1.0, v114
	v_rcp_f32_e32 v127, v114
	v_pk_mul_f32 v[90:91], v[90:91], v[196:197] op_sel_hi:[1,0]
	v_mul_f32_e32 v131, 0x45800000, v130
	v_cndmask_b32_e32 v132, v130, v131, vcc
	v_lshl_or_b32 v130, s86, 7, v199
	v_ashrrev_i32_e32 v131, 31, v130
	v_pk_mul_f32 v[114:115], v[124:125], v[126:127]
	v_lshl_add_u64 v[130:131], v[130:131], 1, s[28:29]
	v_pk_mul_f32 v[124:125], v[116:117], v[114:115]
	v_cvt_pk_bf16_f32 v114, v118, v119
	v_cvt_pk_bf16_f32 v115, v120, v121
	v_cvt_pk_bf16_f32 v116, v122, v123
	v_cvt_pk_bf16_f32 v117, v124, v125
	v_mad_i64_i32 v[118:119], s[0:1], v194, s35, v[130:131]
	global_store_dwordx4 v[118:119], v[114:117], off
	v_pk_mul_f32 v[94:95], v[94:95], v[196:197] op_sel_hi:[1,0]
	v_pk_mul_f32 v[86:87], v[86:87], v[196:197] op_sel_hi:[1,0]
	v_mul_f32_e32 v115, 0xbfb8aa3b, v106
	v_exp_f32_e32 v115, v115
	v_mul_f32_e32 v114, 0xbfb8aa3b, v110
	v_exp_f32_e32 v114, v114
	v_pk_mul_f32 v[92:93], v[92:93], v[196:197] op_sel_hi:[1,0]
	v_add_f32_e32 v115, 1.0, v115
	v_rcp_f32_e32 v116, v115
	v_mul_f32_e32 v115, 0xbfb8aa3b, v111
	v_exp_f32_e32 v115, v115
	v_add_f32_e32 v114, 1.0, v114
	v_rcp_f32_e32 v114, v114
	v_pk_mul_f32 v[82:83], v[82:83], v[196:197] op_sel_hi:[1,0]
	v_add_f32_e32 v115, 1.0, v115
	v_rcp_f32_e32 v115, v115
	v_pk_mul_f32 v[96:97], v[96:97], v[196:197] op_sel_hi:[1,0]
	v_pk_mul_f32 v[88:89], v[88:89], v[196:197] op_sel_hi:[1,0]
	v_pk_mul_f32 v[84:85], v[84:85], v[196:197] op_sel_hi:[1,0]
	v_pk_mul_f32 v[110:111], v[110:111], v[114:115]
	v_pk_mul_f32 v[74:75], v[74:75], v[192:193] op_sel_hi:[1,0]
	v_pk_mul_f32 v[102:103], v[102:103], v[110:111]
	v_mul_f32_e32 v110, 0xbfb8aa3b, v107
	v_exp_f32_e32 v110, v110
	v_pk_mul_f32 v[78:79], v[78:79], v[192:193] op_sel_hi:[1,0]
; template <class Epi>
; DEVI void gemm_phase(LAS unsigned char* lds, const Gemm g, const Epi& E) {
;     ...
; #pragma unroll
;                 for (int mm = 0; mm < 2; ++mm) {
;                     const int m = m0 + mm;
;                     const int r = row0 + ai * HALF + m * 16; float rs = 1.f, part = 0.f;
;                     if constexpr (Epi::RS) rs = rsv[ai * 4 + m];
;                     if constexpr (Epi::PAIR) E.pair8(cur.b, r, cur.pn * HALF + wc * 32 + 8 * fq, acc[ai][0][m][0] * rs, acc[ai][0][m][1] * rs, acc[ai][1][m][0] * rs, acc[ai][1][m][1] * rs);
	v_pk_mul_f32 v[70:71], v[70:71], v[192:193] op_sel_hi:[1,0]
	v_pk_mul_f32 v[76:77], v[76:77], v[192:193] op_sel_hi:[1,0]
	v_add_f32_e32 v110, 1.0, v110
	v_rcp_f32_e32 v117, v110
	v_pk_mul_f32 v[66:67], v[66:67], v[192:193] op_sel_hi:[1,0]
	v_pk_mul_f32 v[80:81], v[80:81], v[192:193] op_sel_hi:[1,0]
	v_pk_mul_f32 v[72:73], v[72:73], v[192:193] op_sel_hi:[1,0]
	v_pk_mul_f32 v[106:107], v[106:107], v[116:117]
	v_pk_mul_f32 v[68:69], v[68:69], v[192:193] op_sel_hi:[1,0]
	v_pk_mul_f32 v[106:107], v[98:99], v[106:107]
	v_mul_f32_e32 v99, 0xbfb8aa3b, v108
	v_exp_f32_e32 v99, v99
	v_mul_f32_e32 v98, 0xbfb8aa3b, v112
	v_exp_f32_e32 v98, v98
	v_pk_mul_f32 v[54:55], v[54:55], v[140:141] op_sel_hi:[1,0]
	v_add_f32_e32 v99, 1.0, v99
	v_rcp_f32_e32 v110, v99
	v_mul_f32_e32 v99, 0xbfb8aa3b, v113
	v_exp_f32_e32 v99, v99
	v_add_f32_e32 v98, 1.0, v98
	v_rcp_f32_e32 v98, v98
	v_pk_mul_f32 v[50:51], v[50:51], v[140:141] op_sel_hi:[1,0]
	v_add_f32_e32 v99, 1.0, v99
	v_rcp_f32_e32 v99, v99
	v_pk_mul_f32 v[58:59], v[58:59], v[140:141] op_sel_hi:[1,0]
	v_pk_mul_f32 v[56:57], v[56:57], v[140:141] op_sel_hi:[1,0]
	v_pk_mul_f32 v[52:53], v[52:53], v[140:141] op_sel_hi:[1,0]
	v_pk_mul_f32 v[98:99], v[112:113], v[98:99]
	v_pk_mul_f32 v[62:63], v[62:63], v[140:141] op_sel_hi:[1,0]
	v_pk_mul_f32 v[104:105], v[104:105], v[98:99]
	v_mul_f32_e32 v98, 0xbfb8aa3b, v109
	v_exp_f32_e32 v98, v98
	v_pk_mul_f32 v[60:61], v[60:61], v[140:141] op_sel_hi:[1,0]
	v_pk_mul_f32 v[64:65], v[64:65], v[140:141] op_sel_hi:[1,0]
	v_pk_mul_f32 v[38:39], v[38:39], v[138:139] op_sel_hi:[1,0]
	v_add_f32_e32 v98, 1.0, v98
	v_rcp_f32_e32 v111, v98
	v_pk_mul_f32 v[34:35], v[34:35], v[138:139] op_sel_hi:[1,0]
	v_pk_mul_f32 v[42:43], v[42:43], v[138:139] op_sel_hi:[1,0]
	v_pk_mul_f32 v[40:41], v[40:41], v[138:139] op_sel_hi:[1,0]
	v_pk_mul_f32 v[98:99], v[108:109], v[110:111]
	v_pk_mul_f32 v[36:37], v[36:37], v[138:139] op_sel_hi:[1,0]
	v_pk_mul_f32 v[108:109], v[100:101], v[98:99]
	v_cvt_pk_bf16_f32 v98, v102, v103
	v_cvt_pk_bf16_f32 v99, v104, v105
	v_cvt_pk_bf16_f32 v100, v106, v107
	v_cvt_pk_bf16_f32 v101, v108, v109
	v_mad_i64_i32 v[102:103], s[0:1], v190, s35, v[130:131]
	global_store_dwordx4 v[102:103], v[98:101], off
	v_pk_mul_f32 v[46:47], v[46:47], v[138:139] op_sel_hi:[1,0]
	v_pk_mul_f32 v[44:45], v[44:45], v[138:139] op_sel_hi:[1,0]
	v_mul_f32_e32 v99, 0xbfb8aa3b, v90
	v_exp_f32_e32 v99, v99
	v_mul_f32_e32 v98, 0xbfb8aa3b, v94
	v_exp_f32_e32 v98, v98
	v_pk_mul_f32 v[48:49], v[48:49], v[138:139] op_sel_hi:[1,0]
	v_add_f32_e32 v99, 1.0, v99
	v_rcp_f32_e32 v100, v99
	v_mul_f32_e32 v99, 0xbfb8aa3b, v95
	v_exp_f32_e32 v99, v99
	v_add_f32_e32 v98, 1.0, v98
	v_rcp_f32_e32 v98, v98
	v_pk_mul_f32 v[22:23], v[22:23], v[134:135] op_sel_hi:[1,0]
	v_add_f32_e32 v99, 1.0, v99
	v_rcp_f32_e32 v99, v99
	v_pk_mul_f32 v[18:19], v[18:19], v[134:135] op_sel_hi:[1,0]
	v_pk_mul_f32 v[26:27], v[26:27], v[134:135] op_sel_hi:[1,0]
	v_pk_mul_f32 v[24:25], v[24:25], v[134:135] op_sel_hi:[1,0]
	v_pk_mul_f32 v[94:95], v[94:95], v[98:99]
	v_pk_mul_f32 v[20:21], v[20:21], v[134:135] op_sel_hi:[1,0]
	v_pk_mul_f32 v[86:87], v[86:87], v[94:95]
	v_mul_f32_e32 v94, 0xbfb8aa3b, v91
	v_exp_f32_e32 v94, v94
	v_pk_mul_f32 v[30:31], v[30:31], v[134:135] op_sel_hi:[1,0]
	v_pk_mul_f32 v[28:29], v[28:29], v[134:135] op_sel_hi:[1,0]
	v_pk_mul_f32 v[32:33], v[32:33], v[134:135] op_sel_hi:[1,0]
	v_add_f32_e32 v94, 1.0, v94
	v_rcp_f32_e32 v101, v94
	v_pk_mul_f32 v[4:5], v[4:5], v[132:133] op_sel_hi:[1,0]
	v_pk_mul_f32 v[0:1], v[0:1], v[132:133] op_sel_hi:[1,0]
	v_pk_mul_f32 v[10:11], v[10:11], v[132:133] op_sel_hi:[1,0]
	v_pk_mul_f32 v[90:91], v[90:91], v[100:101]
	v_pk_mul_f32 v[6:7], v[6:7], v[132:133] op_sel_hi:[1,0]
	v_pk_mul_f32 v[90:91], v[82:83], v[90:91]
	v_mul_f32_e32 v83, 0xbfb8aa3b, v92
	v_exp_f32_e32 v83, v83
	v_mul_f32_e32 v82, 0xbfb8aa3b, v96
	v_exp_f32_e32 v82, v82
	v_pk_mul_f32 v[2:3], v[2:3], v[132:133] op_sel_hi:[1,0]
	v_add_f32_e32 v83, 1.0, v83
	v_rcp_f32_e32 v94, v83
	v_mul_f32_e32 v83, 0xbfb8aa3b, v97
	v_exp_f32_e32 v83, v83
	v_add_f32_e32 v82, 1.0, v82
	v_rcp_f32_e32 v82, v82
	v_pk_mul_f32 v[14:15], v[14:15], v[132:133] op_sel_hi:[1,0]
	v_add_f32_e32 v83, 1.0, v83
	v_rcp_f32_e32 v83, v83
	v_pk_mul_f32 v[12:13], v[12:13], v[132:133] op_sel_hi:[1,0]
	v_pk_mul_f32 v[16:17], v[16:17], v[132:133] op_sel_hi:[1,0]
	s_and_b64 vcc, exec, s[2:3]
	v_pk_mul_f32 v[82:83], v[96:97], v[82:83]
	s_mov_b32 s86, s8
	v_pk_mul_f32 v[88:89], v[88:89], v[82:83]
	v_mul_f32_e32 v82, 0xbfb8aa3b, v93
	v_exp_f32_e32 v82, v82
	s_mov_b32 s4, s6
	v_add_f32_e32 v82, 1.0, v82
	v_rcp_f32_e32 v95, v82
	s_nop 0
	v_pk_mul_f32 v[82:83], v[92:93], v[94:95]
	s_nop 0
	v_pk_mul_f32 v[92:93], v[84:85], v[82:83]
	v_cvt_pk_bf16_f32 v82, v86, v87
	v_cvt_pk_bf16_f32 v83, v88, v89
	v_cvt_pk_bf16_f32 v84, v90, v91
	v_cvt_pk_bf16_f32 v85, v92, v93
	v_mad_i64_i32 v[86:87], s[0:1], v188, s35, v[130:131]
	global_store_dwordx4 v[86:87], v[82:85], off
	s_nop 1
	v_mul_f32_e32 v83, 0xbfb8aa3b, v74
	v_exp_f32_e32 v83, v83
	v_mul_f32_e32 v82, 0xbfb8aa3b, v78
	v_exp_f32_e32 v82, v82
	v_add_f32_e32 v83, 1.0, v83
	v_rcp_f32_e32 v84, v83
	v_mul_f32_e32 v83, 0xbfb8aa3b, v79
	v_exp_f32_e32 v83, v83
	v_add_f32_e32 v82, 1.0, v82
	v_rcp_f32_e32 v82, v82
	v_add_f32_e32 v83, 1.0, v83
	v_rcp_f32_e32 v83, v83
	s_nop 0
	v_pk_mul_f32 v[78:79], v[78:79], v[82:83]
	s_nop 0
	v_pk_mul_f32 v[70:71], v[70:71], v[78:79]
	v_mul_f32_e32 v78, 0xbfb8aa3b, v75
	v_exp_f32_e32 v78, v78
	s_nop 0
	v_add_f32_e32 v78, 1.0, v78
	v_rcp_f32_e32 v85, v78
	s_nop 0
	v_pk_mul_f32 v[74:75], v[74:75], v[84:85]
	s_nop 0
	v_pk_mul_f32 v[74:75], v[66:67], v[74:75]
	v_mul_f32_e32 v67, 0xbfb8aa3b, v76
; template <class Epi>
; DEVI void gemm_phase(LAS unsigned char* lds, const Gemm g, const Epi& E) {
;     ...
; #pragma unroll
;                 for (int mm = 0; mm < 2; ++mm) {
;                     const int m = m0 + mm;
;                     const int r = row0 + ai * HALF + m * 16; float rs = 1.f, part = 0.f;
;                     if constexpr (Epi::RS) rs = rsv[ai * 4 + m];
;                     if constexpr (Epi::PAIR) E.pair8(cur.b, r, cur.pn * HALF + wc * 32 + 8 * fq, acc[ai][0][m][0] * rs, acc[ai][0][m][1] * rs, acc[ai][1][m][0] * rs, acc[ai][1][m][1] * rs);
	v_exp_f32_e32 v67, v67
	v_mul_f32_e32 v66, 0xbfb8aa3b, v80
	v_exp_f32_e32 v66, v66
	v_add_f32_e32 v67, 1.0, v67
	v_rcp_f32_e32 v78, v67
	v_mul_f32_e32 v67, 0xbfb8aa3b, v81
	v_exp_f32_e32 v67, v67
	v_add_f32_e32 v66, 1.0, v66
	v_rcp_f32_e32 v66, v66
	v_add_f32_e32 v67, 1.0, v67
	v_rcp_f32_e32 v67, v67
	s_nop 0
	v_pk_mul_f32 v[66:67], v[80:81], v[66:67]
	s_nop 0
	v_pk_mul_f32 v[72:73], v[72:73], v[66:67]
	v_mul_f32_e32 v66, 0xbfb8aa3b, v77
	v_exp_f32_e32 v66, v66
	s_nop 0
	v_add_f32_e32 v66, 1.0, v66
	v_rcp_f32_e32 v79, v66
	s_nop 0
	v_pk_mul_f32 v[66:67], v[76:77], v[78:79]
	s_nop 0
	v_pk_mul_f32 v[76:77], v[68:69], v[66:67]
	v_cvt_pk_bf16_f32 v66, v70, v71
	v_cvt_pk_bf16_f32 v67, v72, v73
	v_cvt_pk_bf16_f32 v68, v74, v75
	v_cvt_pk_bf16_f32 v69, v76, v77
	v_mad_i64_i32 v[70:71], s[0:1], v186, s35, v[130:131]
	global_store_dwordx4 v[70:71], v[66:69], off
	s_nop 1
	v_mul_f32_e32 v67, 0xbfb8aa3b, v54
	v_exp_f32_e32 v67, v67
	v_mul_f32_e32 v66, 0xbfb8aa3b, v50
	v_exp_f32_e32 v66, v66
	v_add_f32_e32 v67, 1.0, v67
	v_rcp_f32_e32 v68, v67
	v_mul_f32_e32 v67, 0xbfb8aa3b, v51
	v_exp_f32_e32 v67, v67
	v_add_f32_e32 v66, 1.0, v66
	v_rcp_f32_e32 v66, v66
	v_add_f32_e32 v67, 1.0, v67
	v_rcp_f32_e32 v67, v67
	s_nop 0
	v_pk_mul_f32 v[50:51], v[50:51], v[66:67]
	s_nop 0
	v_pk_mul_f32 v[50:51], v[58:59], v[50:51]
	v_mul_f32_e32 v58, 0xbfb8aa3b, v55
	v_exp_f32_e32 v58, v58
	v_mul_f32_e32 v59, 0xbfb8aa3b, v56
	v_exp_f32_e32 v59, v59
	v_cvt_pk_bf16_f32 v50, v50, v51
	v_add_f32_e32 v58, 1.0, v58
	v_rcp_f32_e32 v69, v58
	v_add_f32_e32 v59, 1.0, v59
	v_mul_f32_e32 v58, 0xbfb8aa3b, v52
	v_exp_f32_e32 v58, v58
	v_pk_mul_f32 v[54:55], v[54:55], v[68:69]
	v_add_f32_e32 v58, 1.0, v58
	v_pk_mul_f32 v[54:55], v[62:63], v[54:55]
	v_rcp_f32_e32 v62, v59
	v_mul_f32_e32 v59, 0xbfb8aa3b, v53
	v_exp_f32_e32 v59, v59
	v_rcp_f32_e32 v58, v58
	v_add_f32_e32 v59, 1.0, v59
	v_rcp_f32_e32 v59, v59
	s_nop 0
	v_pk_mul_f32 v[52:53], v[52:53], v[58:59]
	v_mul_f32_e32 v58, 0xbfb8aa3b, v57
	v_exp_f32_e32 v58, v58
	v_pk_mul_f32 v[52:53], v[60:61], v[52:53]
	v_add_f32_e32 v58, 1.0, v58
	v_rcp_f32_e32 v63, v58
	v_cvt_pk_bf16_f32 v51, v52, v53
	v_cvt_pk_bf16_f32 v52, v54, v55
	v_mad_i64_i32 v[54:55], s[0:1], v184, s35, v[130:131]
	v_pk_mul_f32 v[56:57], v[56:57], v[62:63]
	s_nop 0
	v_pk_mul_f32 v[56:57], v[64:65], v[56:57]
	s_nop 0
	v_cvt_pk_bf16_f32 v53, v56, v57
	global_store_dwordx4 v[54:55], v[50:53], off
	s_nop 1
	v_mul_f32_e32 v51, 0xbfb8aa3b, v38
	v_exp_f32_e32 v51, v51
	v_mul_f32_e32 v50, 0xbfb8aa3b, v34
	v_exp_f32_e32 v50, v50
	v_add_f32_e32 v51, 1.0, v51
	v_rcp_f32_e32 v52, v51
	v_mul_f32_e32 v51, 0xbfb8aa3b, v35
	v_exp_f32_e32 v51, v51
	v_add_f32_e32 v50, 1.0, v50
	v_rcp_f32_e32 v50, v50
	v_add_f32_e32 v51, 1.0, v51
	v_rcp_f32_e32 v51, v51
	s_nop 0
	v_pk_mul_f32 v[34:35], v[34:35], v[50:51]
	s_nop 0
	v_pk_mul_f32 v[34:35], v[42:43], v[34:35]
	v_mul_f32_e32 v42, 0xbfb8aa3b, v39
	v_exp_f32_e32 v42, v42
	v_mul_f32_e32 v43, 0xbfb8aa3b, v40
	v_exp_f32_e32 v43, v43
	v_cvt_pk_bf16_f32 v34, v34, v35
	v_add_f32_e32 v42, 1.0, v42
	v_rcp_f32_e32 v53, v42
	v_add_f32_e32 v43, 1.0, v43
	v_mul_f32_e32 v42, 0xbfb8aa3b, v36
	v_exp_f32_e32 v42, v42
	v_pk_mul_f32 v[38:39], v[38:39], v[52:53]
	v_add_f32_e32 v42, 1.0, v42
	v_pk_mul_f32 v[38:39], v[46:47], v[38:39]
	v_rcp_f32_e32 v46, v43
	v_mul_f32_e32 v43, 0xbfb8aa3b, v37
	v_exp_f32_e32 v43, v43
	v_rcp_f32_e32 v42, v42
	v_add_f32_e32 v43, 1.0, v43
	v_rcp_f32_e32 v43, v43
	s_nop 0
	v_pk_mul_f32 v[36:37], v[36:37], v[42:43]
	v_mul_f32_e32 v42, 0xbfb8aa3b, v41
	v_exp_f32_e32 v42, v42
	v_pk_mul_f32 v[36:37], v[44:45], v[36:37]
	v_add_f32_e32 v42, 1.0, v42
	v_rcp_f32_e32 v47, v42
	v_cvt_pk_bf16_f32 v35, v36, v37
	v_cvt_pk_bf16_f32 v36, v38, v39
	v_mad_i64_i32 v[38:39], s[0:1], v182, s35, v[130:131]
	v_pk_mul_f32 v[40:41], v[40:41], v[46:47]
	s_nop 0
	v_pk_mul_f32 v[40:41], v[48:49], v[40:41]
	s_nop 0
	v_cvt_pk_bf16_f32 v37, v40, v41
	global_store_dwordx4 v[38:39], v[34:37], off
	s_nop 1
	v_mul_f32_e32 v35, 0xbfb8aa3b, v22
	v_exp_f32_e32 v35, v35
	v_mul_f32_e32 v34, 0xbfb8aa3b, v18
	v_exp_f32_e32 v34, v34
	v_add_f32_e32 v35, 1.0, v35
	v_rcp_f32_e32 v36, v35
	v_mul_f32_e32 v35, 0xbfb8aa3b, v19
	v_exp_f32_e32 v35, v35
	v_add_f32_e32 v34, 1.0, v34
	v_rcp_f32_e32 v34, v34
	v_add_f32_e32 v35, 1.0, v35
	v_rcp_f32_e32 v35, v35
	s_nop 0
	v_pk_mul_f32 v[18:19], v[18:19], v[34:35]
	s_nop 0
	v_pk_mul_f32 v[18:19], v[26:27], v[18:19]
	v_mul_f32_e32 v26, 0xbfb8aa3b, v23
	v_exp_f32_e32 v26, v26
	v_mul_f32_e32 v27, 0xbfb8aa3b, v24
	v_exp_f32_e32 v27, v27
	v_cvt_pk_bf16_f32 v18, v18, v19
	v_add_f32_e32 v26, 1.0, v26
	v_rcp_f32_e32 v37, v26
	v_add_f32_e32 v27, 1.0, v27
	v_mul_f32_e32 v26, 0xbfb8aa3b, v20
	v_exp_f32_e32 v26, v26
	v_pk_mul_f32 v[22:23], v[22:23], v[36:37]
	v_add_f32_e32 v26, 1.0, v26
	v_pk_mul_f32 v[22:23], v[30:31], v[22:23]
	v_rcp_f32_e32 v30, v27
	v_mul_f32_e32 v27, 0xbfb8aa3b, v21
	v_exp_f32_e32 v27, v27
	v_rcp_f32_e32 v26, v26
	v_add_f32_e32 v27, 1.0, v27
	v_rcp_f32_e32 v27, v27
	s_nop 0
	v_pk_mul_f32 v[20:21], v[20:21], v[26:27]
	v_mul_f32_e32 v26, 0xbfb8aa3b, v25
	v_exp_f32_e32 v26, v26
	v_pk_mul_f32 v[20:21], v[28:29], v[20:21]
	v_add_f32_e32 v26, 1.0, v26
	v_rcp_f32_e32 v31, v26
	v_cvt_pk_bf16_f32 v19, v20, v21
	v_cvt_pk_bf16_f32 v20, v22, v23
	v_mad_i64_i32 v[22:23], s[0:1], v180, s35, v[130:131]
	v_pk_mul_f32 v[24:25], v[24:25], v[30:31]
	s_nop 0
	v_pk_mul_f32 v[24:25], v[32:33], v[24:25]
	s_nop 0
	v_cvt_pk_bf16_f32 v21, v24, v25
	global_store_dwordx4 v[22:23], v[18:21], off
	s_nop 1
	v_mul_f32_e32 v19, 0xbfb8aa3b, v4
	v_exp_f32_e32 v19, v19
	v_mul_f32_e32 v18, 0xbfb8aa3b, v0
	v_exp_f32_e32 v18, v18
	v_add_f32_e32 v19, 1.0, v19
	v_rcp_f32_e32 v20, v19
	v_mul_f32_e32 v19, 0xbfb8aa3b, v1
	v_exp_f32_e32 v19, v19
	v_add_f32_e32 v18, 1.0, v18
	v_rcp_f32_e32 v18, v18
	v_add_f32_e32 v19, 1.0, v19
	v_rcp_f32_e32 v19, v19
	s_nop 0
	v_pk_mul_f32 v[0:1], v[0:1], v[18:19]
	s_nop 0
	v_pk_mul_f32 v[0:1], v[10:11], v[0:1]
	v_mul_f32_e32 v10, 0xbfb8aa3b, v5
	v_exp_f32_e32 v10, v10
	v_mul_f32_e32 v11, 0xbfb8aa3b, v6
	v_exp_f32_e32 v11, v11
	v_cvt_pk_bf16_f32 v0, v0, v1
	v_add_f32_e32 v10, 1.0, v10
	v_rcp_f32_e32 v21, v10
	v_add_f32_e32 v11, 1.0, v11
	v_mul_f32_e32 v10, 0xbfb8aa3b, v2
	v_exp_f32_e32 v10, v10
	v_pk_mul_f32 v[4:5], v[4:5], v[20:21]
	v_add_f32_e32 v10, 1.0, v10
	v_pk_mul_f32 v[4:5], v[14:15], v[4:5]
	v_rcp_f32_e32 v14, v11
	v_mul_f32_e32 v11, 0xbfb8aa3b, v3
	v_exp_f32_e32 v11, v11
	v_rcp_f32_e32 v10, v10
	v_add_f32_e32 v11, 1.0, v11
	v_rcp_f32_e32 v11, v11
	s_nop 0
	v_pk_mul_f32 v[2:3], v[2:3], v[10:11]
	v_mul_f32_e32 v10, 0xbfb8aa3b, v7
	v_exp_f32_e32 v10, v10
	v_pk_mul_f32 v[2:3], v[12:13], v[2:3]
	v_add_f32_e32 v10, 1.0, v10
	v_rcp_f32_e32 v15, v10
	v_cvt_pk_bf16_f32 v1, v2, v3
	v_cvt_pk_bf16_f32 v2, v4, v5
	v_mad_i64_i32 v[4:5], s[0:1], v178, s35, v[130:131]
	v_pk_mul_f32 v[6:7], v[6:7], v[14:15]
	s_nop 0
	v_pk_mul_f32 v[6:7], v[16:17], v[6:7]
	s_nop 0
	v_cvt_pk_bf16_f32 v3, v6, v7
	global_store_dwordx4 v[4:5], v[0:3], off
	s_cbranch_vccz .LBB0_1669
; #define PG8_WAIT_V(n) asm volatile("s_waitcnt vmcnt(" #n ")" ::: "memory")
; #define PG8_BAR __builtin_amdgcn_s_barrier()
; template <class Epi>
; DEVI void gemm_phase(LAS unsigned char* lds, const Gemm g, const Epi& E) {
;     ...
;     PG8_WAIT_V(0);
;     if (wr == 0) PG8_BAR;
;     PG8_BAR;
	s_waitcnt vmcnt(0)
	s_cmpk_gt_u32 s66, 0xff
	s_cbranch_scc1 .LBB0_1676
	s_barrier

; #define PG8_STAGE(bufoff, gbase, voff) do { _Pragma("unroll") for (int _i = 0; _i < 2; ++_i) \
;         __builtin_amdgcn_global_load_lds((const unsigned*)((const char*)(gbase) + (voff)[_i]), (LAS unsigned*)(lds + (bufoff) + ldsw + _i * 8192), 16, 0, 0); } while (0)
; #define PG8_LDA(dst, b, h) do { _Pragma("unroll") for (int m = 0; m < 4; ++m) _Pragma("unroll") for (int k = 0; k < 2; ++k) dst[m][k] = *(const LAS bf16x8*)(lds + PG8_SA(b, h) + aoff + m * 2048 + k * 1024); } while (0)
; #define PG8_LDB(dst, b, h) do { _Pragma("unroll") for (int n = 0; n < 2; ++n) _Pragma("unroll") for (int k = 0; k < 2; ++k) dst[n][k] = *(const LAS bf16x8*)(lds + PG8_SB(b, h) + boff + n * 2048 + k * 1024); } while (0)
; #define PG8_MMA(ai, bj, At, Bt) do { __builtin_amdgcn_s_setprio(1); _Pragma("unroll") for (int m = 0; m < 4; ++m) _Pragma("unroll") for (int n = 0; n < 2; ++n) _Pragma("unroll") for (int k = 0; k < 2; ++k) \
;         acc[ai][bj][m][n] = __builtin_amdgcn_mfma_f32_16x16x32_bf16(Bt[n][k], At[m][k], acc[ai][bj][m][n], 0, 0, 0); __builtin_amdgcn_s_setprio(0); } while (0)
; #define PG8_WAIT_V(n) asm volatile("s_waitcnt vmcnt(" #n ")" ::: "memory")
; #define PG8_WAIT_L(n) asm volatile("s_waitcnt lgkmcnt(" #n ")" ::: "memory")
; #define PG8_BAR __builtin_amdgcn_s_barrier()
; template <class Epi>
; DEVI void gemm_phase(LAS unsigned char* lds, const Gemm g, const Epi& E) {
;     ...
;         for (int t = 0; t < nt; t += 2) {
;             const bool last = (t == nt - 2);
;             const char* a1 = cA + (size_t)(t + 1) * kstep;
;             const char* a2 = last ? nA : cA + (size_t)(t + 2) * kstep; const char* b2 = last ? nB : cB + (size_t)(t + 2) * kstep;
;             const char* a3 = a2 + kstep; const char* b3 = b2 + kstep;
;             PG8_LDB(B0, 0, 0); PG8_SCHED; PG8_LDA(At, 0, 0); PG8_STAGE(PG8_SA(1, 1), a1 + hstepA, voffA);
;             PG8_WAIT_L(8); PG8_BAR; PG8_WAIT_L(0); PG8_MMA(0, 0, At, B0); PG8_BAR; PG8_SCHED;
;             PG8_LDB(B1, 0, 1); PG8_STAGE(PG8_SB(0, 0), b2, voffB);
;             PG8_BAR; PG8_WAIT_L(0); PG8_MMA(0, 1, At, B1); PG8_BAR;
;             PG8_LDA(At, 0, 1); PG8_STAGE(PG8_SA(0, 0), a2, voffA);
;             PG8_BAR; PG8_WAIT_L(0); PG8_MMA(1, 0, At, B0); PG8_BAR; PG8_SCHED;
;             PG8_STAGE(PG8_SB(0, 1), b2 + hstepB, voffB);
;             PG8_WAIT_V(6); PG8_BAR; PG8_MMA(1, 1, At, B1); PG8_BAR;
.LBB0_1747:
	s_add_u32 s36, s16, 0x100
	s_addc_u32 s37, s17, 0
	s_add_i32 s19, 0, 0x10000
	v_add_u32_e32 v142, s19, v191
	ds_read_b128 v[130:133], v142
	ds_read_b128 v[134:137], v142 offset:1024
	ds_read_b128 v[138:141], v142 offset:2048
	ds_read_b128 v[142:145], v142 offset:3072
	s_cmp_eq_u32 s18, 40
	s_cselect_b32 s69, s9, s37
	s_cselect_b32 s68, s8, s36
	s_cselect_b32 s47, s11, s13
	s_cselect_b32 s46, s10, s1
	s_add_i32 m0, s81, 0xc000
	ds_read_b128 v[178:181], v196
	ds_read_b128 v[182:185], v196 offset:1024
	ds_read_b128 v[186:189], v196 offset:2048
	ds_read_b128 v[198:201], v196 offset:3072
	ds_read_b128 v[202:205], v196 offset:4096
	ds_read_b128 v[206:209], v196 offset:5120
	ds_read_b128 v[214:217], v196 offset:6144
	ds_read_b128 v[218:221], v196 offset:7168
	global_load_lds_dwordx4 v152, s[16:17]
	s_add_i32 m0, s81, 0xe000
	s_nop 0
	global_load_lds_dwordx4 v176, s[16:17]
	s_waitcnt lgkmcnt(8)
	s_barrier
	s_waitcnt lgkmcnt(0)
	v_mfma_f32_16x16x32_bf16 v[126:129], v[130:133], v[178:181], v[126:129]
	v_mfma_f32_16x16x32_bf16 v[122:125], v[138:141], v[178:181], v[122:125]
	v_mfma_f32_16x16x32_bf16 v[110:113], v[130:133], v[186:189], v[110:113]
	v_mfma_f32_16x16x32_bf16 v[106:109], v[138:141], v[186:189], v[106:109]
	v_mfma_f32_16x16x32_bf16 v[94:97], v[130:133], v[202:205], v[94:97]
	v_mfma_f32_16x16x32_bf16 v[90:93], v[138:141], v[202:205], v[90:93]
	v_mfma_f32_16x16x32_bf16 v[78:81], v[130:133], v[214:217], v[78:81]
	v_mfma_f32_16x16x32_bf16 v[74:77], v[138:141], v[214:217], v[74:77]
	v_mfma_f32_16x16x32_bf16 v[126:129], v[134:137], v[182:185], v[126:129]
	v_mfma_f32_16x16x32_bf16 v[122:125], v[142:145], v[182:185], v[122:125]
	v_mfma_f32_16x16x32_bf16 v[110:113], v[134:137], v[198:201], v[110:113]
	v_mfma_f32_16x16x32_bf16 v[106:109], v[142:145], v[198:201], v[106:109]
	v_mfma_f32_16x16x32_bf16 v[94:97], v[134:137], v[206:209], v[94:97]
	v_mfma_f32_16x16x32_bf16 v[90:93], v[142:145], v[206:209], v[90:93]
	v_mfma_f32_16x16x32_bf16 v[78:81], v[134:137], v[218:221], v[78:81]
	v_mfma_f32_16x16x32_bf16 v[74:77], v[142:145], v[218:221], v[74:77]
	s_barrier
	s_add_i32 s26, 0, 0x14000
	v_add_u32_e32 v162, s26, v191
	s_add_i32 s16, s19, s80
	ds_read_b128 v[222:225], v162
	ds_read_b128 v[226:229], v162 offset:1024
	ds_read_b128 v[230:233], v162 offset:2048
	ds_read_b128 v[234:237], v162 offset:3072
	v_lshl_add_u64 v[162:163], s[46:47], 0, v[8:9]
	s_mov_b32 m0, s16
	v_lshl_add_u64 v[164:165], s[46:47], 0, v[150:151]
	global_load_lds_dwordx4 v[162:163], off
	s_add_i32 m0, s16, 0x2000
	s_nop 0
	global_load_lds_dwordx4 v[164:165], off
	s_barrier
	s_waitcnt lgkmcnt(0)
	v_mfma_f32_16x16x32_bf16 v[118:121], v[222:225], v[178:181], v[118:121]
	v_mfma_f32_16x16x32_bf16 v[114:117], v[230:233], v[178:181], v[114:117]
	v_mfma_f32_16x16x32_bf16 v[102:105], v[222:225], v[186:189], v[102:105]
	v_mfma_f32_16x16x32_bf16 v[98:101], v[230:233], v[186:189], v[98:101]
	v_mfma_f32_16x16x32_bf16 v[86:89], v[222:225], v[202:205], v[86:89]
	v_mfma_f32_16x16x32_bf16 v[82:85], v[230:233], v[202:205], v[82:85]
	v_mfma_f32_16x16x32_bf16 v[70:73], v[222:225], v[214:217], v[70:73]
	v_mfma_f32_16x16x32_bf16 v[66:69], v[230:233], v[214:217], v[66:69]
	v_mfma_f32_16x16x32_bf16 v[118:121], v[226:229], v[182:185], v[118:121]
	v_mfma_f32_16x16x32_bf16 v[114:117], v[234:237], v[182:185], v[114:117]
	v_mfma_f32_16x16x32_bf16 v[102:105], v[226:229], v[198:201], v[102:105]
	v_mfma_f32_16x16x32_bf16 v[98:101], v[234:237], v[198:201], v[98:101]
	v_mfma_f32_16x16x32_bf16 v[86:89], v[226:229], v[206:209], v[86:89]
	v_mfma_f32_16x16x32_bf16 v[82:85], v[234:237], v[206:209], v[82:85]
	v_mfma_f32_16x16x32_bf16 v[70:73], v[226:229], v[218:221], v[70:73]
	v_mfma_f32_16x16x32_bf16 v[66:69], v[234:237], v[218:221], v[66:69]
	s_mov_b32 m0, s81
	v_lshl_add_u64 v[238:239], s[68:69], 0, v[146:147]
	s_barrier
	ds_read_b128 v[178:181], v196 offset:16384
	ds_read_b128 v[182:185], v196 offset:17408
	ds_read_b128 v[186:189], v196 offset:18432
	ds_read_b128 v[198:201], v196 offset:19456
	ds_read_b128 v[202:205], v196 offset:20480
	ds_read_b128 v[206:209], v196 offset:21504
	ds_read_b128 v[214:217], v196 offset:22528
	ds_read_b128 v[218:221], v196 offset:23552
	global_load_lds_dwordx4 v[238:239], off
	s_mov_b32 m0, s82
	v_lshl_add_u64 v[240:241], s[68:69], 0, v[148:149]
	global_load_lds_dwordx4 v[240:241], off
	s_barrier
	s_waitcnt lgkmcnt(0)
	v_mfma_f32_16x16x32_bf16 v[62:65], v[130:133], v[178:181], v[62:65]
	v_mfma_f32_16x16x32_bf16 v[58:61], v[138:141], v[178:181], v[58:61]
	v_mfma_f32_16x16x32_bf16 v[46:49], v[130:133], v[186:189], v[46:49]
	v_mfma_f32_16x16x32_bf16 v[42:45], v[138:141], v[186:189], v[42:45]
	v_mfma_f32_16x16x32_bf16 v[30:33], v[130:133], v[202:205], v[30:33]
	v_mfma_f32_16x16x32_bf16 v[26:29], v[138:141], v[202:205], v[26:29]
	v_mfma_f32_16x16x32_bf16 v[14:17], v[130:133], v[214:217], v[14:17]
	v_mfma_f32_16x16x32_bf16 v[10:13], v[138:141], v[214:217], v[10:13]
	v_mfma_f32_16x16x32_bf16 v[62:65], v[134:137], v[182:185], v[62:65]
	v_mfma_f32_16x16x32_bf16 v[58:61], v[142:145], v[182:185], v[58:61]
	v_mfma_f32_16x16x32_bf16 v[46:49], v[134:137], v[198:201], v[46:49]
	v_mfma_f32_16x16x32_bf16 v[42:45], v[142:145], v[198:201], v[42:45]
	v_mfma_f32_16x16x32_bf16 v[30:33], v[134:137], v[206:209], v[30:33]
	v_mfma_f32_16x16x32_bf16 v[26:29], v[142:145], v[206:209], v[26:29]
	v_mfma_f32_16x16x32_bf16 v[14:17], v[134:137], v[218:221], v[14:17]
	v_mfma_f32_16x16x32_bf16 v[10:13], v[142:145], v[218:221], v[10:13]
	s_barrier
	s_add_u32 s16, s46, 0xb0000
	s_addc_u32 s17, s47, 0
	s_add_i32 s19, s26, s80
	s_mov_b32 m0, s19
	s_nop 0
	global_load_lds_dwordx4 v8, s[16:17]
	s_add_i32 m0, s19, 0x2000
	s_nop 0
	global_load_lds_dwordx4 v150, s[16:17]
	s_waitcnt vmcnt(6)
	s_barrier
; #define PG8_STAGE(bufoff, gbase, voff) do { _Pragma("unroll") for (int _i = 0; _i < 2; ++_i) \
;         __builtin_amdgcn_global_load_lds((const unsigned*)((const char*)(gbase) + (voff)[_i]), (LAS unsigned*)(lds + (bufoff) + ldsw + _i * 8192), 16, 0, 0); } while (0)
; #define PG8_LDA(dst, b, h) do { _Pragma("unroll") for (int m = 0; m < 4; ++m) _Pragma("unroll") for (int k = 0; k < 2; ++k) dst[m][k] = *(const LAS bf16x8*)(lds + PG8_SA(b, h) + aoff + m * 2048 + k * 1024); } while (0)
; #define PG8_LDB(dst, b, h) do { _Pragma("unroll") for (int n = 0; n < 2; ++n) _Pragma("unroll") for (int k = 0; k < 2; ++k) dst[n][k] = *(const LAS bf16x8*)(lds + PG8_SB(b, h) + boff + n * 2048 + k * 1024); } while (0)
; #define PG8_MMA(ai, bj, At, Bt) do { __builtin_amdgcn_s_setprio(1); _Pragma("unroll") for (int m = 0; m < 4; ++m) _Pragma("unroll") for (int n = 0; n < 2; ++n) _Pragma("unroll") for (int k = 0; k < 2; ++k) \
;         acc[ai][bj][m][n] = __builtin_amdgcn_mfma_f32_16x16x32_bf16(Bt[n][k], At[m][k], acc[ai][bj][m][n], 0, 0, 0); __builtin_amdgcn_s_setprio(0); } while (0)
; #define PG8_WAIT_V(n) asm volatile("s_waitcnt vmcnt(" #n ")" ::: "memory")
; #define PG8_WAIT_L(n) asm volatile("s_waitcnt lgkmcnt(" #n ")" ::: "memory")
; #define PG8_BAR __builtin_amdgcn_s_barrier()
; #define PG8_SCHED __builtin_amdgcn_sched_barrier(0)
; template <class Epi>
; DEVI void gemm_phase(LAS unsigned char* lds, const Gemm g, const Epi& E) {
;     ...
;             PG8_WAIT_V(6); PG8_BAR; PG8_MMA(1, 1, At, B1); PG8_BAR;
;             PG8_LDB(B0, 1, 0); PG8_SCHED; PG8_LDA(At, 1, 0); PG8_STAGE(PG8_SA(0, 1), a2 + hstepA, voffA);
;             PG8_WAIT_L(8); PG8_BAR; PG8_WAIT_L(0); PG8_MMA(0, 0, At, B0); PG8_BAR; PG8_SCHED;
;             PG8_LDB(B1, 1, 1); PG8_STAGE(PG8_SB(1, 0), b3, voffB);
;             PG8_BAR; PG8_WAIT_L(0); PG8_MMA(0, 1, At, B1); PG8_BAR;
;             PG8_LDA(At, 1, 1); PG8_STAGE(PG8_SA(1, 0), a3, voffA);
;             PG8_BAR; PG8_WAIT_L(0); PG8_MMA(1, 0, At, B0); PG8_BAR; PG8_SCHED;
	v_mfma_f32_16x16x32_bf16 v[54:57], v[222:225], v[178:181], v[54:57]
	v_mfma_f32_16x16x32_bf16 v[50:53], v[230:233], v[178:181], v[50:53]
	v_mfma_f32_16x16x32_bf16 v[38:41], v[222:225], v[186:189], v[38:41]
	v_mfma_f32_16x16x32_bf16 v[34:37], v[230:233], v[186:189], v[34:37]
	v_mfma_f32_16x16x32_bf16 v[22:25], v[222:225], v[202:205], v[22:25]
	v_mfma_f32_16x16x32_bf16 v[18:21], v[230:233], v[202:205], v[18:21]
	v_mfma_f32_16x16x32_bf16 v[4:7], v[222:225], v[214:217], v[4:7]
	v_mfma_f32_16x16x32_bf16 v[0:3], v[230:233], v[214:217], v[0:3]
	v_mfma_f32_16x16x32_bf16 v[54:57], v[226:229], v[182:185], v[54:57]
	v_mfma_f32_16x16x32_bf16 v[50:53], v[234:237], v[182:185], v[50:53]
	v_mfma_f32_16x16x32_bf16 v[38:41], v[226:229], v[198:201], v[38:41]
	v_mfma_f32_16x16x32_bf16 v[34:37], v[234:237], v[198:201], v[34:37]
	v_mfma_f32_16x16x32_bf16 v[22:25], v[226:229], v[206:209], v[22:25]
	v_mfma_f32_16x16x32_bf16 v[18:21], v[234:237], v[206:209], v[18:21]
	v_mfma_f32_16x16x32_bf16 v[4:7], v[226:229], v[218:221], v[4:7]
	v_mfma_f32_16x16x32_bf16 v[0:3], v[234:237], v[218:221], v[0:3]
	s_add_i32 s19, 0, 0x18000
	v_add_u32_e32 v142, s19, v191
	s_barrier
	ds_read_b128 v[130:133], v142
	ds_read_b128 v[134:137], v142 offset:1024
	ds_read_b128 v[138:141], v142 offset:2048
	ds_read_b128 v[142:145], v142 offset:3072
	s_add_u32 s16, s68, 0xb0000
	s_addc_u32 s17, s69, 0
	s_mov_b32 m0, s83
	ds_read_b128 v[178:181], v196 offset:32768
	ds_read_b128 v[182:185], v196 offset:33792
	ds_read_b128 v[186:189], v196 offset:34816
	ds_read_b128 v[198:201], v196 offset:35840
	ds_read_b128 v[202:205], v196 offset:36864
	ds_read_b128 v[206:209], v196 offset:37888
	ds_read_b128 v[214:217], v196 offset:38912
	ds_read_b128 v[218:221], v196 offset:39936
	global_load_lds_dwordx4 v146, s[16:17]
	s_mov_b32 m0, s84
	s_nop 0
	global_load_lds_dwordx4 v148, s[16:17]
	s_waitcnt lgkmcnt(8)
	s_barrier
	s_waitcnt lgkmcnt(0)
	v_mfma_f32_16x16x32_bf16 v[126:129], v[130:133], v[178:181], v[126:129]
	v_mfma_f32_16x16x32_bf16 v[122:125], v[138:141], v[178:181], v[122:125]
	v_mfma_f32_16x16x32_bf16 v[110:113], v[130:133], v[186:189], v[110:113]
	v_mfma_f32_16x16x32_bf16 v[106:109], v[138:141], v[186:189], v[106:109]
	v_mfma_f32_16x16x32_bf16 v[94:97], v[130:133], v[202:205], v[94:97]
	v_mfma_f32_16x16x32_bf16 v[90:93], v[138:141], v[202:205], v[90:93]
	v_mfma_f32_16x16x32_bf16 v[78:81], v[130:133], v[214:217], v[78:81]
	v_mfma_f32_16x16x32_bf16 v[74:77], v[138:141], v[214:217], v[74:77]
	v_mfma_f32_16x16x32_bf16 v[126:129], v[134:137], v[182:185], v[126:129]
	v_mfma_f32_16x16x32_bf16 v[122:125], v[142:145], v[182:185], v[122:125]
	v_mfma_f32_16x16x32_bf16 v[110:113], v[134:137], v[198:201], v[110:113]
	v_mfma_f32_16x16x32_bf16 v[106:109], v[142:145], v[198:201], v[106:109]
	v_mfma_f32_16x16x32_bf16 v[94:97], v[134:137], v[206:209], v[94:97]
	v_mfma_f32_16x16x32_bf16 v[90:93], v[142:145], v[206:209], v[90:93]
	v_mfma_f32_16x16x32_bf16 v[78:81], v[134:137], v[218:221], v[78:81]
	v_mfma_f32_16x16x32_bf16 v[74:77], v[142:145], v[218:221], v[74:77]
	s_barrier
	s_add_i32 s26, 0, 0x1c000
	s_add_i32 s16, s19, s80
	v_add_u32_e32 v197, s26, v191
	v_lshl_add_u64 v[162:163], v[162:163], 0, s[70:71]
	s_mov_b32 m0, s16
	ds_read_b128 v[222:225], v197
	ds_read_b128 v[226:229], v197 offset:1024
	ds_read_b128 v[230:233], v197 offset:2048
	ds_read_b128 v[234:237], v197 offset:3072
	global_load_lds_dwordx4 v[162:163], off
	s_add_i32 m0, s16, 0x2000
	v_lshl_add_u64 v[162:163], v[164:165], 0, s[70:71]
	global_load_lds_dwordx4 v[162:163], off
	s_barrier
	s_waitcnt lgkmcnt(0)
	v_mfma_f32_16x16x32_bf16 v[118:121], v[222:225], v[178:181], v[118:121]
	v_mfma_f32_16x16x32_bf16 v[114:117], v[230:233], v[178:181], v[114:117]
	v_mfma_f32_16x16x32_bf16 v[102:105], v[222:225], v[186:189], v[102:105]
	v_mfma_f32_16x16x32_bf16 v[98:101], v[230:233], v[186:189], v[98:101]
	v_mfma_f32_16x16x32_bf16 v[86:89], v[222:225], v[202:205], v[86:89]
	v_mfma_f32_16x16x32_bf16 v[82:85], v[230:233], v[202:205], v[82:85]
	v_mfma_f32_16x16x32_bf16 v[70:73], v[222:225], v[214:217], v[70:73]
	v_mfma_f32_16x16x32_bf16 v[66:69], v[230:233], v[214:217], v[66:69]
	v_mfma_f32_16x16x32_bf16 v[118:121], v[226:229], v[182:185], v[118:121]
	v_mfma_f32_16x16x32_bf16 v[114:117], v[234:237], v[182:185], v[114:117]
	v_mfma_f32_16x16x32_bf16 v[102:105], v[226:229], v[198:201], v[102:105]
	v_mfma_f32_16x16x32_bf16 v[98:101], v[234:237], v[198:201], v[98:101]
	v_mfma_f32_16x16x32_bf16 v[86:89], v[226:229], v[206:209], v[86:89]
	v_mfma_f32_16x16x32_bf16 v[82:85], v[234:237], v[206:209], v[82:85]
	v_mfma_f32_16x16x32_bf16 v[70:73], v[226:229], v[218:221], v[70:73]
	v_mfma_f32_16x16x32_bf16 v[66:69], v[234:237], v[218:221], v[66:69]
	s_mov_b32 m0, s76
	v_lshl_add_u64 v[162:163], v[238:239], 0, s[70:71]
	s_barrier
	ds_read_b128 v[178:181], v196 offset:49152
	ds_read_b128 v[182:185], v196 offset:50176
	ds_read_b128 v[186:189], v196 offset:51200
	ds_read_b128 v[198:201], v196 offset:52224
	ds_read_b128 v[202:205], v196 offset:53248
	ds_read_b128 v[206:209], v196 offset:54272
	ds_read_b128 v[214:217], v196 offset:55296
	ds_read_b128 v[218:221], v196 offset:56320
	global_load_lds_dwordx4 v[162:163], off
	s_mov_b32 m0, s77
	v_lshl_add_u64 v[162:163], v[240:241], 0, s[70:71]
	global_load_lds_dwordx4 v[162:163], off
	s_barrier
; #define LAS __attribute__((address_space(3)))
;     DEVI f32x4 load(int r, int c) const { const bf16x4 y = *(const bf16x4*)(Y + (size_t)r * DM + c); return (f32x4){bf2f((u16)y[0]), bf2f((u16)y[1]), bf2f((u16)y[2]), bf2f((u16)y[3])}; }
; template <class Epi>
; DEVI void gemm_phase(LAS unsigned char* lds, const Gemm g, const Epi& E) {
;     ...
;             for (int am = 0; am < 4; ++am) {
;                 const int ai = am >> 1, m0 = (am & 1) * 2;
;                 f32x4 pre[2][2][2];
;                 if constexpr (Epi::PRE) {
; #pragma unroll
;                     for (int m = 0; m < 2; ++m)
; #pragma unroll
;                         for (int bj = 0; bj < 2; ++bj)
; #pragma unroll
;                             for (int n = 0; n < 2; ++n) pre[m][bj][n] = E.load(row0 + ai * HALF + (m0 + m) * 16, col0 + bj * HALF + n * NST);
;                 }
; #pragma unroll
;                 for (int mm = 0; mm < 2; ++mm) {
;                     const int m = m0 + mm;
;                     const int r = row0 + ai * HALF + m * 16; float rs = 1.f, part = 0.f;
;                     if constexpr (Epi::RS) rs = rsv[ai * 4 + m];
;                     if constexpr (Epi::PAIR) E.pair8(cur.b, r, cur.pn * HALF + wc * 32 + 8 * fq, acc[ai][0][m][0] * rs, acc[ai][0][m][1] * rs, acc[ai][1][m][0] * rs, acc[ai][1][m][1] * rs);
;                     else
; #pragma unroll
;                     for (int bj = 0; bj < 2; ++bj) {
;                         const int c = col0 + bj * HALF; f32x4 v0 = acc[ai][bj][m][0], v1 = acc[ai][bj][m][1];
;                         if constexpr (Epi::RS) { v0 = v0 * rs; v1 = v1 * rs; }
;                         if constexpr (Epi::PRE) part += E.frag_pre8(cur.b, r, c, v0, v1, pre[mm][bj][0], pre[mm][bj][1]);
;                         else if constexpr (Epi::PERM) E.frag8(cur.b, r, c, v0, v1);
;                         else { E.frag(cur.b, r, c, v0); E.frag(cur.b, r, c + 16, v1); }
;                     }
;                     if constexpr (Epi::SSQ) { part += __shfl_xor(part, 16); part += __shfl_xor(part, 32); if (fq == 0) ((LAS float*)(lds + 131072))[(wr * 4 + wc) * 128 + ai * 64 + m * 16 + fr] = part; }
	s_waitcnt lgkmcnt(0)
	v_mfma_f32_16x16x32_bf16 v[62:65], v[130:133], v[178:181], v[62:65]
	v_mfma_f32_16x16x32_bf16 v[58:61], v[138:141], v[178:181], v[58:61]
	v_mfma_f32_16x16x32_bf16 v[46:49], v[130:133], v[186:189], v[46:49]
	v_mfma_f32_16x16x32_bf16 v[42:45], v[138:141], v[186:189], v[42:45]
	v_mfma_f32_16x16x32_bf16 v[30:33], v[130:133], v[202:205], v[30:33]
	v_mfma_f32_16x16x32_bf16 v[26:29], v[138:141], v[202:205], v[26:29]
	v_mfma_f32_16x16x32_bf16 v[14:17], v[130:133], v[214:217], v[14:17]
	v_mfma_f32_16x16x32_bf16 v[10:13], v[138:141], v[214:217], v[10:13]
	v_mfma_f32_16x16x32_bf16 v[62:65], v[134:137], v[182:185], v[62:65]
	v_mfma_f32_16x16x32_bf16 v[58:61], v[142:145], v[182:185], v[58:61]
	v_mfma_f32_16x16x32_bf16 v[46:49], v[134:137], v[198:201], v[46:49]
	v_mfma_f32_16x16x32_bf16 v[42:45], v[142:145], v[198:201], v[42:45]
	v_mfma_f32_16x16x32_bf16 v[30:33], v[134:137], v[206:209], v[30:33]
	v_mfma_f32_16x16x32_bf16 v[26:29], v[142:145], v[206:209], v[26:29]
	v_mfma_f32_16x16x32_bf16 v[14:17], v[134:137], v[218:221], v[14:17]
	v_mfma_f32_16x16x32_bf16 v[10:13], v[142:145], v[218:221], v[10:13]
	s_barrier
	s_add_u32 s16, s46, 0xb0080
	s_addc_u32 s17, s47, 0
	s_add_i32 s19, s26, s80
	s_mov_b32 m0, s19
	s_nop 0
	global_load_lds_dwordx4 v8, s[16:17]
	s_add_i32 m0, s19, 0x2000
	s_nop 0
	global_load_lds_dwordx4 v150, s[16:17]
	s_waitcnt vmcnt(6)
	s_barrier
	v_mfma_f32_16x16x32_bf16 v[54:57], v[222:225], v[178:181], v[54:57]
	v_mfma_f32_16x16x32_bf16 v[50:53], v[230:233], v[178:181], v[50:53]
	v_mfma_f32_16x16x32_bf16 v[38:41], v[222:225], v[186:189], v[38:41]
	v_mfma_f32_16x16x32_bf16 v[34:37], v[230:233], v[186:189], v[34:37]
	v_mfma_f32_16x16x32_bf16 v[22:25], v[222:225], v[202:205], v[22:25]
	v_mfma_f32_16x16x32_bf16 v[18:21], v[230:233], v[202:205], v[18:21]
	v_mfma_f32_16x16x32_bf16 v[4:7], v[222:225], v[214:217], v[4:7]
	v_mfma_f32_16x16x32_bf16 v[0:3], v[230:233], v[214:217], v[0:3]
	v_mfma_f32_16x16x32_bf16 v[54:57], v[226:229], v[182:185], v[54:57]
	v_mfma_f32_16x16x32_bf16 v[50:53], v[234:237], v[182:185], v[50:53]
	v_mfma_f32_16x16x32_bf16 v[38:41], v[226:229], v[198:201], v[38:41]
	v_mfma_f32_16x16x32_bf16 v[34:37], v[234:237], v[198:201], v[34:37]
	v_mfma_f32_16x16x32_bf16 v[22:25], v[226:229], v[206:209], v[22:25]
	v_mfma_f32_16x16x32_bf16 v[18:21], v[234:237], v[206:209], v[18:21]
	v_mfma_f32_16x16x32_bf16 v[4:7], v[226:229], v[218:221], v[4:7]
	v_mfma_f32_16x16x32_bf16 v[0:3], v[234:237], v[218:221], v[0:3]
	s_add_i32 s18, s18, 2
	s_add_u32 s1, s1, 0x100
	s_addc_u32 s13, s13, 0
	s_cmp_gt_u32 s18, 41
	s_mov_b64 s[16:17], s[36:37]
	s_barrier
	s_cbranch_scc0 .LBB0_1747
	s_setprio 0
	s_lshl_b32 s0, s0, 8
	v_add_u32_e32 v182, s0, v190
	v_lshl_or_b32 v180, s12, 8, v195
	v_ashrrev_i32_e32 v183, 31, v182
	v_lshlrev_b64 v[130:131], 12, v[182:183]
	v_ashrrev_i32_e32 v181, 31, v180
	v_lshl_add_u64 v[130:131], s[30:31], 0, v[130:131]
	v_lshlrev_b64 v[184:185], 2, v[180:181]
	v_lshl_add_u64 v[162:163], v[130:131], 0, v[184:185]
	global_load_dwordx4 v[200:203], v[162:163], off
	global_load_dwordx4 v[204:207], v[162:163], off offset:16
	global_load_dwordx4 v[214:217], v[162:163], off offset:512
	global_load_dwordx4 v[218:221], v[162:163], off offset:528
	v_or_b32_e32 v188, 16, v182
	v_ashrrev_i32_e32 v189, 31, v188
	v_lshlrev_b64 v[130:131], 12, v[188:189]
	v_lshl_add_u64 v[130:131], s[30:31], 0, v[130:131]
	v_lshl_add_u64 v[186:187], v[130:131], 0, v[184:185]
	global_load_dwordx4 v[138:141], v[186:187], off offset:16
	global_load_dwordx4 v[142:145], v[186:187], off
	global_load_dwordx4 v[130:133], v[186:187], off offset:528
	global_load_dwordx4 v[134:137], v[186:187], off offset:512
	v_and_b32_e32 v165, 64, v155
	v_xor_b32_e32 v164, 16, v155
	v_add_u32_e32 v165, 64, v165
	v_xor_b32_e32 v179, 32, v155
	v_cmp_lt_i32_e32 vcc, v164, v165
	v_or_b32_e32 v178, 0x80, v180
	s_waitcnt vmcnt(0)
	v_pk_add_f32 v[128:129], v[128:129], v[202:203]
	v_cndmask_b32_e32 v164, v155, v164, vcc
	v_cmp_lt_i32_e32 vcc, v179, v165
	v_lshlrev_b32_e32 v198, 2, v164
	v_pk_add_f32 v[126:127], v[126:127], v[200:201]
	v_cndmask_b32_e32 v165, v155, v179, vcc
	v_lshlrev_b32_e32 v197, 2, v165
	v_lshlrev_b64 v[164:165], 10, v[182:183]
	v_pk_add_f32 v[124:125], v[124:125], v[206:207]
	v_pk_add_f32 v[122:123], v[122:123], v[204:205]
	v_pk_add_f32 v[120:121], v[120:121], v[216:217]
	v_pk_add_f32 v[118:119], v[118:119], v[214:215]
	v_pk_add_f32 v[202:203], v[116:117], v[220:221]
	v_pk_add_f32 v[200:201], v[114:115], v[218:219]
	v_lshl_add_u64 v[208:209], v[164:165], 0, v[180:181]
	global_store_dwordx4 v[162:163], v[126:129], off
	global_store_dwordx4 v[162:163], v[122:125], off offset:16
	v_cvt_pk_bf16_f32 v114, v126, v127
	v_cvt_pk_bf16_f32 v115, v128, v129
	v_cvt_pk_bf16_f32 v116, v122, v123
	v_cvt_pk_bf16_f32 v117, v124, v125
	v_mul_f32_e32 v127, v127, v127
	v_mul_f32_e32 v129, v129, v129
	v_mul_f32_e32 v123, v123, v123
	v_mul_f32_e32 v125, v125, v125
	v_mul_f32_e32 v183, v119, v119
	v_mul_f32_e32 v199, v121, v121
	v_mul_f32_e32 v204, v201, v201
	v_mul_f32_e32 v205, v203, v203
	v_lshl_add_u64 v[208:209], v[208:209], 1, s[24:25]
	v_fmac_f32_e32 v127, v126, v126
	v_fmac_f32_e32 v129, v128, v128
	v_fmac_f32_e32 v123, v122, v122
	v_fmac_f32_e32 v125, v124, v124
	v_fmac_f32_e32 v183, v118, v118
	v_fmac_f32_e32 v199, v120, v120
	v_fmac_f32_e32 v204, v200, v200
	v_fmac_f32_e32 v205, v202, v202
	global_store_dwordx4 v[208:209], v[114:117], off
	v_ashrrev_i32_e32 v179, 31, v178
	v_lshl_add_u64 v[164:165], v[164:165], 0, v[178:179]
	v_add_f32_e32 v114, v127, v129
	v_add_f32_e32 v115, v123, v125
	v_add_f32_e32 v116, v183, v199
	v_add_f32_e32 v117, v204, v205
	v_add_f32_e32 v114, v114, v115
	v_add_f32_e32 v115, v116, v117
	v_add_f32_e32 v114, v114, v115
	ds_bpermute_b32 v115, v198, v114
	global_store_dwordx4 v[162:163], v[118:121], off offset:512
	global_store_dwordx4 v[162:163], v[200:203], off offset:528
	v_cvt_pk_bf16_f32 v116, v118, v119
	v_cvt_pk_bf16_f32 v117, v120, v121
	v_cvt_pk_bf16_f32 v118, v200, v201
	s_waitcnt lgkmcnt(0)
	v_add_f32_e32 v114, v114, v115
	ds_bpermute_b32 v115, v197, v114
	v_cvt_pk_bf16_f32 v119, v202, v203
	v_lshl_add_u64 v[120:121], v[164:165], 1, s[24:25]
	global_store_dwordx4 v[120:121], v[116:119], off
	s_and_saveexec_b64 s[16:17], s[2:3]
	s_cbranch_execz .LBB0_1750
	s_waitcnt lgkmcnt(0)
	v_add_f32_e32 v114, v114, v115
	ds_write_b32 v192, v114
